# scan consumer loop: each step's LDS read burst re-issued in first-use order (a first, then w/v/k, b, r) with all lgkmcnt waits of the loop body re-derived
# baseline (speedup 1.0000x reference)
; #define SCAN_STEP(w0, w1, a0, a1, b0, b1, k0, k1, r0, r1, vi, vj, t) do { \
;                 SCAN_ROW(S0, S1, S2, S3, w0, w1, a0, a1, b0, b1, k0, k1, r0, r1, vi, (t) * 512); \
;                 SCAN_ROW(T0, T1, T2, T3, w0, w1, a0, a1, b0, b1, k0, k1, r0, r1, vj, (t) * 512 + 256); } while (0)
;     ...
;             const float* bb = bufs + (c & 1) * (16 * 384) + js;
;             const float* bv = bufs + (c & 1) * (16 * 384) + 320 + i0;
;             float* yb = ybuf + (c & 1) * 8192 + w * 64 + lane;
;             f32x4 w0, w1, a0, a1, b0, b1, k0, k1, r0, r1; float vi, vj;
;             f32x4 W0, W1, A0, A1, B0, B1, K0, K1, R0, R1; float VI, VJ;
;     ...
;             SCAN_LOAD(w0, w1, a0, a1, b0, b1, k0, k1, r0, r1, vi, vj, 0);
; #pragma unroll
;             for (int t = 0; t < 16; t += 2) {
;                 SCAN_LOAD(W0, W1, A0, A1, B0, B1, K0, K1, R0, R1, VI, VJ, t + 1);
;                 SCAN_STEP(w0, w1, a0, a1, b0, b1, k0, k1, r0, r1, vi, vj, t);
.LBB0_1395:
	s_and_b32 s8, s1, 1
	s_mul_i32 s9, s8, 0x6000
	v_lshl_add_u32 v27, s8, 15, v18
	s_add_i32 s8, s9, 0
	v_lshl_add_u32 v21, v16, 2, s8
	v_lshl_add_u32 v20, v17, 2, s8
	v_add_u32_e32 v29, 0x400, v21
	v_add_u32_e32 v112, 0x800, v21
	ds_read_b128 v[38:41], v20 offset:256
	ds_read_b128 v[42:45], v20 offset:272
	ds_read_b128 v[54:57], v20 offset:768
	ds_read2_b32 v[110:111], v29 offset0:64 offset1:72
	ds_read_b128 v[58:61], v20 offset:784
	ds_read_b128 v[30:33], v20
	ds_read_b128 v[34:37], v20 offset:16
	ds_read_b128 v[46:49], v20 offset:512
	ds_read_b128 v[50:53], v20 offset:528
	ds_read_b128 v[62:65], v20 offset:1024
	ds_read_b128 v[66:69], v20 offset:1040
	ds_read_b128 v[78:81], v20 offset:1792
	ds_read_b128 v[82:85], v20 offset:1808
	ds_read2_b32 v[112:113], v112 offset0:192 offset1:200
	s_waitcnt vmcnt(3)
	ds_read_b128 v[70:73], v20 offset:1536
	ds_read_b128 v[74:77], v20 offset:1552
	s_waitcnt vmcnt(2)
	ds_read_b128 v[94:97], v20 offset:2304
	ds_read_b128 v[98:101], v20 offset:2320
	ds_read_b128 v[86:89], v20 offset:2048
	ds_read_b128 v[90:93], v20 offset:2064
	ds_read_b128 v[102:105], v20 offset:2560
	ds_read_b128 v[106:109], v20 offset:2576
	s_waitcnt lgkmcnt(14)
	v_pk_mul_f32 v[114:115], v[8:9], v[38:39]
	v_pk_mul_f32 v[116:117], v[12:13], v[42:43]
	v_pk_mul_f32 v[38:39], v[4:5], v[38:39]
	v_pk_mul_f32 v[42:43], v[0:1], v[42:43]
	v_pk_fma_f32 v[114:115], v[10:11], v[40:41], v[114:115]
	v_pk_fma_f32 v[116:117], v[14:15], v[44:45], v[116:117]
	v_pk_mul_f32 v[118:119], v[54:55], v[110:111] op_sel_hi:[1,0]
	v_pk_mul_f32 v[120:121], v[56:57], v[110:111] op_sel_hi:[1,0]
	v_pk_mul_f32 v[122:123], v[58:59], v[110:111] op_sel_hi:[1,0]
	v_pk_mul_f32 v[124:125], v[60:61], v[110:111] op_sel_hi:[1,0]
	v_mov_b32_e32 v110, v111
	v_pk_fma_f32 v[38:39], v[6:7], v[40:41], v[38:39]
	v_pk_fma_f32 v[40:41], v[2:3], v[44:45], v[42:43]
	v_pk_add_f32 v[44:45], v[114:115], v[116:117]
	v_pk_mul_f32 v[54:55], v[54:55], v[110:111] op_sel_hi:[1,0]
	v_pk_add_f32 v[38:39], v[38:39], v[40:41]
	v_pk_fma_f32 v[8:9], v[8:9], v[30:31], v[118:119]
	v_add_f32_e32 v29, v44, v45
	v_pk_fma_f32 v[4:5], v[4:5], v[30:31], v[54:55]
	v_add_f32_e32 v30, v38, v39
	v_add_f32_dpp v29, v29, v29 quad_perm:[1,0,3,2] row_mask:0xf bank_mask:0xf bound_ctrl:1
	v_pk_mul_f32 v[56:57], v[56:57], v[110:111] op_sel_hi:[1,0]
	v_add_f32_dpp v30, v30, v30 quad_perm:[1,0,3,2] row_mask:0xf bank_mask:0xf bound_ctrl:1
	v_pk_mul_f32 v[58:59], v[58:59], v[110:111] op_sel_hi:[1,0]
	v_add_f32_dpp v29, v29, v29 quad_perm:[2,3,0,1] row_mask:0xf bank_mask:0xf bound_ctrl:1
	v_add_f32_dpp v31, v30, v30 quad_perm:[2,3,0,1] row_mask:0xf bank_mask:0xf bound_ctrl:1
	v_pk_fma_f32 v[10:11], v[10:11], v[32:33], v[120:121]
	v_pk_fma_f32 v[12:13], v[12:13], v[34:35], v[122:123]
	v_pk_mul_f32 v[60:61], v[60:61], v[110:111] op_sel_hi:[1,0]
	v_pk_fma_f32 v[6:7], v[6:7], v[32:33], v[56:57]
	v_pk_fma_f32 v[0:1], v[0:1], v[34:35], v[58:59]
	v_add_f32_dpp v30, v29, v29 row_half_mirror row_mask:0xf bank_mask:0xf bound_ctrl:1
	v_add_f32_dpp v32, v31, v31 row_half_mirror row_mask:0xf bank_mask:0xf bound_ctrl:1
	v_pk_fma_f32 v[14:15], v[14:15], v[36:37], v[124:125]
	v_pk_fma_f32 v[2:3], v[2:3], v[36:37], v[60:61]
	v_pk_fma_f32 v[8:9], v[46:47], v[30:31], v[8:9] op_sel_hi:[1,0,1]
	s_waitcnt lgkmcnt(13)
	v_pk_fma_f32 v[12:13], v[50:51], v[30:31], v[12:13] op_sel_hi:[1,0,1]
	v_pk_fma_f32 v[4:5], v[46:47], v[32:33], v[4:5] op_sel_hi:[1,0,1]
	v_pk_fma_f32 v[0:1], v[50:51], v[32:33], v[0:1] op_sel_hi:[1,0,1]
	v_pk_fma_f32 v[10:11], v[48:49], v[30:31], v[10:11] op_sel_hi:[1,0,1]
	v_pk_fma_f32 v[14:15], v[52:53], v[30:31], v[14:15] op_sel_hi:[1,0,1]
	v_pk_fma_f32 v[6:7], v[48:49], v[32:33], v[6:7] op_sel_hi:[1,0,1]
	v_pk_fma_f32 v[2:3], v[52:53], v[32:33], v[2:3] op_sel_hi:[1,0,1]
	s_waitcnt lgkmcnt(10)
	v_pk_mul_f32 v[30:31], v[62:63], v[8:9]
	v_pk_mul_f32 v[32:33], v[66:67], v[12:13]
	v_pk_mul_f32 v[34:35], v[62:63], v[4:5]
	v_pk_mul_f32 v[36:37], v[66:67], v[0:1]
	v_pk_mul_f32 v[38:39], v[78:79], v[8:9]
	s_waitcnt lgkmcnt(7)
	v_pk_mul_f32 v[40:41], v[82:83], v[12:13]
	v_pk_mul_f32 v[48:49], v[78:79], v[4:5]
	v_pk_mul_f32 v[50:51], v[82:83], v[0:1]
	v_mov_b32_e32 v42, v113
	v_pk_mul_f32 v[8:9], v[70:71], v[8:9]
	v_pk_mul_f32 v[44:45], v[72:73], v[10:11]
	s_waitcnt lgkmcnt(6)
	v_pk_mul_f32 v[46:47], v[76:77], v[14:15]
	v_pk_mul_f32 v[4:5], v[70:71], v[4:5]
	v_pk_mul_f32 v[52:53], v[72:73], v[6:7]
	v_pk_mul_f32 v[0:1], v[74:75], v[0:1]
	v_pk_mul_f32 v[54:55], v[76:77], v[2:3]
	v_pk_fma_f32 v[30:31], v[64:65], v[10:11], v[30:31]
	v_pk_fma_f32 v[32:33], v[68:69], v[14:15], v[32:33]
	v_pk_fma_f32 v[34:35], v[64:65], v[6:7], v[34:35]
	v_pk_fma_f32 v[36:37], v[68:69], v[2:3], v[36:37]
	v_pk_fma_f32 v[10:11], v[80:81], v[10:11], v[38:39]
	v_pk_fma_f32 v[14:15], v[84:85], v[14:15], v[40:41]
	v_pk_fma_f32 v[6:7], v[80:81], v[6:7], v[48:49]
	v_pk_fma_f32 v[2:3], v[84:85], v[2:3], v[50:51]
	s_waitcnt lgkmcnt(4)
; #define SCAN_STEP(w0, w1, a0, a1, b0, b1, k0, k1, r0, r1, vi, vj, t) do { \
;                 SCAN_ROW(S0, S1, S2, S3, w0, w1, a0, a1, b0, b1, k0, k1, r0, r1, vi, (t) * 512); \
;                 SCAN_ROW(T0, T1, T2, T3, w0, w1, a0, a1, b0, b1, k0, k1, r0, r1, vj, (t) * 512 + 256); } while (0)
;     ...
;             SCAN_LOAD(w0, w1, a0, a1, b0, b1, k0, k1, r0, r1, vi, vj, 0);
; #pragma unroll
;             for (int t = 0; t < 16; t += 2) {
;                 SCAN_LOAD(W0, W1, A0, A1, B0, B1, K0, K1, R0, R1, VI, VJ, t + 1);
;                 SCAN_STEP(w0, w1, a0, a1, b0, b1, k0, k1, r0, r1, vi, vj, t);
;                 if (t + 2 < 16) SCAN_LOAD(w0, w1, a0, a1, b0, b1, k0, k1, r0, r1, vi, vj, t + 2);
;                 SCAN_STEP(W0, W1, A0, A1, B0, B1, K0, K1, R0, R1, VI, VJ, t + 1);
	v_pk_fma_f32 v[56:57], v[94:95], v[112:113], v[8:9] op_sel_hi:[1,0,1]
	v_pk_fma_f32 v[64:65], v[94:95], v[42:43], v[4:5] op_sel_hi:[1,0,1]
	v_pk_fma_f32 v[68:69], v[98:99], v[42:43], v[0:1] op_sel_hi:[1,0,1]
	v_pk_add_f32 v[0:1], v[30:31], v[32:33]
	v_pk_add_f32 v[4:5], v[34:35], v[36:37]
	v_pk_add_f32 v[8:9], v[10:11], v[14:15]
	v_pk_add_f32 v[2:3], v[6:7], v[2:3]
	v_add_f32_e32 v0, v0, v1
	v_add_f32_e32 v1, v4, v5
	v_add_f32_e32 v4, v8, v9
	v_add_f32_e32 v2, v2, v3
	v_add_u32_e32 v126, 0x1000, v21
	v_add_f32_dpp v29, v4, v4 quad_perm:[1,0,3,2] row_mask:0xf bank_mask:0xf bound_ctrl:1
	v_add_f32_dpp v72, v2, v2 quad_perm:[1,0,3,2] row_mask:0xf bank_mask:0xf bound_ctrl:1
	v_pk_mul_f32 v[12:13], v[74:75], v[12:13]
	ds_write2st64_b32 v27, v0, v1 offset0:192 offset1:196
	v_add_f32_dpp v29, v29, v29 quad_perm:[2,3,0,1] row_mask:0xf bank_mask:0xf bound_ctrl:1
	v_add_f32_dpp v73, v72, v72 quad_perm:[2,3,0,1] row_mask:0xf bank_mask:0xf bound_ctrl:1
	v_pk_fma_f32 v[58:59], v[96:97], v[112:113], v[44:45] op_sel_hi:[1,0,1]
	v_pk_fma_f32 v[60:61], v[98:99], v[112:113], v[12:13] op_sel_hi:[1,0,1]
	v_pk_fma_f32 v[62:63], v[100:101], v[112:113], v[46:47] op_sel_hi:[1,0,1]
	v_pk_fma_f32 v[66:67], v[96:97], v[42:43], v[52:53] op_sel_hi:[1,0,1]
	v_pk_fma_f32 v[54:55], v[100:101], v[42:43], v[54:55] op_sel_hi:[1,0,1]
	ds_read_b128 v[42:45], v20 offset:3328
	ds_read_b128 v[38:41], v20 offset:3344
	ds_read_b128 v[46:49], v20 offset:3072
	ds_read_b128 v[50:53], v20 offset:3088
	ds_read2_b32 v[70:71], v126 offset0:64 offset1:72
	ds_read_b128 v[12:15], v20 offset:3840
	ds_read_b128 v[8:11], v20 offset:3856
	ds_read_b128 v[34:37], v20 offset:3584
	ds_read_b128 v[30:33], v20 offset:3600
	ds_read_b128 v[4:7], v20 offset:4096
	ds_read_b128 v[0:3], v20 offset:4112
	v_add_f32_dpp v72, v29, v29 row_half_mirror row_mask:0xf bank_mask:0xf bound_ctrl:1
	v_add_f32_dpp v74, v73, v73 row_half_mirror row_mask:0xf bank_mask:0xf bound_ctrl:1
	s_waitcnt lgkmcnt(14)
	v_pk_fma_f32 v[56:57], v[86:87], v[72:73], v[56:57] op_sel_hi:[1,0,1]
	v_pk_fma_f32 v[60:61], v[90:91], v[72:73], v[60:61] op_sel_hi:[1,0,1]
	v_pk_fma_f32 v[64:65], v[86:87], v[74:75], v[64:65] op_sel_hi:[1,0,1]
	v_pk_fma_f32 v[68:69], v[90:91], v[74:75], v[68:69] op_sel_hi:[1,0,1]
	v_pk_fma_f32 v[58:59], v[88:89], v[72:73], v[58:59] op_sel_hi:[1,0,1]
	v_pk_fma_f32 v[62:63], v[92:93], v[72:73], v[62:63] op_sel_hi:[1,0,1]
	v_pk_fma_f32 v[66:67], v[88:89], v[74:75], v[66:67] op_sel_hi:[1,0,1]
	v_pk_fma_f32 v[54:55], v[92:93], v[74:75], v[54:55] op_sel_hi:[1,0,1]
	s_waitcnt lgkmcnt(12)
	v_pk_mul_f32 v[72:73], v[102:103], v[56:57]
	v_pk_mul_f32 v[74:75], v[106:107], v[60:61]
	v_pk_mul_f32 v[76:77], v[102:103], v[64:65]
	v_pk_mul_f32 v[78:79], v[106:107], v[68:69]
	v_pk_fma_f32 v[72:73], v[104:105], v[58:59], v[72:73]
	v_pk_fma_f32 v[74:75], v[108:109], v[62:63], v[74:75]
	v_pk_fma_f32 v[76:77], v[104:105], v[66:67], v[76:77]
	v_pk_fma_f32 v[78:79], v[108:109], v[54:55], v[78:79]
	v_pk_add_f32 v[72:73], v[72:73], v[74:75]
	v_pk_add_f32 v[74:75], v[76:77], v[78:79]
	s_waitcnt lgkmcnt(8)
	v_pk_mul_f32 v[76:77], v[42:43], v[56:57]
	v_pk_mul_f32 v[78:79], v[38:39], v[60:61]
	v_pk_mul_f32 v[42:43], v[42:43], v[64:65]
	v_pk_mul_f32 v[38:39], v[38:39], v[68:69]
	v_pk_mul_f32 v[80:81], v[48:49], v[58:59]
	s_waitcnt lgkmcnt(7)
	v_pk_mul_f32 v[82:83], v[52:53], v[62:63]
	v_pk_fma_f32 v[58:59], v[44:45], v[58:59], v[76:77]
	v_pk_fma_f32 v[62:63], v[40:41], v[62:63], v[78:79]
	v_pk_fma_f32 v[42:43], v[44:45], v[66:67], v[42:43]
	v_pk_fma_f32 v[38:39], v[40:41], v[54:55], v[38:39]
	v_pk_mul_f32 v[56:57], v[46:47], v[56:57]
	v_pk_mul_f32 v[46:47], v[46:47], v[64:65]
	v_add_f32_e32 v29, v72, v73
	v_add_f32_e32 v64, v74, v75
	v_pk_add_f32 v[86:87], v[62:63], v[58:59]
	v_pk_add_f32 v[88:89], v[38:39], v[42:43]
	ds_write2st64_b32 v27, v29, v64 offset0:200 offset1:204
	v_add_f32_e32 v29, v86, v87
	v_add_f32_e32 v86, v88, v89
	v_pk_mul_f32 v[60:61], v[50:51], v[60:61]
	s_waitcnt lgkmcnt(7)
	v_mov_b32_e32 v84, v71
	v_pk_mul_f32 v[48:49], v[48:49], v[66:67]
	v_pk_mul_f32 v[50:51], v[50:51], v[68:69]
	v_pk_mul_f32 v[52:53], v[52:53], v[54:55]
	v_add_f32_dpp v29, v29, v29 quad_perm:[1,0,3,2] row_mask:0xf bank_mask:0xf bound_ctrl:1
	v_add_f32_dpp v86, v86, v86 quad_perm:[1,0,3,2] row_mask:0xf bank_mask:0xf bound_ctrl:1
	v_add_u32_e32 v127, 0x1400, v21
	s_waitcnt lgkmcnt(5)
	v_pk_fma_f32 v[72:73], v[70:71], v[12:13], v[56:57] op_sel_hi:[0,1,1]
	v_pk_fma_f32 v[74:75], v[70:71], v[14:15], v[80:81] op_sel_hi:[0,1,1]
	v_pk_fma_f32 v[76:77], v[70:71], v[8:9], v[60:61] op_sel_hi:[0,1,1]
	v_pk_fma_f32 v[70:71], v[70:71], v[10:11], v[82:83] op_sel_hi:[0,1,1]
	v_pk_fma_f32 v[78:79], v[84:85], v[12:13], v[46:47] op_sel_hi:[0,1,1]
	v_pk_fma_f32 v[80:81], v[84:85], v[14:15], v[48:49] op_sel_hi:[0,1,1]
	v_pk_fma_f32 v[82:83], v[84:85], v[8:9], v[50:51] op_sel_hi:[0,1,1]
	v_pk_fma_f32 v[84:85], v[84:85], v[10:11], v[52:53] op_sel_hi:[0,1,1]
	ds_read_b128 v[38:41], v20 offset:4864
	ds_read_b128 v[42:45], v20 offset:4880
	ds_read_b128 v[8:11], v20 offset:4608
	ds_read_b128 v[12:15], v20 offset:4624
	ds_read2_b32 v[90:91], v127 offset0:192 offset1:200
	ds_read_b128 v[54:57], v20 offset:5376
	ds_read_b128 v[58:61], v20 offset:5392
	ds_read_b128 v[46:49], v20 offset:5120
	ds_read_b128 v[50:53], v20 offset:5136
	ds_read_b128 v[62:65], v20 offset:5632
	ds_read_b128 v[66:69], v20 offset:5648
	v_add_f32_dpp v29, v29, v29 quad_perm:[2,3,0,1] row_mask:0xf bank_mask:0xf bound_ctrl:1
	v_add_f32_dpp v87, v86, v86 quad_perm:[2,3,0,1] row_mask:0xf bank_mask:0xf bound_ctrl:1
	v_add_u32_e32 v128, 0x1c00, v21
	v_add_f32_dpp v86, v29, v29 row_half_mirror row_mask:0xf bank_mask:0xf bound_ctrl:1
	v_add_f32_dpp v88, v87, v87 row_half_mirror row_mask:0xf bank_mask:0xf bound_ctrl:1
	s_waitcnt lgkmcnt(14)
; #define SCAN_STEP(w0, w1, a0, a1, b0, b1, k0, k1, r0, r1, vi, vj, t) do { \
;                 SCAN_ROW(S0, S1, S2, S3, w0, w1, a0, a1, b0, b1, k0, k1, r0, r1, vi, (t) * 512); \
;                 SCAN_ROW(T0, T1, T2, T3, w0, w1, a0, a1, b0, b1, k0, k1, r0, r1, vj, (t) * 512 + 256); } while (0)
;     ...
;             SCAN_LOAD(w0, w1, a0, a1, b0, b1, k0, k1, r0, r1, vi, vj, 0);
; #pragma unroll
;             for (int t = 0; t < 16; t += 2) {
;                 SCAN_LOAD(W0, W1, A0, A1, B0, B1, K0, K1, R0, R1, VI, VJ, t + 1);
;                 SCAN_STEP(w0, w1, a0, a1, b0, b1, k0, k1, r0, r1, vi, vj, t);
;                 if (t + 2 < 16) SCAN_LOAD(w0, w1, a0, a1, b0, b1, k0, k1, r0, r1, vi, vj, t + 2);
;                 SCAN_STEP(W0, W1, A0, A1, B0, B1, K0, K1, R0, R1, VI, VJ, t + 1);
	v_pk_fma_f32 v[72:73], v[34:35], v[86:87], v[72:73] op_sel_hi:[1,0,1]
	v_pk_fma_f32 v[76:77], v[30:31], v[86:87], v[76:77] op_sel_hi:[1,0,1]
	v_pk_fma_f32 v[34:35], v[34:35], v[88:89], v[78:79] op_sel_hi:[1,0,1]
	v_pk_fma_f32 v[30:31], v[30:31], v[88:89], v[82:83] op_sel_hi:[1,0,1]
	v_pk_fma_f32 v[74:75], v[36:37], v[86:87], v[74:75] op_sel_hi:[1,0,1]
	v_pk_fma_f32 v[70:71], v[32:33], v[86:87], v[70:71] op_sel_hi:[1,0,1]
	v_pk_fma_f32 v[36:37], v[36:37], v[88:89], v[80:81] op_sel_hi:[1,0,1]
	v_pk_fma_f32 v[32:33], v[32:33], v[88:89], v[84:85] op_sel_hi:[1,0,1]
	s_waitcnt lgkmcnt(12)
	v_pk_mul_f32 v[78:79], v[4:5], v[72:73]
	v_pk_mul_f32 v[80:81], v[0:1], v[76:77]
	v_pk_mul_f32 v[4:5], v[4:5], v[34:35]
	v_pk_mul_f32 v[0:1], v[0:1], v[30:31]
	s_waitcnt lgkmcnt(8)
	v_pk_mul_f32 v[82:83], v[38:39], v[72:73]
	v_pk_mul_f32 v[84:85], v[42:43], v[76:77]
	v_pk_mul_f32 v[38:39], v[38:39], v[34:35]
	v_pk_mul_f32 v[42:43], v[42:43], v[30:31]
	v_pk_mul_f32 v[72:73], v[8:9], v[72:73]
	v_pk_mul_f32 v[86:87], v[10:11], v[74:75]
	s_waitcnt lgkmcnt(7)
	v_pk_mul_f32 v[76:77], v[12:13], v[76:77]
	v_pk_mul_f32 v[88:89], v[14:15], v[70:71]
	v_pk_mul_f32 v[8:9], v[8:9], v[34:35]
	v_pk_mul_f32 v[10:11], v[10:11], v[36:37]
	v_pk_mul_f32 v[12:13], v[12:13], v[30:31]
	v_pk_mul_f32 v[14:15], v[14:15], v[32:33]
	v_pk_fma_f32 v[30:31], v[6:7], v[74:75], v[78:79]
	v_pk_fma_f32 v[34:35], v[2:3], v[70:71], v[80:81]
	v_pk_fma_f32 v[4:5], v[6:7], v[36:37], v[4:5]
	v_pk_fma_f32 v[0:1], v[2:3], v[32:33], v[0:1]
	v_pk_fma_f32 v[2:3], v[40:41], v[74:75], v[82:83]
	v_pk_fma_f32 v[6:7], v[44:45], v[70:71], v[84:85]
	v_pk_fma_f32 v[36:37], v[40:41], v[36:37], v[38:39]
	v_pk_fma_f32 v[32:33], v[44:45], v[32:33], v[42:43]
	s_waitcnt lgkmcnt(5)
	v_mov_b32_e32 v92, v91
	v_pk_add_f32 v[0:1], v[4:5], v[0:1]
	v_pk_add_f32 v[2:3], v[2:3], v[6:7]
	v_pk_add_f32 v[4:5], v[36:37], v[32:33]
	v_pk_fma_f32 v[78:79], v[54:55], v[92:93], v[8:9] op_sel_hi:[1,0,1]
	v_pk_add_f32 v[8:9], v[30:31], v[34:35]
	v_add_f32_e32 v0, v0, v1
	v_add_f32_e32 v1, v2, v3
	v_add_f32_e32 v2, v4, v5
	s_waitcnt lgkmcnt(4)
	v_pk_fma_f32 v[74:75], v[58:59], v[90:91], v[76:77] op_sel_hi:[1,0,1]
	v_pk_fma_f32 v[76:77], v[60:61], v[90:91], v[88:89] op_sel_hi:[1,0,1]
	v_add_f32_e32 v6, v8, v9
	v_add_f32_dpp v29, v1, v1 quad_perm:[1,0,3,2] row_mask:0xf bank_mask:0xf bound_ctrl:1
	v_add_f32_dpp v88, v2, v2 quad_perm:[1,0,3,2] row_mask:0xf bank_mask:0xf bound_ctrl:1
	ds_write2st64_b32 v27, v6, v0 offset0:208 offset1:212
	v_add_f32_dpp v29, v29, v29 quad_perm:[2,3,0,1] row_mask:0xf bank_mask:0xf bound_ctrl:1
	v_add_f32_dpp v89, v88, v88 quad_perm:[2,3,0,1] row_mask:0xf bank_mask:0xf bound_ctrl:1
	v_pk_fma_f32 v[70:71], v[54:55], v[90:91], v[72:73] op_sel_hi:[1,0,1]
	v_pk_fma_f32 v[72:73], v[56:57], v[90:91], v[86:87] op_sel_hi:[1,0,1]
	v_pk_fma_f32 v[80:81], v[56:57], v[92:93], v[10:11] op_sel_hi:[1,0,1]
	v_pk_fma_f32 v[82:83], v[58:59], v[92:93], v[12:13] op_sel_hi:[1,0,1]
	v_pk_fma_f32 v[84:85], v[60:61], v[92:93], v[14:15] op_sel_hi:[1,0,1]
	ds_read_b128 v[42:45], v20 offset:6400
	ds_read_b128 v[38:41], v20 offset:6416
	ds_read_b128 v[54:57], v20 offset:6144
	ds_read_b128 v[58:61], v20 offset:6160
	ds_read2_b32 v[86:87], v128 offset0:64 offset1:72
	ds_read_b128 v[12:15], v20 offset:6912
	ds_read_b128 v[8:11], v20 offset:6928
	ds_read_b128 v[34:37], v20 offset:6656
	ds_read_b128 v[30:33], v20 offset:6672
	ds_read_b128 v[4:7], v20 offset:7168
	ds_read_b128 v[0:3], v20 offset:7184
	v_add_f32_dpp v88, v29, v29 row_half_mirror row_mask:0xf bank_mask:0xf bound_ctrl:1
	v_add_f32_dpp v90, v89, v89 row_half_mirror row_mask:0xf bank_mask:0xf bound_ctrl:1
	s_waitcnt lgkmcnt(14)
	v_pk_fma_f32 v[70:71], v[46:47], v[88:89], v[70:71] op_sel_hi:[1,0,1]
	v_pk_fma_f32 v[74:75], v[50:51], v[88:89], v[74:75] op_sel_hi:[1,0,1]
	v_pk_fma_f32 v[46:47], v[46:47], v[90:91], v[78:79] op_sel_hi:[1,0,1]
	v_pk_fma_f32 v[50:51], v[50:51], v[90:91], v[82:83] op_sel_hi:[1,0,1]
	v_pk_fma_f32 v[72:73], v[48:49], v[88:89], v[72:73] op_sel_hi:[1,0,1]
	v_pk_fma_f32 v[76:77], v[52:53], v[88:89], v[76:77] op_sel_hi:[1,0,1]
	v_pk_fma_f32 v[48:49], v[48:49], v[90:91], v[80:81] op_sel_hi:[1,0,1]
	v_pk_fma_f32 v[52:53], v[52:53], v[90:91], v[84:85] op_sel_hi:[1,0,1]
	s_waitcnt lgkmcnt(12)
	v_pk_mul_f32 v[78:79], v[62:63], v[70:71]
	v_pk_mul_f32 v[80:81], v[66:67], v[74:75]
	v_pk_mul_f32 v[62:63], v[62:63], v[46:47]
	v_pk_mul_f32 v[66:67], v[66:67], v[50:51]
	v_pk_fma_f32 v[78:79], v[64:65], v[72:73], v[78:79]
	v_pk_fma_f32 v[62:63], v[64:65], v[48:49], v[62:63]
	v_pk_fma_f32 v[64:65], v[68:69], v[52:53], v[66:67]
	v_pk_fma_f32 v[80:81], v[68:69], v[76:77], v[80:81]
	v_pk_add_f32 v[62:63], v[62:63], v[64:65]
	s_waitcnt lgkmcnt(9)
	v_pk_mul_f32 v[64:65], v[42:43], v[70:71]
	v_pk_mul_f32 v[68:69], v[38:39], v[74:75]
	v_pk_mul_f32 v[42:43], v[42:43], v[46:47]
	v_pk_mul_f32 v[38:39], v[38:39], v[50:51]
	v_pk_add_f32 v[66:67], v[78:79], v[80:81]
	s_waitcnt lgkmcnt(7)
	v_pk_mul_f32 v[70:71], v[54:55], v[70:71]
	v_pk_mul_f32 v[78:79], v[56:57], v[72:73]
	v_pk_mul_f32 v[74:75], v[58:59], v[74:75]
	v_pk_mul_f32 v[80:81], v[60:61], v[76:77]
	v_pk_mul_f32 v[46:47], v[54:55], v[46:47]
	v_pk_mul_f32 v[54:55], v[56:57], v[48:49]
	v_pk_mul_f32 v[50:51], v[58:59], v[50:51]
	v_pk_mul_f32 v[56:57], v[60:61], v[52:53]
	v_pk_fma_f32 v[58:59], v[44:45], v[72:73], v[64:65]
	v_pk_fma_f32 v[60:61], v[40:41], v[76:77], v[68:69]
	v_pk_fma_f32 v[42:43], v[44:45], v[48:49], v[42:43]
	v_pk_fma_f32 v[38:39], v[40:41], v[52:53], v[38:39]
	s_waitcnt lgkmcnt(5)
	v_mov_b32_e32 v82, v87
	v_add_f32_e32 v29, v66, v67
	v_add_f32_e32 v62, v62, v63
	v_pk_fma_f32 v[70:71], v[86:87], v[12:13], v[70:71] op_sel_hi:[0,1,1]
	v_pk_fma_f32 v[72:73], v[86:87], v[14:15], v[78:79] op_sel_hi:[0,1,1]
	s_waitcnt lgkmcnt(4)
; #define SCAN_STEP(w0, w1, a0, a1, b0, b1, k0, k1, r0, r1, vi, vj, t) do { \
;                 SCAN_ROW(S0, S1, S2, S3, w0, w1, a0, a1, b0, b1, k0, k1, r0, r1, vi, (t) * 512); \
;                 SCAN_ROW(T0, T1, T2, T3, w0, w1, a0, a1, b0, b1, k0, k1, r0, r1, vj, (t) * 512 + 256); } while (0)
;     ...
;             SCAN_LOAD(w0, w1, a0, a1, b0, b1, k0, k1, r0, r1, vi, vj, 0);
; #pragma unroll
;             for (int t = 0; t < 16; t += 2) {
;                 SCAN_LOAD(W0, W1, A0, A1, B0, B1, K0, K1, R0, R1, VI, VJ, t + 1);
;                 SCAN_STEP(w0, w1, a0, a1, b0, b1, k0, k1, r0, r1, vi, vj, t);
;                 if (t + 2 < 16) SCAN_LOAD(w0, w1, a0, a1, b0, b1, k0, k1, r0, r1, vi, vj, t + 2);
;                 SCAN_STEP(W0, W1, A0, A1, B0, B1, K0, K1, R0, R1, VI, VJ, t + 1);
	v_pk_fma_f32 v[74:75], v[86:87], v[8:9], v[74:75] op_sel_hi:[0,1,1]
	v_pk_fma_f32 v[76:77], v[86:87], v[10:11], v[80:81] op_sel_hi:[0,1,1]
	v_pk_add_f32 v[86:87], v[60:61], v[58:59]
	v_pk_add_f32 v[88:89], v[38:39], v[42:43]
	ds_write2st64_b32 v27, v29, v62 offset0:216 offset1:220
	v_add_f32_e32 v29, v86, v87
	v_add_f32_e32 v86, v88, v89
	v_add_u32_e32 v129, 0x2000, v21
	v_add_f32_dpp v29, v29, v29 quad_perm:[1,0,3,2] row_mask:0xf bank_mask:0xf bound_ctrl:1
	v_add_f32_dpp v86, v86, v86 quad_perm:[1,0,3,2] row_mask:0xf bank_mask:0xf bound_ctrl:1
	v_pk_fma_f32 v[78:79], v[82:83], v[12:13], v[46:47] op_sel_hi:[0,1,1]
	v_pk_fma_f32 v[80:81], v[82:83], v[14:15], v[54:55] op_sel_hi:[0,1,1]
	v_pk_fma_f32 v[84:85], v[82:83], v[8:9], v[50:51] op_sel_hi:[0,1,1]
	v_pk_fma_f32 v[82:83], v[82:83], v[10:11], v[56:57] op_sel_hi:[0,1,1]
	ds_read_b128 v[38:41], v20 offset:7936
	ds_read_b128 v[42:45], v20 offset:7952
	ds_read_b128 v[8:11], v20 offset:7680
	ds_read_b128 v[12:15], v20 offset:7696
	ds_read2_b32 v[90:91], v129 offset0:192 offset1:200
	ds_read_b128 v[54:57], v20 offset:8448
	ds_read_b128 v[58:61], v20 offset:8464
	ds_read_b128 v[46:49], v20 offset:8192
	ds_read_b128 v[50:53], v20 offset:8208
	ds_read_b128 v[62:65], v20 offset:8704
	ds_read_b128 v[66:69], v20 offset:8720
	v_add_f32_dpp v29, v29, v29 quad_perm:[2,3,0,1] row_mask:0xf bank_mask:0xf bound_ctrl:1
	v_add_f32_dpp v87, v86, v86 quad_perm:[2,3,0,1] row_mask:0xf bank_mask:0xf bound_ctrl:1
	v_add_u32_e32 v130, 0x2800, v21
	v_add_f32_dpp v86, v29, v29 row_half_mirror row_mask:0xf bank_mask:0xf bound_ctrl:1
	v_add_f32_dpp v88, v87, v87 row_half_mirror row_mask:0xf bank_mask:0xf bound_ctrl:1
	s_waitcnt lgkmcnt(14)
	v_pk_fma_f32 v[70:71], v[34:35], v[86:87], v[70:71] op_sel_hi:[1,0,1]
	v_pk_fma_f32 v[74:75], v[30:31], v[86:87], v[74:75] op_sel_hi:[1,0,1]
	v_pk_fma_f32 v[34:35], v[34:35], v[88:89], v[78:79] op_sel_hi:[1,0,1]
	v_pk_fma_f32 v[30:31], v[30:31], v[88:89], v[84:85] op_sel_hi:[1,0,1]
	v_pk_fma_f32 v[72:73], v[36:37], v[86:87], v[72:73] op_sel_hi:[1,0,1]
	v_pk_fma_f32 v[76:77], v[32:33], v[86:87], v[76:77] op_sel_hi:[1,0,1]
	v_pk_fma_f32 v[36:37], v[36:37], v[88:89], v[80:81] op_sel_hi:[1,0,1]
	v_pk_fma_f32 v[32:33], v[32:33], v[88:89], v[82:83] op_sel_hi:[1,0,1]
	s_waitcnt lgkmcnt(12)
	v_pk_mul_f32 v[78:79], v[4:5], v[70:71]
	v_pk_mul_f32 v[80:81], v[0:1], v[74:75]
	v_pk_mul_f32 v[4:5], v[4:5], v[34:35]
	v_pk_mul_f32 v[0:1], v[0:1], v[30:31]
	s_waitcnt lgkmcnt(8)
	v_pk_mul_f32 v[82:83], v[38:39], v[70:71]
	v_pk_mul_f32 v[84:85], v[42:43], v[74:75]
	v_pk_mul_f32 v[38:39], v[38:39], v[34:35]
	v_pk_mul_f32 v[42:43], v[42:43], v[30:31]
	v_pk_mul_f32 v[70:71], v[8:9], v[70:71]
	v_pk_mul_f32 v[86:87], v[10:11], v[72:73]
	s_waitcnt lgkmcnt(7)
	v_pk_mul_f32 v[74:75], v[12:13], v[74:75]
	v_pk_mul_f32 v[88:89], v[14:15], v[76:77]
	v_pk_mul_f32 v[8:9], v[8:9], v[34:35]
	v_pk_mul_f32 v[10:11], v[10:11], v[36:37]
	v_pk_mul_f32 v[12:13], v[12:13], v[30:31]
	v_pk_mul_f32 v[14:15], v[14:15], v[32:33]
	v_pk_fma_f32 v[30:31], v[6:7], v[72:73], v[78:79]
	v_pk_fma_f32 v[34:35], v[2:3], v[76:77], v[80:81]
	v_pk_fma_f32 v[4:5], v[6:7], v[36:37], v[4:5]
	v_pk_fma_f32 v[0:1], v[2:3], v[32:33], v[0:1]
	v_pk_fma_f32 v[2:3], v[40:41], v[72:73], v[82:83]
	v_pk_fma_f32 v[6:7], v[44:45], v[76:77], v[84:85]
	v_pk_fma_f32 v[36:37], v[40:41], v[36:37], v[38:39]
	v_pk_fma_f32 v[32:33], v[44:45], v[32:33], v[42:43]
	s_waitcnt lgkmcnt(5)
	v_mov_b32_e32 v92, v91
	v_pk_add_f32 v[0:1], v[4:5], v[0:1]
	v_pk_add_f32 v[2:3], v[2:3], v[6:7]
	v_pk_add_f32 v[4:5], v[36:37], v[32:33]
	v_pk_fma_f32 v[78:79], v[54:55], v[92:93], v[8:9] op_sel_hi:[1,0,1]
	v_pk_add_f32 v[8:9], v[30:31], v[34:35]
	v_add_f32_e32 v0, v0, v1
	v_add_f32_e32 v1, v2, v3
	v_add_f32_e32 v2, v4, v5
	s_waitcnt lgkmcnt(4)
	v_pk_fma_f32 v[76:77], v[60:61], v[90:91], v[88:89] op_sel_hi:[1,0,1]
	v_add_f32_e32 v6, v8, v9
	v_add_f32_dpp v29, v1, v1 quad_perm:[1,0,3,2] row_mask:0xf bank_mask:0xf bound_ctrl:1
	v_add_f32_dpp v88, v2, v2 quad_perm:[1,0,3,2] row_mask:0xf bank_mask:0xf bound_ctrl:1
	ds_write2st64_b32 v27, v6, v0 offset0:224 offset1:228
	v_add_f32_dpp v29, v29, v29 quad_perm:[2,3,0,1] row_mask:0xf bank_mask:0xf bound_ctrl:1
	v_add_f32_dpp v89, v88, v88 quad_perm:[2,3,0,1] row_mask:0xf bank_mask:0xf bound_ctrl:1
	v_pk_fma_f32 v[70:71], v[54:55], v[90:91], v[70:71] op_sel_hi:[1,0,1]
	v_pk_fma_f32 v[72:73], v[56:57], v[90:91], v[86:87] op_sel_hi:[1,0,1]
	v_pk_fma_f32 v[74:75], v[58:59], v[90:91], v[74:75] op_sel_hi:[1,0,1]
	v_pk_fma_f32 v[80:81], v[56:57], v[92:93], v[10:11] op_sel_hi:[1,0,1]
	v_pk_fma_f32 v[82:83], v[58:59], v[92:93], v[12:13] op_sel_hi:[1,0,1]
	v_pk_fma_f32 v[84:85], v[60:61], v[92:93], v[14:15] op_sel_hi:[1,0,1]
	ds_read_b128 v[42:45], v20 offset:9472
	ds_read_b128 v[38:41], v20 offset:9488
	ds_read_b128 v[54:57], v20 offset:9216
	ds_read_b128 v[58:61], v20 offset:9232
	ds_read2_b32 v[86:87], v130 offset0:64 offset1:72
	ds_read_b128 v[12:15], v20 offset:9984
	ds_read_b128 v[8:11], v20 offset:10000
	ds_read_b128 v[34:37], v20 offset:9728
	ds_read_b128 v[30:33], v20 offset:9744
	ds_read_b128 v[4:7], v20 offset:10240
	ds_read_b128 v[0:3], v20 offset:10256
	v_add_f32_dpp v88, v29, v29 row_half_mirror row_mask:0xf bank_mask:0xf bound_ctrl:1
	v_add_f32_dpp v90, v89, v89 row_half_mirror row_mask:0xf bank_mask:0xf bound_ctrl:1
	s_waitcnt lgkmcnt(14)
	v_pk_fma_f32 v[70:71], v[46:47], v[88:89], v[70:71] op_sel_hi:[1,0,1]
	v_pk_fma_f32 v[74:75], v[50:51], v[88:89], v[74:75] op_sel_hi:[1,0,1]
	v_pk_fma_f32 v[46:47], v[46:47], v[90:91], v[78:79] op_sel_hi:[1,0,1]
	v_pk_fma_f32 v[50:51], v[50:51], v[90:91], v[82:83] op_sel_hi:[1,0,1]
	v_pk_fma_f32 v[72:73], v[48:49], v[88:89], v[72:73] op_sel_hi:[1,0,1]
	v_pk_fma_f32 v[76:77], v[52:53], v[88:89], v[76:77] op_sel_hi:[1,0,1]
	v_pk_fma_f32 v[48:49], v[48:49], v[90:91], v[80:81] op_sel_hi:[1,0,1]
	v_pk_fma_f32 v[52:53], v[52:53], v[90:91], v[84:85] op_sel_hi:[1,0,1]
	s_waitcnt lgkmcnt(12)
; #define SCAN_STEP(w0, w1, a0, a1, b0, b1, k0, k1, r0, r1, vi, vj, t) do { \
;                 SCAN_ROW(S0, S1, S2, S3, w0, w1, a0, a1, b0, b1, k0, k1, r0, r1, vi, (t) * 512); \
;                 SCAN_ROW(T0, T1, T2, T3, w0, w1, a0, a1, b0, b1, k0, k1, r0, r1, vj, (t) * 512 + 256); } while (0)
;     ...
;             SCAN_LOAD(w0, w1, a0, a1, b0, b1, k0, k1, r0, r1, vi, vj, 0);
; #pragma unroll
;             for (int t = 0; t < 16; t += 2) {
;                 SCAN_LOAD(W0, W1, A0, A1, B0, B1, K0, K1, R0, R1, VI, VJ, t + 1);
;                 SCAN_STEP(w0, w1, a0, a1, b0, b1, k0, k1, r0, r1, vi, vj, t);
;                 if (t + 2 < 16) SCAN_LOAD(w0, w1, a0, a1, b0, b1, k0, k1, r0, r1, vi, vj, t + 2);
;                 SCAN_STEP(W0, W1, A0, A1, B0, B1, K0, K1, R0, R1, VI, VJ, t + 1);
	v_pk_mul_f32 v[78:79], v[62:63], v[70:71]
	v_pk_mul_f32 v[80:81], v[66:67], v[74:75]
	v_pk_mul_f32 v[62:63], v[62:63], v[46:47]
	v_pk_mul_f32 v[66:67], v[66:67], v[50:51]
	v_pk_fma_f32 v[78:79], v[64:65], v[72:73], v[78:79]
	v_pk_fma_f32 v[62:63], v[64:65], v[48:49], v[62:63]
	v_pk_fma_f32 v[64:65], v[68:69], v[52:53], v[66:67]
	v_pk_fma_f32 v[80:81], v[68:69], v[76:77], v[80:81]
	v_pk_add_f32 v[62:63], v[62:63], v[64:65]
	s_waitcnt lgkmcnt(9)
	v_pk_mul_f32 v[64:65], v[42:43], v[70:71]
	v_pk_mul_f32 v[68:69], v[38:39], v[74:75]
	v_pk_mul_f32 v[42:43], v[42:43], v[46:47]
	v_pk_mul_f32 v[38:39], v[38:39], v[50:51]
	v_pk_add_f32 v[66:67], v[78:79], v[80:81]
	s_waitcnt lgkmcnt(7)
	v_pk_mul_f32 v[70:71], v[54:55], v[70:71]
	v_pk_mul_f32 v[78:79], v[56:57], v[72:73]
	v_pk_mul_f32 v[74:75], v[58:59], v[74:75]
	v_pk_mul_f32 v[80:81], v[60:61], v[76:77]
	v_pk_mul_f32 v[46:47], v[54:55], v[46:47]
	v_pk_mul_f32 v[54:55], v[56:57], v[48:49]
	v_pk_mul_f32 v[50:51], v[58:59], v[50:51]
	v_pk_mul_f32 v[56:57], v[60:61], v[52:53]
	v_pk_fma_f32 v[58:59], v[44:45], v[72:73], v[64:65]
	v_pk_fma_f32 v[60:61], v[40:41], v[76:77], v[68:69]
	v_pk_fma_f32 v[42:43], v[44:45], v[48:49], v[42:43]
	v_pk_fma_f32 v[38:39], v[40:41], v[52:53], v[38:39]
	s_waitcnt lgkmcnt(5)
	v_mov_b32_e32 v82, v87
	v_add_f32_e32 v29, v66, v67
	v_add_f32_e32 v62, v62, v63
	v_pk_fma_f32 v[70:71], v[86:87], v[12:13], v[70:71] op_sel_hi:[0,1,1]
	v_pk_fma_f32 v[72:73], v[86:87], v[14:15], v[78:79] op_sel_hi:[0,1,1]
	s_waitcnt lgkmcnt(4)
	v_pk_fma_f32 v[74:75], v[86:87], v[8:9], v[74:75] op_sel_hi:[0,1,1]
	v_pk_fma_f32 v[76:77], v[86:87], v[10:11], v[80:81] op_sel_hi:[0,1,1]
	v_pk_add_f32 v[86:87], v[60:61], v[58:59]
	v_pk_add_f32 v[88:89], v[38:39], v[42:43]
	ds_write2st64_b32 v27, v29, v62 offset0:232 offset1:236
	v_add_f32_e32 v29, v86, v87
	v_add_f32_e32 v86, v88, v89
	v_add_u32_e32 v131, 0x2c00, v21
	v_add_f32_dpp v29, v29, v29 quad_perm:[1,0,3,2] row_mask:0xf bank_mask:0xf bound_ctrl:1
	v_add_f32_dpp v86, v86, v86 quad_perm:[1,0,3,2] row_mask:0xf bank_mask:0xf bound_ctrl:1
	v_pk_fma_f32 v[78:79], v[82:83], v[12:13], v[46:47] op_sel_hi:[0,1,1]
	v_pk_fma_f32 v[80:81], v[82:83], v[14:15], v[54:55] op_sel_hi:[0,1,1]
	v_pk_fma_f32 v[84:85], v[82:83], v[8:9], v[50:51] op_sel_hi:[0,1,1]
	v_pk_fma_f32 v[82:83], v[82:83], v[10:11], v[56:57] op_sel_hi:[0,1,1]
	ds_read_b128 v[38:41], v20 offset:11008
	ds_read_b128 v[42:45], v20 offset:11024
	ds_read_b128 v[8:11], v20 offset:10752
	ds_read_b128 v[12:15], v20 offset:10768
	ds_read2_b32 v[90:91], v131 offset0:192 offset1:200
	ds_read_b128 v[54:57], v20 offset:11520
	ds_read_b128 v[58:61], v20 offset:11536
	ds_read_b128 v[46:49], v20 offset:11264
	ds_read_b128 v[50:53], v20 offset:11280
	ds_read_b128 v[62:65], v20 offset:11776
	ds_read_b128 v[66:69], v20 offset:11792
	v_add_f32_dpp v29, v29, v29 quad_perm:[2,3,0,1] row_mask:0xf bank_mask:0xf bound_ctrl:1
	v_add_f32_dpp v87, v86, v86 quad_perm:[2,3,0,1] row_mask:0xf bank_mask:0xf bound_ctrl:1
	v_add_u32_e32 v132, 0x3400, v21
	v_add_f32_dpp v86, v29, v29 row_half_mirror row_mask:0xf bank_mask:0xf bound_ctrl:1
	v_add_f32_dpp v88, v87, v87 row_half_mirror row_mask:0xf bank_mask:0xf bound_ctrl:1
	s_waitcnt lgkmcnt(14)
	v_pk_fma_f32 v[70:71], v[34:35], v[86:87], v[70:71] op_sel_hi:[1,0,1]
	v_pk_fma_f32 v[74:75], v[30:31], v[86:87], v[74:75] op_sel_hi:[1,0,1]
	v_pk_fma_f32 v[34:35], v[34:35], v[88:89], v[78:79] op_sel_hi:[1,0,1]
	v_pk_fma_f32 v[30:31], v[30:31], v[88:89], v[84:85] op_sel_hi:[1,0,1]
	v_pk_fma_f32 v[72:73], v[36:37], v[86:87], v[72:73] op_sel_hi:[1,0,1]
	v_pk_fma_f32 v[76:77], v[32:33], v[86:87], v[76:77] op_sel_hi:[1,0,1]
	v_pk_fma_f32 v[36:37], v[36:37], v[88:89], v[80:81] op_sel_hi:[1,0,1]
	v_pk_fma_f32 v[32:33], v[32:33], v[88:89], v[82:83] op_sel_hi:[1,0,1]
	s_waitcnt lgkmcnt(12)
	v_pk_mul_f32 v[78:79], v[4:5], v[70:71]
	v_pk_mul_f32 v[80:81], v[0:1], v[74:75]
	v_pk_mul_f32 v[4:5], v[4:5], v[34:35]
	v_pk_mul_f32 v[0:1], v[0:1], v[30:31]
	s_waitcnt lgkmcnt(8)
	v_pk_mul_f32 v[82:83], v[38:39], v[70:71]
	v_pk_mul_f32 v[84:85], v[42:43], v[74:75]
	v_pk_mul_f32 v[38:39], v[38:39], v[34:35]
	v_pk_mul_f32 v[42:43], v[42:43], v[30:31]
	v_pk_mul_f32 v[70:71], v[8:9], v[70:71]
	v_pk_mul_f32 v[86:87], v[10:11], v[72:73]
	s_waitcnt lgkmcnt(7)
	v_pk_mul_f32 v[74:75], v[12:13], v[74:75]
	v_pk_mul_f32 v[88:89], v[14:15], v[76:77]
	v_pk_mul_f32 v[8:9], v[8:9], v[34:35]
	v_pk_mul_f32 v[10:11], v[10:11], v[36:37]
	v_pk_mul_f32 v[12:13], v[12:13], v[30:31]
	v_pk_mul_f32 v[14:15], v[14:15], v[32:33]
	v_pk_fma_f32 v[30:31], v[6:7], v[72:73], v[78:79]
	v_pk_fma_f32 v[34:35], v[2:3], v[76:77], v[80:81]
	v_pk_fma_f32 v[4:5], v[6:7], v[36:37], v[4:5]
	v_pk_fma_f32 v[0:1], v[2:3], v[32:33], v[0:1]
	v_pk_fma_f32 v[2:3], v[40:41], v[72:73], v[82:83]
	v_pk_fma_f32 v[6:7], v[44:45], v[76:77], v[84:85]
	v_pk_fma_f32 v[36:37], v[40:41], v[36:37], v[38:39]
	v_pk_fma_f32 v[32:33], v[44:45], v[32:33], v[42:43]
	s_waitcnt lgkmcnt(5)
	v_mov_b32_e32 v92, v91
	v_pk_add_f32 v[0:1], v[4:5], v[0:1]
	v_pk_add_f32 v[2:3], v[2:3], v[6:7]
	v_pk_add_f32 v[4:5], v[36:37], v[32:33]
	v_pk_fma_f32 v[78:79], v[54:55], v[92:93], v[8:9] op_sel_hi:[1,0,1]
	v_pk_add_f32 v[8:9], v[30:31], v[34:35]
	v_add_f32_e32 v0, v0, v1
	v_add_f32_e32 v1, v2, v3
	v_add_f32_e32 v2, v4, v5
	s_waitcnt lgkmcnt(4)
; #define SCAN_STEP(w0, w1, a0, a1, b0, b1, k0, k1, r0, r1, vi, vj, t) do { \
;                 SCAN_ROW(S0, S1, S2, S3, w0, w1, a0, a1, b0, b1, k0, k1, r0, r1, vi, (t) * 512); \
;                 SCAN_ROW(T0, T1, T2, T3, w0, w1, a0, a1, b0, b1, k0, k1, r0, r1, vj, (t) * 512 + 256); } while (0)
;     ...
;             SCAN_LOAD(w0, w1, a0, a1, b0, b1, k0, k1, r0, r1, vi, vj, 0);
; #pragma unroll
;             for (int t = 0; t < 16; t += 2) {
;                 SCAN_LOAD(W0, W1, A0, A1, B0, B1, K0, K1, R0, R1, VI, VJ, t + 1);
;                 SCAN_STEP(w0, w1, a0, a1, b0, b1, k0, k1, r0, r1, vi, vj, t);
;                 if (t + 2 < 16) SCAN_LOAD(w0, w1, a0, a1, b0, b1, k0, k1, r0, r1, vi, vj, t + 2);
;                 SCAN_STEP(W0, W1, A0, A1, B0, B1, K0, K1, R0, R1, VI, VJ, t + 1);
	v_pk_fma_f32 v[76:77], v[60:61], v[90:91], v[88:89] op_sel_hi:[1,0,1]
	v_add_f32_e32 v6, v8, v9
	v_add_f32_dpp v29, v1, v1 quad_perm:[1,0,3,2] row_mask:0xf bank_mask:0xf bound_ctrl:1
	v_add_f32_dpp v88, v2, v2 quad_perm:[1,0,3,2] row_mask:0xf bank_mask:0xf bound_ctrl:1
	ds_write2st64_b32 v27, v6, v0 offset0:240 offset1:244
	v_add_f32_dpp v29, v29, v29 quad_perm:[2,3,0,1] row_mask:0xf bank_mask:0xf bound_ctrl:1
	v_add_f32_dpp v89, v88, v88 quad_perm:[2,3,0,1] row_mask:0xf bank_mask:0xf bound_ctrl:1
	v_pk_fma_f32 v[70:71], v[54:55], v[90:91], v[70:71] op_sel_hi:[1,0,1]
	v_pk_fma_f32 v[72:73], v[56:57], v[90:91], v[86:87] op_sel_hi:[1,0,1]
	v_pk_fma_f32 v[74:75], v[58:59], v[90:91], v[74:75] op_sel_hi:[1,0,1]
	v_pk_fma_f32 v[80:81], v[56:57], v[92:93], v[10:11] op_sel_hi:[1,0,1]
	v_pk_fma_f32 v[82:83], v[58:59], v[92:93], v[12:13] op_sel_hi:[1,0,1]
	v_pk_fma_f32 v[84:85], v[60:61], v[92:93], v[14:15] op_sel_hi:[1,0,1]
	ds_read_b128 v[42:45], v20 offset:12544
	ds_read_b128 v[38:41], v20 offset:12560
	ds_read_b128 v[54:57], v20 offset:12288
	ds_read_b128 v[58:61], v20 offset:12304
	ds_read2_b32 v[86:87], v132 offset0:64 offset1:72
	ds_read_b128 v[12:15], v20 offset:13056
	ds_read_b128 v[8:11], v20 offset:13072
	ds_read_b128 v[34:37], v20 offset:12800
	ds_read_b128 v[30:33], v20 offset:12816
	ds_read_b128 v[4:7], v20 offset:13312
	ds_read_b128 v[0:3], v20 offset:13328
	v_add_f32_dpp v88, v29, v29 row_half_mirror row_mask:0xf bank_mask:0xf bound_ctrl:1
	v_add_f32_dpp v90, v89, v89 row_half_mirror row_mask:0xf bank_mask:0xf bound_ctrl:1
	s_waitcnt lgkmcnt(14)
	v_pk_fma_f32 v[70:71], v[46:47], v[88:89], v[70:71] op_sel_hi:[1,0,1]
	v_pk_fma_f32 v[74:75], v[50:51], v[88:89], v[74:75] op_sel_hi:[1,0,1]
	v_pk_fma_f32 v[46:47], v[46:47], v[90:91], v[78:79] op_sel_hi:[1,0,1]
	v_pk_fma_f32 v[50:51], v[50:51], v[90:91], v[82:83] op_sel_hi:[1,0,1]
	v_pk_fma_f32 v[72:73], v[48:49], v[88:89], v[72:73] op_sel_hi:[1,0,1]
	v_pk_fma_f32 v[76:77], v[52:53], v[88:89], v[76:77] op_sel_hi:[1,0,1]
	v_pk_fma_f32 v[48:49], v[48:49], v[90:91], v[80:81] op_sel_hi:[1,0,1]
	v_pk_fma_f32 v[52:53], v[52:53], v[90:91], v[84:85] op_sel_hi:[1,0,1]
	s_waitcnt lgkmcnt(12)
	v_pk_mul_f32 v[78:79], v[62:63], v[70:71]
	v_pk_mul_f32 v[80:81], v[66:67], v[74:75]
	v_pk_mul_f32 v[62:63], v[62:63], v[46:47]
	v_pk_mul_f32 v[66:67], v[66:67], v[50:51]
	v_pk_fma_f32 v[78:79], v[64:65], v[72:73], v[78:79]
	v_pk_fma_f32 v[62:63], v[64:65], v[48:49], v[62:63]
	v_pk_fma_f32 v[64:65], v[68:69], v[52:53], v[66:67]
	v_pk_fma_f32 v[80:81], v[68:69], v[76:77], v[80:81]
	v_pk_add_f32 v[62:63], v[62:63], v[64:65]
	s_waitcnt lgkmcnt(9)
	v_pk_mul_f32 v[64:65], v[42:43], v[70:71]
	v_pk_mul_f32 v[68:69], v[38:39], v[74:75]
	v_pk_mul_f32 v[42:43], v[42:43], v[46:47]
	v_pk_mul_f32 v[38:39], v[38:39], v[50:51]
	v_pk_add_f32 v[66:67], v[78:79], v[80:81]
	s_waitcnt lgkmcnt(7)
	v_pk_mul_f32 v[70:71], v[54:55], v[70:71]
	v_pk_mul_f32 v[78:79], v[56:57], v[72:73]
	v_pk_mul_f32 v[74:75], v[58:59], v[74:75]
	v_pk_mul_f32 v[80:81], v[60:61], v[76:77]
	v_pk_mul_f32 v[46:47], v[54:55], v[46:47]
	v_pk_mul_f32 v[54:55], v[56:57], v[48:49]
	v_pk_mul_f32 v[50:51], v[58:59], v[50:51]
	v_pk_mul_f32 v[56:57], v[60:61], v[52:53]
	v_pk_fma_f32 v[58:59], v[44:45], v[72:73], v[64:65]
	v_pk_fma_f32 v[60:61], v[40:41], v[76:77], v[68:69]
	v_pk_fma_f32 v[42:43], v[44:45], v[48:49], v[42:43]
	v_pk_fma_f32 v[38:39], v[40:41], v[52:53], v[38:39]
	s_waitcnt lgkmcnt(5)
	v_mov_b32_e32 v82, v87
	v_add_f32_e32 v29, v66, v67
	v_add_f32_e32 v62, v62, v63
	v_pk_fma_f32 v[70:71], v[86:87], v[12:13], v[70:71] op_sel_hi:[0,1,1]
	v_pk_fma_f32 v[72:73], v[86:87], v[14:15], v[78:79] op_sel_hi:[0,1,1]
	s_waitcnt lgkmcnt(4)
	v_pk_fma_f32 v[74:75], v[86:87], v[8:9], v[74:75] op_sel_hi:[0,1,1]
	v_pk_fma_f32 v[76:77], v[86:87], v[10:11], v[80:81] op_sel_hi:[0,1,1]
	v_pk_add_f32 v[86:87], v[60:61], v[58:59]
	v_pk_add_f32 v[88:89], v[38:39], v[42:43]
	v_add_u32_e32 v19, 0xc000, v27
	v_add_u32_e32 v28, 0x3800, v21
	ds_write2st64_b32 v27, v29, v62 offset0:248 offset1:252
	v_add_f32_e32 v27, v86, v87
	v_add_f32_e32 v86, v88, v89
	v_pk_fma_f32 v[78:79], v[82:83], v[12:13], v[46:47] op_sel_hi:[0,1,1]
	v_pk_fma_f32 v[80:81], v[82:83], v[14:15], v[54:55] op_sel_hi:[0,1,1]
	v_pk_fma_f32 v[84:85], v[82:83], v[8:9], v[50:51] op_sel_hi:[0,1,1]
	v_pk_fma_f32 v[82:83], v[82:83], v[10:11], v[56:57] op_sel_hi:[0,1,1]
	ds_read2_b32 v[28:29], v28 offset0:192 offset1:200
	ds_read_b128 v[38:41], v20 offset:14080
	ds_read_b128 v[42:45], v20 offset:14096
	ds_read_b128 v[8:11], v20 offset:13824
	ds_read_b128 v[12:15], v20 offset:13840
	ds_read_b128 v[54:57], v20 offset:14592
	ds_read_b128 v[58:61], v20 offset:14608
	ds_read_b128 v[46:49], v20 offset:14336
	ds_read_b128 v[50:53], v20 offset:14352
	ds_read_b128 v[62:65], v20 offset:14848
	ds_read_b128 v[66:69], v20 offset:14864
	v_add_f32_dpp v27, v27, v27 quad_perm:[1,0,3,2] row_mask:0xf bank_mask:0xf bound_ctrl:1
	v_add_f32_dpp v86, v86, v86 quad_perm:[1,0,3,2] row_mask:0xf bank_mask:0xf bound_ctrl:1
	v_add_u32_e32 v26, 0x4000, v21
	v_add_f32_dpp v27, v27, v27 quad_perm:[2,3,0,1] row_mask:0xf bank_mask:0xf bound_ctrl:1
	v_add_f32_dpp v87, v86, v86 quad_perm:[2,3,0,1] row_mask:0xf bank_mask:0xf bound_ctrl:1
	s_waitcnt lgkmcnt(10)
; #define SCAN_STEP(w0, w1, a0, a1, b0, b1, k0, k1, r0, r1, vi, vj, t) do { \
;                 SCAN_ROW(S0, S1, S2, S3, w0, w1, a0, a1, b0, b1, k0, k1, r0, r1, vi, (t) * 512); \
;                 SCAN_ROW(T0, T1, T2, T3, w0, w1, a0, a1, b0, b1, k0, k1, r0, r1, vj, (t) * 512 + 256); } while (0)
;     ...
;             SCAN_LOAD(w0, w1, a0, a1, b0, b1, k0, k1, r0, r1, vi, vj, 0);
; #pragma unroll
;             for (int t = 0; t < 16; t += 2) {
;                 SCAN_LOAD(W0, W1, A0, A1, B0, B1, K0, K1, R0, R1, VI, VJ, t + 1);
;                 SCAN_STEP(w0, w1, a0, a1, b0, b1, k0, k1, r0, r1, vi, vj, t);
;                 if (t + 2 < 16) SCAN_LOAD(w0, w1, a0, a1, b0, b1, k0, k1, r0, r1, vi, vj, t + 2);
;                 SCAN_STEP(W0, W1, A0, A1, B0, B1, K0, K1, R0, R1, VI, VJ, t + 1);
	v_mov_b32_e32 v90, v29
	v_add_f32_dpp v86, v27, v27 row_half_mirror row_mask:0xf bank_mask:0xf bound_ctrl:1
	v_add_f32_dpp v88, v87, v87 row_half_mirror row_mask:0xf bank_mask:0xf bound_ctrl:1
	v_pk_fma_f32 v[70:71], v[34:35], v[86:87], v[70:71] op_sel_hi:[1,0,1]
	v_pk_fma_f32 v[72:73], v[36:37], v[86:87], v[72:73] op_sel_hi:[1,0,1]
	v_pk_fma_f32 v[74:75], v[30:31], v[86:87], v[74:75] op_sel_hi:[1,0,1]
	v_pk_fma_f32 v[76:77], v[32:33], v[86:87], v[76:77] op_sel_hi:[1,0,1]
	v_pk_fma_f32 v[34:35], v[34:35], v[88:89], v[78:79] op_sel_hi:[1,0,1]
	v_pk_fma_f32 v[30:31], v[30:31], v[88:89], v[84:85] op_sel_hi:[1,0,1]
	v_pk_fma_f32 v[36:37], v[36:37], v[88:89], v[80:81] op_sel_hi:[1,0,1]
	v_pk_fma_f32 v[32:33], v[32:33], v[88:89], v[82:83] op_sel_hi:[1,0,1]
	v_pk_mul_f32 v[78:79], v[4:5], v[70:71]
	v_pk_mul_f32 v[80:81], v[0:1], v[74:75]
	v_pk_mul_f32 v[4:5], v[4:5], v[34:35]
	v_pk_mul_f32 v[0:1], v[0:1], v[30:31]
	s_waitcnt lgkmcnt(6)
	v_pk_mul_f32 v[82:83], v[38:39], v[70:71]
	v_pk_mul_f32 v[84:85], v[42:43], v[74:75]
	v_pk_mul_f32 v[70:71], v[8:9], v[70:71]
	v_pk_mul_f32 v[86:87], v[10:11], v[72:73]
	v_pk_mul_f32 v[74:75], v[12:13], v[74:75]
	v_pk_mul_f32 v[88:89], v[14:15], v[76:77]
	v_pk_mul_f32 v[38:39], v[38:39], v[34:35]
	v_pk_mul_f32 v[42:43], v[42:43], v[30:31]
	v_pk_mul_f32 v[8:9], v[8:9], v[34:35]
	v_pk_mul_f32 v[12:13], v[12:13], v[30:31]
	v_pk_mul_f32 v[14:15], v[14:15], v[32:33]
	v_pk_fma_f32 v[30:31], v[6:7], v[72:73], v[78:79]
	v_pk_fma_f32 v[34:35], v[2:3], v[76:77], v[80:81]
	v_pk_fma_f32 v[4:5], v[6:7], v[36:37], v[4:5]
	v_pk_fma_f32 v[0:1], v[2:3], v[32:33], v[0:1]
	v_pk_fma_f32 v[2:3], v[40:41], v[72:73], v[82:83]
	v_pk_fma_f32 v[6:7], v[44:45], v[76:77], v[84:85]
	s_waitcnt lgkmcnt(4)
	v_pk_fma_f32 v[70:71], v[54:55], v[28:29], v[70:71] op_sel_hi:[1,0,1]
	v_pk_fma_f32 v[72:73], v[56:57], v[28:29], v[86:87] op_sel_hi:[1,0,1]
	v_pk_fma_f32 v[74:75], v[58:59], v[28:29], v[74:75] op_sel_hi:[1,0,1]
	v_pk_fma_f32 v[76:77], v[60:61], v[28:29], v[88:89] op_sel_hi:[1,0,1]
	v_pk_fma_f32 v[28:29], v[40:41], v[36:37], v[38:39]
	v_pk_fma_f32 v[32:33], v[44:45], v[32:33], v[42:43]
	v_pk_add_f32 v[0:1], v[4:5], v[0:1]
	v_pk_add_f32 v[2:3], v[2:3], v[6:7]
	v_pk_add_f32 v[4:5], v[28:29], v[32:33]
	v_pk_fma_f32 v[78:79], v[54:55], v[90:91], v[8:9] op_sel_hi:[1,0,1]
	v_pk_add_f32 v[8:9], v[30:31], v[34:35]
	v_add_f32_e32 v0, v0, v1
	v_add_f32_e32 v1, v2, v3
	v_add_f32_e32 v2, v4, v5
	v_add_f32_e32 v6, v8, v9
	v_add_f32_dpp v84, v1, v1 quad_perm:[1,0,3,2] row_mask:0xf bank_mask:0xf bound_ctrl:1
	v_add_f32_dpp v85, v2, v2 quad_perm:[1,0,3,2] row_mask:0xf bank_mask:0xf bound_ctrl:1
	v_pk_mul_f32 v[10:11], v[10:11], v[36:37]
	ds_write2st64_b32 v19, v6, v0 offset0:64 offset1:68
	v_add_f32_dpp v84, v84, v84 quad_perm:[2,3,0,1] row_mask:0xf bank_mask:0xf bound_ctrl:1
	v_add_f32_dpp v85, v85, v85 quad_perm:[2,3,0,1] row_mask:0xf bank_mask:0xf bound_ctrl:1
	v_pk_fma_f32 v[80:81], v[56:57], v[90:91], v[10:11] op_sel_hi:[1,0,1]
	v_pk_fma_f32 v[58:59], v[58:59], v[90:91], v[12:13] op_sel_hi:[1,0,1]
	v_pk_fma_f32 v[60:61], v[60:61], v[90:91], v[14:15] op_sel_hi:[1,0,1]
	ds_read2_b32 v[82:83], v26 offset0:64 offset1:72
	ds_read_b128 v[0:3], v20 offset:16400
	ds_read_b128 v[4:7], v20 offset:16384
	ds_read_b128 v[8:11], v20 offset:16144
	ds_read_b128 v[12:15], v20 offset:16128
	ds_read_b128 v[26:29], v20 offset:15888
	ds_read_b128 v[30:33], v20 offset:15872
	ds_read_b128 v[34:37], v20 offset:15632
	ds_read_b128 v[38:41], v20 offset:15616
	ds_read_b128 v[42:45], v20 offset:15360
	ds_read_b128 v[54:57], v20 offset:15376
	v_add_f32_dpp v84, v84, v84 row_half_mirror row_mask:0xf bank_mask:0xf bound_ctrl:1
	v_add_f32_dpp v86, v85, v85 row_half_mirror row_mask:0xf bank_mask:0xf bound_ctrl:1
	s_waitcnt lgkmcnt(14)
	v_pk_fma_f32 v[70:71], v[46:47], v[84:85], v[70:71] op_sel_hi:[1,0,1]
	v_pk_fma_f32 v[74:75], v[50:51], v[84:85], v[74:75] op_sel_hi:[1,0,1]
	v_pk_fma_f32 v[46:47], v[46:47], v[86:87], v[78:79] op_sel_hi:[1,0,1]
	v_pk_fma_f32 v[50:51], v[50:51], v[86:87], v[58:59] op_sel_hi:[1,0,1]
	v_pk_fma_f32 v[72:73], v[48:49], v[84:85], v[72:73] op_sel_hi:[1,0,1]
	v_pk_fma_f32 v[76:77], v[52:53], v[84:85], v[76:77] op_sel_hi:[1,0,1]
	v_pk_fma_f32 v[48:49], v[48:49], v[86:87], v[80:81] op_sel_hi:[1,0,1]
	v_pk_fma_f32 v[52:53], v[52:53], v[86:87], v[60:61] op_sel_hi:[1,0,1]
	s_waitcnt lgkmcnt(12)
	v_pk_mul_f32 v[58:59], v[62:63], v[70:71]
	v_pk_mul_f32 v[60:61], v[66:67], v[74:75]
	v_pk_mul_f32 v[62:63], v[62:63], v[46:47]
	v_pk_mul_f32 v[66:67], v[66:67], v[50:51]
	v_pk_fma_f32 v[58:59], v[64:65], v[72:73], v[58:59]
	v_pk_fma_f32 v[60:61], v[68:69], v[76:77], v[60:61]
	v_pk_fma_f32 v[62:63], v[64:65], v[48:49], v[62:63]
	v_pk_fma_f32 v[64:65], v[68:69], v[52:53], v[66:67]
	v_pk_add_f32 v[58:59], v[58:59], v[60:61]
	v_pk_add_f32 v[60:61], v[62:63], v[64:65]
	s_waitcnt lgkmcnt(1)
	v_pk_mul_f32 v[62:63], v[38:39], v[70:71]
	v_pk_mul_f32 v[64:65], v[34:35], v[74:75]
	v_pk_mul_f32 v[38:39], v[38:39], v[46:47]
	v_pk_mul_f32 v[34:35], v[34:35], v[50:51]
	v_pk_mul_f32 v[66:67], v[42:43], v[70:71]
	v_pk_mul_f32 v[68:69], v[44:45], v[72:73]
	s_waitcnt lgkmcnt(0)
; #define SCAN_STEP(w0, w1, a0, a1, b0, b1, k0, k1, r0, r1, vi, vj, t) do { \
;                 SCAN_ROW(S0, S1, S2, S3, w0, w1, a0, a1, b0, b1, k0, k1, r0, r1, vi, (t) * 512); \
;                 SCAN_ROW(T0, T1, T2, T3, w0, w1, a0, a1, b0, b1, k0, k1, r0, r1, vj, (t) * 512 + 256); } while (0)
;     ...
;             SCAN_LOAD(w0, w1, a0, a1, b0, b1, k0, k1, r0, r1, vi, vj, 0);
; #pragma unroll
;             for (int t = 0; t < 16; t += 2) {
;                 SCAN_LOAD(W0, W1, A0, A1, B0, B1, K0, K1, R0, R1, VI, VJ, t + 1);
;                 SCAN_STEP(w0, w1, a0, a1, b0, b1, k0, k1, r0, r1, vi, vj, t);
;                 if (t + 2 < 16) SCAN_LOAD(w0, w1, a0, a1, b0, b1, k0, k1, r0, r1, vi, vj, t + 2);
;                 SCAN_STEP(W0, W1, A0, A1, B0, B1, K0, K1, R0, R1, VI, VJ, t + 1);
	v_pk_mul_f32 v[70:71], v[54:55], v[74:75]
	v_pk_mul_f32 v[74:75], v[56:57], v[76:77]
	v_pk_mul_f32 v[42:43], v[42:43], v[46:47]
	v_pk_mul_f32 v[46:47], v[54:55], v[50:51]
	v_pk_mul_f32 v[50:51], v[56:57], v[52:53]
	v_add_f32_e32 v58, v58, v59
	v_add_f32_e32 v59, v60, v61
	v_pk_fma_f32 v[54:55], v[40:41], v[72:73], v[62:63]
	v_pk_fma_f32 v[56:57], v[36:37], v[76:77], v[64:65]
	v_pk_fma_f32 v[38:39], v[40:41], v[48:49], v[38:39]
	v_pk_fma_f32 v[34:35], v[36:37], v[52:53], v[34:35]
	v_add_u32_e32 v25, 0x4400, v21
	v_mov_b32_e32 v78, v83
	v_pk_mul_f32 v[44:45], v[44:45], v[48:49]
	v_pk_fma_f32 v[66:67], v[82:83], v[12:13], v[66:67] op_sel_hi:[0,1,1]
	v_pk_fma_f32 v[68:69], v[82:83], v[14:15], v[68:69] op_sel_hi:[0,1,1]
	v_pk_fma_f32 v[70:71], v[82:83], v[8:9], v[70:71] op_sel_hi:[0,1,1]
	v_pk_fma_f32 v[72:73], v[82:83], v[10:11], v[74:75] op_sel_hi:[0,1,1]
	ds_write2st64_b32 v19, v58, v59 offset0:72 offset1:76
	v_pk_add_f32 v[82:83], v[56:57], v[54:55]
	v_pk_add_f32 v[84:85], v[34:35], v[38:39]
	v_pk_fma_f32 v[74:75], v[78:79], v[12:13], v[42:43] op_sel_hi:[0,1,1]
	v_pk_fma_f32 v[76:77], v[78:79], v[14:15], v[44:45] op_sel_hi:[0,1,1]
	v_pk_fma_f32 v[80:81], v[78:79], v[8:9], v[46:47] op_sel_hi:[0,1,1]
	v_pk_fma_f32 v[78:79], v[78:79], v[10:11], v[50:51] op_sel_hi:[0,1,1]
	ds_read2_b32 v[86:87], v25 offset0:192 offset1:200
	ds_read_b128 v[34:37], v20 offset:17152
	ds_read_b128 v[38:41], v20 offset:17168
	ds_read_b128 v[8:11], v20 offset:16896
	ds_read_b128 v[12:15], v20 offset:16912
	ds_read_b128 v[50:53], v20 offset:17664
	ds_read_b128 v[54:57], v20 offset:17680
	ds_read_b128 v[42:45], v20 offset:17408
	ds_read_b128 v[46:49], v20 offset:17424
	ds_read_b128 v[58:61], v20 offset:17920
	ds_read_b128 v[62:65], v20 offset:17936
	v_add_f32_e32 v25, v82, v83
	v_add_f32_e32 v82, v84, v85
	v_add_u32_e32 v24, 0x4c00, v21
	v_add_f32_dpp v25, v25, v25 quad_perm:[1,0,3,2] row_mask:0xf bank_mask:0xf bound_ctrl:1
	v_add_f32_dpp v82, v82, v82 quad_perm:[1,0,3,2] row_mask:0xf bank_mask:0xf bound_ctrl:1
	s_waitcnt lgkmcnt(10)
	v_mov_b32_e32 v88, v87
	v_add_f32_dpp v25, v25, v25 quad_perm:[2,3,0,1] row_mask:0xf bank_mask:0xf bound_ctrl:1
	v_add_f32_dpp v83, v82, v82 quad_perm:[2,3,0,1] row_mask:0xf bank_mask:0xf bound_ctrl:1
	v_add_u32_e32 v23, 0x5000, v21
	v_add_f32_dpp v82, v25, v25 row_half_mirror row_mask:0xf bank_mask:0xf bound_ctrl:1
	v_add_f32_dpp v84, v83, v83 row_half_mirror row_mask:0xf bank_mask:0xf bound_ctrl:1
	v_pk_fma_f32 v[66:67], v[30:31], v[82:83], v[66:67] op_sel_hi:[1,0,1]
	v_pk_fma_f32 v[70:71], v[26:27], v[82:83], v[70:71] op_sel_hi:[1,0,1]
	v_pk_fma_f32 v[30:31], v[30:31], v[84:85], v[74:75] op_sel_hi:[1,0,1]
	v_pk_fma_f32 v[26:27], v[26:27], v[84:85], v[80:81] op_sel_hi:[1,0,1]
	v_pk_fma_f32 v[68:69], v[32:33], v[82:83], v[68:69] op_sel_hi:[1,0,1]
	v_pk_fma_f32 v[72:73], v[28:29], v[82:83], v[72:73] op_sel_hi:[1,0,1]
	v_pk_fma_f32 v[32:33], v[32:33], v[84:85], v[76:77] op_sel_hi:[1,0,1]
	v_pk_fma_f32 v[28:29], v[28:29], v[84:85], v[78:79] op_sel_hi:[1,0,1]
	v_pk_mul_f32 v[74:75], v[4:5], v[66:67]
	v_pk_mul_f32 v[76:77], v[0:1], v[70:71]
	v_pk_mul_f32 v[4:5], v[4:5], v[30:31]
	v_pk_mul_f32 v[0:1], v[0:1], v[26:27]
	s_waitcnt lgkmcnt(7)
	v_pk_mul_f32 v[78:79], v[34:35], v[66:67]
	v_pk_mul_f32 v[80:81], v[38:39], v[70:71]
	v_pk_mul_f32 v[34:35], v[34:35], v[30:31]
	v_pk_mul_f32 v[38:39], v[38:39], v[26:27]
	v_pk_mul_f32 v[66:67], v[8:9], v[66:67]
	v_pk_mul_f32 v[82:83], v[10:11], v[68:69]
	s_waitcnt lgkmcnt(6)
	v_pk_mul_f32 v[70:71], v[12:13], v[70:71]
	v_pk_mul_f32 v[84:85], v[14:15], v[72:73]
	v_pk_mul_f32 v[8:9], v[8:9], v[30:31]
	v_pk_mul_f32 v[10:11], v[10:11], v[32:33]
	v_pk_mul_f32 v[12:13], v[12:13], v[26:27]
	v_pk_mul_f32 v[14:15], v[14:15], v[28:29]
	v_pk_fma_f32 v[26:27], v[6:7], v[68:69], v[74:75]
	v_pk_fma_f32 v[30:31], v[2:3], v[72:73], v[76:77]
	v_pk_fma_f32 v[4:5], v[6:7], v[32:33], v[4:5]
	v_pk_fma_f32 v[0:1], v[2:3], v[28:29], v[0:1]
	v_pk_fma_f32 v[2:3], v[36:37], v[68:69], v[78:79]
	v_pk_fma_f32 v[6:7], v[40:41], v[72:73], v[80:81]
	v_pk_fma_f32 v[32:33], v[36:37], v[32:33], v[34:35]
	v_pk_fma_f32 v[28:29], v[40:41], v[28:29], v[38:39]
	v_pk_add_f32 v[0:1], v[4:5], v[0:1]
	v_pk_add_f32 v[2:3], v[2:3], v[6:7]
	v_pk_add_f32 v[4:5], v[32:33], v[28:29]
	s_waitcnt lgkmcnt(5)
	v_pk_fma_f32 v[40:41], v[50:51], v[88:89], v[8:9] op_sel_hi:[1,0,1]
	v_pk_add_f32 v[8:9], v[26:27], v[30:31]
	v_add_f32_e32 v0, v0, v1
	v_add_f32_e32 v1, v2, v3
	v_add_f32_e32 v2, v4, v5
	v_pk_fma_f32 v[68:69], v[52:53], v[86:87], v[82:83] op_sel_hi:[1,0,1]
	v_add_f32_e32 v6, v8, v9
	v_add_f32_dpp v82, v1, v1 quad_perm:[1,0,3,2] row_mask:0xf bank_mask:0xf bound_ctrl:1
	v_add_f32_dpp v83, v2, v2 quad_perm:[1,0,3,2] row_mask:0xf bank_mask:0xf bound_ctrl:1
	ds_write2st64_b32 v19, v6, v0 offset0:80 offset1:84
	v_add_f32_dpp v82, v82, v82 quad_perm:[2,3,0,1] row_mask:0xf bank_mask:0xf bound_ctrl:1
	v_add_f32_dpp v83, v83, v83 quad_perm:[2,3,0,1] row_mask:0xf bank_mask:0xf bound_ctrl:1
	v_pk_fma_f32 v[66:67], v[50:51], v[86:87], v[66:67] op_sel_hi:[1,0,1]
	s_waitcnt lgkmcnt(5)
	v_pk_fma_f32 v[70:71], v[54:55], v[86:87], v[70:71] op_sel_hi:[1,0,1]
	v_pk_fma_f32 v[72:73], v[56:57], v[86:87], v[84:85] op_sel_hi:[1,0,1]
	v_pk_fma_f32 v[74:75], v[52:53], v[88:89], v[10:11] op_sel_hi:[1,0,1]
	v_pk_fma_f32 v[76:77], v[54:55], v[88:89], v[12:13] op_sel_hi:[1,0,1]
	v_pk_fma_f32 v[78:79], v[56:57], v[88:89], v[14:15] op_sel_hi:[1,0,1]
	ds_read2_b32 v[80:81], v24 offset0:64 offset1:72
	ds_read_b128 v[0:3], v20 offset:19472
	ds_read_b128 v[4:7], v20 offset:19456
	ds_read_b128 v[8:11], v20 offset:19216
	ds_read_b128 v[12:15], v20 offset:19200
	ds_read_b128 v[24:27], v20 offset:18960
	ds_read_b128 v[28:31], v20 offset:18944
	ds_read_b128 v[32:35], v20 offset:18704
	ds_read_b128 v[36:39], v20 offset:18688
	ds_read_b128 v[50:53], v20 offset:18432
	ds_read_b128 v[54:57], v20 offset:18448
	v_add_f32_dpp v82, v82, v82 row_half_mirror row_mask:0xf bank_mask:0xf bound_ctrl:1
	v_add_f32_dpp v84, v83, v83 row_half_mirror row_mask:0xf bank_mask:0xf bound_ctrl:1
	s_waitcnt lgkmcnt(14)
; #define SCAN_STEP(w0, w1, a0, a1, b0, b1, k0, k1, r0, r1, vi, vj, t) do { \
;                 SCAN_ROW(S0, S1, S2, S3, w0, w1, a0, a1, b0, b1, k0, k1, r0, r1, vi, (t) * 512); \
;                 SCAN_ROW(T0, T1, T2, T3, w0, w1, a0, a1, b0, b1, k0, k1, r0, r1, vj, (t) * 512 + 256); } while (0)
;     ...
;             SCAN_LOAD(w0, w1, a0, a1, b0, b1, k0, k1, r0, r1, vi, vj, 0);
; #pragma unroll
;             for (int t = 0; t < 16; t += 2) {
;                 SCAN_LOAD(W0, W1, A0, A1, B0, B1, K0, K1, R0, R1, VI, VJ, t + 1);
;                 SCAN_STEP(w0, w1, a0, a1, b0, b1, k0, k1, r0, r1, vi, vj, t);
;                 if (t + 2 < 16) SCAN_LOAD(w0, w1, a0, a1, b0, b1, k0, k1, r0, r1, vi, vj, t + 2);
;                 SCAN_STEP(W0, W1, A0, A1, B0, B1, K0, K1, R0, R1, VI, VJ, t + 1);
	v_pk_fma_f32 v[66:67], v[42:43], v[82:83], v[66:67] op_sel_hi:[1,0,1]
	v_pk_fma_f32 v[68:69], v[44:45], v[82:83], v[68:69] op_sel_hi:[1,0,1]
	v_pk_fma_f32 v[70:71], v[46:47], v[82:83], v[70:71] op_sel_hi:[1,0,1]
	v_pk_fma_f32 v[40:41], v[42:43], v[84:85], v[40:41] op_sel_hi:[1,0,1]
	v_pk_fma_f32 v[42:43], v[44:45], v[84:85], v[74:75] op_sel_hi:[1,0,1]
	v_pk_fma_f32 v[44:45], v[46:47], v[84:85], v[76:77] op_sel_hi:[1,0,1]
	v_pk_fma_f32 v[72:73], v[48:49], v[82:83], v[72:73] op_sel_hi:[1,0,1]
	v_pk_fma_f32 v[46:47], v[48:49], v[84:85], v[78:79] op_sel_hi:[1,0,1]
	s_waitcnt lgkmcnt(12)
	v_pk_mul_f32 v[48:49], v[58:59], v[66:67]
	v_pk_mul_f32 v[74:75], v[62:63], v[70:71]
	v_pk_mul_f32 v[58:59], v[58:59], v[40:41]
	v_pk_mul_f32 v[62:63], v[62:63], v[44:45]
	v_pk_fma_f32 v[48:49], v[60:61], v[68:69], v[48:49]
	v_pk_fma_f32 v[74:75], v[64:65], v[72:73], v[74:75]
	v_pk_fma_f32 v[58:59], v[60:61], v[42:43], v[58:59]
	v_pk_fma_f32 v[60:61], v[64:65], v[46:47], v[62:63]
	v_pk_add_f32 v[48:49], v[48:49], v[74:75]
	v_pk_add_f32 v[58:59], v[58:59], v[60:61]
	s_waitcnt lgkmcnt(1)
	v_pk_mul_f32 v[60:61], v[36:37], v[66:67]
	v_pk_mul_f32 v[62:63], v[32:33], v[70:71]
	v_pk_mul_f32 v[36:37], v[36:37], v[40:41]
	v_pk_mul_f32 v[32:33], v[32:33], v[44:45]
	v_pk_mul_f32 v[64:65], v[50:51], v[66:67]
	v_pk_mul_f32 v[66:67], v[52:53], v[68:69]
	s_waitcnt lgkmcnt(0)
	v_pk_mul_f32 v[70:71], v[54:55], v[70:71]
	v_pk_mul_f32 v[74:75], v[56:57], v[72:73]
	v_pk_mul_f32 v[40:41], v[50:51], v[40:41]
	v_pk_mul_f32 v[50:51], v[52:53], v[42:43]
	v_pk_mul_f32 v[44:45], v[54:55], v[44:45]
	v_pk_mul_f32 v[52:53], v[56:57], v[46:47]
	v_add_f32_e32 v56, v48, v49
	v_add_f32_e32 v57, v58, v59
	v_pk_fma_f32 v[48:49], v[38:39], v[68:69], v[60:61]
	v_pk_fma_f32 v[54:55], v[34:35], v[72:73], v[62:63]
	v_pk_fma_f32 v[36:37], v[38:39], v[42:43], v[36:37]
	v_pk_fma_f32 v[32:33], v[34:35], v[46:47], v[32:33]
	v_mov_b32_e32 v76, v81
	v_pk_fma_f32 v[64:65], v[80:81], v[12:13], v[64:65] op_sel_hi:[0,1,1]
	v_pk_fma_f32 v[66:67], v[80:81], v[14:15], v[66:67] op_sel_hi:[0,1,1]
	v_pk_fma_f32 v[68:69], v[80:81], v[8:9], v[70:71] op_sel_hi:[0,1,1]
	v_pk_fma_f32 v[70:71], v[80:81], v[10:11], v[74:75] op_sel_hi:[0,1,1]
	ds_write2st64_b32 v19, v56, v57 offset0:88 offset1:92
	v_pk_add_f32 v[80:81], v[54:55], v[48:49]
	v_pk_add_f32 v[82:83], v[32:33], v[36:37]
	v_pk_fma_f32 v[72:73], v[76:77], v[12:13], v[40:41] op_sel_hi:[0,1,1]
	v_pk_fma_f32 v[74:75], v[76:77], v[14:15], v[50:51] op_sel_hi:[0,1,1]
	v_pk_fma_f32 v[78:79], v[76:77], v[8:9], v[44:45] op_sel_hi:[0,1,1]
	v_pk_fma_f32 v[76:77], v[76:77], v[10:11], v[52:53] op_sel_hi:[0,1,1]
	ds_read2_b32 v[84:85], v23 offset0:192 offset1:200
	ds_read_b128 v[32:35], v20 offset:20224
	ds_read_b128 v[36:39], v20 offset:20240
	ds_read_b128 v[8:11], v20 offset:19968
	ds_read_b128 v[12:15], v20 offset:19984
	ds_read_b128 v[48:51], v20 offset:20736
	ds_read_b128 v[52:55], v20 offset:20752
	ds_read_b128 v[40:43], v20 offset:20480
	ds_read_b128 v[44:47], v20 offset:20496
	ds_read_b128 v[56:59], v20 offset:20992
	ds_read_b128 v[60:63], v20 offset:21008
	v_add_f32_e32 v23, v80, v81
	v_add_f32_e32 v80, v82, v83
	v_add_u32_e32 v22, 0x5800, v21
	v_add_f32_dpp v23, v23, v23 quad_perm:[1,0,3,2] row_mask:0xf bank_mask:0xf bound_ctrl:1
	v_add_f32_dpp v80, v80, v80 quad_perm:[1,0,3,2] row_mask:0xf bank_mask:0xf bound_ctrl:1
	s_waitcnt lgkmcnt(10)
	v_mov_b32_e32 v86, v85
	v_add_f32_dpp v23, v23, v23 quad_perm:[2,3,0,1] row_mask:0xf bank_mask:0xf bound_ctrl:1
	v_add_f32_dpp v81, v80, v80 quad_perm:[2,3,0,1] row_mask:0xf bank_mask:0xf bound_ctrl:1
	v_add_u32_e32 v21, 0x5c00, v21
	v_add_f32_dpp v80, v23, v23 row_half_mirror row_mask:0xf bank_mask:0xf bound_ctrl:1
	v_add_f32_dpp v82, v81, v81 row_half_mirror row_mask:0xf bank_mask:0xf bound_ctrl:1
	v_pk_fma_f32 v[64:65], v[28:29], v[80:81], v[64:65] op_sel_hi:[1,0,1]
	v_pk_fma_f32 v[68:69], v[24:25], v[80:81], v[68:69] op_sel_hi:[1,0,1]
	v_pk_fma_f32 v[28:29], v[28:29], v[82:83], v[72:73] op_sel_hi:[1,0,1]
	v_pk_fma_f32 v[24:25], v[24:25], v[82:83], v[78:79] op_sel_hi:[1,0,1]
	v_pk_fma_f32 v[66:67], v[30:31], v[80:81], v[66:67] op_sel_hi:[1,0,1]
	v_pk_fma_f32 v[70:71], v[26:27], v[80:81], v[70:71] op_sel_hi:[1,0,1]
	v_pk_fma_f32 v[30:31], v[30:31], v[82:83], v[74:75] op_sel_hi:[1,0,1]
	v_pk_fma_f32 v[26:27], v[26:27], v[82:83], v[76:77] op_sel_hi:[1,0,1]
	v_pk_mul_f32 v[72:73], v[4:5], v[64:65]
	v_pk_mul_f32 v[74:75], v[0:1], v[68:69]
	v_pk_mul_f32 v[4:5], v[4:5], v[28:29]
	v_pk_mul_f32 v[0:1], v[0:1], v[24:25]
	s_waitcnt lgkmcnt(7)
	v_pk_mul_f32 v[76:77], v[32:33], v[64:65]
	v_pk_mul_f32 v[78:79], v[36:37], v[68:69]
	v_pk_mul_f32 v[32:33], v[32:33], v[28:29]
	v_pk_mul_f32 v[36:37], v[36:37], v[24:25]
	v_pk_mul_f32 v[64:65], v[8:9], v[64:65]
	v_pk_mul_f32 v[80:81], v[10:11], v[66:67]
	s_waitcnt lgkmcnt(6)
	v_pk_mul_f32 v[68:69], v[12:13], v[68:69]
	v_pk_mul_f32 v[82:83], v[14:15], v[70:71]
	v_pk_mul_f32 v[8:9], v[8:9], v[28:29]
	v_pk_mul_f32 v[10:11], v[10:11], v[30:31]
	v_pk_mul_f32 v[12:13], v[12:13], v[24:25]
	v_pk_mul_f32 v[14:15], v[14:15], v[26:27]
	v_pk_fma_f32 v[24:25], v[6:7], v[66:67], v[72:73]
	v_pk_fma_f32 v[28:29], v[2:3], v[70:71], v[74:75]
	v_pk_fma_f32 v[4:5], v[6:7], v[30:31], v[4:5]
	v_pk_fma_f32 v[0:1], v[2:3], v[26:27], v[0:1]
	v_pk_fma_f32 v[2:3], v[34:35], v[66:67], v[76:77]
	v_pk_fma_f32 v[6:7], v[38:39], v[70:71], v[78:79]
	v_pk_fma_f32 v[30:31], v[34:35], v[30:31], v[32:33]
	v_pk_fma_f32 v[26:27], v[38:39], v[26:27], v[36:37]
	v_pk_add_f32 v[0:1], v[4:5], v[0:1]
	v_pk_add_f32 v[2:3], v[2:3], v[6:7]
	v_pk_add_f32 v[4:5], v[30:31], v[26:27]
	s_waitcnt lgkmcnt(5)
; #define SCAN_STEP(w0, w1, a0, a1, b0, b1, k0, k1, r0, r1, vi, vj, t) do { \
;                 SCAN_ROW(S0, S1, S2, S3, w0, w1, a0, a1, b0, b1, k0, k1, r0, r1, vi, (t) * 512); \
;                 SCAN_ROW(T0, T1, T2, T3, w0, w1, a0, a1, b0, b1, k0, k1, r0, r1, vj, (t) * 512 + 256); } while (0)
;     ...
;             SCAN_LOAD(w0, w1, a0, a1, b0, b1, k0, k1, r0, r1, vi, vj, 0);
; #pragma unroll
;             for (int t = 0; t < 16; t += 2) {
;                 SCAN_LOAD(W0, W1, A0, A1, B0, B1, K0, K1, R0, R1, VI, VJ, t + 1);
;                 SCAN_STEP(w0, w1, a0, a1, b0, b1, k0, k1, r0, r1, vi, vj, t);
;                 if (t + 2 < 16) SCAN_LOAD(w0, w1, a0, a1, b0, b1, k0, k1, r0, r1, vi, vj, t + 2);
;                 SCAN_STEP(W0, W1, A0, A1, B0, B1, K0, K1, R0, R1, VI, VJ, t + 1);
	v_pk_fma_f32 v[38:39], v[48:49], v[86:87], v[8:9] op_sel_hi:[1,0,1]
	v_pk_add_f32 v[8:9], v[24:25], v[28:29]
	v_add_f32_e32 v0, v0, v1
	v_add_f32_e32 v1, v2, v3
	v_add_f32_e32 v2, v4, v5
	v_pk_fma_f32 v[66:67], v[50:51], v[84:85], v[80:81] op_sel_hi:[1,0,1]
	v_add_f32_e32 v6, v8, v9
	v_add_f32_dpp v80, v1, v1 quad_perm:[1,0,3,2] row_mask:0xf bank_mask:0xf bound_ctrl:1
	v_add_f32_dpp v81, v2, v2 quad_perm:[1,0,3,2] row_mask:0xf bank_mask:0xf bound_ctrl:1
	ds_write2st64_b32 v19, v6, v0 offset0:96 offset1:100
	v_add_f32_dpp v80, v80, v80 quad_perm:[2,3,0,1] row_mask:0xf bank_mask:0xf bound_ctrl:1
	v_add_f32_dpp v81, v81, v81 quad_perm:[2,3,0,1] row_mask:0xf bank_mask:0xf bound_ctrl:1
	v_pk_fma_f32 v[64:65], v[48:49], v[84:85], v[64:65] op_sel_hi:[1,0,1]
	s_waitcnt lgkmcnt(5)
	v_pk_fma_f32 v[68:69], v[52:53], v[84:85], v[68:69] op_sel_hi:[1,0,1]
	v_pk_fma_f32 v[70:71], v[54:55], v[84:85], v[82:83] op_sel_hi:[1,0,1]
	v_pk_fma_f32 v[72:73], v[50:51], v[86:87], v[10:11] op_sel_hi:[1,0,1]
	v_pk_fma_f32 v[74:75], v[52:53], v[86:87], v[12:13] op_sel_hi:[1,0,1]
	v_pk_fma_f32 v[76:77], v[54:55], v[86:87], v[14:15] op_sel_hi:[1,0,1]
	ds_read2_b32 v[78:79], v22 offset0:64 offset1:72
	ds_read_b128 v[0:3], v20 offset:22544
	ds_read_b128 v[4:7], v20 offset:22528
	ds_read_b128 v[8:11], v20 offset:22288
	ds_read_b128 v[12:15], v20 offset:22272
	ds_read_b128 v[22:25], v20 offset:22032
	ds_read_b128 v[26:29], v20 offset:22016
	ds_read_b128 v[30:33], v20 offset:21776
	ds_read_b128 v[34:37], v20 offset:21760
	ds_read_b128 v[48:51], v20 offset:21504
	ds_read_b128 v[52:55], v20 offset:21520
	v_add_f32_dpp v80, v80, v80 row_half_mirror row_mask:0xf bank_mask:0xf bound_ctrl:1
	v_add_f32_dpp v82, v81, v81 row_half_mirror row_mask:0xf bank_mask:0xf bound_ctrl:1
	s_waitcnt lgkmcnt(14)
	v_pk_fma_f32 v[64:65], v[40:41], v[80:81], v[64:65] op_sel_hi:[1,0,1]
	v_pk_fma_f32 v[66:67], v[42:43], v[80:81], v[66:67] op_sel_hi:[1,0,1]
	v_pk_fma_f32 v[68:69], v[44:45], v[80:81], v[68:69] op_sel_hi:[1,0,1]
	v_pk_fma_f32 v[38:39], v[40:41], v[82:83], v[38:39] op_sel_hi:[1,0,1]
	v_pk_fma_f32 v[40:41], v[42:43], v[82:83], v[72:73] op_sel_hi:[1,0,1]
	v_pk_fma_f32 v[42:43], v[44:45], v[82:83], v[74:75] op_sel_hi:[1,0,1]
	v_pk_fma_f32 v[70:71], v[46:47], v[80:81], v[70:71] op_sel_hi:[1,0,1]
	v_pk_fma_f32 v[44:45], v[46:47], v[82:83], v[76:77] op_sel_hi:[1,0,1]
	s_waitcnt lgkmcnt(12)
	v_pk_mul_f32 v[46:47], v[56:57], v[64:65]
	v_pk_mul_f32 v[72:73], v[60:61], v[68:69]
	v_pk_mul_f32 v[56:57], v[56:57], v[38:39]
	v_pk_mul_f32 v[60:61], v[60:61], v[42:43]
	v_pk_fma_f32 v[46:47], v[58:59], v[66:67], v[46:47]
	v_pk_fma_f32 v[72:73], v[62:63], v[70:71], v[72:73]
	v_pk_fma_f32 v[56:57], v[58:59], v[40:41], v[56:57]
	v_pk_fma_f32 v[58:59], v[62:63], v[44:45], v[60:61]
	v_pk_add_f32 v[46:47], v[46:47], v[72:73]
	v_pk_add_f32 v[56:57], v[56:57], v[58:59]
	s_waitcnt lgkmcnt(1)
	v_pk_mul_f32 v[58:59], v[34:35], v[64:65]
	v_pk_mul_f32 v[60:61], v[30:31], v[68:69]
	v_pk_mul_f32 v[34:35], v[34:35], v[38:39]
	v_pk_mul_f32 v[30:31], v[30:31], v[42:43]
	v_pk_mul_f32 v[62:63], v[48:49], v[64:65]
	v_pk_mul_f32 v[64:65], v[50:51], v[66:67]
	s_waitcnt lgkmcnt(0)
	v_pk_mul_f32 v[68:69], v[52:53], v[68:69]
	v_pk_mul_f32 v[72:73], v[54:55], v[70:71]
	v_pk_mul_f32 v[38:39], v[48:49], v[38:39]
	v_pk_mul_f32 v[48:49], v[50:51], v[40:41]
	v_pk_mul_f32 v[42:43], v[52:53], v[42:43]
	v_pk_mul_f32 v[50:51], v[54:55], v[44:45]
	v_add_f32_e32 v54, v46, v47
	v_pk_fma_f32 v[46:47], v[36:37], v[66:67], v[58:59]
	v_pk_fma_f32 v[52:53], v[32:33], v[70:71], v[60:61]
	v_pk_fma_f32 v[34:35], v[36:37], v[40:41], v[34:35]
	v_pk_fma_f32 v[30:31], v[32:33], v[44:45], v[30:31]
	v_mov_b32_e32 v74, v79
	v_add_f32_e32 v55, v56, v57
	v_pk_fma_f32 v[62:63], v[78:79], v[12:13], v[62:63] op_sel_hi:[0,1,1]
	v_pk_fma_f32 v[64:65], v[78:79], v[14:15], v[64:65] op_sel_hi:[0,1,1]
	v_pk_fma_f32 v[66:67], v[78:79], v[8:9], v[68:69] op_sel_hi:[0,1,1]
	v_pk_fma_f32 v[68:69], v[78:79], v[10:11], v[72:73] op_sel_hi:[0,1,1]
	v_pk_add_f32 v[78:79], v[52:53], v[46:47]
	v_pk_add_f32 v[80:81], v[30:31], v[34:35]
	ds_write2st64_b32 v19, v54, v55 offset0:104 offset1:108
	v_add_f32_e32 v78, v78, v79
	v_add_f32_e32 v79, v80, v81
	v_pk_fma_f32 v[70:71], v[74:75], v[12:13], v[38:39] op_sel_hi:[0,1,1]
	v_pk_fma_f32 v[72:73], v[74:75], v[14:15], v[48:49] op_sel_hi:[0,1,1]
	v_pk_fma_f32 v[76:77], v[74:75], v[8:9], v[42:43] op_sel_hi:[0,1,1]
	v_pk_fma_f32 v[74:75], v[74:75], v[10:11], v[50:51] op_sel_hi:[0,1,1]
	ds_read_b128 v[8:11], v20 offset:23040
	ds_read_b128 v[12:15], v20 offset:23056
	ds_read_b128 v[30:33], v20 offset:23296
	ds_read_b128 v[34:37], v20 offset:23312
	ds_read_b128 v[38:41], v20 offset:23552
	ds_read_b128 v[42:45], v20 offset:23568
	ds_read_b128 v[46:49], v20 offset:23808
	ds_read_b128 v[50:53], v20 offset:23824
	ds_read_b128 v[54:57], v20 offset:24064
	ds_read_b128 v[58:61], v20 offset:24080
	ds_read2_b32 v[20:21], v21 offset0:192 offset1:200
	v_add_f32_dpp v78, v78, v78 quad_perm:[1,0,3,2] row_mask:0xf bank_mask:0xf bound_ctrl:1
	v_add_f32_dpp v79, v79, v79 quad_perm:[1,0,3,2] row_mask:0xf bank_mask:0xf bound_ctrl:1
	s_add_i32 s1, s1, 1
	v_add_f32_dpp v78, v78, v78 quad_perm:[2,3,0,1] row_mask:0xf bank_mask:0xf bound_ctrl:1
	v_add_f32_dpp v79, v79, v79 quad_perm:[2,3,0,1] row_mask:0xf bank_mask:0xf bound_ctrl:1
	s_waitcnt lgkmcnt(0)
; #define SCAN_STEP(w0, w1, a0, a1, b0, b1, k0, k1, r0, r1, vi, vj, t) do { \
;                 SCAN_ROW(S0, S1, S2, S3, w0, w1, a0, a1, b0, b1, k0, k1, r0, r1, vi, (t) * 512); \
;                 SCAN_ROW(T0, T1, T2, T3, w0, w1, a0, a1, b0, b1, k0, k1, r0, r1, vj, (t) * 512 + 256); } while (0)
;     ...
;             SCAN_LOAD(w0, w1, a0, a1, b0, b1, k0, k1, r0, r1, vi, vj, 0);
; #pragma unroll
;             for (int t = 0; t < 16; t += 2) {
;                 SCAN_LOAD(W0, W1, A0, A1, B0, B1, K0, K1, R0, R1, VI, VJ, t + 1);
;                 SCAN_STEP(w0, w1, a0, a1, b0, b1, k0, k1, r0, r1, vi, vj, t);
;                 if (t + 2 < 16) SCAN_LOAD(w0, w1, a0, a1, b0, b1, k0, k1, r0, r1, vi, vj, t + 2);
;                 SCAN_STEP(W0, W1, A0, A1, B0, B1, K0, K1, R0, R1, VI, VJ, t + 1);
;             }
;     ...
;             __syncthreads();
;         }
;         float* so = P.out + (samp ? O_RS + ((size_t)(l * 16 + b) * 16 + h) * 4096 : O_RP + ((size_t)(l * 4 + b) * 16 + h) * 4096) + js;
;         f32x4 o0, o1; o0.xy = S0; o0.zw = S1; o1.xy = S2; o1.zw = S3;
;         *(f32x4*)(so + i0 * 64) = o0; *(f32x4*)(so + i0 * 64 + 4) = o1;
;         o0.xy = T0; o0.zw = T1; o1.xy = T2; o1.zw = T3;
;         *(f32x4*)(so + i1 * 64) = o0; *(f32x4*)(so + i1 * 64 + 4) = o1;
	v_mov_b32_e32 v82, v21
	v_add_f32_dpp v78, v78, v78 row_half_mirror row_mask:0xf bank_mask:0xf bound_ctrl:1
	v_add_f32_dpp v80, v79, v79 row_half_mirror row_mask:0xf bank_mask:0xf bound_ctrl:1
	v_pk_fma_f32 v[62:63], v[26:27], v[78:79], v[62:63] op_sel_hi:[1,0,1]
	v_pk_fma_f32 v[66:67], v[22:23], v[78:79], v[66:67] op_sel_hi:[1,0,1]
	v_pk_fma_f32 v[26:27], v[26:27], v[80:81], v[70:71] op_sel_hi:[1,0,1]
	v_pk_fma_f32 v[22:23], v[22:23], v[80:81], v[76:77] op_sel_hi:[1,0,1]
	v_pk_fma_f32 v[64:65], v[28:29], v[78:79], v[64:65] op_sel_hi:[1,0,1]
	v_pk_fma_f32 v[68:69], v[24:25], v[78:79], v[68:69] op_sel_hi:[1,0,1]
	v_pk_fma_f32 v[28:29], v[28:29], v[80:81], v[72:73] op_sel_hi:[1,0,1]
	v_pk_fma_f32 v[24:25], v[24:25], v[80:81], v[74:75] op_sel_hi:[1,0,1]
	v_pk_mul_f32 v[70:71], v[4:5], v[62:63]
	v_pk_mul_f32 v[72:73], v[0:1], v[66:67]
	v_pk_mul_f32 v[4:5], v[4:5], v[26:27]
	v_pk_mul_f32 v[0:1], v[0:1], v[22:23]
	v_pk_mul_f32 v[74:75], v[30:31], v[62:63]
	v_pk_mul_f32 v[76:77], v[34:35], v[66:67]
	v_pk_mul_f32 v[30:31], v[30:31], v[26:27]
	v_pk_mul_f32 v[34:35], v[34:35], v[22:23]
	v_pk_mul_f32 v[62:63], v[8:9], v[62:63]
	v_pk_mul_f32 v[78:79], v[10:11], v[64:65]
	v_pk_mul_f32 v[66:67], v[12:13], v[66:67]
	v_pk_mul_f32 v[80:81], v[14:15], v[68:69]
	v_pk_mul_f32 v[8:9], v[8:9], v[26:27]
	v_pk_mul_f32 v[10:11], v[10:11], v[28:29]
	v_pk_mul_f32 v[12:13], v[12:13], v[22:23]
	v_pk_mul_f32 v[14:15], v[14:15], v[24:25]
	v_pk_fma_f32 v[22:23], v[6:7], v[64:65], v[70:71]
	v_pk_fma_f32 v[26:27], v[2:3], v[68:69], v[72:73]
	v_pk_fma_f32 v[4:5], v[6:7], v[28:29], v[4:5]
	v_pk_fma_f32 v[0:1], v[2:3], v[24:25], v[0:1]
	v_pk_fma_f32 v[2:3], v[32:33], v[64:65], v[74:75]
	v_pk_fma_f32 v[6:7], v[36:37], v[68:69], v[76:77]
	v_pk_fma_f32 v[28:29], v[32:33], v[28:29], v[30:31]
	v_pk_fma_f32 v[24:25], v[36:37], v[24:25], v[34:35]
	v_pk_fma_f32 v[30:31], v[46:47], v[82:83], v[8:9] op_sel_hi:[1,0,1]
	v_pk_add_f32 v[8:9], v[22:23], v[26:27]
	v_pk_add_f32 v[0:1], v[4:5], v[0:1]
	v_pk_add_f32 v[2:3], v[2:3], v[6:7]
	v_pk_add_f32 v[4:5], v[28:29], v[24:25]
	v_add_f32_e32 v6, v8, v9
	v_add_f32_e32 v0, v0, v1
	v_add_f32_e32 v1, v2, v3
	v_add_f32_e32 v2, v4, v5
	ds_write2st64_b32 v19, v6, v0 offset0:112 offset1:116
	v_add_f32_dpp v0, v1, v1 quad_perm:[1,0,3,2] row_mask:0xf bank_mask:0xf bound_ctrl:1
	v_add_f32_dpp v1, v2, v2 quad_perm:[1,0,3,2] row_mask:0xf bank_mask:0xf bound_ctrl:1
	v_pk_fma_f32 v[62:63], v[46:47], v[20:21], v[62:63] op_sel_hi:[1,0,1]
	v_add_f32_dpp v0, v0, v0 quad_perm:[2,3,0,1] row_mask:0xf bank_mask:0xf bound_ctrl:1
	v_add_f32_dpp v1, v1, v1 quad_perm:[2,3,0,1] row_mask:0xf bank_mask:0xf bound_ctrl:1
	v_pk_fma_f32 v[64:65], v[48:49], v[20:21], v[78:79] op_sel_hi:[1,0,1]
	v_pk_fma_f32 v[66:67], v[50:51], v[20:21], v[66:67] op_sel_hi:[1,0,1]
	v_pk_fma_f32 v[20:21], v[52:53], v[20:21], v[80:81] op_sel_hi:[1,0,1]
	v_pk_fma_f32 v[34:35], v[50:51], v[82:83], v[12:13] op_sel_hi:[1,0,1]
	v_add_f32_dpp v0, v0, v0 row_half_mirror row_mask:0xf bank_mask:0xf bound_ctrl:1
	v_add_f32_dpp v2, v1, v1 row_half_mirror row_mask:0xf bank_mask:0xf bound_ctrl:1
	v_pk_fma_f32 v[32:33], v[48:49], v[82:83], v[10:11] op_sel_hi:[1,0,1]
	v_pk_fma_f32 v[36:37], v[52:53], v[82:83], v[14:15] op_sel_hi:[1,0,1]
	v_pk_fma_f32 v[8:9], v[38:39], v[0:1], v[62:63] op_sel_hi:[1,0,1]
	v_pk_fma_f32 v[10:11], v[40:41], v[0:1], v[64:65] op_sel_hi:[1,0,1]
	v_pk_fma_f32 v[12:13], v[42:43], v[0:1], v[66:67] op_sel_hi:[1,0,1]
	v_pk_fma_f32 v[14:15], v[44:45], v[0:1], v[20:21] op_sel_hi:[1,0,1]
	v_pk_fma_f32 v[4:5], v[38:39], v[2:3], v[30:31] op_sel_hi:[1,0,1]
	v_pk_fma_f32 v[0:1], v[42:43], v[2:3], v[34:35] op_sel_hi:[1,0,1]
	v_pk_fma_f32 v[6:7], v[40:41], v[2:3], v[32:33] op_sel_hi:[1,0,1]
	v_pk_fma_f32 v[2:3], v[44:45], v[2:3], v[36:37] op_sel_hi:[1,0,1]
	v_pk_mul_f32 v[20:21], v[54:55], v[8:9]
	v_pk_mul_f32 v[22:23], v[58:59], v[12:13]
	v_pk_mul_f32 v[24:25], v[54:55], v[4:5]
	v_pk_mul_f32 v[26:27], v[58:59], v[0:1]
	v_pk_fma_f32 v[20:21], v[56:57], v[10:11], v[20:21]
	v_pk_fma_f32 v[22:23], v[60:61], v[14:15], v[22:23]
	v_pk_fma_f32 v[24:25], v[56:57], v[6:7], v[24:25]
	v_pk_fma_f32 v[26:27], v[60:61], v[2:3], v[26:27]
	v_pk_add_f32 v[20:21], v[20:21], v[22:23]
	v_pk_add_f32 v[22:23], v[24:25], v[26:27]
	s_cmpk_eq_i32 s1, 0xc8
	v_add_f32_e32 v20, v20, v21
	v_add_f32_e32 v21, v22, v23
	ds_write2st64_b32 v19, v20, v21 offset0:120 offset1:124
	s_waitcnt lgkmcnt(0)
	s_barrier
	s_cbranch_scc0 .LBB0_1395
	s_lshl_b64 s[6:7], s[6:7], 18
	s_add_u32 s1, s72, s6
	s_addc_u32 s6, s73, s7
	s_lshl_b32 s0, s0, 14
	s_add_u32 s0, s1, s0
	s_addc_u32 s1, s6, 0
	v_lshlrev_b32_e32 v18, 2, v17
	v_mov_b32_e32 v19, 0
	v_lshlrev_b32_e32 v16, 6, v16
	v_lshl_add_u64 v[18:19], s[0:1], 0, v[18:19]
	v_ashrrev_i32_e32 v17, 31, v16
	v_lshl_add_u64 v[16:17], v[16:17], 2, v[18:19]
	s_mov_b64 s[0:1], 0x8500000
	v_lshl_add_u64 v[18:19], v[16:17], 0, s[0:1]
	s_mov_b32 s0, 0x8500000
	v_add_co_u32_e32 v16, vcc, s0, v16
	s_nop 1
	v_addc_co_u32_e32 v17, vcc, 0, v17, vcc
	global_store_dwordx4 v[16:17], v[8:11], off
	global_store_dwordx4 v[18:19], v[12:15], off offset:16
	global_store_dwordx4 v[18:19], v[4:7], off offset:2048
	global_store_dwordx4 v[18:19], v[0:3], off offset:2064

; #define SCAN_STEP(w0, w1, a0, a1, b0, b1, k0, k1, r0, r1, vi, vj, t) do { \
;                 SCAN_ROW(S0, S1, S2, S3, w0, w1, a0, a1, b0, b1, k0, k1, r0, r1, vi, (t) * 512); \
;                 SCAN_ROW(T0, T1, T2, T3, w0, w1, a0, a1, b0, b1, k0, k1, r0, r1, vj, (t) * 512 + 256); } while (0)
;     ...
;         for (int c = c0; c < nch; ++c) {
;             const float* bb = bufs + (c & 1) * (16 * 384) + js;
;             const float* bv = bufs + (c & 1) * (16 * 384) + 320 + i0;
;             float* yb = ybuf + (c & 1) * 8192 + w * 64 + lane;
;             f32x4 w0, w1, a0, a1, b0, b1, k0, k1, r0, r1; float vi, vj;
;             f32x4 W0, W1, A0, A1, B0, B1, K0, K1, R0, R1; float VI, VJ;
;     ...
;             SCAN_LOAD(w0, w1, a0, a1, b0, b1, k0, k1, r0, r1, vi, vj, 0);
; #pragma unroll
;             for (int t = 0; t < 16; t += 2) {
;                 SCAN_LOAD(W0, W1, A0, A1, B0, B1, K0, K1, R0, R1, VI, VJ, t + 1);
;                 SCAN_STEP(w0, w1, a0, a1, b0, b1, k0, k1, r0, r1, vi, vj, t);
;                 if (t + 2 < 16) SCAN_LOAD(w0, w1, a0, a1, b0, b1, k0, k1, r0, r1, vi, vj, t + 2);
;                 SCAN_STEP(W0, W1, A0, A1, B0, B1, K0, K1, R0, R1, VI, VJ, t + 1);
.LBB0_1812:
	s_and_b32 s6, s1, 1
	s_mul_i32 s7, s6, 0x6000
	v_lshl_add_u32 v29, s6, 15, v20
	s_add_i32 s6, s7, 0
	v_lshl_add_u32 v23, v17, 2, s6
	v_lshl_add_u32 v22, v16, 2, s6
	v_add_u32_e32 v31, 0x400, v23
	v_add_u32_e32 v114, 0x800, v23
	ds_read_b128 v[40:43], v22 offset:256
	ds_read_b128 v[44:47], v22 offset:272
	ds_read_b128 v[56:59], v22 offset:768
	ds_read2_b32 v[112:113], v31 offset0:64 offset1:72
	ds_read_b128 v[60:63], v22 offset:784
	ds_read_b128 v[32:35], v22
	ds_read_b128 v[36:39], v22 offset:16
	ds_read_b128 v[48:51], v22 offset:512
	ds_read_b128 v[52:55], v22 offset:528
	ds_read_b128 v[64:67], v22 offset:1024
	ds_read_b128 v[68:71], v22 offset:1040
	ds_read_b128 v[80:83], v22 offset:1792
	ds_read_b128 v[84:87], v22 offset:1808
	s_waitcnt vmcnt(8)
	ds_read2_b32 v[114:115], v114 offset0:192 offset1:200
	s_waitcnt vmcnt(7)
	ds_read_b128 v[72:75], v22 offset:1536
	s_waitcnt vmcnt(6)
	ds_read_b128 v[76:79], v22 offset:1552
	ds_read_b128 v[100:103], v22 offset:2320
	ds_read_b128 v[96:99], v22 offset:2304
	ds_read_b128 v[88:91], v22 offset:2048
	ds_read_b128 v[92:95], v22 offset:2064
	ds_read_b128 v[104:107], v22 offset:2560
	ds_read_b128 v[108:111], v22 offset:2576
	s_waitcnt vmcnt(1)
	s_waitcnt lgkmcnt(14)
	v_pk_mul_f32 v[116:117], v[12:13], v[40:41]
	v_pk_mul_f32 v[118:119], v[8:9], v[44:45]
	v_pk_mul_f32 v[40:41], v[0:1], v[40:41]
	s_waitcnt vmcnt(0)
	v_pk_mul_f32 v[44:45], v[4:5], v[44:45]
	v_pk_fma_f32 v[116:117], v[14:15], v[42:43], v[116:117]
	v_pk_fma_f32 v[118:119], v[10:11], v[46:47], v[118:119]
	v_pk_mul_f32 v[120:121], v[56:57], v[112:113] op_sel_hi:[1,0]
	v_pk_mul_f32 v[122:123], v[58:59], v[112:113] op_sel_hi:[1,0]
	v_pk_mul_f32 v[124:125], v[60:61], v[112:113] op_sel_hi:[1,0]
	v_pk_mul_f32 v[126:127], v[62:63], v[112:113] op_sel_hi:[1,0]
	v_mov_b32_e32 v112, v113
	v_pk_fma_f32 v[40:41], v[2:3], v[42:43], v[40:41]
	v_pk_fma_f32 v[42:43], v[6:7], v[46:47], v[44:45]
	v_pk_add_f32 v[46:47], v[116:117], v[118:119]
	v_pk_mul_f32 v[56:57], v[56:57], v[112:113] op_sel_hi:[1,0]
	v_pk_add_f32 v[40:41], v[40:41], v[42:43]
	v_pk_fma_f32 v[12:13], v[12:13], v[32:33], v[120:121]
	v_add_f32_e32 v31, v46, v47
	v_pk_fma_f32 v[0:1], v[0:1], v[32:33], v[56:57]
	v_add_f32_e32 v32, v40, v41
	v_add_f32_dpp v31, v31, v31 quad_perm:[1,0,3,2] row_mask:0xf bank_mask:0xf bound_ctrl:1
	v_pk_mul_f32 v[58:59], v[58:59], v[112:113] op_sel_hi:[1,0]
	v_add_f32_dpp v32, v32, v32 quad_perm:[1,0,3,2] row_mask:0xf bank_mask:0xf bound_ctrl:1
	v_pk_mul_f32 v[60:61], v[60:61], v[112:113] op_sel_hi:[1,0]
	v_add_f32_dpp v31, v31, v31 quad_perm:[2,3,0,1] row_mask:0xf bank_mask:0xf bound_ctrl:1
	v_add_f32_dpp v33, v32, v32 quad_perm:[2,3,0,1] row_mask:0xf bank_mask:0xf bound_ctrl:1
	v_pk_fma_f32 v[14:15], v[14:15], v[34:35], v[122:123]
	v_pk_fma_f32 v[8:9], v[8:9], v[36:37], v[124:125]
	v_pk_mul_f32 v[62:63], v[62:63], v[112:113] op_sel_hi:[1,0]
	v_pk_fma_f32 v[2:3], v[2:3], v[34:35], v[58:59]
	v_pk_fma_f32 v[4:5], v[4:5], v[36:37], v[60:61]
	v_add_f32_dpp v32, v31, v31 row_half_mirror row_mask:0xf bank_mask:0xf bound_ctrl:1
	v_add_f32_dpp v34, v33, v33 row_half_mirror row_mask:0xf bank_mask:0xf bound_ctrl:1
	v_pk_fma_f32 v[10:11], v[10:11], v[38:39], v[126:127]
	v_pk_fma_f32 v[6:7], v[6:7], v[38:39], v[62:63]
	v_pk_fma_f32 v[12:13], v[48:49], v[32:33], v[12:13] op_sel_hi:[1,0,1]
	s_waitcnt lgkmcnt(13)
	v_pk_fma_f32 v[8:9], v[52:53], v[32:33], v[8:9] op_sel_hi:[1,0,1]
	v_pk_fma_f32 v[0:1], v[48:49], v[34:35], v[0:1] op_sel_hi:[1,0,1]
	v_pk_fma_f32 v[4:5], v[52:53], v[34:35], v[4:5] op_sel_hi:[1,0,1]
	v_pk_fma_f32 v[14:15], v[50:51], v[32:33], v[14:15] op_sel_hi:[1,0,1]
	v_pk_fma_f32 v[10:11], v[54:55], v[32:33], v[10:11] op_sel_hi:[1,0,1]
	v_pk_fma_f32 v[2:3], v[50:51], v[34:35], v[2:3] op_sel_hi:[1,0,1]
	v_pk_fma_f32 v[6:7], v[54:55], v[34:35], v[6:7] op_sel_hi:[1,0,1]
	s_waitcnt lgkmcnt(10)
	v_pk_mul_f32 v[32:33], v[64:65], v[12:13]
	v_pk_mul_f32 v[34:35], v[68:69], v[8:9]
	v_pk_mul_f32 v[36:37], v[64:65], v[0:1]
	v_pk_mul_f32 v[38:39], v[68:69], v[4:5]
	v_pk_mul_f32 v[40:41], v[80:81], v[12:13]
	s_waitcnt lgkmcnt(7)
	v_pk_mul_f32 v[42:43], v[84:85], v[8:9]
	v_pk_mul_f32 v[50:51], v[80:81], v[0:1]
	v_pk_mul_f32 v[52:53], v[84:85], v[4:5]
	v_mov_b32_e32 v44, v115
	v_pk_mul_f32 v[46:47], v[74:75], v[14:15]
	s_waitcnt lgkmcnt(6)
	v_pk_mul_f32 v[8:9], v[76:77], v[8:9]
	v_pk_mul_f32 v[48:49], v[78:79], v[10:11]
	v_pk_mul_f32 v[0:1], v[72:73], v[0:1]
	v_pk_mul_f32 v[54:55], v[74:75], v[2:3]
	v_pk_mul_f32 v[4:5], v[76:77], v[4:5]
	v_pk_mul_f32 v[56:57], v[78:79], v[6:7]
	v_pk_fma_f32 v[32:33], v[66:67], v[14:15], v[32:33]
	v_pk_fma_f32 v[34:35], v[70:71], v[10:11], v[34:35]
	v_pk_fma_f32 v[36:37], v[66:67], v[2:3], v[36:37]
	v_pk_fma_f32 v[38:39], v[70:71], v[6:7], v[38:39]
	v_pk_fma_f32 v[14:15], v[82:83], v[14:15], v[40:41]
	v_pk_fma_f32 v[10:11], v[86:87], v[10:11], v[42:43]
	v_pk_fma_f32 v[2:3], v[82:83], v[2:3], v[50:51]
	v_pk_fma_f32 v[6:7], v[86:87], v[6:7], v[52:53]
	s_waitcnt lgkmcnt(4)
; #define SCAN_STEP(w0, w1, a0, a1, b0, b1, k0, k1, r0, r1, vi, vj, t) do { \
;                 SCAN_ROW(S0, S1, S2, S3, w0, w1, a0, a1, b0, b1, k0, k1, r0, r1, vi, (t) * 512); \
;                 SCAN_ROW(T0, T1, T2, T3, w0, w1, a0, a1, b0, b1, k0, k1, r0, r1, vj, (t) * 512 + 256); } while (0)
;     ...
;             SCAN_LOAD(w0, w1, a0, a1, b0, b1, k0, k1, r0, r1, vi, vj, 0);
; #pragma unroll
;             for (int t = 0; t < 16; t += 2) {
;                 SCAN_LOAD(W0, W1, A0, A1, B0, B1, K0, K1, R0, R1, VI, VJ, t + 1);
;                 SCAN_STEP(w0, w1, a0, a1, b0, b1, k0, k1, r0, r1, vi, vj, t);
;                 if (t + 2 < 16) SCAN_LOAD(w0, w1, a0, a1, b0, b1, k0, k1, r0, r1, vi, vj, t + 2);
;                 SCAN_STEP(W0, W1, A0, A1, B0, B1, K0, K1, R0, R1, VI, VJ, t + 1);
	v_pk_fma_f32 v[62:63], v[100:101], v[114:115], v[8:9] op_sel_hi:[1,0,1]
	v_pk_fma_f32 v[66:67], v[96:97], v[44:45], v[0:1] op_sel_hi:[1,0,1]
	v_pk_fma_f32 v[70:71], v[100:101], v[44:45], v[4:5] op_sel_hi:[1,0,1]
	v_pk_add_f32 v[0:1], v[32:33], v[34:35]
	v_pk_add_f32 v[4:5], v[36:37], v[38:39]
	v_pk_add_f32 v[8:9], v[14:15], v[10:11]
	v_pk_add_f32 v[2:3], v[2:3], v[6:7]
	v_add_f32_e32 v0, v0, v1
	v_add_f32_e32 v1, v4, v5
	v_add_f32_e32 v4, v8, v9
	v_add_f32_e32 v2, v2, v3
	v_add_u32_e32 v128, 0x1000, v23
	v_add_f32_dpp v31, v4, v4 quad_perm:[1,0,3,2] row_mask:0xf bank_mask:0xf bound_ctrl:1
	v_add_f32_dpp v74, v2, v2 quad_perm:[1,0,3,2] row_mask:0xf bank_mask:0xf bound_ctrl:1
	v_pk_mul_f32 v[12:13], v[72:73], v[12:13]
	ds_write2st64_b32 v29, v0, v1 offset0:192 offset1:196
	v_add_f32_dpp v31, v31, v31 quad_perm:[2,3,0,1] row_mask:0xf bank_mask:0xf bound_ctrl:1
	v_add_f32_dpp v75, v74, v74 quad_perm:[2,3,0,1] row_mask:0xf bank_mask:0xf bound_ctrl:1
	v_pk_fma_f32 v[58:59], v[96:97], v[114:115], v[12:13] op_sel_hi:[1,0,1]
	v_pk_fma_f32 v[60:61], v[98:99], v[114:115], v[46:47] op_sel_hi:[1,0,1]
	v_pk_fma_f32 v[64:65], v[102:103], v[114:115], v[48:49] op_sel_hi:[1,0,1]
	v_pk_fma_f32 v[68:69], v[98:99], v[44:45], v[54:55] op_sel_hi:[1,0,1]
	v_pk_fma_f32 v[56:57], v[102:103], v[44:45], v[56:57] op_sel_hi:[1,0,1]
	ds_read_b128 v[44:47], v22 offset:3328
	ds_read_b128 v[40:43], v22 offset:3344
	ds_read_b128 v[48:51], v22 offset:3072
	ds_read_b128 v[52:55], v22 offset:3088
	ds_read2_b32 v[72:73], v128 offset0:64 offset1:72
	ds_read_b128 v[12:15], v22 offset:3840
	ds_read_b128 v[8:11], v22 offset:3856
	ds_read_b128 v[36:39], v22 offset:3584
	ds_read_b128 v[32:35], v22 offset:3600
	ds_read_b128 v[4:7], v22 offset:4096
	ds_read_b128 v[0:3], v22 offset:4112
	v_add_f32_dpp v74, v31, v31 row_half_mirror row_mask:0xf bank_mask:0xf bound_ctrl:1
	v_add_f32_dpp v76, v75, v75 row_half_mirror row_mask:0xf bank_mask:0xf bound_ctrl:1
	s_waitcnt lgkmcnt(14)
	v_pk_fma_f32 v[58:59], v[88:89], v[74:75], v[58:59] op_sel_hi:[1,0,1]
	v_pk_fma_f32 v[62:63], v[92:93], v[74:75], v[62:63] op_sel_hi:[1,0,1]
	v_pk_fma_f32 v[66:67], v[88:89], v[76:77], v[66:67] op_sel_hi:[1,0,1]
	v_pk_fma_f32 v[70:71], v[92:93], v[76:77], v[70:71] op_sel_hi:[1,0,1]
	v_pk_fma_f32 v[60:61], v[90:91], v[74:75], v[60:61] op_sel_hi:[1,0,1]
	v_pk_fma_f32 v[64:65], v[94:95], v[74:75], v[64:65] op_sel_hi:[1,0,1]
	v_pk_fma_f32 v[68:69], v[90:91], v[76:77], v[68:69] op_sel_hi:[1,0,1]
	v_pk_fma_f32 v[56:57], v[94:95], v[76:77], v[56:57] op_sel_hi:[1,0,1]
	s_waitcnt lgkmcnt(12)
	v_pk_mul_f32 v[74:75], v[104:105], v[58:59]
	v_pk_mul_f32 v[76:77], v[108:109], v[62:63]
	v_pk_mul_f32 v[78:79], v[104:105], v[66:67]
	v_pk_mul_f32 v[80:81], v[108:109], v[70:71]
	v_pk_fma_f32 v[74:75], v[106:107], v[60:61], v[74:75]
	v_pk_fma_f32 v[76:77], v[110:111], v[64:65], v[76:77]
	v_pk_fma_f32 v[78:79], v[106:107], v[68:69], v[78:79]
	v_pk_fma_f32 v[80:81], v[110:111], v[56:57], v[80:81]
	v_pk_add_f32 v[74:75], v[74:75], v[76:77]
	v_pk_add_f32 v[76:77], v[78:79], v[80:81]
	s_waitcnt lgkmcnt(8)
	v_pk_mul_f32 v[78:79], v[44:45], v[58:59]
	v_pk_mul_f32 v[80:81], v[40:41], v[62:63]
	v_pk_mul_f32 v[44:45], v[44:45], v[66:67]
	v_pk_mul_f32 v[40:41], v[40:41], v[70:71]
	v_pk_mul_f32 v[82:83], v[50:51], v[60:61]
	s_waitcnt lgkmcnt(7)
	v_pk_mul_f32 v[84:85], v[54:55], v[64:65]
	v_pk_fma_f32 v[60:61], v[46:47], v[60:61], v[78:79]
	v_pk_fma_f32 v[64:65], v[42:43], v[64:65], v[80:81]
	v_pk_fma_f32 v[44:45], v[46:47], v[68:69], v[44:45]
	v_pk_fma_f32 v[40:41], v[42:43], v[56:57], v[40:41]
	v_pk_mul_f32 v[58:59], v[48:49], v[58:59]
	v_pk_mul_f32 v[48:49], v[48:49], v[66:67]
	v_add_f32_e32 v31, v74, v75
	v_add_f32_e32 v66, v76, v77
	v_pk_add_f32 v[88:89], v[64:65], v[60:61]
	v_pk_add_f32 v[90:91], v[40:41], v[44:45]
	ds_write2st64_b32 v29, v31, v66 offset0:200 offset1:204
	v_add_f32_e32 v31, v88, v89
	v_add_f32_e32 v88, v90, v91
	v_pk_mul_f32 v[62:63], v[52:53], v[62:63]
	s_waitcnt lgkmcnt(7)
	v_mov_b32_e32 v86, v73
	v_pk_mul_f32 v[50:51], v[50:51], v[68:69]
	v_pk_mul_f32 v[52:53], v[52:53], v[70:71]
	v_pk_mul_f32 v[54:55], v[54:55], v[56:57]
	v_add_f32_dpp v31, v31, v31 quad_perm:[1,0,3,2] row_mask:0xf bank_mask:0xf bound_ctrl:1
	v_add_f32_dpp v88, v88, v88 quad_perm:[1,0,3,2] row_mask:0xf bank_mask:0xf bound_ctrl:1
	v_add_u32_e32 v129, 0x1400, v23
	s_waitcnt lgkmcnt(5)
	v_pk_fma_f32 v[74:75], v[72:73], v[12:13], v[58:59] op_sel_hi:[0,1,1]
	v_pk_fma_f32 v[76:77], v[72:73], v[14:15], v[82:83] op_sel_hi:[0,1,1]
	v_pk_fma_f32 v[78:79], v[72:73], v[8:9], v[62:63] op_sel_hi:[0,1,1]
	v_pk_fma_f32 v[72:73], v[72:73], v[10:11], v[84:85] op_sel_hi:[0,1,1]
	v_pk_fma_f32 v[80:81], v[86:87], v[12:13], v[48:49] op_sel_hi:[0,1,1]
	v_pk_fma_f32 v[82:83], v[86:87], v[14:15], v[50:51] op_sel_hi:[0,1,1]
	v_pk_fma_f32 v[84:85], v[86:87], v[8:9], v[52:53] op_sel_hi:[0,1,1]
	v_pk_fma_f32 v[86:87], v[86:87], v[10:11], v[54:55] op_sel_hi:[0,1,1]
	ds_read_b128 v[40:43], v22 offset:4864
	ds_read_b128 v[44:47], v22 offset:4880
	ds_read_b128 v[8:11], v22 offset:4608
	ds_read_b128 v[12:15], v22 offset:4624
	ds_read2_b32 v[92:93], v129 offset0:192 offset1:200
	ds_read_b128 v[56:59], v22 offset:5376
	ds_read_b128 v[60:63], v22 offset:5392
	ds_read_b128 v[48:51], v22 offset:5120
	ds_read_b128 v[52:55], v22 offset:5136
	ds_read_b128 v[64:67], v22 offset:5632
	ds_read_b128 v[68:71], v22 offset:5648
	v_add_f32_dpp v31, v31, v31 quad_perm:[2,3,0,1] row_mask:0xf bank_mask:0xf bound_ctrl:1
	v_add_f32_dpp v89, v88, v88 quad_perm:[2,3,0,1] row_mask:0xf bank_mask:0xf bound_ctrl:1
	v_add_u32_e32 v130, 0x1c00, v23
	v_add_f32_dpp v88, v31, v31 row_half_mirror row_mask:0xf bank_mask:0xf bound_ctrl:1
	v_add_f32_dpp v90, v89, v89 row_half_mirror row_mask:0xf bank_mask:0xf bound_ctrl:1
	s_waitcnt lgkmcnt(14)
; #define SCAN_STEP(w0, w1, a0, a1, b0, b1, k0, k1, r0, r1, vi, vj, t) do { \
;                 SCAN_ROW(S0, S1, S2, S3, w0, w1, a0, a1, b0, b1, k0, k1, r0, r1, vi, (t) * 512); \
;                 SCAN_ROW(T0, T1, T2, T3, w0, w1, a0, a1, b0, b1, k0, k1, r0, r1, vj, (t) * 512 + 256); } while (0)
;     ...
;             SCAN_LOAD(w0, w1, a0, a1, b0, b1, k0, k1, r0, r1, vi, vj, 0);
; #pragma unroll
;             for (int t = 0; t < 16; t += 2) {
;                 SCAN_LOAD(W0, W1, A0, A1, B0, B1, K0, K1, R0, R1, VI, VJ, t + 1);
;                 SCAN_STEP(w0, w1, a0, a1, b0, b1, k0, k1, r0, r1, vi, vj, t);
;                 if (t + 2 < 16) SCAN_LOAD(w0, w1, a0, a1, b0, b1, k0, k1, r0, r1, vi, vj, t + 2);
;                 SCAN_STEP(W0, W1, A0, A1, B0, B1, K0, K1, R0, R1, VI, VJ, t + 1);
	v_pk_fma_f32 v[74:75], v[36:37], v[88:89], v[74:75] op_sel_hi:[1,0,1]
	v_pk_fma_f32 v[78:79], v[32:33], v[88:89], v[78:79] op_sel_hi:[1,0,1]
	v_pk_fma_f32 v[36:37], v[36:37], v[90:91], v[80:81] op_sel_hi:[1,0,1]
	v_pk_fma_f32 v[32:33], v[32:33], v[90:91], v[84:85] op_sel_hi:[1,0,1]
	v_pk_fma_f32 v[76:77], v[38:39], v[88:89], v[76:77] op_sel_hi:[1,0,1]
	v_pk_fma_f32 v[72:73], v[34:35], v[88:89], v[72:73] op_sel_hi:[1,0,1]
	v_pk_fma_f32 v[38:39], v[38:39], v[90:91], v[82:83] op_sel_hi:[1,0,1]
	v_pk_fma_f32 v[34:35], v[34:35], v[90:91], v[86:87] op_sel_hi:[1,0,1]
	s_waitcnt lgkmcnt(12)
	v_pk_mul_f32 v[80:81], v[4:5], v[74:75]
	v_pk_mul_f32 v[82:83], v[0:1], v[78:79]
	v_pk_mul_f32 v[4:5], v[4:5], v[36:37]
	v_pk_mul_f32 v[0:1], v[0:1], v[32:33]
	s_waitcnt lgkmcnt(8)
	v_pk_mul_f32 v[84:85], v[40:41], v[74:75]
	v_pk_mul_f32 v[86:87], v[44:45], v[78:79]
	v_pk_mul_f32 v[40:41], v[40:41], v[36:37]
	v_pk_mul_f32 v[44:45], v[44:45], v[32:33]
	v_pk_mul_f32 v[74:75], v[8:9], v[74:75]
	v_pk_mul_f32 v[88:89], v[10:11], v[76:77]
	s_waitcnt lgkmcnt(7)
	v_pk_mul_f32 v[78:79], v[12:13], v[78:79]
	v_pk_mul_f32 v[90:91], v[14:15], v[72:73]
	v_pk_mul_f32 v[8:9], v[8:9], v[36:37]
	v_pk_mul_f32 v[10:11], v[10:11], v[38:39]
	v_pk_mul_f32 v[12:13], v[12:13], v[32:33]
	v_pk_mul_f32 v[14:15], v[14:15], v[34:35]
	v_pk_fma_f32 v[32:33], v[6:7], v[76:77], v[80:81]
	v_pk_fma_f32 v[36:37], v[2:3], v[72:73], v[82:83]
	v_pk_fma_f32 v[4:5], v[6:7], v[38:39], v[4:5]
	v_pk_fma_f32 v[0:1], v[2:3], v[34:35], v[0:1]
	v_pk_fma_f32 v[2:3], v[42:43], v[76:77], v[84:85]
	v_pk_fma_f32 v[6:7], v[46:47], v[72:73], v[86:87]
	v_pk_fma_f32 v[38:39], v[42:43], v[38:39], v[40:41]
	v_pk_fma_f32 v[34:35], v[46:47], v[34:35], v[44:45]
	s_waitcnt lgkmcnt(5)
	v_mov_b32_e32 v94, v93
	v_pk_add_f32 v[0:1], v[4:5], v[0:1]
	v_pk_add_f32 v[2:3], v[2:3], v[6:7]
	v_pk_add_f32 v[4:5], v[38:39], v[34:35]
	v_pk_fma_f32 v[80:81], v[56:57], v[94:95], v[8:9] op_sel_hi:[1,0,1]
	v_pk_add_f32 v[8:9], v[32:33], v[36:37]
	v_add_f32_e32 v0, v0, v1
	v_add_f32_e32 v1, v2, v3
	v_add_f32_e32 v2, v4, v5
	s_waitcnt lgkmcnt(4)
	v_pk_fma_f32 v[76:77], v[60:61], v[92:93], v[78:79] op_sel_hi:[1,0,1]
	v_pk_fma_f32 v[78:79], v[62:63], v[92:93], v[90:91] op_sel_hi:[1,0,1]
	v_add_f32_e32 v6, v8, v9
	v_add_f32_dpp v31, v1, v1 quad_perm:[1,0,3,2] row_mask:0xf bank_mask:0xf bound_ctrl:1
	v_add_f32_dpp v90, v2, v2 quad_perm:[1,0,3,2] row_mask:0xf bank_mask:0xf bound_ctrl:1
	ds_write2st64_b32 v29, v6, v0 offset0:208 offset1:212
	v_add_f32_dpp v31, v31, v31 quad_perm:[2,3,0,1] row_mask:0xf bank_mask:0xf bound_ctrl:1
	v_add_f32_dpp v91, v90, v90 quad_perm:[2,3,0,1] row_mask:0xf bank_mask:0xf bound_ctrl:1
	v_pk_fma_f32 v[72:73], v[56:57], v[92:93], v[74:75] op_sel_hi:[1,0,1]
	v_pk_fma_f32 v[74:75], v[58:59], v[92:93], v[88:89] op_sel_hi:[1,0,1]
	v_pk_fma_f32 v[82:83], v[58:59], v[94:95], v[10:11] op_sel_hi:[1,0,1]
	v_pk_fma_f32 v[84:85], v[60:61], v[94:95], v[12:13] op_sel_hi:[1,0,1]
	v_pk_fma_f32 v[86:87], v[62:63], v[94:95], v[14:15] op_sel_hi:[1,0,1]
	ds_read_b128 v[44:47], v22 offset:6400
	ds_read_b128 v[40:43], v22 offset:6416
	ds_read_b128 v[56:59], v22 offset:6144
	ds_read_b128 v[60:63], v22 offset:6160
	ds_read2_b32 v[88:89], v130 offset0:64 offset1:72
	ds_read_b128 v[12:15], v22 offset:6912
	ds_read_b128 v[8:11], v22 offset:6928
	ds_read_b128 v[36:39], v22 offset:6656
	ds_read_b128 v[32:35], v22 offset:6672
	ds_read_b128 v[4:7], v22 offset:7168
	ds_read_b128 v[0:3], v22 offset:7184
	v_add_f32_dpp v90, v31, v31 row_half_mirror row_mask:0xf bank_mask:0xf bound_ctrl:1
	v_add_f32_dpp v92, v91, v91 row_half_mirror row_mask:0xf bank_mask:0xf bound_ctrl:1
	s_waitcnt lgkmcnt(14)
	v_pk_fma_f32 v[72:73], v[48:49], v[90:91], v[72:73] op_sel_hi:[1,0,1]
	v_pk_fma_f32 v[76:77], v[52:53], v[90:91], v[76:77] op_sel_hi:[1,0,1]
	v_pk_fma_f32 v[48:49], v[48:49], v[92:93], v[80:81] op_sel_hi:[1,0,1]
	v_pk_fma_f32 v[52:53], v[52:53], v[92:93], v[84:85] op_sel_hi:[1,0,1]
	v_pk_fma_f32 v[74:75], v[50:51], v[90:91], v[74:75] op_sel_hi:[1,0,1]
	v_pk_fma_f32 v[78:79], v[54:55], v[90:91], v[78:79] op_sel_hi:[1,0,1]
	v_pk_fma_f32 v[50:51], v[50:51], v[92:93], v[82:83] op_sel_hi:[1,0,1]
	v_pk_fma_f32 v[54:55], v[54:55], v[92:93], v[86:87] op_sel_hi:[1,0,1]
	s_waitcnt lgkmcnt(12)
	v_pk_mul_f32 v[80:81], v[64:65], v[72:73]
	v_pk_mul_f32 v[82:83], v[68:69], v[76:77]
	v_pk_mul_f32 v[64:65], v[64:65], v[48:49]
	v_pk_mul_f32 v[68:69], v[68:69], v[52:53]
	v_pk_fma_f32 v[80:81], v[66:67], v[74:75], v[80:81]
	v_pk_fma_f32 v[64:65], v[66:67], v[50:51], v[64:65]
	v_pk_fma_f32 v[66:67], v[70:71], v[54:55], v[68:69]
	v_pk_fma_f32 v[82:83], v[70:71], v[78:79], v[82:83]
	v_pk_add_f32 v[64:65], v[64:65], v[66:67]
	s_waitcnt lgkmcnt(9)
	v_pk_mul_f32 v[66:67], v[44:45], v[72:73]
	v_pk_mul_f32 v[70:71], v[40:41], v[76:77]
	v_pk_mul_f32 v[44:45], v[44:45], v[48:49]
	v_pk_mul_f32 v[40:41], v[40:41], v[52:53]
	v_pk_add_f32 v[68:69], v[80:81], v[82:83]
	s_waitcnt lgkmcnt(7)
	v_pk_mul_f32 v[72:73], v[56:57], v[72:73]
	v_pk_mul_f32 v[80:81], v[58:59], v[74:75]
	v_pk_mul_f32 v[76:77], v[60:61], v[76:77]
	v_pk_mul_f32 v[82:83], v[62:63], v[78:79]
	v_pk_mul_f32 v[48:49], v[56:57], v[48:49]
	v_pk_mul_f32 v[56:57], v[58:59], v[50:51]
	v_pk_mul_f32 v[52:53], v[60:61], v[52:53]
	v_pk_mul_f32 v[58:59], v[62:63], v[54:55]
	v_pk_fma_f32 v[60:61], v[46:47], v[74:75], v[66:67]
	v_pk_fma_f32 v[62:63], v[42:43], v[78:79], v[70:71]
	v_pk_fma_f32 v[44:45], v[46:47], v[50:51], v[44:45]
	v_pk_fma_f32 v[40:41], v[42:43], v[54:55], v[40:41]
	s_waitcnt lgkmcnt(5)
	v_mov_b32_e32 v84, v89
	v_add_f32_e32 v31, v68, v69
	v_add_f32_e32 v64, v64, v65
	v_pk_fma_f32 v[72:73], v[88:89], v[12:13], v[72:73] op_sel_hi:[0,1,1]
	v_pk_fma_f32 v[74:75], v[88:89], v[14:15], v[80:81] op_sel_hi:[0,1,1]
	s_waitcnt lgkmcnt(4)
; #define SCAN_STEP(w0, w1, a0, a1, b0, b1, k0, k1, r0, r1, vi, vj, t) do { \
;                 SCAN_ROW(S0, S1, S2, S3, w0, w1, a0, a1, b0, b1, k0, k1, r0, r1, vi, (t) * 512); \
;                 SCAN_ROW(T0, T1, T2, T3, w0, w1, a0, a1, b0, b1, k0, k1, r0, r1, vj, (t) * 512 + 256); } while (0)
;     ...
;             SCAN_LOAD(w0, w1, a0, a1, b0, b1, k0, k1, r0, r1, vi, vj, 0);
; #pragma unroll
;             for (int t = 0; t < 16; t += 2) {
;                 SCAN_LOAD(W0, W1, A0, A1, B0, B1, K0, K1, R0, R1, VI, VJ, t + 1);
;                 SCAN_STEP(w0, w1, a0, a1, b0, b1, k0, k1, r0, r1, vi, vj, t);
;                 if (t + 2 < 16) SCAN_LOAD(w0, w1, a0, a1, b0, b1, k0, k1, r0, r1, vi, vj, t + 2);
;                 SCAN_STEP(W0, W1, A0, A1, B0, B1, K0, K1, R0, R1, VI, VJ, t + 1);
	v_pk_fma_f32 v[76:77], v[88:89], v[8:9], v[76:77] op_sel_hi:[0,1,1]
	v_pk_fma_f32 v[78:79], v[88:89], v[10:11], v[82:83] op_sel_hi:[0,1,1]
	v_pk_add_f32 v[88:89], v[62:63], v[60:61]
	v_pk_add_f32 v[90:91], v[40:41], v[44:45]
	ds_write2st64_b32 v29, v31, v64 offset0:216 offset1:220
	v_add_f32_e32 v31, v88, v89
	v_add_f32_e32 v88, v90, v91
	v_add_u32_e32 v131, 0x2000, v23
	v_add_f32_dpp v31, v31, v31 quad_perm:[1,0,3,2] row_mask:0xf bank_mask:0xf bound_ctrl:1
	v_add_f32_dpp v88, v88, v88 quad_perm:[1,0,3,2] row_mask:0xf bank_mask:0xf bound_ctrl:1
	v_pk_fma_f32 v[80:81], v[84:85], v[12:13], v[48:49] op_sel_hi:[0,1,1]
	v_pk_fma_f32 v[82:83], v[84:85], v[14:15], v[56:57] op_sel_hi:[0,1,1]
	v_pk_fma_f32 v[86:87], v[84:85], v[8:9], v[52:53] op_sel_hi:[0,1,1]
	v_pk_fma_f32 v[84:85], v[84:85], v[10:11], v[58:59] op_sel_hi:[0,1,1]
	ds_read_b128 v[40:43], v22 offset:7936
	ds_read_b128 v[44:47], v22 offset:7952
	ds_read_b128 v[8:11], v22 offset:7680
	ds_read_b128 v[12:15], v22 offset:7696
	ds_read2_b32 v[92:93], v131 offset0:192 offset1:200
	ds_read_b128 v[56:59], v22 offset:8448
	ds_read_b128 v[60:63], v22 offset:8464
	ds_read_b128 v[48:51], v22 offset:8192
	ds_read_b128 v[52:55], v22 offset:8208
	ds_read_b128 v[64:67], v22 offset:8704
	ds_read_b128 v[68:71], v22 offset:8720
	v_add_f32_dpp v31, v31, v31 quad_perm:[2,3,0,1] row_mask:0xf bank_mask:0xf bound_ctrl:1
	v_add_f32_dpp v89, v88, v88 quad_perm:[2,3,0,1] row_mask:0xf bank_mask:0xf bound_ctrl:1
	v_add_u32_e32 v132, 0x2800, v23
	v_add_f32_dpp v88, v31, v31 row_half_mirror row_mask:0xf bank_mask:0xf bound_ctrl:1
	v_add_f32_dpp v90, v89, v89 row_half_mirror row_mask:0xf bank_mask:0xf bound_ctrl:1
	s_waitcnt lgkmcnt(14)
	v_pk_fma_f32 v[72:73], v[36:37], v[88:89], v[72:73] op_sel_hi:[1,0,1]
	v_pk_fma_f32 v[76:77], v[32:33], v[88:89], v[76:77] op_sel_hi:[1,0,1]
	v_pk_fma_f32 v[36:37], v[36:37], v[90:91], v[80:81] op_sel_hi:[1,0,1]
	v_pk_fma_f32 v[32:33], v[32:33], v[90:91], v[86:87] op_sel_hi:[1,0,1]
	v_pk_fma_f32 v[74:75], v[38:39], v[88:89], v[74:75] op_sel_hi:[1,0,1]
	v_pk_fma_f32 v[78:79], v[34:35], v[88:89], v[78:79] op_sel_hi:[1,0,1]
	v_pk_fma_f32 v[38:39], v[38:39], v[90:91], v[82:83] op_sel_hi:[1,0,1]
	v_pk_fma_f32 v[34:35], v[34:35], v[90:91], v[84:85] op_sel_hi:[1,0,1]
	s_waitcnt lgkmcnt(12)
	v_pk_mul_f32 v[80:81], v[4:5], v[72:73]
	v_pk_mul_f32 v[82:83], v[0:1], v[76:77]
	v_pk_mul_f32 v[4:5], v[4:5], v[36:37]
	v_pk_mul_f32 v[0:1], v[0:1], v[32:33]
	s_waitcnt lgkmcnt(8)
	v_pk_mul_f32 v[84:85], v[40:41], v[72:73]
	v_pk_mul_f32 v[86:87], v[44:45], v[76:77]
	v_pk_mul_f32 v[40:41], v[40:41], v[36:37]
	v_pk_mul_f32 v[44:45], v[44:45], v[32:33]
	v_pk_mul_f32 v[72:73], v[8:9], v[72:73]
	v_pk_mul_f32 v[88:89], v[10:11], v[74:75]
	s_waitcnt lgkmcnt(7)
	v_pk_mul_f32 v[76:77], v[12:13], v[76:77]
	v_pk_mul_f32 v[90:91], v[14:15], v[78:79]
	v_pk_mul_f32 v[8:9], v[8:9], v[36:37]
	v_pk_mul_f32 v[10:11], v[10:11], v[38:39]
	v_pk_mul_f32 v[12:13], v[12:13], v[32:33]
	v_pk_mul_f32 v[14:15], v[14:15], v[34:35]
	v_pk_fma_f32 v[32:33], v[6:7], v[74:75], v[80:81]
	v_pk_fma_f32 v[36:37], v[2:3], v[78:79], v[82:83]
	v_pk_fma_f32 v[4:5], v[6:7], v[38:39], v[4:5]
	v_pk_fma_f32 v[0:1], v[2:3], v[34:35], v[0:1]
	v_pk_fma_f32 v[2:3], v[42:43], v[74:75], v[84:85]
	v_pk_fma_f32 v[6:7], v[46:47], v[78:79], v[86:87]
	v_pk_fma_f32 v[38:39], v[42:43], v[38:39], v[40:41]
	v_pk_fma_f32 v[34:35], v[46:47], v[34:35], v[44:45]
	s_waitcnt lgkmcnt(5)
	v_mov_b32_e32 v94, v93
	v_pk_add_f32 v[0:1], v[4:5], v[0:1]
	v_pk_add_f32 v[2:3], v[2:3], v[6:7]
	v_pk_add_f32 v[4:5], v[38:39], v[34:35]
	v_pk_fma_f32 v[80:81], v[56:57], v[94:95], v[8:9] op_sel_hi:[1,0,1]
	v_pk_add_f32 v[8:9], v[32:33], v[36:37]
	v_add_f32_e32 v0, v0, v1
	v_add_f32_e32 v1, v2, v3
	v_add_f32_e32 v2, v4, v5
	s_waitcnt lgkmcnt(4)
	v_pk_fma_f32 v[78:79], v[62:63], v[92:93], v[90:91] op_sel_hi:[1,0,1]
	v_add_f32_e32 v6, v8, v9
	v_add_f32_dpp v31, v1, v1 quad_perm:[1,0,3,2] row_mask:0xf bank_mask:0xf bound_ctrl:1
	v_add_f32_dpp v90, v2, v2 quad_perm:[1,0,3,2] row_mask:0xf bank_mask:0xf bound_ctrl:1
	ds_write2st64_b32 v29, v6, v0 offset0:224 offset1:228
	v_add_f32_dpp v31, v31, v31 quad_perm:[2,3,0,1] row_mask:0xf bank_mask:0xf bound_ctrl:1
	v_add_f32_dpp v91, v90, v90 quad_perm:[2,3,0,1] row_mask:0xf bank_mask:0xf bound_ctrl:1
	v_pk_fma_f32 v[72:73], v[56:57], v[92:93], v[72:73] op_sel_hi:[1,0,1]
	v_pk_fma_f32 v[74:75], v[58:59], v[92:93], v[88:89] op_sel_hi:[1,0,1]
	v_pk_fma_f32 v[76:77], v[60:61], v[92:93], v[76:77] op_sel_hi:[1,0,1]
	v_pk_fma_f32 v[82:83], v[58:59], v[94:95], v[10:11] op_sel_hi:[1,0,1]
	v_pk_fma_f32 v[84:85], v[60:61], v[94:95], v[12:13] op_sel_hi:[1,0,1]
	v_pk_fma_f32 v[86:87], v[62:63], v[94:95], v[14:15] op_sel_hi:[1,0,1]
	ds_read_b128 v[44:47], v22 offset:9472
	ds_read_b128 v[40:43], v22 offset:9488
	ds_read_b128 v[56:59], v22 offset:9216
	ds_read_b128 v[60:63], v22 offset:9232
	ds_read2_b32 v[88:89], v132 offset0:64 offset1:72
	ds_read_b128 v[12:15], v22 offset:9984
	ds_read_b128 v[8:11], v22 offset:10000
	ds_read_b128 v[36:39], v22 offset:9728
	ds_read_b128 v[32:35], v22 offset:9744
	ds_read_b128 v[4:7], v22 offset:10240
	ds_read_b128 v[0:3], v22 offset:10256
	v_add_f32_dpp v90, v31, v31 row_half_mirror row_mask:0xf bank_mask:0xf bound_ctrl:1
	v_add_f32_dpp v92, v91, v91 row_half_mirror row_mask:0xf bank_mask:0xf bound_ctrl:1
	s_waitcnt lgkmcnt(14)
	v_pk_fma_f32 v[72:73], v[48:49], v[90:91], v[72:73] op_sel_hi:[1,0,1]
	v_pk_fma_f32 v[76:77], v[52:53], v[90:91], v[76:77] op_sel_hi:[1,0,1]
	v_pk_fma_f32 v[48:49], v[48:49], v[92:93], v[80:81] op_sel_hi:[1,0,1]
	v_pk_fma_f32 v[52:53], v[52:53], v[92:93], v[84:85] op_sel_hi:[1,0,1]
	v_pk_fma_f32 v[74:75], v[50:51], v[90:91], v[74:75] op_sel_hi:[1,0,1]
	v_pk_fma_f32 v[78:79], v[54:55], v[90:91], v[78:79] op_sel_hi:[1,0,1]
	v_pk_fma_f32 v[50:51], v[50:51], v[92:93], v[82:83] op_sel_hi:[1,0,1]
	v_pk_fma_f32 v[54:55], v[54:55], v[92:93], v[86:87] op_sel_hi:[1,0,1]
	s_waitcnt lgkmcnt(12)
; #define SCAN_STEP(w0, w1, a0, a1, b0, b1, k0, k1, r0, r1, vi, vj, t) do { \
;                 SCAN_ROW(S0, S1, S2, S3, w0, w1, a0, a1, b0, b1, k0, k1, r0, r1, vi, (t) * 512); \
;                 SCAN_ROW(T0, T1, T2, T3, w0, w1, a0, a1, b0, b1, k0, k1, r0, r1, vj, (t) * 512 + 256); } while (0)
;     ...
;             SCAN_LOAD(w0, w1, a0, a1, b0, b1, k0, k1, r0, r1, vi, vj, 0);
; #pragma unroll
;             for (int t = 0; t < 16; t += 2) {
;                 SCAN_LOAD(W0, W1, A0, A1, B0, B1, K0, K1, R0, R1, VI, VJ, t + 1);
;                 SCAN_STEP(w0, w1, a0, a1, b0, b1, k0, k1, r0, r1, vi, vj, t);
;                 if (t + 2 < 16) SCAN_LOAD(w0, w1, a0, a1, b0, b1, k0, k1, r0, r1, vi, vj, t + 2);
;                 SCAN_STEP(W0, W1, A0, A1, B0, B1, K0, K1, R0, R1, VI, VJ, t + 1);
	v_pk_mul_f32 v[80:81], v[64:65], v[72:73]
	v_pk_mul_f32 v[82:83], v[68:69], v[76:77]
	v_pk_mul_f32 v[64:65], v[64:65], v[48:49]
	v_pk_mul_f32 v[68:69], v[68:69], v[52:53]
	v_pk_fma_f32 v[80:81], v[66:67], v[74:75], v[80:81]
	v_pk_fma_f32 v[64:65], v[66:67], v[50:51], v[64:65]
	v_pk_fma_f32 v[66:67], v[70:71], v[54:55], v[68:69]
	v_pk_fma_f32 v[82:83], v[70:71], v[78:79], v[82:83]
	v_pk_add_f32 v[64:65], v[64:65], v[66:67]
	s_waitcnt lgkmcnt(9)
	v_pk_mul_f32 v[66:67], v[44:45], v[72:73]
	v_pk_mul_f32 v[70:71], v[40:41], v[76:77]
	v_pk_mul_f32 v[44:45], v[44:45], v[48:49]
	v_pk_mul_f32 v[40:41], v[40:41], v[52:53]
	v_pk_add_f32 v[68:69], v[80:81], v[82:83]
	s_waitcnt lgkmcnt(7)
	v_pk_mul_f32 v[72:73], v[56:57], v[72:73]
	v_pk_mul_f32 v[80:81], v[58:59], v[74:75]
	v_pk_mul_f32 v[76:77], v[60:61], v[76:77]
	v_pk_mul_f32 v[82:83], v[62:63], v[78:79]
	v_pk_mul_f32 v[48:49], v[56:57], v[48:49]
	v_pk_mul_f32 v[56:57], v[58:59], v[50:51]
	v_pk_mul_f32 v[52:53], v[60:61], v[52:53]
	v_pk_mul_f32 v[58:59], v[62:63], v[54:55]
	v_pk_fma_f32 v[60:61], v[46:47], v[74:75], v[66:67]
	v_pk_fma_f32 v[62:63], v[42:43], v[78:79], v[70:71]
	v_pk_fma_f32 v[44:45], v[46:47], v[50:51], v[44:45]
	v_pk_fma_f32 v[40:41], v[42:43], v[54:55], v[40:41]
	s_waitcnt lgkmcnt(5)
	v_mov_b32_e32 v84, v89
	v_add_f32_e32 v31, v68, v69
	v_add_f32_e32 v64, v64, v65
	v_pk_fma_f32 v[72:73], v[88:89], v[12:13], v[72:73] op_sel_hi:[0,1,1]
	v_pk_fma_f32 v[74:75], v[88:89], v[14:15], v[80:81] op_sel_hi:[0,1,1]
	s_waitcnt lgkmcnt(4)
	v_pk_fma_f32 v[76:77], v[88:89], v[8:9], v[76:77] op_sel_hi:[0,1,1]
	v_pk_fma_f32 v[78:79], v[88:89], v[10:11], v[82:83] op_sel_hi:[0,1,1]
	v_pk_add_f32 v[88:89], v[62:63], v[60:61]
	v_pk_add_f32 v[90:91], v[40:41], v[44:45]
	ds_write2st64_b32 v29, v31, v64 offset0:232 offset1:236
	v_add_f32_e32 v31, v88, v89
	v_add_f32_e32 v88, v90, v91
	v_add_u32_e32 v133, 0x2c00, v23
	v_add_f32_dpp v31, v31, v31 quad_perm:[1,0,3,2] row_mask:0xf bank_mask:0xf bound_ctrl:1
	v_add_f32_dpp v88, v88, v88 quad_perm:[1,0,3,2] row_mask:0xf bank_mask:0xf bound_ctrl:1
	v_pk_fma_f32 v[80:81], v[84:85], v[12:13], v[48:49] op_sel_hi:[0,1,1]
	v_pk_fma_f32 v[82:83], v[84:85], v[14:15], v[56:57] op_sel_hi:[0,1,1]
	v_pk_fma_f32 v[86:87], v[84:85], v[8:9], v[52:53] op_sel_hi:[0,1,1]
	v_pk_fma_f32 v[84:85], v[84:85], v[10:11], v[58:59] op_sel_hi:[0,1,1]
	ds_read_b128 v[40:43], v22 offset:11008
	ds_read_b128 v[44:47], v22 offset:11024
	ds_read_b128 v[8:11], v22 offset:10752
	ds_read_b128 v[12:15], v22 offset:10768
	ds_read2_b32 v[92:93], v133 offset0:192 offset1:200
	ds_read_b128 v[56:59], v22 offset:11520
	ds_read_b128 v[60:63], v22 offset:11536
	ds_read_b128 v[48:51], v22 offset:11264
	ds_read_b128 v[52:55], v22 offset:11280
	ds_read_b128 v[64:67], v22 offset:11776
	ds_read_b128 v[68:71], v22 offset:11792
	v_add_f32_dpp v31, v31, v31 quad_perm:[2,3,0,1] row_mask:0xf bank_mask:0xf bound_ctrl:1
	v_add_f32_dpp v89, v88, v88 quad_perm:[2,3,0,1] row_mask:0xf bank_mask:0xf bound_ctrl:1
	v_add_u32_e32 v134, 0x3400, v23
	v_add_f32_dpp v88, v31, v31 row_half_mirror row_mask:0xf bank_mask:0xf bound_ctrl:1
	v_add_f32_dpp v90, v89, v89 row_half_mirror row_mask:0xf bank_mask:0xf bound_ctrl:1
	s_waitcnt lgkmcnt(14)
	v_pk_fma_f32 v[72:73], v[36:37], v[88:89], v[72:73] op_sel_hi:[1,0,1]
	v_pk_fma_f32 v[76:77], v[32:33], v[88:89], v[76:77] op_sel_hi:[1,0,1]
	v_pk_fma_f32 v[36:37], v[36:37], v[90:91], v[80:81] op_sel_hi:[1,0,1]
	v_pk_fma_f32 v[32:33], v[32:33], v[90:91], v[86:87] op_sel_hi:[1,0,1]
	v_pk_fma_f32 v[74:75], v[38:39], v[88:89], v[74:75] op_sel_hi:[1,0,1]
	v_pk_fma_f32 v[78:79], v[34:35], v[88:89], v[78:79] op_sel_hi:[1,0,1]
	v_pk_fma_f32 v[38:39], v[38:39], v[90:91], v[82:83] op_sel_hi:[1,0,1]
	v_pk_fma_f32 v[34:35], v[34:35], v[90:91], v[84:85] op_sel_hi:[1,0,1]
	s_waitcnt lgkmcnt(12)
	v_pk_mul_f32 v[80:81], v[4:5], v[72:73]
	v_pk_mul_f32 v[82:83], v[0:1], v[76:77]
	v_pk_mul_f32 v[4:5], v[4:5], v[36:37]
	v_pk_mul_f32 v[0:1], v[0:1], v[32:33]
	s_waitcnt lgkmcnt(8)
	v_pk_mul_f32 v[84:85], v[40:41], v[72:73]
	v_pk_mul_f32 v[86:87], v[44:45], v[76:77]
	v_pk_mul_f32 v[40:41], v[40:41], v[36:37]
	v_pk_mul_f32 v[44:45], v[44:45], v[32:33]
	v_pk_mul_f32 v[72:73], v[8:9], v[72:73]
	v_pk_mul_f32 v[88:89], v[10:11], v[74:75]
	s_waitcnt lgkmcnt(7)
	v_pk_mul_f32 v[76:77], v[12:13], v[76:77]
	v_pk_mul_f32 v[90:91], v[14:15], v[78:79]
	v_pk_mul_f32 v[8:9], v[8:9], v[36:37]
	v_pk_mul_f32 v[10:11], v[10:11], v[38:39]
	v_pk_mul_f32 v[12:13], v[12:13], v[32:33]
	v_pk_mul_f32 v[14:15], v[14:15], v[34:35]
	v_pk_fma_f32 v[32:33], v[6:7], v[74:75], v[80:81]
	v_pk_fma_f32 v[36:37], v[2:3], v[78:79], v[82:83]
	v_pk_fma_f32 v[4:5], v[6:7], v[38:39], v[4:5]
	v_pk_fma_f32 v[0:1], v[2:3], v[34:35], v[0:1]
	v_pk_fma_f32 v[2:3], v[42:43], v[74:75], v[84:85]
	v_pk_fma_f32 v[6:7], v[46:47], v[78:79], v[86:87]
	v_pk_fma_f32 v[38:39], v[42:43], v[38:39], v[40:41]
	v_pk_fma_f32 v[34:35], v[46:47], v[34:35], v[44:45]
	s_waitcnt lgkmcnt(5)
	v_mov_b32_e32 v94, v93
	v_pk_add_f32 v[0:1], v[4:5], v[0:1]
	v_pk_add_f32 v[2:3], v[2:3], v[6:7]
	v_pk_add_f32 v[4:5], v[38:39], v[34:35]
	v_pk_fma_f32 v[80:81], v[56:57], v[94:95], v[8:9] op_sel_hi:[1,0,1]
	v_pk_add_f32 v[8:9], v[32:33], v[36:37]
	v_add_f32_e32 v0, v0, v1
	v_add_f32_e32 v1, v2, v3
	v_add_f32_e32 v2, v4, v5
	s_waitcnt lgkmcnt(4)
; #define SCAN_STEP(w0, w1, a0, a1, b0, b1, k0, k1, r0, r1, vi, vj, t) do { \
;                 SCAN_ROW(S0, S1, S2, S3, w0, w1, a0, a1, b0, b1, k0, k1, r0, r1, vi, (t) * 512); \
;                 SCAN_ROW(T0, T1, T2, T3, w0, w1, a0, a1, b0, b1, k0, k1, r0, r1, vj, (t) * 512 + 256); } while (0)
;     ...
;             SCAN_LOAD(w0, w1, a0, a1, b0, b1, k0, k1, r0, r1, vi, vj, 0);
; #pragma unroll
;             for (int t = 0; t < 16; t += 2) {
;                 SCAN_LOAD(W0, W1, A0, A1, B0, B1, K0, K1, R0, R1, VI, VJ, t + 1);
;                 SCAN_STEP(w0, w1, a0, a1, b0, b1, k0, k1, r0, r1, vi, vj, t);
;                 if (t + 2 < 16) SCAN_LOAD(w0, w1, a0, a1, b0, b1, k0, k1, r0, r1, vi, vj, t + 2);
;                 SCAN_STEP(W0, W1, A0, A1, B0, B1, K0, K1, R0, R1, VI, VJ, t + 1);
	v_pk_fma_f32 v[78:79], v[62:63], v[92:93], v[90:91] op_sel_hi:[1,0,1]
	v_add_f32_e32 v6, v8, v9
	v_add_f32_dpp v31, v1, v1 quad_perm:[1,0,3,2] row_mask:0xf bank_mask:0xf bound_ctrl:1
	v_add_f32_dpp v90, v2, v2 quad_perm:[1,0,3,2] row_mask:0xf bank_mask:0xf bound_ctrl:1
	ds_write2st64_b32 v29, v6, v0 offset0:240 offset1:244
	v_add_f32_dpp v31, v31, v31 quad_perm:[2,3,0,1] row_mask:0xf bank_mask:0xf bound_ctrl:1
	v_add_f32_dpp v91, v90, v90 quad_perm:[2,3,0,1] row_mask:0xf bank_mask:0xf bound_ctrl:1
	v_pk_fma_f32 v[72:73], v[56:57], v[92:93], v[72:73] op_sel_hi:[1,0,1]
	v_pk_fma_f32 v[74:75], v[58:59], v[92:93], v[88:89] op_sel_hi:[1,0,1]
	v_pk_fma_f32 v[76:77], v[60:61], v[92:93], v[76:77] op_sel_hi:[1,0,1]
	v_pk_fma_f32 v[82:83], v[58:59], v[94:95], v[10:11] op_sel_hi:[1,0,1]
	v_pk_fma_f32 v[84:85], v[60:61], v[94:95], v[12:13] op_sel_hi:[1,0,1]
	v_pk_fma_f32 v[86:87], v[62:63], v[94:95], v[14:15] op_sel_hi:[1,0,1]
	ds_read_b128 v[44:47], v22 offset:12544
	ds_read_b128 v[40:43], v22 offset:12560
	ds_read_b128 v[56:59], v22 offset:12288
	ds_read_b128 v[60:63], v22 offset:12304
	ds_read2_b32 v[88:89], v134 offset0:64 offset1:72
	ds_read_b128 v[12:15], v22 offset:13056
	ds_read_b128 v[8:11], v22 offset:13072
	ds_read_b128 v[36:39], v22 offset:12800
	ds_read_b128 v[32:35], v22 offset:12816
	ds_read_b128 v[4:7], v22 offset:13312
	ds_read_b128 v[0:3], v22 offset:13328
	v_add_f32_dpp v90, v31, v31 row_half_mirror row_mask:0xf bank_mask:0xf bound_ctrl:1
	v_add_f32_dpp v92, v91, v91 row_half_mirror row_mask:0xf bank_mask:0xf bound_ctrl:1
	s_waitcnt lgkmcnt(14)
	v_pk_fma_f32 v[72:73], v[48:49], v[90:91], v[72:73] op_sel_hi:[1,0,1]
	v_pk_fma_f32 v[76:77], v[52:53], v[90:91], v[76:77] op_sel_hi:[1,0,1]
	v_pk_fma_f32 v[48:49], v[48:49], v[92:93], v[80:81] op_sel_hi:[1,0,1]
	v_pk_fma_f32 v[52:53], v[52:53], v[92:93], v[84:85] op_sel_hi:[1,0,1]
	v_pk_fma_f32 v[74:75], v[50:51], v[90:91], v[74:75] op_sel_hi:[1,0,1]
	v_pk_fma_f32 v[78:79], v[54:55], v[90:91], v[78:79] op_sel_hi:[1,0,1]
	v_pk_fma_f32 v[50:51], v[50:51], v[92:93], v[82:83] op_sel_hi:[1,0,1]
	v_pk_fma_f32 v[54:55], v[54:55], v[92:93], v[86:87] op_sel_hi:[1,0,1]
	s_waitcnt lgkmcnt(12)
	v_pk_mul_f32 v[80:81], v[64:65], v[72:73]
	v_pk_mul_f32 v[82:83], v[68:69], v[76:77]
	v_pk_mul_f32 v[64:65], v[64:65], v[48:49]
	v_pk_mul_f32 v[68:69], v[68:69], v[52:53]
	v_pk_fma_f32 v[80:81], v[66:67], v[74:75], v[80:81]
	v_pk_fma_f32 v[64:65], v[66:67], v[50:51], v[64:65]
	v_pk_fma_f32 v[66:67], v[70:71], v[54:55], v[68:69]
	v_pk_fma_f32 v[82:83], v[70:71], v[78:79], v[82:83]
	v_pk_add_f32 v[64:65], v[64:65], v[66:67]
	s_waitcnt lgkmcnt(9)
	v_pk_mul_f32 v[66:67], v[44:45], v[72:73]
	v_pk_mul_f32 v[70:71], v[40:41], v[76:77]
	v_pk_mul_f32 v[44:45], v[44:45], v[48:49]
	v_pk_mul_f32 v[40:41], v[40:41], v[52:53]
	v_pk_add_f32 v[68:69], v[80:81], v[82:83]
	s_waitcnt lgkmcnt(7)
	v_pk_mul_f32 v[72:73], v[56:57], v[72:73]
	v_pk_mul_f32 v[80:81], v[58:59], v[74:75]
	v_pk_mul_f32 v[76:77], v[60:61], v[76:77]
	v_pk_mul_f32 v[82:83], v[62:63], v[78:79]
	v_pk_mul_f32 v[48:49], v[56:57], v[48:49]
	v_pk_mul_f32 v[56:57], v[58:59], v[50:51]
	v_pk_mul_f32 v[52:53], v[60:61], v[52:53]
	v_pk_mul_f32 v[58:59], v[62:63], v[54:55]
	v_pk_fma_f32 v[60:61], v[46:47], v[74:75], v[66:67]
	v_pk_fma_f32 v[62:63], v[42:43], v[78:79], v[70:71]
	v_pk_fma_f32 v[44:45], v[46:47], v[50:51], v[44:45]
	v_pk_fma_f32 v[40:41], v[42:43], v[54:55], v[40:41]
	s_waitcnt lgkmcnt(5)
	v_mov_b32_e32 v84, v89
	v_add_f32_e32 v31, v68, v69
	v_add_f32_e32 v64, v64, v65
	v_pk_fma_f32 v[72:73], v[88:89], v[12:13], v[72:73] op_sel_hi:[0,1,1]
	v_pk_fma_f32 v[74:75], v[88:89], v[14:15], v[80:81] op_sel_hi:[0,1,1]
	s_waitcnt lgkmcnt(4)
	v_pk_fma_f32 v[76:77], v[88:89], v[8:9], v[76:77] op_sel_hi:[0,1,1]
	v_pk_fma_f32 v[78:79], v[88:89], v[10:11], v[82:83] op_sel_hi:[0,1,1]
	v_pk_add_f32 v[88:89], v[62:63], v[60:61]
	v_pk_add_f32 v[90:91], v[40:41], v[44:45]
	v_add_u32_e32 v21, 0xc000, v29
	v_add_u32_e32 v30, 0x3800, v23
	ds_write2st64_b32 v29, v31, v64 offset0:248 offset1:252
	v_add_f32_e32 v29, v88, v89
	v_add_f32_e32 v88, v90, v91
	v_pk_fma_f32 v[80:81], v[84:85], v[12:13], v[48:49] op_sel_hi:[0,1,1]
	v_pk_fma_f32 v[82:83], v[84:85], v[14:15], v[56:57] op_sel_hi:[0,1,1]
	v_pk_fma_f32 v[86:87], v[84:85], v[8:9], v[52:53] op_sel_hi:[0,1,1]
	v_pk_fma_f32 v[84:85], v[84:85], v[10:11], v[58:59] op_sel_hi:[0,1,1]
	ds_read2_b32 v[30:31], v30 offset0:192 offset1:200
	ds_read_b128 v[40:43], v22 offset:14080
	ds_read_b128 v[44:47], v22 offset:14096
	ds_read_b128 v[8:11], v22 offset:13824
	ds_read_b128 v[12:15], v22 offset:13840
	ds_read_b128 v[56:59], v22 offset:14592
	ds_read_b128 v[60:63], v22 offset:14608
	ds_read_b128 v[48:51], v22 offset:14336
	ds_read_b128 v[52:55], v22 offset:14352
	ds_read_b128 v[64:67], v22 offset:14848
	ds_read_b128 v[68:71], v22 offset:14864
	v_add_f32_dpp v29, v29, v29 quad_perm:[1,0,3,2] row_mask:0xf bank_mask:0xf bound_ctrl:1
	v_add_f32_dpp v88, v88, v88 quad_perm:[1,0,3,2] row_mask:0xf bank_mask:0xf bound_ctrl:1
	v_add_u32_e32 v28, 0x4000, v23
	v_add_f32_dpp v29, v29, v29 quad_perm:[2,3,0,1] row_mask:0xf bank_mask:0xf bound_ctrl:1
	v_add_f32_dpp v89, v88, v88 quad_perm:[2,3,0,1] row_mask:0xf bank_mask:0xf bound_ctrl:1
	s_waitcnt lgkmcnt(10)
; #define SCAN_STEP(w0, w1, a0, a1, b0, b1, k0, k1, r0, r1, vi, vj, t) do { \
;                 SCAN_ROW(S0, S1, S2, S3, w0, w1, a0, a1, b0, b1, k0, k1, r0, r1, vi, (t) * 512); \
;                 SCAN_ROW(T0, T1, T2, T3, w0, w1, a0, a1, b0, b1, k0, k1, r0, r1, vj, (t) * 512 + 256); } while (0)
;     ...
;             SCAN_LOAD(w0, w1, a0, a1, b0, b1, k0, k1, r0, r1, vi, vj, 0);
; #pragma unroll
;             for (int t = 0; t < 16; t += 2) {
;                 SCAN_LOAD(W0, W1, A0, A1, B0, B1, K0, K1, R0, R1, VI, VJ, t + 1);
;                 SCAN_STEP(w0, w1, a0, a1, b0, b1, k0, k1, r0, r1, vi, vj, t);
;                 if (t + 2 < 16) SCAN_LOAD(w0, w1, a0, a1, b0, b1, k0, k1, r0, r1, vi, vj, t + 2);
;                 SCAN_STEP(W0, W1, A0, A1, B0, B1, K0, K1, R0, R1, VI, VJ, t + 1);
	v_mov_b32_e32 v92, v31
	v_add_f32_dpp v88, v29, v29 row_half_mirror row_mask:0xf bank_mask:0xf bound_ctrl:1
	v_add_f32_dpp v90, v89, v89 row_half_mirror row_mask:0xf bank_mask:0xf bound_ctrl:1
	v_pk_fma_f32 v[72:73], v[36:37], v[88:89], v[72:73] op_sel_hi:[1,0,1]
	v_pk_fma_f32 v[74:75], v[38:39], v[88:89], v[74:75] op_sel_hi:[1,0,1]
	v_pk_fma_f32 v[76:77], v[32:33], v[88:89], v[76:77] op_sel_hi:[1,0,1]
	v_pk_fma_f32 v[78:79], v[34:35], v[88:89], v[78:79] op_sel_hi:[1,0,1]
	v_pk_fma_f32 v[36:37], v[36:37], v[90:91], v[80:81] op_sel_hi:[1,0,1]
	v_pk_fma_f32 v[32:33], v[32:33], v[90:91], v[86:87] op_sel_hi:[1,0,1]
	v_pk_fma_f32 v[38:39], v[38:39], v[90:91], v[82:83] op_sel_hi:[1,0,1]
	v_pk_fma_f32 v[34:35], v[34:35], v[90:91], v[84:85] op_sel_hi:[1,0,1]
	v_pk_mul_f32 v[80:81], v[4:5], v[72:73]
	v_pk_mul_f32 v[82:83], v[0:1], v[76:77]
	v_pk_mul_f32 v[4:5], v[4:5], v[36:37]
	v_pk_mul_f32 v[0:1], v[0:1], v[32:33]
	s_waitcnt lgkmcnt(6)
	v_pk_mul_f32 v[84:85], v[40:41], v[72:73]
	v_pk_mul_f32 v[86:87], v[44:45], v[76:77]
	v_pk_mul_f32 v[72:73], v[8:9], v[72:73]
	v_pk_mul_f32 v[88:89], v[10:11], v[74:75]
	v_pk_mul_f32 v[76:77], v[12:13], v[76:77]
	v_pk_mul_f32 v[90:91], v[14:15], v[78:79]
	v_pk_mul_f32 v[40:41], v[40:41], v[36:37]
	v_pk_mul_f32 v[44:45], v[44:45], v[32:33]
	v_pk_mul_f32 v[8:9], v[8:9], v[36:37]
	v_pk_mul_f32 v[12:13], v[12:13], v[32:33]
	v_pk_mul_f32 v[14:15], v[14:15], v[34:35]
	v_pk_fma_f32 v[32:33], v[6:7], v[74:75], v[80:81]
	v_pk_fma_f32 v[36:37], v[2:3], v[78:79], v[82:83]
	v_pk_fma_f32 v[4:5], v[6:7], v[38:39], v[4:5]
	v_pk_fma_f32 v[0:1], v[2:3], v[34:35], v[0:1]
	v_pk_fma_f32 v[2:3], v[42:43], v[74:75], v[84:85]
	v_pk_fma_f32 v[6:7], v[46:47], v[78:79], v[86:87]
	s_waitcnt lgkmcnt(4)
	v_pk_fma_f32 v[72:73], v[56:57], v[30:31], v[72:73] op_sel_hi:[1,0,1]
	v_pk_fma_f32 v[74:75], v[58:59], v[30:31], v[88:89] op_sel_hi:[1,0,1]
	v_pk_fma_f32 v[76:77], v[60:61], v[30:31], v[76:77] op_sel_hi:[1,0,1]
	v_pk_fma_f32 v[78:79], v[62:63], v[30:31], v[90:91] op_sel_hi:[1,0,1]
	v_pk_fma_f32 v[30:31], v[42:43], v[38:39], v[40:41]
	v_pk_fma_f32 v[34:35], v[46:47], v[34:35], v[44:45]
	v_pk_add_f32 v[0:1], v[4:5], v[0:1]
	v_pk_add_f32 v[2:3], v[2:3], v[6:7]
	v_pk_add_f32 v[4:5], v[30:31], v[34:35]
	v_pk_fma_f32 v[80:81], v[56:57], v[92:93], v[8:9] op_sel_hi:[1,0,1]
	v_pk_add_f32 v[8:9], v[32:33], v[36:37]
	v_add_f32_e32 v0, v0, v1
	v_add_f32_e32 v1, v2, v3
	v_add_f32_e32 v2, v4, v5
	v_add_f32_e32 v6, v8, v9
	v_add_f32_dpp v86, v1, v1 quad_perm:[1,0,3,2] row_mask:0xf bank_mask:0xf bound_ctrl:1
	v_add_f32_dpp v87, v2, v2 quad_perm:[1,0,3,2] row_mask:0xf bank_mask:0xf bound_ctrl:1
	v_pk_mul_f32 v[10:11], v[10:11], v[38:39]
	ds_write2st64_b32 v21, v6, v0 offset0:64 offset1:68
	v_add_f32_dpp v86, v86, v86 quad_perm:[2,3,0,1] row_mask:0xf bank_mask:0xf bound_ctrl:1
	v_add_f32_dpp v87, v87, v87 quad_perm:[2,3,0,1] row_mask:0xf bank_mask:0xf bound_ctrl:1
	v_pk_fma_f32 v[82:83], v[58:59], v[92:93], v[10:11] op_sel_hi:[1,0,1]
	v_pk_fma_f32 v[60:61], v[60:61], v[92:93], v[12:13] op_sel_hi:[1,0,1]
	v_pk_fma_f32 v[62:63], v[62:63], v[92:93], v[14:15] op_sel_hi:[1,0,1]
	ds_read2_b32 v[84:85], v28 offset0:64 offset1:72
	ds_read_b128 v[0:3], v22 offset:16400
	ds_read_b128 v[4:7], v22 offset:16384
	ds_read_b128 v[8:11], v22 offset:16144
	ds_read_b128 v[12:15], v22 offset:16128
	ds_read_b128 v[28:31], v22 offset:15888
	ds_read_b128 v[32:35], v22 offset:15872
	ds_read_b128 v[36:39], v22 offset:15632
	ds_read_b128 v[40:43], v22 offset:15616
	ds_read_b128 v[44:47], v22 offset:15360
	ds_read_b128 v[56:59], v22 offset:15376
	v_add_f32_dpp v86, v86, v86 row_half_mirror row_mask:0xf bank_mask:0xf bound_ctrl:1
	v_add_f32_dpp v88, v87, v87 row_half_mirror row_mask:0xf bank_mask:0xf bound_ctrl:1
	s_waitcnt lgkmcnt(14)
	v_pk_fma_f32 v[72:73], v[48:49], v[86:87], v[72:73] op_sel_hi:[1,0,1]
	v_pk_fma_f32 v[76:77], v[52:53], v[86:87], v[76:77] op_sel_hi:[1,0,1]
	v_pk_fma_f32 v[48:49], v[48:49], v[88:89], v[80:81] op_sel_hi:[1,0,1]
	v_pk_fma_f32 v[52:53], v[52:53], v[88:89], v[60:61] op_sel_hi:[1,0,1]
	v_pk_fma_f32 v[74:75], v[50:51], v[86:87], v[74:75] op_sel_hi:[1,0,1]
	v_pk_fma_f32 v[78:79], v[54:55], v[86:87], v[78:79] op_sel_hi:[1,0,1]
	v_pk_fma_f32 v[50:51], v[50:51], v[88:89], v[82:83] op_sel_hi:[1,0,1]
	v_pk_fma_f32 v[54:55], v[54:55], v[88:89], v[62:63] op_sel_hi:[1,0,1]
	s_waitcnt lgkmcnt(12)
	v_pk_mul_f32 v[60:61], v[64:65], v[72:73]
	v_pk_mul_f32 v[62:63], v[68:69], v[76:77]
	v_pk_mul_f32 v[64:65], v[64:65], v[48:49]
	v_pk_mul_f32 v[68:69], v[68:69], v[52:53]
	v_pk_fma_f32 v[60:61], v[66:67], v[74:75], v[60:61]
	v_pk_fma_f32 v[62:63], v[70:71], v[78:79], v[62:63]
	v_pk_fma_f32 v[64:65], v[66:67], v[50:51], v[64:65]
	v_pk_fma_f32 v[66:67], v[70:71], v[54:55], v[68:69]
	v_pk_add_f32 v[60:61], v[60:61], v[62:63]
	v_pk_add_f32 v[62:63], v[64:65], v[66:67]
	s_waitcnt lgkmcnt(1)
	v_pk_mul_f32 v[64:65], v[40:41], v[72:73]
	v_pk_mul_f32 v[66:67], v[36:37], v[76:77]
	v_pk_mul_f32 v[40:41], v[40:41], v[48:49]
	v_pk_mul_f32 v[36:37], v[36:37], v[52:53]
	v_pk_mul_f32 v[68:69], v[44:45], v[72:73]
	v_pk_mul_f32 v[70:71], v[46:47], v[74:75]
	s_waitcnt lgkmcnt(0)
; #define SCAN_STEP(w0, w1, a0, a1, b0, b1, k0, k1, r0, r1, vi, vj, t) do { \
;                 SCAN_ROW(S0, S1, S2, S3, w0, w1, a0, a1, b0, b1, k0, k1, r0, r1, vi, (t) * 512); \
;                 SCAN_ROW(T0, T1, T2, T3, w0, w1, a0, a1, b0, b1, k0, k1, r0, r1, vj, (t) * 512 + 256); } while (0)
;     ...
;             SCAN_LOAD(w0, w1, a0, a1, b0, b1, k0, k1, r0, r1, vi, vj, 0);
; #pragma unroll
;             for (int t = 0; t < 16; t += 2) {
;                 SCAN_LOAD(W0, W1, A0, A1, B0, B1, K0, K1, R0, R1, VI, VJ, t + 1);
;                 SCAN_STEP(w0, w1, a0, a1, b0, b1, k0, k1, r0, r1, vi, vj, t);
;                 if (t + 2 < 16) SCAN_LOAD(w0, w1, a0, a1, b0, b1, k0, k1, r0, r1, vi, vj, t + 2);
;                 SCAN_STEP(W0, W1, A0, A1, B0, B1, K0, K1, R0, R1, VI, VJ, t + 1);
	v_pk_mul_f32 v[72:73], v[56:57], v[76:77]
	v_pk_mul_f32 v[76:77], v[58:59], v[78:79]
	v_pk_mul_f32 v[44:45], v[44:45], v[48:49]
	v_pk_mul_f32 v[48:49], v[56:57], v[52:53]
	v_pk_mul_f32 v[52:53], v[58:59], v[54:55]
	v_add_f32_e32 v60, v60, v61
	v_add_f32_e32 v61, v62, v63
	v_pk_fma_f32 v[56:57], v[42:43], v[74:75], v[64:65]
	v_pk_fma_f32 v[58:59], v[38:39], v[78:79], v[66:67]
	v_pk_fma_f32 v[40:41], v[42:43], v[50:51], v[40:41]
	v_pk_fma_f32 v[36:37], v[38:39], v[54:55], v[36:37]
	v_add_u32_e32 v27, 0x4400, v23
	v_mov_b32_e32 v80, v85
	v_pk_mul_f32 v[46:47], v[46:47], v[50:51]
	v_pk_fma_f32 v[68:69], v[84:85], v[12:13], v[68:69] op_sel_hi:[0,1,1]
	v_pk_fma_f32 v[70:71], v[84:85], v[14:15], v[70:71] op_sel_hi:[0,1,1]
	v_pk_fma_f32 v[72:73], v[84:85], v[8:9], v[72:73] op_sel_hi:[0,1,1]
	v_pk_fma_f32 v[74:75], v[84:85], v[10:11], v[76:77] op_sel_hi:[0,1,1]
	ds_write2st64_b32 v21, v60, v61 offset0:72 offset1:76
	v_pk_add_f32 v[84:85], v[58:59], v[56:57]
	v_pk_add_f32 v[86:87], v[36:37], v[40:41]
	v_pk_fma_f32 v[76:77], v[80:81], v[12:13], v[44:45] op_sel_hi:[0,1,1]
	v_pk_fma_f32 v[78:79], v[80:81], v[14:15], v[46:47] op_sel_hi:[0,1,1]
	v_pk_fma_f32 v[82:83], v[80:81], v[8:9], v[48:49] op_sel_hi:[0,1,1]
	v_pk_fma_f32 v[80:81], v[80:81], v[10:11], v[52:53] op_sel_hi:[0,1,1]
	ds_read2_b32 v[88:89], v27 offset0:192 offset1:200
	ds_read_b128 v[36:39], v22 offset:17152
	ds_read_b128 v[40:43], v22 offset:17168
	ds_read_b128 v[8:11], v22 offset:16896
	ds_read_b128 v[12:15], v22 offset:16912
	ds_read_b128 v[52:55], v22 offset:17664
	ds_read_b128 v[56:59], v22 offset:17680
	ds_read_b128 v[44:47], v22 offset:17408
	ds_read_b128 v[48:51], v22 offset:17424
	ds_read_b128 v[60:63], v22 offset:17920
	ds_read_b128 v[64:67], v22 offset:17936
	v_add_f32_e32 v27, v84, v85
	v_add_f32_e32 v84, v86, v87
	v_add_u32_e32 v26, 0x4c00, v23
	v_add_f32_dpp v27, v27, v27 quad_perm:[1,0,3,2] row_mask:0xf bank_mask:0xf bound_ctrl:1
	v_add_f32_dpp v84, v84, v84 quad_perm:[1,0,3,2] row_mask:0xf bank_mask:0xf bound_ctrl:1
	s_waitcnt lgkmcnt(10)
	v_mov_b32_e32 v90, v89
	v_add_f32_dpp v27, v27, v27 quad_perm:[2,3,0,1] row_mask:0xf bank_mask:0xf bound_ctrl:1
	v_add_f32_dpp v85, v84, v84 quad_perm:[2,3,0,1] row_mask:0xf bank_mask:0xf bound_ctrl:1
	v_add_u32_e32 v25, 0x5000, v23
	v_add_f32_dpp v84, v27, v27 row_half_mirror row_mask:0xf bank_mask:0xf bound_ctrl:1
	v_add_f32_dpp v86, v85, v85 row_half_mirror row_mask:0xf bank_mask:0xf bound_ctrl:1
	v_pk_fma_f32 v[68:69], v[32:33], v[84:85], v[68:69] op_sel_hi:[1,0,1]
	v_pk_fma_f32 v[72:73], v[28:29], v[84:85], v[72:73] op_sel_hi:[1,0,1]
	v_pk_fma_f32 v[32:33], v[32:33], v[86:87], v[76:77] op_sel_hi:[1,0,1]
	v_pk_fma_f32 v[28:29], v[28:29], v[86:87], v[82:83] op_sel_hi:[1,0,1]
	v_pk_fma_f32 v[70:71], v[34:35], v[84:85], v[70:71] op_sel_hi:[1,0,1]
	v_pk_fma_f32 v[74:75], v[30:31], v[84:85], v[74:75] op_sel_hi:[1,0,1]
	v_pk_fma_f32 v[34:35], v[34:35], v[86:87], v[78:79] op_sel_hi:[1,0,1]
	v_pk_fma_f32 v[30:31], v[30:31], v[86:87], v[80:81] op_sel_hi:[1,0,1]
	v_pk_mul_f32 v[76:77], v[4:5], v[68:69]
	v_pk_mul_f32 v[78:79], v[0:1], v[72:73]
	v_pk_mul_f32 v[4:5], v[4:5], v[32:33]
	v_pk_mul_f32 v[0:1], v[0:1], v[28:29]
	s_waitcnt lgkmcnt(7)
	v_pk_mul_f32 v[80:81], v[36:37], v[68:69]
	v_pk_mul_f32 v[82:83], v[40:41], v[72:73]
	v_pk_mul_f32 v[36:37], v[36:37], v[32:33]
	v_pk_mul_f32 v[40:41], v[40:41], v[28:29]
	v_pk_mul_f32 v[68:69], v[8:9], v[68:69]
	v_pk_mul_f32 v[84:85], v[10:11], v[70:71]
	s_waitcnt lgkmcnt(6)
	v_pk_mul_f32 v[72:73], v[12:13], v[72:73]
	v_pk_mul_f32 v[86:87], v[14:15], v[74:75]
	v_pk_mul_f32 v[8:9], v[8:9], v[32:33]
	v_pk_mul_f32 v[10:11], v[10:11], v[34:35]
	v_pk_mul_f32 v[12:13], v[12:13], v[28:29]
	v_pk_mul_f32 v[14:15], v[14:15], v[30:31]
	v_pk_fma_f32 v[28:29], v[6:7], v[70:71], v[76:77]
	v_pk_fma_f32 v[32:33], v[2:3], v[74:75], v[78:79]
	v_pk_fma_f32 v[4:5], v[6:7], v[34:35], v[4:5]
	v_pk_fma_f32 v[0:1], v[2:3], v[30:31], v[0:1]
	v_pk_fma_f32 v[2:3], v[38:39], v[70:71], v[80:81]
	v_pk_fma_f32 v[6:7], v[42:43], v[74:75], v[82:83]
	v_pk_fma_f32 v[34:35], v[38:39], v[34:35], v[36:37]
	v_pk_fma_f32 v[30:31], v[42:43], v[30:31], v[40:41]
	v_pk_add_f32 v[0:1], v[4:5], v[0:1]
	v_pk_add_f32 v[2:3], v[2:3], v[6:7]
	v_pk_add_f32 v[4:5], v[34:35], v[30:31]
	s_waitcnt lgkmcnt(5)
	v_pk_fma_f32 v[42:43], v[52:53], v[90:91], v[8:9] op_sel_hi:[1,0,1]
	v_pk_add_f32 v[8:9], v[28:29], v[32:33]
	v_add_f32_e32 v0, v0, v1
	v_add_f32_e32 v1, v2, v3
	v_add_f32_e32 v2, v4, v5
	v_pk_fma_f32 v[70:71], v[54:55], v[88:89], v[84:85] op_sel_hi:[1,0,1]
	v_add_f32_e32 v6, v8, v9
	v_add_f32_dpp v84, v1, v1 quad_perm:[1,0,3,2] row_mask:0xf bank_mask:0xf bound_ctrl:1
	v_add_f32_dpp v85, v2, v2 quad_perm:[1,0,3,2] row_mask:0xf bank_mask:0xf bound_ctrl:1
	ds_write2st64_b32 v21, v6, v0 offset0:80 offset1:84
	v_add_f32_dpp v84, v84, v84 quad_perm:[2,3,0,1] row_mask:0xf bank_mask:0xf bound_ctrl:1
	v_add_f32_dpp v85, v85, v85 quad_perm:[2,3,0,1] row_mask:0xf bank_mask:0xf bound_ctrl:1
	v_pk_fma_f32 v[68:69], v[52:53], v[88:89], v[68:69] op_sel_hi:[1,0,1]
	s_waitcnt lgkmcnt(5)
	v_pk_fma_f32 v[72:73], v[56:57], v[88:89], v[72:73] op_sel_hi:[1,0,1]
	v_pk_fma_f32 v[74:75], v[58:59], v[88:89], v[86:87] op_sel_hi:[1,0,1]
	v_pk_fma_f32 v[76:77], v[54:55], v[90:91], v[10:11] op_sel_hi:[1,0,1]
	v_pk_fma_f32 v[78:79], v[56:57], v[90:91], v[12:13] op_sel_hi:[1,0,1]
	v_pk_fma_f32 v[80:81], v[58:59], v[90:91], v[14:15] op_sel_hi:[1,0,1]
	ds_read2_b32 v[82:83], v26 offset0:64 offset1:72
	ds_read_b128 v[0:3], v22 offset:19472
	ds_read_b128 v[4:7], v22 offset:19456
	ds_read_b128 v[8:11], v22 offset:19216
	ds_read_b128 v[12:15], v22 offset:19200
	ds_read_b128 v[26:29], v22 offset:18960
	ds_read_b128 v[30:33], v22 offset:18944
	ds_read_b128 v[34:37], v22 offset:18704
	ds_read_b128 v[38:41], v22 offset:18688
	ds_read_b128 v[52:55], v22 offset:18432
	ds_read_b128 v[56:59], v22 offset:18448
	v_add_f32_dpp v84, v84, v84 row_half_mirror row_mask:0xf bank_mask:0xf bound_ctrl:1
	v_add_f32_dpp v86, v85, v85 row_half_mirror row_mask:0xf bank_mask:0xf bound_ctrl:1
	s_waitcnt lgkmcnt(14)
; #define SCAN_STEP(w0, w1, a0, a1, b0, b1, k0, k1, r0, r1, vi, vj, t) do { \
;                 SCAN_ROW(S0, S1, S2, S3, w0, w1, a0, a1, b0, b1, k0, k1, r0, r1, vi, (t) * 512); \
;                 SCAN_ROW(T0, T1, T2, T3, w0, w1, a0, a1, b0, b1, k0, k1, r0, r1, vj, (t) * 512 + 256); } while (0)
;     ...
;             SCAN_LOAD(w0, w1, a0, a1, b0, b1, k0, k1, r0, r1, vi, vj, 0);
; #pragma unroll
;             for (int t = 0; t < 16; t += 2) {
;                 SCAN_LOAD(W0, W1, A0, A1, B0, B1, K0, K1, R0, R1, VI, VJ, t + 1);
;                 SCAN_STEP(w0, w1, a0, a1, b0, b1, k0, k1, r0, r1, vi, vj, t);
;                 if (t + 2 < 16) SCAN_LOAD(w0, w1, a0, a1, b0, b1, k0, k1, r0, r1, vi, vj, t + 2);
;                 SCAN_STEP(W0, W1, A0, A1, B0, B1, K0, K1, R0, R1, VI, VJ, t + 1);
	v_pk_fma_f32 v[68:69], v[44:45], v[84:85], v[68:69] op_sel_hi:[1,0,1]
	v_pk_fma_f32 v[70:71], v[46:47], v[84:85], v[70:71] op_sel_hi:[1,0,1]
	v_pk_fma_f32 v[72:73], v[48:49], v[84:85], v[72:73] op_sel_hi:[1,0,1]
	v_pk_fma_f32 v[42:43], v[44:45], v[86:87], v[42:43] op_sel_hi:[1,0,1]
	v_pk_fma_f32 v[44:45], v[46:47], v[86:87], v[76:77] op_sel_hi:[1,0,1]
	v_pk_fma_f32 v[46:47], v[48:49], v[86:87], v[78:79] op_sel_hi:[1,0,1]
	v_pk_fma_f32 v[74:75], v[50:51], v[84:85], v[74:75] op_sel_hi:[1,0,1]
	v_pk_fma_f32 v[48:49], v[50:51], v[86:87], v[80:81] op_sel_hi:[1,0,1]
	s_waitcnt lgkmcnt(12)
	v_pk_mul_f32 v[50:51], v[60:61], v[68:69]
	v_pk_mul_f32 v[76:77], v[64:65], v[72:73]
	v_pk_mul_f32 v[60:61], v[60:61], v[42:43]
	v_pk_mul_f32 v[64:65], v[64:65], v[46:47]
	v_pk_fma_f32 v[50:51], v[62:63], v[70:71], v[50:51]
	v_pk_fma_f32 v[76:77], v[66:67], v[74:75], v[76:77]
	v_pk_fma_f32 v[60:61], v[62:63], v[44:45], v[60:61]
	v_pk_fma_f32 v[62:63], v[66:67], v[48:49], v[64:65]
	v_pk_add_f32 v[50:51], v[50:51], v[76:77]
	v_pk_add_f32 v[60:61], v[60:61], v[62:63]
	s_waitcnt lgkmcnt(1)
	v_pk_mul_f32 v[62:63], v[38:39], v[68:69]
	v_pk_mul_f32 v[64:65], v[34:35], v[72:73]
	v_pk_mul_f32 v[38:39], v[38:39], v[42:43]
	v_pk_mul_f32 v[34:35], v[34:35], v[46:47]
	v_pk_mul_f32 v[66:67], v[52:53], v[68:69]
	v_pk_mul_f32 v[68:69], v[54:55], v[70:71]
	s_waitcnt lgkmcnt(0)
	v_pk_mul_f32 v[72:73], v[56:57], v[72:73]
	v_pk_mul_f32 v[76:77], v[58:59], v[74:75]
	v_pk_mul_f32 v[42:43], v[52:53], v[42:43]
	v_pk_mul_f32 v[52:53], v[54:55], v[44:45]
	v_pk_mul_f32 v[46:47], v[56:57], v[46:47]
	v_pk_mul_f32 v[54:55], v[58:59], v[48:49]
	v_add_f32_e32 v58, v50, v51
	v_add_f32_e32 v59, v60, v61
	v_pk_fma_f32 v[50:51], v[40:41], v[70:71], v[62:63]
	v_pk_fma_f32 v[56:57], v[36:37], v[74:75], v[64:65]
	v_pk_fma_f32 v[38:39], v[40:41], v[44:45], v[38:39]
	v_pk_fma_f32 v[34:35], v[36:37], v[48:49], v[34:35]
	v_mov_b32_e32 v78, v83
	v_pk_fma_f32 v[66:67], v[82:83], v[12:13], v[66:67] op_sel_hi:[0,1,1]
	v_pk_fma_f32 v[68:69], v[82:83], v[14:15], v[68:69] op_sel_hi:[0,1,1]
	v_pk_fma_f32 v[70:71], v[82:83], v[8:9], v[72:73] op_sel_hi:[0,1,1]
	v_pk_fma_f32 v[72:73], v[82:83], v[10:11], v[76:77] op_sel_hi:[0,1,1]
	ds_write2st64_b32 v21, v58, v59 offset0:88 offset1:92
	v_pk_add_f32 v[82:83], v[56:57], v[50:51]
	v_pk_add_f32 v[84:85], v[34:35], v[38:39]
	v_pk_fma_f32 v[74:75], v[78:79], v[12:13], v[42:43] op_sel_hi:[0,1,1]
	v_pk_fma_f32 v[76:77], v[78:79], v[14:15], v[52:53] op_sel_hi:[0,1,1]
	v_pk_fma_f32 v[80:81], v[78:79], v[8:9], v[46:47] op_sel_hi:[0,1,1]
	v_pk_fma_f32 v[78:79], v[78:79], v[10:11], v[54:55] op_sel_hi:[0,1,1]
	ds_read2_b32 v[86:87], v25 offset0:192 offset1:200
	ds_read_b128 v[34:37], v22 offset:20224
	ds_read_b128 v[38:41], v22 offset:20240
	ds_read_b128 v[8:11], v22 offset:19968
	ds_read_b128 v[12:15], v22 offset:19984
	ds_read_b128 v[50:53], v22 offset:20736
	ds_read_b128 v[54:57], v22 offset:20752
	ds_read_b128 v[42:45], v22 offset:20480
	ds_read_b128 v[46:49], v22 offset:20496
	ds_read_b128 v[58:61], v22 offset:20992
	ds_read_b128 v[62:65], v22 offset:21008
	v_add_f32_e32 v25, v82, v83
	v_add_f32_e32 v82, v84, v85
	v_add_u32_e32 v24, 0x5800, v23
	v_add_f32_dpp v25, v25, v25 quad_perm:[1,0,3,2] row_mask:0xf bank_mask:0xf bound_ctrl:1
	v_add_f32_dpp v82, v82, v82 quad_perm:[1,0,3,2] row_mask:0xf bank_mask:0xf bound_ctrl:1
	s_waitcnt lgkmcnt(10)
	v_mov_b32_e32 v88, v87
	v_add_f32_dpp v25, v25, v25 quad_perm:[2,3,0,1] row_mask:0xf bank_mask:0xf bound_ctrl:1
	v_add_f32_dpp v83, v82, v82 quad_perm:[2,3,0,1] row_mask:0xf bank_mask:0xf bound_ctrl:1
	v_add_u32_e32 v23, 0x5c00, v23
	v_add_f32_dpp v82, v25, v25 row_half_mirror row_mask:0xf bank_mask:0xf bound_ctrl:1
	v_add_f32_dpp v84, v83, v83 row_half_mirror row_mask:0xf bank_mask:0xf bound_ctrl:1
	v_pk_fma_f32 v[66:67], v[30:31], v[82:83], v[66:67] op_sel_hi:[1,0,1]
	v_pk_fma_f32 v[70:71], v[26:27], v[82:83], v[70:71] op_sel_hi:[1,0,1]
	v_pk_fma_f32 v[30:31], v[30:31], v[84:85], v[74:75] op_sel_hi:[1,0,1]
	v_pk_fma_f32 v[26:27], v[26:27], v[84:85], v[80:81] op_sel_hi:[1,0,1]
	v_pk_fma_f32 v[68:69], v[32:33], v[82:83], v[68:69] op_sel_hi:[1,0,1]
	v_pk_fma_f32 v[72:73], v[28:29], v[82:83], v[72:73] op_sel_hi:[1,0,1]
	v_pk_fma_f32 v[32:33], v[32:33], v[84:85], v[76:77] op_sel_hi:[1,0,1]
	v_pk_fma_f32 v[28:29], v[28:29], v[84:85], v[78:79] op_sel_hi:[1,0,1]
	v_pk_mul_f32 v[74:75], v[4:5], v[66:67]
	v_pk_mul_f32 v[76:77], v[0:1], v[70:71]
	v_pk_mul_f32 v[4:5], v[4:5], v[30:31]
	v_pk_mul_f32 v[0:1], v[0:1], v[26:27]
	s_waitcnt lgkmcnt(7)
	v_pk_mul_f32 v[78:79], v[34:35], v[66:67]
	v_pk_mul_f32 v[80:81], v[38:39], v[70:71]
	v_pk_mul_f32 v[34:35], v[34:35], v[30:31]
	v_pk_mul_f32 v[38:39], v[38:39], v[26:27]
	v_pk_mul_f32 v[66:67], v[8:9], v[66:67]
	v_pk_mul_f32 v[82:83], v[10:11], v[68:69]
	s_waitcnt lgkmcnt(6)
	v_pk_mul_f32 v[70:71], v[12:13], v[70:71]
	v_pk_mul_f32 v[84:85], v[14:15], v[72:73]
	v_pk_mul_f32 v[8:9], v[8:9], v[30:31]
	v_pk_mul_f32 v[10:11], v[10:11], v[32:33]
	v_pk_mul_f32 v[12:13], v[12:13], v[26:27]
	v_pk_mul_f32 v[14:15], v[14:15], v[28:29]
	v_pk_fma_f32 v[26:27], v[6:7], v[68:69], v[74:75]
	v_pk_fma_f32 v[30:31], v[2:3], v[72:73], v[76:77]
	v_pk_fma_f32 v[4:5], v[6:7], v[32:33], v[4:5]
	v_pk_fma_f32 v[0:1], v[2:3], v[28:29], v[0:1]
	v_pk_fma_f32 v[2:3], v[36:37], v[68:69], v[78:79]
	v_pk_fma_f32 v[6:7], v[40:41], v[72:73], v[80:81]
	v_pk_fma_f32 v[32:33], v[36:37], v[32:33], v[34:35]
	v_pk_fma_f32 v[28:29], v[40:41], v[28:29], v[38:39]
	v_pk_add_f32 v[0:1], v[4:5], v[0:1]
	v_pk_add_f32 v[2:3], v[2:3], v[6:7]
	v_pk_add_f32 v[4:5], v[32:33], v[28:29]
	s_waitcnt lgkmcnt(5)
; #define SCAN_STEP(w0, w1, a0, a1, b0, b1, k0, k1, r0, r1, vi, vj, t) do { \
;                 SCAN_ROW(S0, S1, S2, S3, w0, w1, a0, a1, b0, b1, k0, k1, r0, r1, vi, (t) * 512); \
;                 SCAN_ROW(T0, T1, T2, T3, w0, w1, a0, a1, b0, b1, k0, k1, r0, r1, vj, (t) * 512 + 256); } while (0)
;     ...
;             SCAN_LOAD(w0, w1, a0, a1, b0, b1, k0, k1, r0, r1, vi, vj, 0);
; #pragma unroll
;             for (int t = 0; t < 16; t += 2) {
;                 SCAN_LOAD(W0, W1, A0, A1, B0, B1, K0, K1, R0, R1, VI, VJ, t + 1);
;                 SCAN_STEP(w0, w1, a0, a1, b0, b1, k0, k1, r0, r1, vi, vj, t);
;                 if (t + 2 < 16) SCAN_LOAD(w0, w1, a0, a1, b0, b1, k0, k1, r0, r1, vi, vj, t + 2);
;                 SCAN_STEP(W0, W1, A0, A1, B0, B1, K0, K1, R0, R1, VI, VJ, t + 1);
	v_pk_fma_f32 v[40:41], v[50:51], v[88:89], v[8:9] op_sel_hi:[1,0,1]
	v_pk_add_f32 v[8:9], v[26:27], v[30:31]
	v_add_f32_e32 v0, v0, v1
	v_add_f32_e32 v1, v2, v3
	v_add_f32_e32 v2, v4, v5
	v_pk_fma_f32 v[68:69], v[52:53], v[86:87], v[82:83] op_sel_hi:[1,0,1]
	v_add_f32_e32 v6, v8, v9
	v_add_f32_dpp v82, v1, v1 quad_perm:[1,0,3,2] row_mask:0xf bank_mask:0xf bound_ctrl:1
	v_add_f32_dpp v83, v2, v2 quad_perm:[1,0,3,2] row_mask:0xf bank_mask:0xf bound_ctrl:1
	ds_write2st64_b32 v21, v6, v0 offset0:96 offset1:100
	v_add_f32_dpp v82, v82, v82 quad_perm:[2,3,0,1] row_mask:0xf bank_mask:0xf bound_ctrl:1
	v_add_f32_dpp v83, v83, v83 quad_perm:[2,3,0,1] row_mask:0xf bank_mask:0xf bound_ctrl:1
	v_pk_fma_f32 v[66:67], v[50:51], v[86:87], v[66:67] op_sel_hi:[1,0,1]
	s_waitcnt lgkmcnt(5)
	v_pk_fma_f32 v[70:71], v[54:55], v[86:87], v[70:71] op_sel_hi:[1,0,1]
	v_pk_fma_f32 v[72:73], v[56:57], v[86:87], v[84:85] op_sel_hi:[1,0,1]
	v_pk_fma_f32 v[74:75], v[52:53], v[88:89], v[10:11] op_sel_hi:[1,0,1]
	v_pk_fma_f32 v[76:77], v[54:55], v[88:89], v[12:13] op_sel_hi:[1,0,1]
	v_pk_fma_f32 v[78:79], v[56:57], v[88:89], v[14:15] op_sel_hi:[1,0,1]
	ds_read2_b32 v[80:81], v24 offset0:64 offset1:72
	ds_read_b128 v[0:3], v22 offset:22544
	ds_read_b128 v[4:7], v22 offset:22528
	ds_read_b128 v[8:11], v22 offset:22288
	ds_read_b128 v[12:15], v22 offset:22272
	ds_read_b128 v[24:27], v22 offset:22032
	ds_read_b128 v[28:31], v22 offset:22016
	ds_read_b128 v[32:35], v22 offset:21776
	ds_read_b128 v[36:39], v22 offset:21760
	ds_read_b128 v[50:53], v22 offset:21504
	ds_read_b128 v[54:57], v22 offset:21520
	v_add_f32_dpp v82, v82, v82 row_half_mirror row_mask:0xf bank_mask:0xf bound_ctrl:1
	v_add_f32_dpp v84, v83, v83 row_half_mirror row_mask:0xf bank_mask:0xf bound_ctrl:1
	s_waitcnt lgkmcnt(14)
	v_pk_fma_f32 v[66:67], v[42:43], v[82:83], v[66:67] op_sel_hi:[1,0,1]
	v_pk_fma_f32 v[68:69], v[44:45], v[82:83], v[68:69] op_sel_hi:[1,0,1]
	v_pk_fma_f32 v[70:71], v[46:47], v[82:83], v[70:71] op_sel_hi:[1,0,1]
	v_pk_fma_f32 v[40:41], v[42:43], v[84:85], v[40:41] op_sel_hi:[1,0,1]
	v_pk_fma_f32 v[42:43], v[44:45], v[84:85], v[74:75] op_sel_hi:[1,0,1]
	v_pk_fma_f32 v[44:45], v[46:47], v[84:85], v[76:77] op_sel_hi:[1,0,1]
	v_pk_fma_f32 v[72:73], v[48:49], v[82:83], v[72:73] op_sel_hi:[1,0,1]
	v_pk_fma_f32 v[46:47], v[48:49], v[84:85], v[78:79] op_sel_hi:[1,0,1]
	s_waitcnt lgkmcnt(12)
	v_pk_mul_f32 v[48:49], v[58:59], v[66:67]
	v_pk_mul_f32 v[74:75], v[62:63], v[70:71]
	v_pk_mul_f32 v[58:59], v[58:59], v[40:41]
	v_pk_mul_f32 v[62:63], v[62:63], v[44:45]
	v_pk_fma_f32 v[48:49], v[60:61], v[68:69], v[48:49]
	v_pk_fma_f32 v[74:75], v[64:65], v[72:73], v[74:75]
	v_pk_fma_f32 v[58:59], v[60:61], v[42:43], v[58:59]
	v_pk_fma_f32 v[60:61], v[64:65], v[46:47], v[62:63]
	v_pk_add_f32 v[48:49], v[48:49], v[74:75]
	v_pk_add_f32 v[58:59], v[58:59], v[60:61]
	s_waitcnt lgkmcnt(1)
	v_pk_mul_f32 v[60:61], v[36:37], v[66:67]
	v_pk_mul_f32 v[62:63], v[32:33], v[70:71]
	v_pk_mul_f32 v[36:37], v[36:37], v[40:41]
	v_pk_mul_f32 v[32:33], v[32:33], v[44:45]
	v_pk_mul_f32 v[64:65], v[50:51], v[66:67]
	v_pk_mul_f32 v[66:67], v[52:53], v[68:69]
	s_waitcnt lgkmcnt(0)
	v_pk_mul_f32 v[70:71], v[54:55], v[70:71]
	v_pk_mul_f32 v[74:75], v[56:57], v[72:73]
	v_pk_mul_f32 v[40:41], v[50:51], v[40:41]
	v_pk_mul_f32 v[50:51], v[52:53], v[42:43]
	v_pk_mul_f32 v[44:45], v[54:55], v[44:45]
	v_pk_mul_f32 v[52:53], v[56:57], v[46:47]
	v_add_f32_e32 v56, v48, v49
	v_pk_fma_f32 v[48:49], v[38:39], v[68:69], v[60:61]
	v_pk_fma_f32 v[54:55], v[34:35], v[72:73], v[62:63]
	v_pk_fma_f32 v[36:37], v[38:39], v[42:43], v[36:37]
	v_pk_fma_f32 v[32:33], v[34:35], v[46:47], v[32:33]
	v_mov_b32_e32 v76, v81
	v_add_f32_e32 v57, v58, v59
	v_pk_fma_f32 v[64:65], v[80:81], v[12:13], v[64:65] op_sel_hi:[0,1,1]
	v_pk_fma_f32 v[66:67], v[80:81], v[14:15], v[66:67] op_sel_hi:[0,1,1]
	v_pk_fma_f32 v[68:69], v[80:81], v[8:9], v[70:71] op_sel_hi:[0,1,1]
	v_pk_fma_f32 v[70:71], v[80:81], v[10:11], v[74:75] op_sel_hi:[0,1,1]
	v_pk_add_f32 v[80:81], v[54:55], v[48:49]
	v_pk_add_f32 v[82:83], v[32:33], v[36:37]
	ds_write2st64_b32 v21, v56, v57 offset0:104 offset1:108
	v_add_f32_e32 v80, v80, v81
	v_add_f32_e32 v81, v82, v83
	v_pk_fma_f32 v[72:73], v[76:77], v[12:13], v[40:41] op_sel_hi:[0,1,1]
	v_pk_fma_f32 v[74:75], v[76:77], v[14:15], v[50:51] op_sel_hi:[0,1,1]
	v_pk_fma_f32 v[78:79], v[76:77], v[8:9], v[44:45] op_sel_hi:[0,1,1]
	v_pk_fma_f32 v[76:77], v[76:77], v[10:11], v[52:53] op_sel_hi:[0,1,1]
	ds_read_b128 v[8:11], v22 offset:23040
	ds_read_b128 v[12:15], v22 offset:23056
	ds_read_b128 v[32:35], v22 offset:23296
	ds_read_b128 v[36:39], v22 offset:23312
	ds_read_b128 v[40:43], v22 offset:23552
	ds_read_b128 v[44:47], v22 offset:23568
	ds_read_b128 v[48:51], v22 offset:23808
	ds_read_b128 v[52:55], v22 offset:23824
	ds_read_b128 v[56:59], v22 offset:24064
	ds_read_b128 v[60:63], v22 offset:24080
	ds_read2_b32 v[22:23], v23 offset0:192 offset1:200
	v_add_f32_dpp v80, v80, v80 quad_perm:[1,0,3,2] row_mask:0xf bank_mask:0xf bound_ctrl:1
	v_add_f32_dpp v81, v81, v81 quad_perm:[1,0,3,2] row_mask:0xf bank_mask:0xf bound_ctrl:1
	s_add_i32 s1, s1, 1
	v_add_f32_dpp v80, v80, v80 quad_perm:[2,3,0,1] row_mask:0xf bank_mask:0xf bound_ctrl:1
	v_add_f32_dpp v81, v81, v81 quad_perm:[2,3,0,1] row_mask:0xf bank_mask:0xf bound_ctrl:1
	s_waitcnt lgkmcnt(0)
; #define SCAN_STEP(w0, w1, a0, a1, b0, b1, k0, k1, r0, r1, vi, vj, t) do { \
;                 SCAN_ROW(S0, S1, S2, S3, w0, w1, a0, a1, b0, b1, k0, k1, r0, r1, vi, (t) * 512); \
;                 SCAN_ROW(T0, T1, T2, T3, w0, w1, a0, a1, b0, b1, k0, k1, r0, r1, vj, (t) * 512 + 256); } while (0)
;     ...
;             SCAN_LOAD(w0, w1, a0, a1, b0, b1, k0, k1, r0, r1, vi, vj, 0);
; #pragma unroll
;             for (int t = 0; t < 16; t += 2) {
;                 SCAN_LOAD(W0, W1, A0, A1, B0, B1, K0, K1, R0, R1, VI, VJ, t + 1);
;                 SCAN_STEP(w0, w1, a0, a1, b0, b1, k0, k1, r0, r1, vi, vj, t);
;                 if (t + 2 < 16) SCAN_LOAD(w0, w1, a0, a1, b0, b1, k0, k1, r0, r1, vi, vj, t + 2);
;                 SCAN_STEP(W0, W1, A0, A1, B0, B1, K0, K1, R0, R1, VI, VJ, t + 1);
;             }
;     ...
;             __syncthreads();
;         }
;         float* so = P.out + (samp ? O_RS + ((size_t)(l * 16 + b) * 16 + h) * 4096 : O_RP + ((size_t)(l * 4 + b) * 16 + h) * 4096) + js;
;         f32x4 o0, o1; o0.xy = S0; o0.zw = S1; o1.xy = S2; o1.zw = S3;
;         *(f32x4*)(so + i0 * 64) = o0; *(f32x4*)(so + i0 * 64 + 4) = o1;
;         o0.xy = T0; o0.zw = T1; o1.xy = T2; o1.zw = T3;
;         *(f32x4*)(so + i1 * 64) = o0; *(f32x4*)(so + i1 * 64 + 4) = o1;
	v_mov_b32_e32 v84, v23
	v_add_f32_dpp v80, v80, v80 row_half_mirror row_mask:0xf bank_mask:0xf bound_ctrl:1
	v_add_f32_dpp v82, v81, v81 row_half_mirror row_mask:0xf bank_mask:0xf bound_ctrl:1
	v_pk_fma_f32 v[64:65], v[28:29], v[80:81], v[64:65] op_sel_hi:[1,0,1]
	v_pk_fma_f32 v[68:69], v[24:25], v[80:81], v[68:69] op_sel_hi:[1,0,1]
	v_pk_fma_f32 v[28:29], v[28:29], v[82:83], v[72:73] op_sel_hi:[1,0,1]
	v_pk_fma_f32 v[24:25], v[24:25], v[82:83], v[78:79] op_sel_hi:[1,0,1]
	v_pk_fma_f32 v[66:67], v[30:31], v[80:81], v[66:67] op_sel_hi:[1,0,1]
	v_pk_fma_f32 v[70:71], v[26:27], v[80:81], v[70:71] op_sel_hi:[1,0,1]
	v_pk_fma_f32 v[30:31], v[30:31], v[82:83], v[74:75] op_sel_hi:[1,0,1]
	v_pk_fma_f32 v[26:27], v[26:27], v[82:83], v[76:77] op_sel_hi:[1,0,1]
	v_pk_mul_f32 v[72:73], v[4:5], v[64:65]
	v_pk_mul_f32 v[74:75], v[0:1], v[68:69]
	v_pk_mul_f32 v[4:5], v[4:5], v[28:29]
	v_pk_mul_f32 v[0:1], v[0:1], v[24:25]
	v_pk_mul_f32 v[76:77], v[32:33], v[64:65]
	v_pk_mul_f32 v[78:79], v[36:37], v[68:69]
	v_pk_mul_f32 v[32:33], v[32:33], v[28:29]
	v_pk_mul_f32 v[36:37], v[36:37], v[24:25]
	v_pk_mul_f32 v[64:65], v[8:9], v[64:65]
	v_pk_mul_f32 v[80:81], v[10:11], v[66:67]
	v_pk_mul_f32 v[68:69], v[12:13], v[68:69]
	v_pk_mul_f32 v[82:83], v[14:15], v[70:71]
	v_pk_mul_f32 v[8:9], v[8:9], v[28:29]
	v_pk_mul_f32 v[10:11], v[10:11], v[30:31]
	v_pk_mul_f32 v[12:13], v[12:13], v[24:25]
	v_pk_mul_f32 v[14:15], v[14:15], v[26:27]
	v_pk_fma_f32 v[24:25], v[6:7], v[66:67], v[72:73]
	v_pk_fma_f32 v[28:29], v[2:3], v[70:71], v[74:75]
	v_pk_fma_f32 v[4:5], v[6:7], v[30:31], v[4:5]
	v_pk_fma_f32 v[0:1], v[2:3], v[26:27], v[0:1]
	v_pk_fma_f32 v[2:3], v[34:35], v[66:67], v[76:77]
	v_pk_fma_f32 v[6:7], v[38:39], v[70:71], v[78:79]
	v_pk_fma_f32 v[30:31], v[34:35], v[30:31], v[32:33]
	v_pk_fma_f32 v[26:27], v[38:39], v[26:27], v[36:37]
	v_pk_fma_f32 v[32:33], v[48:49], v[84:85], v[8:9] op_sel_hi:[1,0,1]
	v_pk_add_f32 v[8:9], v[24:25], v[28:29]
	v_pk_add_f32 v[0:1], v[4:5], v[0:1]
	v_pk_add_f32 v[2:3], v[2:3], v[6:7]
	v_pk_add_f32 v[4:5], v[30:31], v[26:27]
	v_add_f32_e32 v6, v8, v9
	v_add_f32_e32 v0, v0, v1
	v_add_f32_e32 v1, v2, v3
	v_add_f32_e32 v2, v4, v5
	ds_write2st64_b32 v21, v6, v0 offset0:112 offset1:116
	v_add_f32_dpp v0, v1, v1 quad_perm:[1,0,3,2] row_mask:0xf bank_mask:0xf bound_ctrl:1
	v_add_f32_dpp v1, v2, v2 quad_perm:[1,0,3,2] row_mask:0xf bank_mask:0xf bound_ctrl:1
	v_pk_fma_f32 v[64:65], v[48:49], v[22:23], v[64:65] op_sel_hi:[1,0,1]
	v_add_f32_dpp v0, v0, v0 quad_perm:[2,3,0,1] row_mask:0xf bank_mask:0xf bound_ctrl:1
	v_add_f32_dpp v1, v1, v1 quad_perm:[2,3,0,1] row_mask:0xf bank_mask:0xf bound_ctrl:1
	v_pk_fma_f32 v[66:67], v[50:51], v[22:23], v[80:81] op_sel_hi:[1,0,1]
	v_pk_fma_f32 v[68:69], v[52:53], v[22:23], v[68:69] op_sel_hi:[1,0,1]
	v_pk_fma_f32 v[22:23], v[54:55], v[22:23], v[82:83] op_sel_hi:[1,0,1]
	v_pk_fma_f32 v[36:37], v[52:53], v[84:85], v[12:13] op_sel_hi:[1,0,1]
	v_add_f32_dpp v0, v0, v0 row_half_mirror row_mask:0xf bank_mask:0xf bound_ctrl:1
	v_add_f32_dpp v6, v1, v1 row_half_mirror row_mask:0xf bank_mask:0xf bound_ctrl:1
	v_pk_fma_f32 v[34:35], v[50:51], v[84:85], v[10:11] op_sel_hi:[1,0,1]
	v_pk_fma_f32 v[38:39], v[54:55], v[84:85], v[14:15] op_sel_hi:[1,0,1]
	v_pk_fma_f32 v[12:13], v[40:41], v[0:1], v[64:65] op_sel_hi:[1,0,1]
	v_pk_fma_f32 v[14:15], v[42:43], v[0:1], v[66:67] op_sel_hi:[1,0,1]
	v_pk_fma_f32 v[8:9], v[44:45], v[0:1], v[68:69] op_sel_hi:[1,0,1]
	v_pk_fma_f32 v[10:11], v[46:47], v[0:1], v[22:23] op_sel_hi:[1,0,1]
	v_pk_fma_f32 v[0:1], v[40:41], v[6:7], v[32:33] op_sel_hi:[1,0,1]
	v_pk_fma_f32 v[4:5], v[44:45], v[6:7], v[36:37] op_sel_hi:[1,0,1]
	v_pk_fma_f32 v[2:3], v[42:43], v[6:7], v[34:35] op_sel_hi:[1,0,1]
	v_pk_fma_f32 v[6:7], v[46:47], v[6:7], v[38:39] op_sel_hi:[1,0,1]
	v_pk_mul_f32 v[22:23], v[56:57], v[12:13]
	v_pk_mul_f32 v[24:25], v[60:61], v[8:9]
	v_pk_mul_f32 v[26:27], v[56:57], v[0:1]
	v_pk_mul_f32 v[28:29], v[60:61], v[4:5]
	v_pk_fma_f32 v[22:23], v[58:59], v[14:15], v[22:23]
	v_pk_fma_f32 v[24:25], v[62:63], v[10:11], v[24:25]
	v_pk_fma_f32 v[26:27], v[58:59], v[2:3], v[26:27]
	v_pk_fma_f32 v[28:29], v[62:63], v[6:7], v[28:29]
	v_pk_add_f32 v[22:23], v[22:23], v[24:25]
	v_pk_add_f32 v[24:25], v[26:27], v[28:29]
	s_cmpk_eq_i32 s1, 0x100
	v_add_f32_e32 v22, v22, v23
	v_add_f32_e32 v23, v24, v25
	ds_write2st64_b32 v21, v22, v23 offset0:120 offset1:124
	s_waitcnt lgkmcnt(0)
	s_barrier
	s_cbranch_scc0 .LBB0_1812
	s_add_u32 s1, s72, s4
	s_addc_u32 s4, s73, s5
	s_add_u32 s0, s1, s0
	s_addc_u32 s1, s4, 0
	v_lshlrev_b32_e32 v16, 2, v16
	v_mov_b32_e32 v17, 0
	v_lshl_add_u64 v[16:17], s[0:1], 0, v[16:17]
	v_lshl_add_u64 v[16:17], v[18:19], 2, v[16:17]
	s_mov_b64 s[0:1], 0x8500000
	v_lshl_add_u64 v[18:19], v[16:17], 0, s[0:1]
	v_add_co_u32_e32 v16, vcc, 0x8500000, v16
	s_nop 1
	v_addc_co_u32_e32 v17, vcc, 0, v17, vcc
	global_store_dwordx4 v[16:17], v[12:15], off
	global_store_dwordx4 v[18:19], v[8:11], off offset:16
	global_store_dwordx4 v[18:19], v[0:3], off offset:2048
	global_store_dwordx4 v[18:19], v[4:7], off offset:2064

; #define SCAN_STEP(w0, w1, a0, a1, b0, b1, k0, k1, r0, r1, vi, vj, t) do { \
;                 SCAN_ROW(S0, S1, S2, S3, w0, w1, a0, a1, b0, b1, k0, k1, r0, r1, vi, (t) * 512); \
;                 SCAN_ROW(T0, T1, T2, T3, w0, w1, a0, a1, b0, b1, k0, k1, r0, r1, vj, (t) * 512 + 256); } while (0)
;     ...
;         for (int c = c0; c < nch; ++c) {
;             const float* bb = bufs + (c & 1) * (16 * 384) + js;
;             const float* bv = bufs + (c & 1) * (16 * 384) + 320 + i0;
;             float* yb = ybuf + (c & 1) * 8192 + w * 64 + lane;
;             f32x4 w0, w1, a0, a1, b0, b1, k0, k1, r0, r1; float vi, vj;
;             f32x4 W0, W1, A0, A1, B0, B1, K0, K1, R0, R1; float VI, VJ;
;     ...
;             SCAN_LOAD(w0, w1, a0, a1, b0, b1, k0, k1, r0, r1, vi, vj, 0);
; #pragma unroll
;             for (int t = 0; t < 16; t += 2) {
;                 SCAN_LOAD(W0, W1, A0, A1, B0, B1, K0, K1, R0, R1, VI, VJ, t + 1);
;                 SCAN_STEP(w0, w1, a0, a1, b0, b1, k0, k1, r0, r1, vi, vj, t);
;                 if (t + 2 < 16) SCAN_LOAD(w0, w1, a0, a1, b0, b1, k0, k1, r0, r1, vi, vj, t + 2);
;                 SCAN_STEP(W0, W1, A0, A1, B0, B1, K0, K1, R0, R1, VI, VJ, t + 1);
.LBB0_3706:
	s_and_b32 s10, s3, 1
	s_mul_i32 s4, s10, 0x6000
	s_add_i32 s4, s4, 0
	v_lshl_add_u32 v21, v16, 2, s4
	v_lshl_add_u32 v20, v17, 2, s4
	v_add_u32_e32 v29, 0x400, v21
	v_add_u32_e32 v112, 0x800, v21
	ds_read_b128 v[38:41], v20 offset:256
	ds_read_b128 v[42:45], v20 offset:272
	ds_read_b128 v[54:57], v20 offset:768
	ds_read2_b32 v[110:111], v29 offset0:64 offset1:72
	ds_read_b128 v[58:61], v20 offset:784
	ds_read_b128 v[30:33], v20
	ds_read_b128 v[34:37], v20 offset:16
	ds_read_b128 v[46:49], v20 offset:512
	ds_read_b128 v[50:53], v20 offset:528
	ds_read_b128 v[62:65], v20 offset:1024
	ds_read_b128 v[66:69], v20 offset:1040
	ds_read_b128 v[78:81], v20 offset:1792
	ds_read_b128 v[82:85], v20 offset:1808
	ds_read2_b32 v[112:113], v112 offset0:192 offset1:200
	s_waitcnt vmcnt(3)
	ds_read_b128 v[70:73], v20 offset:1536
	ds_read_b128 v[74:77], v20 offset:1552
	s_waitcnt vmcnt(2)
	ds_read_b128 v[94:97], v20 offset:2304
	ds_read_b128 v[98:101], v20 offset:2320
	ds_read_b128 v[86:89], v20 offset:2048
	ds_read_b128 v[90:93], v20 offset:2064
	ds_read_b128 v[102:105], v20 offset:2560
	ds_read_b128 v[106:109], v20 offset:2576
	s_waitcnt lgkmcnt(14)
	v_pk_mul_f32 v[114:115], v[8:9], v[38:39]
	v_pk_mul_f32 v[116:117], v[12:13], v[42:43]
	v_pk_mul_f32 v[38:39], v[4:5], v[38:39]
	v_pk_mul_f32 v[42:43], v[0:1], v[42:43]
	v_pk_fma_f32 v[114:115], v[10:11], v[40:41], v[114:115]
	v_pk_fma_f32 v[116:117], v[14:15], v[44:45], v[116:117]
	v_pk_mul_f32 v[118:119], v[54:55], v[110:111] op_sel_hi:[1,0]
	v_pk_mul_f32 v[120:121], v[56:57], v[110:111] op_sel_hi:[1,0]
	v_pk_mul_f32 v[122:123], v[58:59], v[110:111] op_sel_hi:[1,0]
	v_pk_mul_f32 v[124:125], v[60:61], v[110:111] op_sel_hi:[1,0]
	v_mov_b32_e32 v110, v111
	v_pk_fma_f32 v[38:39], v[6:7], v[40:41], v[38:39]
	v_pk_fma_f32 v[40:41], v[2:3], v[44:45], v[42:43]
	v_pk_add_f32 v[44:45], v[114:115], v[116:117]
	v_pk_mul_f32 v[54:55], v[54:55], v[110:111] op_sel_hi:[1,0]
	v_pk_add_f32 v[38:39], v[38:39], v[40:41]
	v_pk_fma_f32 v[8:9], v[8:9], v[30:31], v[118:119]
	v_add_f32_e32 v29, v44, v45
	v_pk_fma_f32 v[4:5], v[4:5], v[30:31], v[54:55]
	v_add_f32_e32 v30, v38, v39
	v_add_f32_dpp v29, v29, v29 quad_perm:[1,0,3,2] row_mask:0xf bank_mask:0xf bound_ctrl:1
	v_pk_mul_f32 v[56:57], v[56:57], v[110:111] op_sel_hi:[1,0]
	v_add_f32_dpp v30, v30, v30 quad_perm:[1,0,3,2] row_mask:0xf bank_mask:0xf bound_ctrl:1
	v_pk_mul_f32 v[58:59], v[58:59], v[110:111] op_sel_hi:[1,0]
	v_add_f32_dpp v29, v29, v29 quad_perm:[2,3,0,1] row_mask:0xf bank_mask:0xf bound_ctrl:1
	v_add_f32_dpp v31, v30, v30 quad_perm:[2,3,0,1] row_mask:0xf bank_mask:0xf bound_ctrl:1
	v_pk_fma_f32 v[10:11], v[10:11], v[32:33], v[120:121]
	v_pk_fma_f32 v[12:13], v[12:13], v[34:35], v[122:123]
	v_pk_mul_f32 v[60:61], v[60:61], v[110:111] op_sel_hi:[1,0]
	v_pk_fma_f32 v[6:7], v[6:7], v[32:33], v[56:57]
	v_pk_fma_f32 v[0:1], v[0:1], v[34:35], v[58:59]
	v_add_f32_dpp v30, v29, v29 row_half_mirror row_mask:0xf bank_mask:0xf bound_ctrl:1
	v_add_f32_dpp v32, v31, v31 row_half_mirror row_mask:0xf bank_mask:0xf bound_ctrl:1
	v_pk_fma_f32 v[14:15], v[14:15], v[36:37], v[124:125]
	v_pk_fma_f32 v[2:3], v[2:3], v[36:37], v[60:61]
	v_pk_fma_f32 v[8:9], v[46:47], v[30:31], v[8:9] op_sel_hi:[1,0,1]
	s_waitcnt lgkmcnt(13)
	v_pk_fma_f32 v[12:13], v[50:51], v[30:31], v[12:13] op_sel_hi:[1,0,1]
	v_pk_fma_f32 v[4:5], v[46:47], v[32:33], v[4:5] op_sel_hi:[1,0,1]
	v_pk_fma_f32 v[0:1], v[50:51], v[32:33], v[0:1] op_sel_hi:[1,0,1]
	v_pk_fma_f32 v[10:11], v[48:49], v[30:31], v[10:11] op_sel_hi:[1,0,1]
	v_pk_fma_f32 v[14:15], v[52:53], v[30:31], v[14:15] op_sel_hi:[1,0,1]
	v_pk_fma_f32 v[6:7], v[48:49], v[32:33], v[6:7] op_sel_hi:[1,0,1]
	v_pk_fma_f32 v[2:3], v[52:53], v[32:33], v[2:3] op_sel_hi:[1,0,1]
	s_waitcnt lgkmcnt(10)
	v_pk_mul_f32 v[30:31], v[62:63], v[8:9]
	v_pk_mul_f32 v[32:33], v[66:67], v[12:13]
	v_pk_mul_f32 v[34:35], v[62:63], v[4:5]
	v_pk_mul_f32 v[36:37], v[66:67], v[0:1]
	v_pk_mul_f32 v[38:39], v[78:79], v[8:9]
	s_waitcnt lgkmcnt(7)
	v_pk_mul_f32 v[40:41], v[82:83], v[12:13]
	v_pk_mul_f32 v[48:49], v[78:79], v[4:5]
	v_pk_mul_f32 v[50:51], v[82:83], v[0:1]
	v_mov_b32_e32 v42, v113
	v_pk_mul_f32 v[8:9], v[70:71], v[8:9]
	v_pk_mul_f32 v[44:45], v[72:73], v[10:11]
	s_waitcnt lgkmcnt(6)
	v_pk_mul_f32 v[46:47], v[76:77], v[14:15]
	v_pk_mul_f32 v[4:5], v[70:71], v[4:5]
	v_pk_mul_f32 v[52:53], v[72:73], v[6:7]
	v_pk_mul_f32 v[0:1], v[74:75], v[0:1]
	v_pk_mul_f32 v[54:55], v[76:77], v[2:3]
	v_pk_fma_f32 v[30:31], v[64:65], v[10:11], v[30:31]
	v_pk_fma_f32 v[32:33], v[68:69], v[14:15], v[32:33]
	v_pk_fma_f32 v[34:35], v[64:65], v[6:7], v[34:35]
	v_pk_fma_f32 v[36:37], v[68:69], v[2:3], v[36:37]
	v_pk_fma_f32 v[10:11], v[80:81], v[10:11], v[38:39]
	v_pk_fma_f32 v[14:15], v[84:85], v[14:15], v[40:41]
	v_pk_fma_f32 v[6:7], v[80:81], v[6:7], v[48:49]
	v_pk_fma_f32 v[2:3], v[84:85], v[2:3], v[50:51]
	s_waitcnt lgkmcnt(4)
; #define SCAN_STEP(w0, w1, a0, a1, b0, b1, k0, k1, r0, r1, vi, vj, t) do { \
;                 SCAN_ROW(S0, S1, S2, S3, w0, w1, a0, a1, b0, b1, k0, k1, r0, r1, vi, (t) * 512); \
;                 SCAN_ROW(T0, T1, T2, T3, w0, w1, a0, a1, b0, b1, k0, k1, r0, r1, vj, (t) * 512 + 256); } while (0)
;     ...
;             SCAN_LOAD(w0, w1, a0, a1, b0, b1, k0, k1, r0, r1, vi, vj, 0);
; #pragma unroll
;             for (int t = 0; t < 16; t += 2) {
;                 SCAN_LOAD(W0, W1, A0, A1, B0, B1, K0, K1, R0, R1, VI, VJ, t + 1);
;                 SCAN_STEP(w0, w1, a0, a1, b0, b1, k0, k1, r0, r1, vi, vj, t);
;                 if (t + 2 < 16) SCAN_LOAD(w0, w1, a0, a1, b0, b1, k0, k1, r0, r1, vi, vj, t + 2);
;                 SCAN_STEP(W0, W1, A0, A1, B0, B1, K0, K1, R0, R1, VI, VJ, t + 1);
	v_pk_fma_f32 v[56:57], v[94:95], v[112:113], v[8:9] op_sel_hi:[1,0,1]
	v_pk_fma_f32 v[64:65], v[94:95], v[42:43], v[4:5] op_sel_hi:[1,0,1]
	v_pk_fma_f32 v[68:69], v[98:99], v[42:43], v[0:1] op_sel_hi:[1,0,1]
	v_pk_add_f32 v[0:1], v[30:31], v[32:33]
	v_pk_add_f32 v[4:5], v[34:35], v[36:37]
	v_pk_add_f32 v[8:9], v[10:11], v[14:15]
	v_pk_add_f32 v[2:3], v[6:7], v[2:3]
	v_add_f32_e32 v0, v0, v1
	v_add_f32_e32 v1, v4, v5
	v_add_f32_e32 v4, v8, v9
	v_add_f32_e32 v2, v2, v3
	v_lshl_add_u32 v27, s10, 15, v18
	v_add_f32_dpp v29, v4, v4 quad_perm:[1,0,3,2] row_mask:0xf bank_mask:0xf bound_ctrl:1
	v_add_f32_dpp v72, v2, v2 quad_perm:[1,0,3,2] row_mask:0xf bank_mask:0xf bound_ctrl:1
	v_add_u32_e32 v126, 0x1000, v21
	v_pk_mul_f32 v[12:13], v[74:75], v[12:13]
	ds_write2st64_b32 v27, v0, v1 offset0:192 offset1:196
	v_add_f32_dpp v29, v29, v29 quad_perm:[2,3,0,1] row_mask:0xf bank_mask:0xf bound_ctrl:1
	v_add_f32_dpp v73, v72, v72 quad_perm:[2,3,0,1] row_mask:0xf bank_mask:0xf bound_ctrl:1
	v_pk_fma_f32 v[58:59], v[96:97], v[112:113], v[44:45] op_sel_hi:[1,0,1]
	v_pk_fma_f32 v[60:61], v[98:99], v[112:113], v[12:13] op_sel_hi:[1,0,1]
	v_pk_fma_f32 v[62:63], v[100:101], v[112:113], v[46:47] op_sel_hi:[1,0,1]
	v_pk_fma_f32 v[66:67], v[96:97], v[42:43], v[52:53] op_sel_hi:[1,0,1]
	v_pk_fma_f32 v[54:55], v[100:101], v[42:43], v[54:55] op_sel_hi:[1,0,1]
	ds_read_b128 v[42:45], v20 offset:3328
	ds_read_b128 v[38:41], v20 offset:3344
	ds_read_b128 v[46:49], v20 offset:3072
	ds_read_b128 v[50:53], v20 offset:3088
	ds_read2_b32 v[70:71], v126 offset0:64 offset1:72
	ds_read_b128 v[12:15], v20 offset:3840
	ds_read_b128 v[8:11], v20 offset:3856
	ds_read_b128 v[34:37], v20 offset:3584
	ds_read_b128 v[30:33], v20 offset:3600
	ds_read_b128 v[4:7], v20 offset:4096
	ds_read_b128 v[0:3], v20 offset:4112
	v_add_f32_dpp v72, v29, v29 row_half_mirror row_mask:0xf bank_mask:0xf bound_ctrl:1
	v_add_f32_dpp v74, v73, v73 row_half_mirror row_mask:0xf bank_mask:0xf bound_ctrl:1
	s_waitcnt lgkmcnt(14)
	v_pk_fma_f32 v[56:57], v[86:87], v[72:73], v[56:57] op_sel_hi:[1,0,1]
	v_pk_fma_f32 v[60:61], v[90:91], v[72:73], v[60:61] op_sel_hi:[1,0,1]
	v_pk_fma_f32 v[64:65], v[86:87], v[74:75], v[64:65] op_sel_hi:[1,0,1]
	v_pk_fma_f32 v[68:69], v[90:91], v[74:75], v[68:69] op_sel_hi:[1,0,1]
	v_pk_fma_f32 v[58:59], v[88:89], v[72:73], v[58:59] op_sel_hi:[1,0,1]
	v_pk_fma_f32 v[62:63], v[92:93], v[72:73], v[62:63] op_sel_hi:[1,0,1]
	v_pk_fma_f32 v[66:67], v[88:89], v[74:75], v[66:67] op_sel_hi:[1,0,1]
	v_pk_fma_f32 v[54:55], v[92:93], v[74:75], v[54:55] op_sel_hi:[1,0,1]
	s_waitcnt lgkmcnt(12)
	v_pk_mul_f32 v[72:73], v[102:103], v[56:57]
	v_pk_mul_f32 v[74:75], v[106:107], v[60:61]
	v_pk_mul_f32 v[76:77], v[102:103], v[64:65]
	v_pk_mul_f32 v[78:79], v[106:107], v[68:69]
	v_pk_fma_f32 v[72:73], v[104:105], v[58:59], v[72:73]
	v_pk_fma_f32 v[74:75], v[108:109], v[62:63], v[74:75]
	v_pk_fma_f32 v[76:77], v[104:105], v[66:67], v[76:77]
	v_pk_fma_f32 v[78:79], v[108:109], v[54:55], v[78:79]
	v_pk_add_f32 v[72:73], v[72:73], v[74:75]
	v_pk_add_f32 v[74:75], v[76:77], v[78:79]
	s_waitcnt lgkmcnt(8)
	v_pk_mul_f32 v[76:77], v[42:43], v[56:57]
	v_pk_mul_f32 v[78:79], v[38:39], v[60:61]
	v_pk_mul_f32 v[42:43], v[42:43], v[64:65]
	v_pk_mul_f32 v[38:39], v[38:39], v[68:69]
	v_pk_mul_f32 v[80:81], v[48:49], v[58:59]
	s_waitcnt lgkmcnt(7)
	v_pk_mul_f32 v[82:83], v[52:53], v[62:63]
	v_pk_fma_f32 v[58:59], v[44:45], v[58:59], v[76:77]
	v_pk_fma_f32 v[62:63], v[40:41], v[62:63], v[78:79]
	v_pk_fma_f32 v[42:43], v[44:45], v[66:67], v[42:43]
	v_pk_fma_f32 v[38:39], v[40:41], v[54:55], v[38:39]
	v_pk_mul_f32 v[56:57], v[46:47], v[56:57]
	v_pk_mul_f32 v[46:47], v[46:47], v[64:65]
	v_add_f32_e32 v29, v72, v73
	v_add_f32_e32 v64, v74, v75
	v_pk_add_f32 v[86:87], v[62:63], v[58:59]
	v_pk_add_f32 v[88:89], v[38:39], v[42:43]
	ds_write2st64_b32 v27, v29, v64 offset0:200 offset1:204
	v_add_f32_e32 v29, v86, v87
	v_add_f32_e32 v86, v88, v89
	v_pk_mul_f32 v[60:61], v[50:51], v[60:61]
	s_waitcnt lgkmcnt(7)
	v_mov_b32_e32 v84, v71
	v_pk_mul_f32 v[48:49], v[48:49], v[66:67]
	v_pk_mul_f32 v[50:51], v[50:51], v[68:69]
	v_pk_mul_f32 v[52:53], v[52:53], v[54:55]
	v_add_f32_dpp v29, v29, v29 quad_perm:[1,0,3,2] row_mask:0xf bank_mask:0xf bound_ctrl:1
	v_add_f32_dpp v86, v86, v86 quad_perm:[1,0,3,2] row_mask:0xf bank_mask:0xf bound_ctrl:1
	v_add_u32_e32 v127, 0x1400, v21
	s_waitcnt lgkmcnt(5)
	v_pk_fma_f32 v[72:73], v[70:71], v[12:13], v[56:57] op_sel_hi:[0,1,1]
	v_pk_fma_f32 v[74:75], v[70:71], v[14:15], v[80:81] op_sel_hi:[0,1,1]
	v_pk_fma_f32 v[76:77], v[70:71], v[8:9], v[60:61] op_sel_hi:[0,1,1]
	v_pk_fma_f32 v[70:71], v[70:71], v[10:11], v[82:83] op_sel_hi:[0,1,1]
	v_pk_fma_f32 v[78:79], v[84:85], v[12:13], v[46:47] op_sel_hi:[0,1,1]
	v_pk_fma_f32 v[80:81], v[84:85], v[14:15], v[48:49] op_sel_hi:[0,1,1]
	v_pk_fma_f32 v[82:83], v[84:85], v[8:9], v[50:51] op_sel_hi:[0,1,1]
	v_pk_fma_f32 v[84:85], v[84:85], v[10:11], v[52:53] op_sel_hi:[0,1,1]
	ds_read_b128 v[38:41], v20 offset:4864
	ds_read_b128 v[42:45], v20 offset:4880
	ds_read_b128 v[8:11], v20 offset:4608
	ds_read_b128 v[12:15], v20 offset:4624
	ds_read2_b32 v[90:91], v127 offset0:192 offset1:200
	ds_read_b128 v[54:57], v20 offset:5376
	ds_read_b128 v[58:61], v20 offset:5392
	ds_read_b128 v[46:49], v20 offset:5120
	ds_read_b128 v[50:53], v20 offset:5136
	ds_read_b128 v[62:65], v20 offset:5632
	ds_read_b128 v[66:69], v20 offset:5648
	v_add_f32_dpp v29, v29, v29 quad_perm:[2,3,0,1] row_mask:0xf bank_mask:0xf bound_ctrl:1
	v_add_f32_dpp v87, v86, v86 quad_perm:[2,3,0,1] row_mask:0xf bank_mask:0xf bound_ctrl:1
	v_add_u32_e32 v128, 0x1c00, v21
	v_add_f32_dpp v86, v29, v29 row_half_mirror row_mask:0xf bank_mask:0xf bound_ctrl:1
	v_add_f32_dpp v88, v87, v87 row_half_mirror row_mask:0xf bank_mask:0xf bound_ctrl:1
	s_waitcnt lgkmcnt(14)
; #define SCAN_STEP(w0, w1, a0, a1, b0, b1, k0, k1, r0, r1, vi, vj, t) do { \
;                 SCAN_ROW(S0, S1, S2, S3, w0, w1, a0, a1, b0, b1, k0, k1, r0, r1, vi, (t) * 512); \
;                 SCAN_ROW(T0, T1, T2, T3, w0, w1, a0, a1, b0, b1, k0, k1, r0, r1, vj, (t) * 512 + 256); } while (0)
;     ...
;             SCAN_LOAD(w0, w1, a0, a1, b0, b1, k0, k1, r0, r1, vi, vj, 0);
; #pragma unroll
;             for (int t = 0; t < 16; t += 2) {
;                 SCAN_LOAD(W0, W1, A0, A1, B0, B1, K0, K1, R0, R1, VI, VJ, t + 1);
;                 SCAN_STEP(w0, w1, a0, a1, b0, b1, k0, k1, r0, r1, vi, vj, t);
;                 if (t + 2 < 16) SCAN_LOAD(w0, w1, a0, a1, b0, b1, k0, k1, r0, r1, vi, vj, t + 2);
;                 SCAN_STEP(W0, W1, A0, A1, B0, B1, K0, K1, R0, R1, VI, VJ, t + 1);
	v_pk_fma_f32 v[72:73], v[34:35], v[86:87], v[72:73] op_sel_hi:[1,0,1]
	v_pk_fma_f32 v[76:77], v[30:31], v[86:87], v[76:77] op_sel_hi:[1,0,1]
	v_pk_fma_f32 v[34:35], v[34:35], v[88:89], v[78:79] op_sel_hi:[1,0,1]
	v_pk_fma_f32 v[30:31], v[30:31], v[88:89], v[82:83] op_sel_hi:[1,0,1]
	v_pk_fma_f32 v[74:75], v[36:37], v[86:87], v[74:75] op_sel_hi:[1,0,1]
	v_pk_fma_f32 v[70:71], v[32:33], v[86:87], v[70:71] op_sel_hi:[1,0,1]
	v_pk_fma_f32 v[36:37], v[36:37], v[88:89], v[80:81] op_sel_hi:[1,0,1]
	v_pk_fma_f32 v[32:33], v[32:33], v[88:89], v[84:85] op_sel_hi:[1,0,1]
	s_waitcnt lgkmcnt(12)
	v_pk_mul_f32 v[78:79], v[4:5], v[72:73]
	v_pk_mul_f32 v[80:81], v[0:1], v[76:77]
	v_pk_mul_f32 v[4:5], v[4:5], v[34:35]
	v_pk_mul_f32 v[0:1], v[0:1], v[30:31]
	s_waitcnt lgkmcnt(8)
	v_pk_mul_f32 v[82:83], v[38:39], v[72:73]
	v_pk_mul_f32 v[84:85], v[42:43], v[76:77]
	v_pk_mul_f32 v[38:39], v[38:39], v[34:35]
	v_pk_mul_f32 v[42:43], v[42:43], v[30:31]
	v_pk_mul_f32 v[72:73], v[8:9], v[72:73]
	v_pk_mul_f32 v[86:87], v[10:11], v[74:75]
	s_waitcnt lgkmcnt(7)
	v_pk_mul_f32 v[76:77], v[12:13], v[76:77]
	v_pk_mul_f32 v[88:89], v[14:15], v[70:71]
	v_pk_mul_f32 v[8:9], v[8:9], v[34:35]
	v_pk_mul_f32 v[10:11], v[10:11], v[36:37]
	v_pk_mul_f32 v[12:13], v[12:13], v[30:31]
	v_pk_mul_f32 v[14:15], v[14:15], v[32:33]
	v_pk_fma_f32 v[30:31], v[6:7], v[74:75], v[78:79]
	v_pk_fma_f32 v[34:35], v[2:3], v[70:71], v[80:81]
	v_pk_fma_f32 v[4:5], v[6:7], v[36:37], v[4:5]
	v_pk_fma_f32 v[0:1], v[2:3], v[32:33], v[0:1]
	v_pk_fma_f32 v[2:3], v[40:41], v[74:75], v[82:83]
	v_pk_fma_f32 v[6:7], v[44:45], v[70:71], v[84:85]
	v_pk_fma_f32 v[36:37], v[40:41], v[36:37], v[38:39]
	v_pk_fma_f32 v[32:33], v[44:45], v[32:33], v[42:43]
	s_waitcnt lgkmcnt(5)
	v_mov_b32_e32 v92, v91
	v_pk_add_f32 v[0:1], v[4:5], v[0:1]
	v_pk_add_f32 v[2:3], v[2:3], v[6:7]
	v_pk_add_f32 v[4:5], v[36:37], v[32:33]
	v_pk_fma_f32 v[78:79], v[54:55], v[92:93], v[8:9] op_sel_hi:[1,0,1]
	v_pk_add_f32 v[8:9], v[30:31], v[34:35]
	v_add_f32_e32 v0, v0, v1
	v_add_f32_e32 v1, v2, v3
	v_add_f32_e32 v2, v4, v5
	s_waitcnt lgkmcnt(4)
	v_pk_fma_f32 v[74:75], v[58:59], v[90:91], v[76:77] op_sel_hi:[1,0,1]
	v_pk_fma_f32 v[76:77], v[60:61], v[90:91], v[88:89] op_sel_hi:[1,0,1]
	v_add_f32_e32 v6, v8, v9
	v_add_f32_dpp v29, v1, v1 quad_perm:[1,0,3,2] row_mask:0xf bank_mask:0xf bound_ctrl:1
	v_add_f32_dpp v88, v2, v2 quad_perm:[1,0,3,2] row_mask:0xf bank_mask:0xf bound_ctrl:1
	ds_write2st64_b32 v27, v6, v0 offset0:208 offset1:212
	v_add_f32_dpp v29, v29, v29 quad_perm:[2,3,0,1] row_mask:0xf bank_mask:0xf bound_ctrl:1
	v_add_f32_dpp v89, v88, v88 quad_perm:[2,3,0,1] row_mask:0xf bank_mask:0xf bound_ctrl:1
	v_pk_fma_f32 v[70:71], v[54:55], v[90:91], v[72:73] op_sel_hi:[1,0,1]
	v_pk_fma_f32 v[72:73], v[56:57], v[90:91], v[86:87] op_sel_hi:[1,0,1]
	v_pk_fma_f32 v[80:81], v[56:57], v[92:93], v[10:11] op_sel_hi:[1,0,1]
	v_pk_fma_f32 v[82:83], v[58:59], v[92:93], v[12:13] op_sel_hi:[1,0,1]
	v_pk_fma_f32 v[84:85], v[60:61], v[92:93], v[14:15] op_sel_hi:[1,0,1]
	ds_read_b128 v[42:45], v20 offset:6400
	ds_read_b128 v[38:41], v20 offset:6416
	ds_read_b128 v[54:57], v20 offset:6144
	ds_read_b128 v[58:61], v20 offset:6160
	ds_read2_b32 v[86:87], v128 offset0:64 offset1:72
	ds_read_b128 v[12:15], v20 offset:6912
	ds_read_b128 v[8:11], v20 offset:6928
	ds_read_b128 v[34:37], v20 offset:6656
	ds_read_b128 v[30:33], v20 offset:6672
	ds_read_b128 v[4:7], v20 offset:7168
	ds_read_b128 v[0:3], v20 offset:7184
	v_add_f32_dpp v88, v29, v29 row_half_mirror row_mask:0xf bank_mask:0xf bound_ctrl:1
	v_add_f32_dpp v90, v89, v89 row_half_mirror row_mask:0xf bank_mask:0xf bound_ctrl:1
	s_waitcnt lgkmcnt(14)
	v_pk_fma_f32 v[70:71], v[46:47], v[88:89], v[70:71] op_sel_hi:[1,0,1]
	v_pk_fma_f32 v[74:75], v[50:51], v[88:89], v[74:75] op_sel_hi:[1,0,1]
	v_pk_fma_f32 v[46:47], v[46:47], v[90:91], v[78:79] op_sel_hi:[1,0,1]
	v_pk_fma_f32 v[50:51], v[50:51], v[90:91], v[82:83] op_sel_hi:[1,0,1]
	v_pk_fma_f32 v[72:73], v[48:49], v[88:89], v[72:73] op_sel_hi:[1,0,1]
	v_pk_fma_f32 v[76:77], v[52:53], v[88:89], v[76:77] op_sel_hi:[1,0,1]
	v_pk_fma_f32 v[48:49], v[48:49], v[90:91], v[80:81] op_sel_hi:[1,0,1]
	v_pk_fma_f32 v[52:53], v[52:53], v[90:91], v[84:85] op_sel_hi:[1,0,1]
	s_waitcnt lgkmcnt(12)
	v_pk_mul_f32 v[78:79], v[62:63], v[70:71]
	v_pk_mul_f32 v[80:81], v[66:67], v[74:75]
	v_pk_mul_f32 v[62:63], v[62:63], v[46:47]
	v_pk_mul_f32 v[66:67], v[66:67], v[50:51]
	v_pk_fma_f32 v[78:79], v[64:65], v[72:73], v[78:79]
	v_pk_fma_f32 v[62:63], v[64:65], v[48:49], v[62:63]
	v_pk_fma_f32 v[64:65], v[68:69], v[52:53], v[66:67]
	v_pk_fma_f32 v[80:81], v[68:69], v[76:77], v[80:81]
	v_pk_add_f32 v[62:63], v[62:63], v[64:65]
	s_waitcnt lgkmcnt(9)
	v_pk_mul_f32 v[64:65], v[42:43], v[70:71]
	v_pk_mul_f32 v[68:69], v[38:39], v[74:75]
	v_pk_mul_f32 v[42:43], v[42:43], v[46:47]
	v_pk_mul_f32 v[38:39], v[38:39], v[50:51]
	v_pk_add_f32 v[66:67], v[78:79], v[80:81]
	s_waitcnt lgkmcnt(7)
	v_pk_mul_f32 v[70:71], v[54:55], v[70:71]
	v_pk_mul_f32 v[78:79], v[56:57], v[72:73]
	v_pk_mul_f32 v[74:75], v[58:59], v[74:75]
	v_pk_mul_f32 v[80:81], v[60:61], v[76:77]
	v_pk_mul_f32 v[46:47], v[54:55], v[46:47]
	v_pk_mul_f32 v[54:55], v[56:57], v[48:49]
	v_pk_mul_f32 v[50:51], v[58:59], v[50:51]
	v_pk_mul_f32 v[56:57], v[60:61], v[52:53]
	v_pk_fma_f32 v[58:59], v[44:45], v[72:73], v[64:65]
	v_pk_fma_f32 v[60:61], v[40:41], v[76:77], v[68:69]
	v_pk_fma_f32 v[42:43], v[44:45], v[48:49], v[42:43]
	v_pk_fma_f32 v[38:39], v[40:41], v[52:53], v[38:39]
	s_waitcnt lgkmcnt(5)
	v_mov_b32_e32 v82, v87
	v_add_f32_e32 v29, v66, v67
	v_add_f32_e32 v62, v62, v63
	v_pk_fma_f32 v[70:71], v[86:87], v[12:13], v[70:71] op_sel_hi:[0,1,1]
	v_pk_fma_f32 v[72:73], v[86:87], v[14:15], v[78:79] op_sel_hi:[0,1,1]
	s_waitcnt lgkmcnt(4)
; #define SCAN_STEP(w0, w1, a0, a1, b0, b1, k0, k1, r0, r1, vi, vj, t) do { \
;                 SCAN_ROW(S0, S1, S2, S3, w0, w1, a0, a1, b0, b1, k0, k1, r0, r1, vi, (t) * 512); \
;                 SCAN_ROW(T0, T1, T2, T3, w0, w1, a0, a1, b0, b1, k0, k1, r0, r1, vj, (t) * 512 + 256); } while (0)
;     ...
;             SCAN_LOAD(w0, w1, a0, a1, b0, b1, k0, k1, r0, r1, vi, vj, 0);
; #pragma unroll
;             for (int t = 0; t < 16; t += 2) {
;                 SCAN_LOAD(W0, W1, A0, A1, B0, B1, K0, K1, R0, R1, VI, VJ, t + 1);
;                 SCAN_STEP(w0, w1, a0, a1, b0, b1, k0, k1, r0, r1, vi, vj, t);
;                 if (t + 2 < 16) SCAN_LOAD(w0, w1, a0, a1, b0, b1, k0, k1, r0, r1, vi, vj, t + 2);
;                 SCAN_STEP(W0, W1, A0, A1, B0, B1, K0, K1, R0, R1, VI, VJ, t + 1);
	v_pk_fma_f32 v[74:75], v[86:87], v[8:9], v[74:75] op_sel_hi:[0,1,1]
	v_pk_fma_f32 v[76:77], v[86:87], v[10:11], v[80:81] op_sel_hi:[0,1,1]
	v_pk_add_f32 v[86:87], v[60:61], v[58:59]
	v_pk_add_f32 v[88:89], v[38:39], v[42:43]
	ds_write2st64_b32 v27, v29, v62 offset0:216 offset1:220
	v_add_f32_e32 v29, v86, v87
	v_add_f32_e32 v86, v88, v89
	v_add_u32_e32 v129, 0x2000, v21
	v_add_f32_dpp v29, v29, v29 quad_perm:[1,0,3,2] row_mask:0xf bank_mask:0xf bound_ctrl:1
	v_add_f32_dpp v86, v86, v86 quad_perm:[1,0,3,2] row_mask:0xf bank_mask:0xf bound_ctrl:1
	v_pk_fma_f32 v[78:79], v[82:83], v[12:13], v[46:47] op_sel_hi:[0,1,1]
	v_pk_fma_f32 v[80:81], v[82:83], v[14:15], v[54:55] op_sel_hi:[0,1,1]
	v_pk_fma_f32 v[84:85], v[82:83], v[8:9], v[50:51] op_sel_hi:[0,1,1]
	v_pk_fma_f32 v[82:83], v[82:83], v[10:11], v[56:57] op_sel_hi:[0,1,1]
	ds_read_b128 v[38:41], v20 offset:7936
	ds_read_b128 v[42:45], v20 offset:7952
	ds_read_b128 v[8:11], v20 offset:7680
	ds_read_b128 v[12:15], v20 offset:7696
	ds_read2_b32 v[90:91], v129 offset0:192 offset1:200
	ds_read_b128 v[54:57], v20 offset:8448
	ds_read_b128 v[58:61], v20 offset:8464
	ds_read_b128 v[46:49], v20 offset:8192
	ds_read_b128 v[50:53], v20 offset:8208
	ds_read_b128 v[62:65], v20 offset:8704
	ds_read_b128 v[66:69], v20 offset:8720
	v_add_f32_dpp v29, v29, v29 quad_perm:[2,3,0,1] row_mask:0xf bank_mask:0xf bound_ctrl:1
	v_add_f32_dpp v87, v86, v86 quad_perm:[2,3,0,1] row_mask:0xf bank_mask:0xf bound_ctrl:1
	v_add_u32_e32 v130, 0x2800, v21
	v_add_f32_dpp v86, v29, v29 row_half_mirror row_mask:0xf bank_mask:0xf bound_ctrl:1
	v_add_f32_dpp v88, v87, v87 row_half_mirror row_mask:0xf bank_mask:0xf bound_ctrl:1
	s_waitcnt lgkmcnt(14)
	v_pk_fma_f32 v[70:71], v[34:35], v[86:87], v[70:71] op_sel_hi:[1,0,1]
	v_pk_fma_f32 v[74:75], v[30:31], v[86:87], v[74:75] op_sel_hi:[1,0,1]
	v_pk_fma_f32 v[34:35], v[34:35], v[88:89], v[78:79] op_sel_hi:[1,0,1]
	v_pk_fma_f32 v[30:31], v[30:31], v[88:89], v[84:85] op_sel_hi:[1,0,1]
	v_pk_fma_f32 v[72:73], v[36:37], v[86:87], v[72:73] op_sel_hi:[1,0,1]
	v_pk_fma_f32 v[76:77], v[32:33], v[86:87], v[76:77] op_sel_hi:[1,0,1]
	v_pk_fma_f32 v[36:37], v[36:37], v[88:89], v[80:81] op_sel_hi:[1,0,1]
	v_pk_fma_f32 v[32:33], v[32:33], v[88:89], v[82:83] op_sel_hi:[1,0,1]
	s_waitcnt lgkmcnt(12)
	v_pk_mul_f32 v[78:79], v[4:5], v[70:71]
	v_pk_mul_f32 v[80:81], v[0:1], v[74:75]
	v_pk_mul_f32 v[4:5], v[4:5], v[34:35]
	v_pk_mul_f32 v[0:1], v[0:1], v[30:31]
	s_waitcnt lgkmcnt(8)
	v_pk_mul_f32 v[82:83], v[38:39], v[70:71]
	v_pk_mul_f32 v[84:85], v[42:43], v[74:75]
	v_pk_mul_f32 v[38:39], v[38:39], v[34:35]
	v_pk_mul_f32 v[42:43], v[42:43], v[30:31]
	v_pk_mul_f32 v[70:71], v[8:9], v[70:71]
	v_pk_mul_f32 v[86:87], v[10:11], v[72:73]
	s_waitcnt lgkmcnt(7)
	v_pk_mul_f32 v[74:75], v[12:13], v[74:75]
	v_pk_mul_f32 v[88:89], v[14:15], v[76:77]
	v_pk_mul_f32 v[8:9], v[8:9], v[34:35]
	v_pk_mul_f32 v[10:11], v[10:11], v[36:37]
	v_pk_mul_f32 v[12:13], v[12:13], v[30:31]
	v_pk_mul_f32 v[14:15], v[14:15], v[32:33]
	v_pk_fma_f32 v[30:31], v[6:7], v[72:73], v[78:79]
	v_pk_fma_f32 v[34:35], v[2:3], v[76:77], v[80:81]
	v_pk_fma_f32 v[4:5], v[6:7], v[36:37], v[4:5]
	v_pk_fma_f32 v[0:1], v[2:3], v[32:33], v[0:1]
	v_pk_fma_f32 v[2:3], v[40:41], v[72:73], v[82:83]
	v_pk_fma_f32 v[6:7], v[44:45], v[76:77], v[84:85]
	v_pk_fma_f32 v[36:37], v[40:41], v[36:37], v[38:39]
	v_pk_fma_f32 v[32:33], v[44:45], v[32:33], v[42:43]
	s_waitcnt lgkmcnt(5)
	v_mov_b32_e32 v92, v91
	v_pk_add_f32 v[0:1], v[4:5], v[0:1]
	v_pk_add_f32 v[2:3], v[2:3], v[6:7]
	v_pk_add_f32 v[4:5], v[36:37], v[32:33]
	v_pk_fma_f32 v[78:79], v[54:55], v[92:93], v[8:9] op_sel_hi:[1,0,1]
	v_pk_add_f32 v[8:9], v[30:31], v[34:35]
	v_add_f32_e32 v0, v0, v1
	v_add_f32_e32 v1, v2, v3
	v_add_f32_e32 v2, v4, v5
	s_waitcnt lgkmcnt(4)
	v_pk_fma_f32 v[76:77], v[60:61], v[90:91], v[88:89] op_sel_hi:[1,0,1]
	v_add_f32_e32 v6, v8, v9
	v_add_f32_dpp v29, v1, v1 quad_perm:[1,0,3,2] row_mask:0xf bank_mask:0xf bound_ctrl:1
	v_add_f32_dpp v88, v2, v2 quad_perm:[1,0,3,2] row_mask:0xf bank_mask:0xf bound_ctrl:1
	ds_write2st64_b32 v27, v6, v0 offset0:224 offset1:228
	v_add_f32_dpp v29, v29, v29 quad_perm:[2,3,0,1] row_mask:0xf bank_mask:0xf bound_ctrl:1
	v_add_f32_dpp v89, v88, v88 quad_perm:[2,3,0,1] row_mask:0xf bank_mask:0xf bound_ctrl:1
	v_pk_fma_f32 v[70:71], v[54:55], v[90:91], v[70:71] op_sel_hi:[1,0,1]
	v_pk_fma_f32 v[72:73], v[56:57], v[90:91], v[86:87] op_sel_hi:[1,0,1]
	v_pk_fma_f32 v[74:75], v[58:59], v[90:91], v[74:75] op_sel_hi:[1,0,1]
	v_pk_fma_f32 v[80:81], v[56:57], v[92:93], v[10:11] op_sel_hi:[1,0,1]
	v_pk_fma_f32 v[82:83], v[58:59], v[92:93], v[12:13] op_sel_hi:[1,0,1]
	v_pk_fma_f32 v[84:85], v[60:61], v[92:93], v[14:15] op_sel_hi:[1,0,1]
	ds_read_b128 v[42:45], v20 offset:9472
	ds_read_b128 v[38:41], v20 offset:9488
	ds_read_b128 v[54:57], v20 offset:9216
	ds_read_b128 v[58:61], v20 offset:9232
	ds_read2_b32 v[86:87], v130 offset0:64 offset1:72
	ds_read_b128 v[12:15], v20 offset:9984
	ds_read_b128 v[8:11], v20 offset:10000
	ds_read_b128 v[34:37], v20 offset:9728
	ds_read_b128 v[30:33], v20 offset:9744
	ds_read_b128 v[4:7], v20 offset:10240
	ds_read_b128 v[0:3], v20 offset:10256
	v_add_f32_dpp v88, v29, v29 row_half_mirror row_mask:0xf bank_mask:0xf bound_ctrl:1
	v_add_f32_dpp v90, v89, v89 row_half_mirror row_mask:0xf bank_mask:0xf bound_ctrl:1
	s_waitcnt lgkmcnt(14)
	v_pk_fma_f32 v[70:71], v[46:47], v[88:89], v[70:71] op_sel_hi:[1,0,1]
	v_pk_fma_f32 v[74:75], v[50:51], v[88:89], v[74:75] op_sel_hi:[1,0,1]
	v_pk_fma_f32 v[46:47], v[46:47], v[90:91], v[78:79] op_sel_hi:[1,0,1]
	v_pk_fma_f32 v[50:51], v[50:51], v[90:91], v[82:83] op_sel_hi:[1,0,1]
	v_pk_fma_f32 v[72:73], v[48:49], v[88:89], v[72:73] op_sel_hi:[1,0,1]
	v_pk_fma_f32 v[76:77], v[52:53], v[88:89], v[76:77] op_sel_hi:[1,0,1]
	v_pk_fma_f32 v[48:49], v[48:49], v[90:91], v[80:81] op_sel_hi:[1,0,1]
	v_pk_fma_f32 v[52:53], v[52:53], v[90:91], v[84:85] op_sel_hi:[1,0,1]
	s_waitcnt lgkmcnt(12)
; #define SCAN_STEP(w0, w1, a0, a1, b0, b1, k0, k1, r0, r1, vi, vj, t) do { \
;                 SCAN_ROW(S0, S1, S2, S3, w0, w1, a0, a1, b0, b1, k0, k1, r0, r1, vi, (t) * 512); \
;                 SCAN_ROW(T0, T1, T2, T3, w0, w1, a0, a1, b0, b1, k0, k1, r0, r1, vj, (t) * 512 + 256); } while (0)
;     ...
;             SCAN_LOAD(w0, w1, a0, a1, b0, b1, k0, k1, r0, r1, vi, vj, 0);
; #pragma unroll
;             for (int t = 0; t < 16; t += 2) {
;                 SCAN_LOAD(W0, W1, A0, A1, B0, B1, K0, K1, R0, R1, VI, VJ, t + 1);
;                 SCAN_STEP(w0, w1, a0, a1, b0, b1, k0, k1, r0, r1, vi, vj, t);
;                 if (t + 2 < 16) SCAN_LOAD(w0, w1, a0, a1, b0, b1, k0, k1, r0, r1, vi, vj, t + 2);
;                 SCAN_STEP(W0, W1, A0, A1, B0, B1, K0, K1, R0, R1, VI, VJ, t + 1);
	v_pk_mul_f32 v[78:79], v[62:63], v[70:71]
	v_pk_mul_f32 v[80:81], v[66:67], v[74:75]
	v_pk_mul_f32 v[62:63], v[62:63], v[46:47]
	v_pk_mul_f32 v[66:67], v[66:67], v[50:51]
	v_pk_fma_f32 v[78:79], v[64:65], v[72:73], v[78:79]
	v_pk_fma_f32 v[62:63], v[64:65], v[48:49], v[62:63]
	v_pk_fma_f32 v[64:65], v[68:69], v[52:53], v[66:67]
	v_pk_fma_f32 v[80:81], v[68:69], v[76:77], v[80:81]
	v_pk_add_f32 v[62:63], v[62:63], v[64:65]
	s_waitcnt lgkmcnt(9)
	v_pk_mul_f32 v[64:65], v[42:43], v[70:71]
	v_pk_mul_f32 v[68:69], v[38:39], v[74:75]
	v_pk_mul_f32 v[42:43], v[42:43], v[46:47]
	v_pk_mul_f32 v[38:39], v[38:39], v[50:51]
	v_pk_add_f32 v[66:67], v[78:79], v[80:81]
	s_waitcnt lgkmcnt(7)
	v_pk_mul_f32 v[70:71], v[54:55], v[70:71]
	v_pk_mul_f32 v[78:79], v[56:57], v[72:73]
	v_pk_mul_f32 v[74:75], v[58:59], v[74:75]
	v_pk_mul_f32 v[80:81], v[60:61], v[76:77]
	v_pk_mul_f32 v[46:47], v[54:55], v[46:47]
	v_pk_mul_f32 v[54:55], v[56:57], v[48:49]
	v_pk_mul_f32 v[50:51], v[58:59], v[50:51]
	v_pk_mul_f32 v[56:57], v[60:61], v[52:53]
	v_pk_fma_f32 v[58:59], v[44:45], v[72:73], v[64:65]
	v_pk_fma_f32 v[60:61], v[40:41], v[76:77], v[68:69]
	v_pk_fma_f32 v[42:43], v[44:45], v[48:49], v[42:43]
	v_pk_fma_f32 v[38:39], v[40:41], v[52:53], v[38:39]
	s_waitcnt lgkmcnt(5)
	v_mov_b32_e32 v82, v87
	v_add_f32_e32 v29, v66, v67
	v_add_f32_e32 v62, v62, v63
	v_pk_fma_f32 v[70:71], v[86:87], v[12:13], v[70:71] op_sel_hi:[0,1,1]
	v_pk_fma_f32 v[72:73], v[86:87], v[14:15], v[78:79] op_sel_hi:[0,1,1]
	s_waitcnt lgkmcnt(4)
	v_pk_fma_f32 v[74:75], v[86:87], v[8:9], v[74:75] op_sel_hi:[0,1,1]
	v_pk_fma_f32 v[76:77], v[86:87], v[10:11], v[80:81] op_sel_hi:[0,1,1]
	v_pk_add_f32 v[86:87], v[60:61], v[58:59]
	v_pk_add_f32 v[88:89], v[38:39], v[42:43]
	ds_write2st64_b32 v27, v29, v62 offset0:232 offset1:236
	v_add_f32_e32 v29, v86, v87
	v_add_f32_e32 v86, v88, v89
	v_add_u32_e32 v131, 0x2c00, v21
	v_add_f32_dpp v29, v29, v29 quad_perm:[1,0,3,2] row_mask:0xf bank_mask:0xf bound_ctrl:1
	v_add_f32_dpp v86, v86, v86 quad_perm:[1,0,3,2] row_mask:0xf bank_mask:0xf bound_ctrl:1
	v_pk_fma_f32 v[78:79], v[82:83], v[12:13], v[46:47] op_sel_hi:[0,1,1]
	v_pk_fma_f32 v[80:81], v[82:83], v[14:15], v[54:55] op_sel_hi:[0,1,1]
	v_pk_fma_f32 v[84:85], v[82:83], v[8:9], v[50:51] op_sel_hi:[0,1,1]
	v_pk_fma_f32 v[82:83], v[82:83], v[10:11], v[56:57] op_sel_hi:[0,1,1]
	ds_read_b128 v[38:41], v20 offset:11008
	ds_read_b128 v[42:45], v20 offset:11024
	ds_read_b128 v[8:11], v20 offset:10752
	ds_read_b128 v[12:15], v20 offset:10768
	ds_read2_b32 v[90:91], v131 offset0:192 offset1:200
	ds_read_b128 v[54:57], v20 offset:11520
	ds_read_b128 v[58:61], v20 offset:11536
	ds_read_b128 v[46:49], v20 offset:11264
	ds_read_b128 v[50:53], v20 offset:11280
	ds_read_b128 v[62:65], v20 offset:11776
	ds_read_b128 v[66:69], v20 offset:11792
	v_add_f32_dpp v29, v29, v29 quad_perm:[2,3,0,1] row_mask:0xf bank_mask:0xf bound_ctrl:1
	v_add_f32_dpp v87, v86, v86 quad_perm:[2,3,0,1] row_mask:0xf bank_mask:0xf bound_ctrl:1
	v_add_u32_e32 v132, 0x3400, v21
	v_add_f32_dpp v86, v29, v29 row_half_mirror row_mask:0xf bank_mask:0xf bound_ctrl:1
	v_add_f32_dpp v88, v87, v87 row_half_mirror row_mask:0xf bank_mask:0xf bound_ctrl:1
	s_waitcnt lgkmcnt(14)
	v_pk_fma_f32 v[70:71], v[34:35], v[86:87], v[70:71] op_sel_hi:[1,0,1]
	v_pk_fma_f32 v[74:75], v[30:31], v[86:87], v[74:75] op_sel_hi:[1,0,1]
	v_pk_fma_f32 v[34:35], v[34:35], v[88:89], v[78:79] op_sel_hi:[1,0,1]
	v_pk_fma_f32 v[30:31], v[30:31], v[88:89], v[84:85] op_sel_hi:[1,0,1]
	v_pk_fma_f32 v[72:73], v[36:37], v[86:87], v[72:73] op_sel_hi:[1,0,1]
	v_pk_fma_f32 v[76:77], v[32:33], v[86:87], v[76:77] op_sel_hi:[1,0,1]
	v_pk_fma_f32 v[36:37], v[36:37], v[88:89], v[80:81] op_sel_hi:[1,0,1]
	v_pk_fma_f32 v[32:33], v[32:33], v[88:89], v[82:83] op_sel_hi:[1,0,1]
	s_waitcnt lgkmcnt(12)
	v_pk_mul_f32 v[78:79], v[4:5], v[70:71]
	v_pk_mul_f32 v[80:81], v[0:1], v[74:75]
	v_pk_mul_f32 v[4:5], v[4:5], v[34:35]
	v_pk_mul_f32 v[0:1], v[0:1], v[30:31]
	s_waitcnt lgkmcnt(8)
	v_pk_mul_f32 v[82:83], v[38:39], v[70:71]
	v_pk_mul_f32 v[84:85], v[42:43], v[74:75]
	v_pk_mul_f32 v[38:39], v[38:39], v[34:35]
	v_pk_mul_f32 v[42:43], v[42:43], v[30:31]
	v_pk_mul_f32 v[70:71], v[8:9], v[70:71]
	v_pk_mul_f32 v[86:87], v[10:11], v[72:73]
	s_waitcnt lgkmcnt(7)
	v_pk_mul_f32 v[74:75], v[12:13], v[74:75]
	v_pk_mul_f32 v[88:89], v[14:15], v[76:77]
	v_pk_mul_f32 v[8:9], v[8:9], v[34:35]
	v_pk_mul_f32 v[10:11], v[10:11], v[36:37]
	v_pk_mul_f32 v[12:13], v[12:13], v[30:31]
	v_pk_mul_f32 v[14:15], v[14:15], v[32:33]
	v_pk_fma_f32 v[30:31], v[6:7], v[72:73], v[78:79]
	v_pk_fma_f32 v[34:35], v[2:3], v[76:77], v[80:81]
	v_pk_fma_f32 v[4:5], v[6:7], v[36:37], v[4:5]
	v_pk_fma_f32 v[0:1], v[2:3], v[32:33], v[0:1]
	v_pk_fma_f32 v[2:3], v[40:41], v[72:73], v[82:83]
	v_pk_fma_f32 v[6:7], v[44:45], v[76:77], v[84:85]
	v_pk_fma_f32 v[36:37], v[40:41], v[36:37], v[38:39]
	v_pk_fma_f32 v[32:33], v[44:45], v[32:33], v[42:43]
	s_waitcnt lgkmcnt(5)
	v_mov_b32_e32 v92, v91
	v_pk_add_f32 v[0:1], v[4:5], v[0:1]
	v_pk_add_f32 v[2:3], v[2:3], v[6:7]
	v_pk_add_f32 v[4:5], v[36:37], v[32:33]
	v_pk_fma_f32 v[78:79], v[54:55], v[92:93], v[8:9] op_sel_hi:[1,0,1]
	v_pk_add_f32 v[8:9], v[30:31], v[34:35]
	v_add_f32_e32 v0, v0, v1
	v_add_f32_e32 v1, v2, v3
	v_add_f32_e32 v2, v4, v5
	s_waitcnt lgkmcnt(4)
; #define SCAN_STEP(w0, w1, a0, a1, b0, b1, k0, k1, r0, r1, vi, vj, t) do { \
;                 SCAN_ROW(S0, S1, S2, S3, w0, w1, a0, a1, b0, b1, k0, k1, r0, r1, vi, (t) * 512); \
;                 SCAN_ROW(T0, T1, T2, T3, w0, w1, a0, a1, b0, b1, k0, k1, r0, r1, vj, (t) * 512 + 256); } while (0)
;     ...
;             SCAN_LOAD(w0, w1, a0, a1, b0, b1, k0, k1, r0, r1, vi, vj, 0);
; #pragma unroll
;             for (int t = 0; t < 16; t += 2) {
;                 SCAN_LOAD(W0, W1, A0, A1, B0, B1, K0, K1, R0, R1, VI, VJ, t + 1);
;                 SCAN_STEP(w0, w1, a0, a1, b0, b1, k0, k1, r0, r1, vi, vj, t);
;                 if (t + 2 < 16) SCAN_LOAD(w0, w1, a0, a1, b0, b1, k0, k1, r0, r1, vi, vj, t + 2);
;                 SCAN_STEP(W0, W1, A0, A1, B0, B1, K0, K1, R0, R1, VI, VJ, t + 1);
	v_pk_fma_f32 v[76:77], v[60:61], v[90:91], v[88:89] op_sel_hi:[1,0,1]
	v_add_f32_e32 v6, v8, v9
	v_add_f32_dpp v29, v1, v1 quad_perm:[1,0,3,2] row_mask:0xf bank_mask:0xf bound_ctrl:1
	v_add_f32_dpp v88, v2, v2 quad_perm:[1,0,3,2] row_mask:0xf bank_mask:0xf bound_ctrl:1
	ds_write2st64_b32 v27, v6, v0 offset0:240 offset1:244
	v_add_f32_dpp v29, v29, v29 quad_perm:[2,3,0,1] row_mask:0xf bank_mask:0xf bound_ctrl:1
	v_add_f32_dpp v89, v88, v88 quad_perm:[2,3,0,1] row_mask:0xf bank_mask:0xf bound_ctrl:1
	v_pk_fma_f32 v[70:71], v[54:55], v[90:91], v[70:71] op_sel_hi:[1,0,1]
	v_pk_fma_f32 v[72:73], v[56:57], v[90:91], v[86:87] op_sel_hi:[1,0,1]
	v_pk_fma_f32 v[74:75], v[58:59], v[90:91], v[74:75] op_sel_hi:[1,0,1]
	v_pk_fma_f32 v[80:81], v[56:57], v[92:93], v[10:11] op_sel_hi:[1,0,1]
	v_pk_fma_f32 v[82:83], v[58:59], v[92:93], v[12:13] op_sel_hi:[1,0,1]
	v_pk_fma_f32 v[84:85], v[60:61], v[92:93], v[14:15] op_sel_hi:[1,0,1]
	ds_read_b128 v[42:45], v20 offset:12544
	ds_read_b128 v[38:41], v20 offset:12560
	ds_read_b128 v[54:57], v20 offset:12288
	ds_read_b128 v[58:61], v20 offset:12304
	ds_read2_b32 v[86:87], v132 offset0:64 offset1:72
	ds_read_b128 v[12:15], v20 offset:13056
	ds_read_b128 v[8:11], v20 offset:13072
	ds_read_b128 v[34:37], v20 offset:12800
	ds_read_b128 v[30:33], v20 offset:12816
	ds_read_b128 v[4:7], v20 offset:13312
	ds_read_b128 v[0:3], v20 offset:13328
	v_add_f32_dpp v88, v29, v29 row_half_mirror row_mask:0xf bank_mask:0xf bound_ctrl:1
	v_add_f32_dpp v90, v89, v89 row_half_mirror row_mask:0xf bank_mask:0xf bound_ctrl:1
	s_waitcnt lgkmcnt(14)
	v_pk_fma_f32 v[70:71], v[46:47], v[88:89], v[70:71] op_sel_hi:[1,0,1]
	v_pk_fma_f32 v[74:75], v[50:51], v[88:89], v[74:75] op_sel_hi:[1,0,1]
	v_pk_fma_f32 v[46:47], v[46:47], v[90:91], v[78:79] op_sel_hi:[1,0,1]
	v_pk_fma_f32 v[50:51], v[50:51], v[90:91], v[82:83] op_sel_hi:[1,0,1]
	v_pk_fma_f32 v[72:73], v[48:49], v[88:89], v[72:73] op_sel_hi:[1,0,1]
	v_pk_fma_f32 v[76:77], v[52:53], v[88:89], v[76:77] op_sel_hi:[1,0,1]
	v_pk_fma_f32 v[48:49], v[48:49], v[90:91], v[80:81] op_sel_hi:[1,0,1]
	v_pk_fma_f32 v[52:53], v[52:53], v[90:91], v[84:85] op_sel_hi:[1,0,1]
	s_waitcnt lgkmcnt(12)
	v_pk_mul_f32 v[78:79], v[62:63], v[70:71]
	v_pk_mul_f32 v[80:81], v[66:67], v[74:75]
	v_pk_mul_f32 v[62:63], v[62:63], v[46:47]
	v_pk_mul_f32 v[66:67], v[66:67], v[50:51]
	v_pk_fma_f32 v[78:79], v[64:65], v[72:73], v[78:79]
	v_pk_fma_f32 v[62:63], v[64:65], v[48:49], v[62:63]
	v_pk_fma_f32 v[64:65], v[68:69], v[52:53], v[66:67]
	v_pk_fma_f32 v[80:81], v[68:69], v[76:77], v[80:81]
	v_pk_add_f32 v[62:63], v[62:63], v[64:65]
	s_waitcnt lgkmcnt(9)
	v_pk_mul_f32 v[64:65], v[42:43], v[70:71]
	v_pk_mul_f32 v[68:69], v[38:39], v[74:75]
	v_pk_mul_f32 v[42:43], v[42:43], v[46:47]
	v_pk_mul_f32 v[38:39], v[38:39], v[50:51]
	v_pk_add_f32 v[66:67], v[78:79], v[80:81]
	s_waitcnt lgkmcnt(7)
	v_pk_mul_f32 v[70:71], v[54:55], v[70:71]
	v_pk_mul_f32 v[78:79], v[56:57], v[72:73]
	v_pk_mul_f32 v[74:75], v[58:59], v[74:75]
	v_pk_mul_f32 v[80:81], v[60:61], v[76:77]
	v_pk_mul_f32 v[46:47], v[54:55], v[46:47]
	v_pk_mul_f32 v[54:55], v[56:57], v[48:49]
	v_pk_mul_f32 v[50:51], v[58:59], v[50:51]
	v_pk_mul_f32 v[56:57], v[60:61], v[52:53]
	v_pk_fma_f32 v[58:59], v[44:45], v[72:73], v[64:65]
	v_pk_fma_f32 v[60:61], v[40:41], v[76:77], v[68:69]
	v_pk_fma_f32 v[42:43], v[44:45], v[48:49], v[42:43]
	v_pk_fma_f32 v[38:39], v[40:41], v[52:53], v[38:39]
	s_waitcnt lgkmcnt(5)
	v_mov_b32_e32 v82, v87
	v_add_f32_e32 v29, v66, v67
	v_add_f32_e32 v62, v62, v63
	v_pk_fma_f32 v[70:71], v[86:87], v[12:13], v[70:71] op_sel_hi:[0,1,1]
	v_pk_fma_f32 v[72:73], v[86:87], v[14:15], v[78:79] op_sel_hi:[0,1,1]
	s_waitcnt lgkmcnt(4)
	v_pk_fma_f32 v[74:75], v[86:87], v[8:9], v[74:75] op_sel_hi:[0,1,1]
	v_pk_fma_f32 v[76:77], v[86:87], v[10:11], v[80:81] op_sel_hi:[0,1,1]
	v_pk_add_f32 v[86:87], v[60:61], v[58:59]
	v_pk_add_f32 v[88:89], v[38:39], v[42:43]
	v_add_u32_e32 v19, 0xc000, v27
	v_add_u32_e32 v28, 0x3800, v21
	ds_write2st64_b32 v27, v29, v62 offset0:248 offset1:252
	v_add_f32_e32 v27, v86, v87
	v_add_f32_e32 v86, v88, v89
	v_pk_fma_f32 v[78:79], v[82:83], v[12:13], v[46:47] op_sel_hi:[0,1,1]
	v_pk_fma_f32 v[80:81], v[82:83], v[14:15], v[54:55] op_sel_hi:[0,1,1]
	v_pk_fma_f32 v[84:85], v[82:83], v[8:9], v[50:51] op_sel_hi:[0,1,1]
	v_pk_fma_f32 v[82:83], v[82:83], v[10:11], v[56:57] op_sel_hi:[0,1,1]
	ds_read2_b32 v[28:29], v28 offset0:192 offset1:200
	ds_read_b128 v[38:41], v20 offset:14080
	ds_read_b128 v[42:45], v20 offset:14096
	ds_read_b128 v[8:11], v20 offset:13824
	ds_read_b128 v[12:15], v20 offset:13840
	ds_read_b128 v[54:57], v20 offset:14592
	ds_read_b128 v[58:61], v20 offset:14608
	ds_read_b128 v[46:49], v20 offset:14336
	ds_read_b128 v[50:53], v20 offset:14352
	ds_read_b128 v[62:65], v20 offset:14848
	ds_read_b128 v[66:69], v20 offset:14864
	v_add_f32_dpp v27, v27, v27 quad_perm:[1,0,3,2] row_mask:0xf bank_mask:0xf bound_ctrl:1
	v_add_f32_dpp v86, v86, v86 quad_perm:[1,0,3,2] row_mask:0xf bank_mask:0xf bound_ctrl:1
	v_add_u32_e32 v26, 0x4000, v21
	v_add_f32_dpp v27, v27, v27 quad_perm:[2,3,0,1] row_mask:0xf bank_mask:0xf bound_ctrl:1
	v_add_f32_dpp v87, v86, v86 quad_perm:[2,3,0,1] row_mask:0xf bank_mask:0xf bound_ctrl:1
	s_waitcnt lgkmcnt(10)
; #define SCAN_STEP(w0, w1, a0, a1, b0, b1, k0, k1, r0, r1, vi, vj, t) do { \
;                 SCAN_ROW(S0, S1, S2, S3, w0, w1, a0, a1, b0, b1, k0, k1, r0, r1, vi, (t) * 512); \
;                 SCAN_ROW(T0, T1, T2, T3, w0, w1, a0, a1, b0, b1, k0, k1, r0, r1, vj, (t) * 512 + 256); } while (0)
;     ...
;             SCAN_LOAD(w0, w1, a0, a1, b0, b1, k0, k1, r0, r1, vi, vj, 0);
; #pragma unroll
;             for (int t = 0; t < 16; t += 2) {
;                 SCAN_LOAD(W0, W1, A0, A1, B0, B1, K0, K1, R0, R1, VI, VJ, t + 1);
;                 SCAN_STEP(w0, w1, a0, a1, b0, b1, k0, k1, r0, r1, vi, vj, t);
;                 if (t + 2 < 16) SCAN_LOAD(w0, w1, a0, a1, b0, b1, k0, k1, r0, r1, vi, vj, t + 2);
;                 SCAN_STEP(W0, W1, A0, A1, B0, B1, K0, K1, R0, R1, VI, VJ, t + 1);
	v_mov_b32_e32 v90, v29
	v_add_f32_dpp v86, v27, v27 row_half_mirror row_mask:0xf bank_mask:0xf bound_ctrl:1
	v_add_f32_dpp v88, v87, v87 row_half_mirror row_mask:0xf bank_mask:0xf bound_ctrl:1
	v_pk_fma_f32 v[70:71], v[34:35], v[86:87], v[70:71] op_sel_hi:[1,0,1]
	v_pk_fma_f32 v[72:73], v[36:37], v[86:87], v[72:73] op_sel_hi:[1,0,1]
	v_pk_fma_f32 v[74:75], v[30:31], v[86:87], v[74:75] op_sel_hi:[1,0,1]
	v_pk_fma_f32 v[76:77], v[32:33], v[86:87], v[76:77] op_sel_hi:[1,0,1]
	v_pk_fma_f32 v[34:35], v[34:35], v[88:89], v[78:79] op_sel_hi:[1,0,1]
	v_pk_fma_f32 v[30:31], v[30:31], v[88:89], v[84:85] op_sel_hi:[1,0,1]
	v_pk_fma_f32 v[36:37], v[36:37], v[88:89], v[80:81] op_sel_hi:[1,0,1]
	v_pk_fma_f32 v[32:33], v[32:33], v[88:89], v[82:83] op_sel_hi:[1,0,1]
	v_pk_mul_f32 v[78:79], v[4:5], v[70:71]
	v_pk_mul_f32 v[80:81], v[0:1], v[74:75]
	v_pk_mul_f32 v[4:5], v[4:5], v[34:35]
	v_pk_mul_f32 v[0:1], v[0:1], v[30:31]
	s_waitcnt lgkmcnt(6)
	v_pk_mul_f32 v[82:83], v[38:39], v[70:71]
	v_pk_mul_f32 v[84:85], v[42:43], v[74:75]
	v_pk_mul_f32 v[70:71], v[8:9], v[70:71]
	v_pk_mul_f32 v[86:87], v[10:11], v[72:73]
	v_pk_mul_f32 v[74:75], v[12:13], v[74:75]
	v_pk_mul_f32 v[88:89], v[14:15], v[76:77]
	v_pk_mul_f32 v[38:39], v[38:39], v[34:35]
	v_pk_mul_f32 v[42:43], v[42:43], v[30:31]
	v_pk_mul_f32 v[8:9], v[8:9], v[34:35]
	v_pk_mul_f32 v[12:13], v[12:13], v[30:31]
	v_pk_mul_f32 v[14:15], v[14:15], v[32:33]
	v_pk_fma_f32 v[30:31], v[6:7], v[72:73], v[78:79]
	v_pk_fma_f32 v[34:35], v[2:3], v[76:77], v[80:81]
	v_pk_fma_f32 v[4:5], v[6:7], v[36:37], v[4:5]
	v_pk_fma_f32 v[0:1], v[2:3], v[32:33], v[0:1]
	v_pk_fma_f32 v[2:3], v[40:41], v[72:73], v[82:83]
	v_pk_fma_f32 v[6:7], v[44:45], v[76:77], v[84:85]
	s_waitcnt lgkmcnt(4)
	v_pk_fma_f32 v[70:71], v[54:55], v[28:29], v[70:71] op_sel_hi:[1,0,1]
	v_pk_fma_f32 v[72:73], v[56:57], v[28:29], v[86:87] op_sel_hi:[1,0,1]
	v_pk_fma_f32 v[74:75], v[58:59], v[28:29], v[74:75] op_sel_hi:[1,0,1]
	v_pk_fma_f32 v[76:77], v[60:61], v[28:29], v[88:89] op_sel_hi:[1,0,1]
	v_pk_fma_f32 v[28:29], v[40:41], v[36:37], v[38:39]
	v_pk_fma_f32 v[32:33], v[44:45], v[32:33], v[42:43]
	v_pk_add_f32 v[0:1], v[4:5], v[0:1]
	v_pk_add_f32 v[2:3], v[2:3], v[6:7]
	v_pk_add_f32 v[4:5], v[28:29], v[32:33]
	v_pk_fma_f32 v[78:79], v[54:55], v[90:91], v[8:9] op_sel_hi:[1,0,1]
	v_pk_add_f32 v[8:9], v[30:31], v[34:35]
	v_add_f32_e32 v0, v0, v1
	v_add_f32_e32 v1, v2, v3
	v_add_f32_e32 v2, v4, v5
	v_add_f32_e32 v6, v8, v9
	v_add_f32_dpp v84, v1, v1 quad_perm:[1,0,3,2] row_mask:0xf bank_mask:0xf bound_ctrl:1
	v_add_f32_dpp v85, v2, v2 quad_perm:[1,0,3,2] row_mask:0xf bank_mask:0xf bound_ctrl:1
	v_pk_mul_f32 v[10:11], v[10:11], v[36:37]
	ds_write2st64_b32 v19, v6, v0 offset0:64 offset1:68
	v_add_f32_dpp v84, v84, v84 quad_perm:[2,3,0,1] row_mask:0xf bank_mask:0xf bound_ctrl:1
	v_add_f32_dpp v85, v85, v85 quad_perm:[2,3,0,1] row_mask:0xf bank_mask:0xf bound_ctrl:1
	v_pk_fma_f32 v[80:81], v[56:57], v[90:91], v[10:11] op_sel_hi:[1,0,1]
	v_pk_fma_f32 v[58:59], v[58:59], v[90:91], v[12:13] op_sel_hi:[1,0,1]
	v_pk_fma_f32 v[60:61], v[60:61], v[90:91], v[14:15] op_sel_hi:[1,0,1]
	ds_read2_b32 v[82:83], v26 offset0:64 offset1:72
	ds_read_b128 v[0:3], v20 offset:16400
	ds_read_b128 v[4:7], v20 offset:16384
	ds_read_b128 v[8:11], v20 offset:16144
	ds_read_b128 v[12:15], v20 offset:16128
	ds_read_b128 v[26:29], v20 offset:15888
	ds_read_b128 v[30:33], v20 offset:15872
	ds_read_b128 v[34:37], v20 offset:15632
	ds_read_b128 v[38:41], v20 offset:15616
	ds_read_b128 v[42:45], v20 offset:15360
	ds_read_b128 v[54:57], v20 offset:15376
	v_add_f32_dpp v84, v84, v84 row_half_mirror row_mask:0xf bank_mask:0xf bound_ctrl:1
	v_add_f32_dpp v86, v85, v85 row_half_mirror row_mask:0xf bank_mask:0xf bound_ctrl:1
	s_waitcnt lgkmcnt(14)
	v_pk_fma_f32 v[70:71], v[46:47], v[84:85], v[70:71] op_sel_hi:[1,0,1]
	v_pk_fma_f32 v[74:75], v[50:51], v[84:85], v[74:75] op_sel_hi:[1,0,1]
	v_pk_fma_f32 v[46:47], v[46:47], v[86:87], v[78:79] op_sel_hi:[1,0,1]
	v_pk_fma_f32 v[50:51], v[50:51], v[86:87], v[58:59] op_sel_hi:[1,0,1]
	v_pk_fma_f32 v[72:73], v[48:49], v[84:85], v[72:73] op_sel_hi:[1,0,1]
	v_pk_fma_f32 v[76:77], v[52:53], v[84:85], v[76:77] op_sel_hi:[1,0,1]
	v_pk_fma_f32 v[48:49], v[48:49], v[86:87], v[80:81] op_sel_hi:[1,0,1]
	v_pk_fma_f32 v[52:53], v[52:53], v[86:87], v[60:61] op_sel_hi:[1,0,1]
	s_waitcnt lgkmcnt(12)
	v_pk_mul_f32 v[58:59], v[62:63], v[70:71]
	v_pk_mul_f32 v[60:61], v[66:67], v[74:75]
	v_pk_mul_f32 v[62:63], v[62:63], v[46:47]
	v_pk_mul_f32 v[66:67], v[66:67], v[50:51]
	v_pk_fma_f32 v[58:59], v[64:65], v[72:73], v[58:59]
	v_pk_fma_f32 v[60:61], v[68:69], v[76:77], v[60:61]
	v_pk_fma_f32 v[62:63], v[64:65], v[48:49], v[62:63]
	v_pk_fma_f32 v[64:65], v[68:69], v[52:53], v[66:67]
	v_pk_add_f32 v[58:59], v[58:59], v[60:61]
	v_pk_add_f32 v[60:61], v[62:63], v[64:65]
	s_waitcnt lgkmcnt(1)
	v_pk_mul_f32 v[62:63], v[38:39], v[70:71]
	v_pk_mul_f32 v[64:65], v[34:35], v[74:75]
	v_pk_mul_f32 v[38:39], v[38:39], v[46:47]
	v_pk_mul_f32 v[34:35], v[34:35], v[50:51]
	v_pk_mul_f32 v[66:67], v[42:43], v[70:71]
	v_pk_mul_f32 v[68:69], v[44:45], v[72:73]
	s_waitcnt lgkmcnt(0)
; #define SCAN_STEP(w0, w1, a0, a1, b0, b1, k0, k1, r0, r1, vi, vj, t) do { \
;                 SCAN_ROW(S0, S1, S2, S3, w0, w1, a0, a1, b0, b1, k0, k1, r0, r1, vi, (t) * 512); \
;                 SCAN_ROW(T0, T1, T2, T3, w0, w1, a0, a1, b0, b1, k0, k1, r0, r1, vj, (t) * 512 + 256); } while (0)
;     ...
;             SCAN_LOAD(w0, w1, a0, a1, b0, b1, k0, k1, r0, r1, vi, vj, 0);
; #pragma unroll
;             for (int t = 0; t < 16; t += 2) {
;                 SCAN_LOAD(W0, W1, A0, A1, B0, B1, K0, K1, R0, R1, VI, VJ, t + 1);
;                 SCAN_STEP(w0, w1, a0, a1, b0, b1, k0, k1, r0, r1, vi, vj, t);
;                 if (t + 2 < 16) SCAN_LOAD(w0, w1, a0, a1, b0, b1, k0, k1, r0, r1, vi, vj, t + 2);
;                 SCAN_STEP(W0, W1, A0, A1, B0, B1, K0, K1, R0, R1, VI, VJ, t + 1);
;             }
	v_pk_mul_f32 v[70:71], v[54:55], v[74:75]
	v_pk_mul_f32 v[74:75], v[56:57], v[76:77]
	v_pk_mul_f32 v[42:43], v[42:43], v[46:47]
	v_pk_mul_f32 v[46:47], v[54:55], v[50:51]
	v_pk_mul_f32 v[50:51], v[56:57], v[52:53]
	v_add_f32_e32 v58, v58, v59
	v_add_f32_e32 v59, v60, v61
	v_pk_fma_f32 v[54:55], v[40:41], v[72:73], v[62:63]
	v_pk_fma_f32 v[56:57], v[36:37], v[76:77], v[64:65]
	v_pk_fma_f32 v[38:39], v[40:41], v[48:49], v[38:39]
	v_pk_fma_f32 v[34:35], v[36:37], v[52:53], v[34:35]
	v_add_u32_e32 v25, 0x4400, v21
	v_mov_b32_e32 v78, v83
	v_pk_mul_f32 v[44:45], v[44:45], v[48:49]
	v_pk_fma_f32 v[66:67], v[82:83], v[12:13], v[66:67] op_sel_hi:[0,1,1]
	v_pk_fma_f32 v[68:69], v[82:83], v[14:15], v[68:69] op_sel_hi:[0,1,1]
	v_pk_fma_f32 v[70:71], v[82:83], v[8:9], v[70:71] op_sel_hi:[0,1,1]
	v_pk_fma_f32 v[72:73], v[82:83], v[10:11], v[74:75] op_sel_hi:[0,1,1]
	ds_write2st64_b32 v19, v58, v59 offset0:72 offset1:76
	v_pk_add_f32 v[82:83], v[56:57], v[54:55]
	v_pk_add_f32 v[84:85], v[34:35], v[38:39]
	v_pk_fma_f32 v[74:75], v[78:79], v[12:13], v[42:43] op_sel_hi:[0,1,1]
	v_pk_fma_f32 v[76:77], v[78:79], v[14:15], v[44:45] op_sel_hi:[0,1,1]
	v_pk_fma_f32 v[80:81], v[78:79], v[8:9], v[46:47] op_sel_hi:[0,1,1]
	v_pk_fma_f32 v[78:79], v[78:79], v[10:11], v[50:51] op_sel_hi:[0,1,1]
	ds_read2_b32 v[86:87], v25 offset0:192 offset1:200
	ds_read_b128 v[34:37], v20 offset:17152
	ds_read_b128 v[38:41], v20 offset:17168
	ds_read_b128 v[8:11], v20 offset:16896
	ds_read_b128 v[12:15], v20 offset:16912
	ds_read_b128 v[50:53], v20 offset:17664
	ds_read_b128 v[54:57], v20 offset:17680
	ds_read_b128 v[42:45], v20 offset:17408
	ds_read_b128 v[46:49], v20 offset:17424
	ds_read_b128 v[58:61], v20 offset:17920
	ds_read_b128 v[62:65], v20 offset:17936
	v_add_f32_e32 v25, v82, v83
	v_add_f32_e32 v82, v84, v85
	v_add_u32_e32 v24, 0x4c00, v21
	v_add_f32_dpp v25, v25, v25 quad_perm:[1,0,3,2] row_mask:0xf bank_mask:0xf bound_ctrl:1
	v_add_f32_dpp v82, v82, v82 quad_perm:[1,0,3,2] row_mask:0xf bank_mask:0xf bound_ctrl:1
	s_waitcnt lgkmcnt(10)
	v_mov_b32_e32 v88, v87
	v_add_f32_dpp v25, v25, v25 quad_perm:[2,3,0,1] row_mask:0xf bank_mask:0xf bound_ctrl:1
	v_add_f32_dpp v83, v82, v82 quad_perm:[2,3,0,1] row_mask:0xf bank_mask:0xf bound_ctrl:1
	v_add_u32_e32 v23, 0x5000, v21
	v_add_f32_dpp v82, v25, v25 row_half_mirror row_mask:0xf bank_mask:0xf bound_ctrl:1
	v_add_f32_dpp v84, v83, v83 row_half_mirror row_mask:0xf bank_mask:0xf bound_ctrl:1
	v_pk_fma_f32 v[66:67], v[30:31], v[82:83], v[66:67] op_sel_hi:[1,0,1]
	v_pk_fma_f32 v[70:71], v[26:27], v[82:83], v[70:71] op_sel_hi:[1,0,1]
	v_pk_fma_f32 v[30:31], v[30:31], v[84:85], v[74:75] op_sel_hi:[1,0,1]
	v_pk_fma_f32 v[26:27], v[26:27], v[84:85], v[80:81] op_sel_hi:[1,0,1]
	v_pk_fma_f32 v[68:69], v[32:33], v[82:83], v[68:69] op_sel_hi:[1,0,1]
	v_pk_fma_f32 v[72:73], v[28:29], v[82:83], v[72:73] op_sel_hi:[1,0,1]
	v_pk_fma_f32 v[32:33], v[32:33], v[84:85], v[76:77] op_sel_hi:[1,0,1]
	v_pk_fma_f32 v[28:29], v[28:29], v[84:85], v[78:79] op_sel_hi:[1,0,1]
	v_pk_mul_f32 v[74:75], v[4:5], v[66:67]
	v_pk_mul_f32 v[76:77], v[0:1], v[70:71]
	v_pk_mul_f32 v[4:5], v[4:5], v[30:31]
	v_pk_mul_f32 v[0:1], v[0:1], v[26:27]
	s_waitcnt lgkmcnt(7)
	v_pk_mul_f32 v[78:79], v[34:35], v[66:67]
	v_pk_mul_f32 v[80:81], v[38:39], v[70:71]
	v_pk_mul_f32 v[34:35], v[34:35], v[30:31]
	v_pk_mul_f32 v[38:39], v[38:39], v[26:27]
	v_pk_mul_f32 v[66:67], v[8:9], v[66:67]
	v_pk_mul_f32 v[82:83], v[10:11], v[68:69]
	s_waitcnt lgkmcnt(6)
	v_pk_mul_f32 v[70:71], v[12:13], v[70:71]
	v_pk_mul_f32 v[84:85], v[14:15], v[72:73]
	v_pk_mul_f32 v[8:9], v[8:9], v[30:31]
	v_pk_mul_f32 v[10:11], v[10:11], v[32:33]
	v_pk_mul_f32 v[12:13], v[12:13], v[26:27]
	v_pk_mul_f32 v[14:15], v[14:15], v[28:29]
	v_pk_fma_f32 v[26:27], v[6:7], v[68:69], v[74:75]
	v_pk_fma_f32 v[30:31], v[2:3], v[72:73], v[76:77]
	v_pk_fma_f32 v[4:5], v[6:7], v[32:33], v[4:5]
	v_pk_fma_f32 v[0:1], v[2:3], v[28:29], v[0:1]
	v_pk_fma_f32 v[2:3], v[36:37], v[68:69], v[78:79]
	v_pk_fma_f32 v[6:7], v[40:41], v[72:73], v[80:81]
	v_pk_fma_f32 v[32:33], v[36:37], v[32:33], v[34:35]
	v_pk_fma_f32 v[28:29], v[40:41], v[28:29], v[38:39]
	v_pk_add_f32 v[0:1], v[4:5], v[0:1]
	v_pk_add_f32 v[2:3], v[2:3], v[6:7]
	v_pk_add_f32 v[4:5], v[32:33], v[28:29]
	s_waitcnt lgkmcnt(5)
	v_pk_fma_f32 v[40:41], v[50:51], v[88:89], v[8:9] op_sel_hi:[1,0,1]
	v_pk_add_f32 v[8:9], v[26:27], v[30:31]
	v_add_f32_e32 v0, v0, v1
	v_add_f32_e32 v1, v2, v3
	v_add_f32_e32 v2, v4, v5
	v_pk_fma_f32 v[68:69], v[52:53], v[86:87], v[82:83] op_sel_hi:[1,0,1]
	v_add_f32_e32 v6, v8, v9
	v_add_f32_dpp v82, v1, v1 quad_perm:[1,0,3,2] row_mask:0xf bank_mask:0xf bound_ctrl:1
	v_add_f32_dpp v83, v2, v2 quad_perm:[1,0,3,2] row_mask:0xf bank_mask:0xf bound_ctrl:1
	ds_write2st64_b32 v19, v6, v0 offset0:80 offset1:84
	v_add_f32_dpp v82, v82, v82 quad_perm:[2,3,0,1] row_mask:0xf bank_mask:0xf bound_ctrl:1
	v_add_f32_dpp v83, v83, v83 quad_perm:[2,3,0,1] row_mask:0xf bank_mask:0xf bound_ctrl:1
	v_pk_fma_f32 v[66:67], v[50:51], v[86:87], v[66:67] op_sel_hi:[1,0,1]
	s_waitcnt lgkmcnt(5)
	v_pk_fma_f32 v[70:71], v[54:55], v[86:87], v[70:71] op_sel_hi:[1,0,1]
	v_pk_fma_f32 v[72:73], v[56:57], v[86:87], v[84:85] op_sel_hi:[1,0,1]
	v_pk_fma_f32 v[74:75], v[52:53], v[88:89], v[10:11] op_sel_hi:[1,0,1]
	v_pk_fma_f32 v[76:77], v[54:55], v[88:89], v[12:13] op_sel_hi:[1,0,1]
	v_pk_fma_f32 v[78:79], v[56:57], v[88:89], v[14:15] op_sel_hi:[1,0,1]
	ds_read2_b32 v[80:81], v24 offset0:64 offset1:72
	ds_read_b128 v[0:3], v20 offset:19472
	ds_read_b128 v[4:7], v20 offset:19456
	ds_read_b128 v[8:11], v20 offset:19216
	ds_read_b128 v[12:15], v20 offset:19200
	ds_read_b128 v[24:27], v20 offset:18960
	ds_read_b128 v[28:31], v20 offset:18944
	ds_read_b128 v[32:35], v20 offset:18704
	ds_read_b128 v[36:39], v20 offset:18688
	ds_read_b128 v[50:53], v20 offset:18432
	ds_read_b128 v[54:57], v20 offset:18448
	v_add_f32_dpp v82, v82, v82 row_half_mirror row_mask:0xf bank_mask:0xf bound_ctrl:1
	v_add_f32_dpp v84, v83, v83 row_half_mirror row_mask:0xf bank_mask:0xf bound_ctrl:1
	s_waitcnt lgkmcnt(14)
; #define SCAN_STEP(w0, w1, a0, a1, b0, b1, k0, k1, r0, r1, vi, vj, t) do { \
;                 SCAN_ROW(S0, S1, S2, S3, w0, w1, a0, a1, b0, b1, k0, k1, r0, r1, vi, (t) * 512); \
;                 SCAN_ROW(T0, T1, T2, T3, w0, w1, a0, a1, b0, b1, k0, k1, r0, r1, vj, (t) * 512 + 256); } while (0)
;     ...
;             SCAN_LOAD(w0, w1, a0, a1, b0, b1, k0, k1, r0, r1, vi, vj, 0);
; #pragma unroll
;             for (int t = 0; t < 16; t += 2) {
;                 SCAN_LOAD(W0, W1, A0, A1, B0, B1, K0, K1, R0, R1, VI, VJ, t + 1);
;                 SCAN_STEP(w0, w1, a0, a1, b0, b1, k0, k1, r0, r1, vi, vj, t);
;                 if (t + 2 < 16) SCAN_LOAD(w0, w1, a0, a1, b0, b1, k0, k1, r0, r1, vi, vj, t + 2);
;                 SCAN_STEP(W0, W1, A0, A1, B0, B1, K0, K1, R0, R1, VI, VJ, t + 1);
;             }
	v_pk_fma_f32 v[66:67], v[42:43], v[82:83], v[66:67] op_sel_hi:[1,0,1]
	v_pk_fma_f32 v[68:69], v[44:45], v[82:83], v[68:69] op_sel_hi:[1,0,1]
	v_pk_fma_f32 v[70:71], v[46:47], v[82:83], v[70:71] op_sel_hi:[1,0,1]
	v_pk_fma_f32 v[40:41], v[42:43], v[84:85], v[40:41] op_sel_hi:[1,0,1]
	v_pk_fma_f32 v[42:43], v[44:45], v[84:85], v[74:75] op_sel_hi:[1,0,1]
	v_pk_fma_f32 v[44:45], v[46:47], v[84:85], v[76:77] op_sel_hi:[1,0,1]
	v_pk_fma_f32 v[72:73], v[48:49], v[82:83], v[72:73] op_sel_hi:[1,0,1]
	v_pk_fma_f32 v[46:47], v[48:49], v[84:85], v[78:79] op_sel_hi:[1,0,1]
	s_waitcnt lgkmcnt(12)
	v_pk_mul_f32 v[48:49], v[58:59], v[66:67]
	v_pk_mul_f32 v[74:75], v[62:63], v[70:71]
	v_pk_mul_f32 v[58:59], v[58:59], v[40:41]
	v_pk_mul_f32 v[62:63], v[62:63], v[44:45]
	v_pk_fma_f32 v[48:49], v[60:61], v[68:69], v[48:49]
	v_pk_fma_f32 v[74:75], v[64:65], v[72:73], v[74:75]
	v_pk_fma_f32 v[58:59], v[60:61], v[42:43], v[58:59]
	v_pk_fma_f32 v[60:61], v[64:65], v[46:47], v[62:63]
	v_pk_add_f32 v[48:49], v[48:49], v[74:75]
	v_pk_add_f32 v[58:59], v[58:59], v[60:61]
	s_waitcnt lgkmcnt(1)
	v_pk_mul_f32 v[60:61], v[36:37], v[66:67]
	v_pk_mul_f32 v[62:63], v[32:33], v[70:71]
	v_pk_mul_f32 v[36:37], v[36:37], v[40:41]
	v_pk_mul_f32 v[32:33], v[32:33], v[44:45]
	v_pk_mul_f32 v[64:65], v[50:51], v[66:67]
	v_pk_mul_f32 v[66:67], v[52:53], v[68:69]
	s_waitcnt lgkmcnt(0)
	v_pk_mul_f32 v[70:71], v[54:55], v[70:71]
	v_pk_mul_f32 v[74:75], v[56:57], v[72:73]
	v_pk_mul_f32 v[40:41], v[50:51], v[40:41]
	v_pk_mul_f32 v[50:51], v[52:53], v[42:43]
	v_pk_mul_f32 v[44:45], v[54:55], v[44:45]
	v_pk_mul_f32 v[52:53], v[56:57], v[46:47]
	v_add_f32_e32 v56, v48, v49
	v_add_f32_e32 v57, v58, v59
	v_pk_fma_f32 v[48:49], v[38:39], v[68:69], v[60:61]
	v_pk_fma_f32 v[54:55], v[34:35], v[72:73], v[62:63]
	v_pk_fma_f32 v[36:37], v[38:39], v[42:43], v[36:37]
	v_pk_fma_f32 v[32:33], v[34:35], v[46:47], v[32:33]
	v_mov_b32_e32 v76, v81
	v_pk_fma_f32 v[64:65], v[80:81], v[12:13], v[64:65] op_sel_hi:[0,1,1]
	v_pk_fma_f32 v[66:67], v[80:81], v[14:15], v[66:67] op_sel_hi:[0,1,1]
	v_pk_fma_f32 v[68:69], v[80:81], v[8:9], v[70:71] op_sel_hi:[0,1,1]
	v_pk_fma_f32 v[70:71], v[80:81], v[10:11], v[74:75] op_sel_hi:[0,1,1]
	ds_write2st64_b32 v19, v56, v57 offset0:88 offset1:92
	v_pk_add_f32 v[80:81], v[54:55], v[48:49]
	v_pk_add_f32 v[82:83], v[32:33], v[36:37]
	v_pk_fma_f32 v[72:73], v[76:77], v[12:13], v[40:41] op_sel_hi:[0,1,1]
	v_pk_fma_f32 v[74:75], v[76:77], v[14:15], v[50:51] op_sel_hi:[0,1,1]
	v_pk_fma_f32 v[78:79], v[76:77], v[8:9], v[44:45] op_sel_hi:[0,1,1]
	v_pk_fma_f32 v[76:77], v[76:77], v[10:11], v[52:53] op_sel_hi:[0,1,1]
	ds_read2_b32 v[84:85], v23 offset0:192 offset1:200
	ds_read_b128 v[32:35], v20 offset:20224
	ds_read_b128 v[36:39], v20 offset:20240
	ds_read_b128 v[8:11], v20 offset:19968
	ds_read_b128 v[12:15], v20 offset:19984
	ds_read_b128 v[48:51], v20 offset:20736
	ds_read_b128 v[52:55], v20 offset:20752
	ds_read_b128 v[40:43], v20 offset:20480
	ds_read_b128 v[44:47], v20 offset:20496
	ds_read_b128 v[56:59], v20 offset:20992
	ds_read_b128 v[60:63], v20 offset:21008
	v_add_f32_e32 v23, v80, v81
	v_add_f32_e32 v80, v82, v83
	v_add_u32_e32 v22, 0x5800, v21
	v_add_f32_dpp v23, v23, v23 quad_perm:[1,0,3,2] row_mask:0xf bank_mask:0xf bound_ctrl:1
	v_add_f32_dpp v80, v80, v80 quad_perm:[1,0,3,2] row_mask:0xf bank_mask:0xf bound_ctrl:1
	s_waitcnt lgkmcnt(10)
	v_mov_b32_e32 v86, v85
	v_add_f32_dpp v23, v23, v23 quad_perm:[2,3,0,1] row_mask:0xf bank_mask:0xf bound_ctrl:1
	v_add_f32_dpp v81, v80, v80 quad_perm:[2,3,0,1] row_mask:0xf bank_mask:0xf bound_ctrl:1
	v_add_u32_e32 v21, 0x5c00, v21
	v_add_f32_dpp v80, v23, v23 row_half_mirror row_mask:0xf bank_mask:0xf bound_ctrl:1
	v_add_f32_dpp v82, v81, v81 row_half_mirror row_mask:0xf bank_mask:0xf bound_ctrl:1
	v_pk_fma_f32 v[64:65], v[28:29], v[80:81], v[64:65] op_sel_hi:[1,0,1]
	v_pk_fma_f32 v[68:69], v[24:25], v[80:81], v[68:69] op_sel_hi:[1,0,1]
	v_pk_fma_f32 v[28:29], v[28:29], v[82:83], v[72:73] op_sel_hi:[1,0,1]
	v_pk_fma_f32 v[24:25], v[24:25], v[82:83], v[78:79] op_sel_hi:[1,0,1]
	v_pk_fma_f32 v[66:67], v[30:31], v[80:81], v[66:67] op_sel_hi:[1,0,1]
	v_pk_fma_f32 v[70:71], v[26:27], v[80:81], v[70:71] op_sel_hi:[1,0,1]
	v_pk_fma_f32 v[30:31], v[30:31], v[82:83], v[74:75] op_sel_hi:[1,0,1]
	v_pk_fma_f32 v[26:27], v[26:27], v[82:83], v[76:77] op_sel_hi:[1,0,1]
	v_pk_mul_f32 v[72:73], v[4:5], v[64:65]
	v_pk_mul_f32 v[74:75], v[0:1], v[68:69]
	v_pk_mul_f32 v[4:5], v[4:5], v[28:29]
	v_pk_mul_f32 v[0:1], v[0:1], v[24:25]
	s_waitcnt lgkmcnt(7)
	v_pk_mul_f32 v[76:77], v[32:33], v[64:65]
	v_pk_mul_f32 v[78:79], v[36:37], v[68:69]
	v_pk_mul_f32 v[32:33], v[32:33], v[28:29]
	v_pk_mul_f32 v[36:37], v[36:37], v[24:25]
	v_pk_mul_f32 v[64:65], v[8:9], v[64:65]
	v_pk_mul_f32 v[80:81], v[10:11], v[66:67]
	s_waitcnt lgkmcnt(6)
	v_pk_mul_f32 v[68:69], v[12:13], v[68:69]
	v_pk_mul_f32 v[82:83], v[14:15], v[70:71]
	v_pk_mul_f32 v[8:9], v[8:9], v[28:29]
	v_pk_mul_f32 v[10:11], v[10:11], v[30:31]
	v_pk_mul_f32 v[12:13], v[12:13], v[24:25]
	v_pk_mul_f32 v[14:15], v[14:15], v[26:27]
	v_pk_fma_f32 v[24:25], v[6:7], v[66:67], v[72:73]
	v_pk_fma_f32 v[28:29], v[2:3], v[70:71], v[74:75]
	v_pk_fma_f32 v[4:5], v[6:7], v[30:31], v[4:5]
	v_pk_fma_f32 v[0:1], v[2:3], v[26:27], v[0:1]
	v_pk_fma_f32 v[2:3], v[34:35], v[66:67], v[76:77]
	v_pk_fma_f32 v[6:7], v[38:39], v[70:71], v[78:79]
	v_pk_fma_f32 v[30:31], v[34:35], v[30:31], v[32:33]
	v_pk_fma_f32 v[26:27], v[38:39], v[26:27], v[36:37]
	v_pk_add_f32 v[0:1], v[4:5], v[0:1]
	v_pk_add_f32 v[2:3], v[2:3], v[6:7]
	v_pk_add_f32 v[4:5], v[30:31], v[26:27]
	s_waitcnt lgkmcnt(5)
; #define SCAN_STEP(w0, w1, a0, a1, b0, b1, k0, k1, r0, r1, vi, vj, t) do { \
;                 SCAN_ROW(S0, S1, S2, S3, w0, w1, a0, a1, b0, b1, k0, k1, r0, r1, vi, (t) * 512); \
;                 SCAN_ROW(T0, T1, T2, T3, w0, w1, a0, a1, b0, b1, k0, k1, r0, r1, vj, (t) * 512 + 256); } while (0)
;     ...
;             SCAN_LOAD(w0, w1, a0, a1, b0, b1, k0, k1, r0, r1, vi, vj, 0);
; #pragma unroll
;             for (int t = 0; t < 16; t += 2) {
;                 SCAN_LOAD(W0, W1, A0, A1, B0, B1, K0, K1, R0, R1, VI, VJ, t + 1);
;                 SCAN_STEP(w0, w1, a0, a1, b0, b1, k0, k1, r0, r1, vi, vj, t);
;                 if (t + 2 < 16) SCAN_LOAD(w0, w1, a0, a1, b0, b1, k0, k1, r0, r1, vi, vj, t + 2);
;                 SCAN_STEP(W0, W1, A0, A1, B0, B1, K0, K1, R0, R1, VI, VJ, t + 1);
;             }
	v_pk_fma_f32 v[38:39], v[48:49], v[86:87], v[8:9] op_sel_hi:[1,0,1]
	v_pk_add_f32 v[8:9], v[24:25], v[28:29]
	v_add_f32_e32 v0, v0, v1
	v_add_f32_e32 v1, v2, v3
	v_add_f32_e32 v2, v4, v5
	v_pk_fma_f32 v[66:67], v[50:51], v[84:85], v[80:81] op_sel_hi:[1,0,1]
	v_add_f32_e32 v6, v8, v9
	v_add_f32_dpp v80, v1, v1 quad_perm:[1,0,3,2] row_mask:0xf bank_mask:0xf bound_ctrl:1
	v_add_f32_dpp v81, v2, v2 quad_perm:[1,0,3,2] row_mask:0xf bank_mask:0xf bound_ctrl:1
	ds_write2st64_b32 v19, v6, v0 offset0:96 offset1:100
	v_add_f32_dpp v80, v80, v80 quad_perm:[2,3,0,1] row_mask:0xf bank_mask:0xf bound_ctrl:1
	v_add_f32_dpp v81, v81, v81 quad_perm:[2,3,0,1] row_mask:0xf bank_mask:0xf bound_ctrl:1
	v_pk_fma_f32 v[64:65], v[48:49], v[84:85], v[64:65] op_sel_hi:[1,0,1]
	s_waitcnt lgkmcnt(5)
	v_pk_fma_f32 v[68:69], v[52:53], v[84:85], v[68:69] op_sel_hi:[1,0,1]
	v_pk_fma_f32 v[70:71], v[54:55], v[84:85], v[82:83] op_sel_hi:[1,0,1]
	v_pk_fma_f32 v[72:73], v[50:51], v[86:87], v[10:11] op_sel_hi:[1,0,1]
	v_pk_fma_f32 v[74:75], v[52:53], v[86:87], v[12:13] op_sel_hi:[1,0,1]
	v_pk_fma_f32 v[76:77], v[54:55], v[86:87], v[14:15] op_sel_hi:[1,0,1]
	ds_read2_b32 v[78:79], v22 offset0:64 offset1:72
	ds_read_b128 v[0:3], v20 offset:22544
	ds_read_b128 v[4:7], v20 offset:22528
	ds_read_b128 v[8:11], v20 offset:22288
	ds_read_b128 v[12:15], v20 offset:22272
	ds_read_b128 v[22:25], v20 offset:22032
	ds_read_b128 v[26:29], v20 offset:22016
	ds_read_b128 v[30:33], v20 offset:21776
	ds_read_b128 v[34:37], v20 offset:21760
	ds_read_b128 v[48:51], v20 offset:21504
	ds_read_b128 v[52:55], v20 offset:21520
	v_add_f32_dpp v80, v80, v80 row_half_mirror row_mask:0xf bank_mask:0xf bound_ctrl:1
	v_add_f32_dpp v82, v81, v81 row_half_mirror row_mask:0xf bank_mask:0xf bound_ctrl:1
	s_waitcnt lgkmcnt(14)
	v_pk_fma_f32 v[64:65], v[40:41], v[80:81], v[64:65] op_sel_hi:[1,0,1]
	v_pk_fma_f32 v[66:67], v[42:43], v[80:81], v[66:67] op_sel_hi:[1,0,1]
	v_pk_fma_f32 v[68:69], v[44:45], v[80:81], v[68:69] op_sel_hi:[1,0,1]
	v_pk_fma_f32 v[38:39], v[40:41], v[82:83], v[38:39] op_sel_hi:[1,0,1]
	v_pk_fma_f32 v[40:41], v[42:43], v[82:83], v[72:73] op_sel_hi:[1,0,1]
	v_pk_fma_f32 v[42:43], v[44:45], v[82:83], v[74:75] op_sel_hi:[1,0,1]
	v_pk_fma_f32 v[70:71], v[46:47], v[80:81], v[70:71] op_sel_hi:[1,0,1]
	v_pk_fma_f32 v[44:45], v[46:47], v[82:83], v[76:77] op_sel_hi:[1,0,1]
	s_waitcnt lgkmcnt(12)
	v_pk_mul_f32 v[46:47], v[56:57], v[64:65]
	v_pk_mul_f32 v[72:73], v[60:61], v[68:69]
	v_pk_mul_f32 v[56:57], v[56:57], v[38:39]
	v_pk_mul_f32 v[60:61], v[60:61], v[42:43]
	v_pk_fma_f32 v[46:47], v[58:59], v[66:67], v[46:47]
	v_pk_fma_f32 v[72:73], v[62:63], v[70:71], v[72:73]
	v_pk_fma_f32 v[56:57], v[58:59], v[40:41], v[56:57]
	v_pk_fma_f32 v[58:59], v[62:63], v[44:45], v[60:61]
	v_pk_add_f32 v[46:47], v[46:47], v[72:73]
	v_pk_add_f32 v[56:57], v[56:57], v[58:59]
	s_waitcnt lgkmcnt(1)
	v_pk_mul_f32 v[58:59], v[34:35], v[64:65]
	v_pk_mul_f32 v[60:61], v[30:31], v[68:69]
	v_pk_mul_f32 v[34:35], v[34:35], v[38:39]
	v_pk_mul_f32 v[30:31], v[30:31], v[42:43]
	v_pk_mul_f32 v[62:63], v[48:49], v[64:65]
	v_pk_mul_f32 v[64:65], v[50:51], v[66:67]
	s_waitcnt lgkmcnt(0)
	v_pk_mul_f32 v[68:69], v[52:53], v[68:69]
	v_pk_mul_f32 v[72:73], v[54:55], v[70:71]
	v_pk_mul_f32 v[38:39], v[48:49], v[38:39]
	v_pk_mul_f32 v[48:49], v[50:51], v[40:41]
	v_pk_mul_f32 v[42:43], v[52:53], v[42:43]
	v_pk_mul_f32 v[50:51], v[54:55], v[44:45]
	v_add_f32_e32 v54, v46, v47
	v_pk_fma_f32 v[46:47], v[36:37], v[66:67], v[58:59]
	v_pk_fma_f32 v[52:53], v[32:33], v[70:71], v[60:61]
	v_pk_fma_f32 v[34:35], v[36:37], v[40:41], v[34:35]
	v_pk_fma_f32 v[30:31], v[32:33], v[44:45], v[30:31]
	v_mov_b32_e32 v74, v79
	v_add_f32_e32 v55, v56, v57
	v_pk_fma_f32 v[62:63], v[78:79], v[12:13], v[62:63] op_sel_hi:[0,1,1]
	v_pk_fma_f32 v[64:65], v[78:79], v[14:15], v[64:65] op_sel_hi:[0,1,1]
	v_pk_fma_f32 v[66:67], v[78:79], v[8:9], v[68:69] op_sel_hi:[0,1,1]
	v_pk_fma_f32 v[68:69], v[78:79], v[10:11], v[72:73] op_sel_hi:[0,1,1]
	v_pk_add_f32 v[78:79], v[52:53], v[46:47]
	v_pk_add_f32 v[80:81], v[30:31], v[34:35]
	ds_write2st64_b32 v19, v54, v55 offset0:104 offset1:108
	v_add_f32_e32 v78, v78, v79
	v_add_f32_e32 v79, v80, v81
	v_pk_fma_f32 v[70:71], v[74:75], v[12:13], v[38:39] op_sel_hi:[0,1,1]
	v_pk_fma_f32 v[72:73], v[74:75], v[14:15], v[48:49] op_sel_hi:[0,1,1]
	v_pk_fma_f32 v[76:77], v[74:75], v[8:9], v[42:43] op_sel_hi:[0,1,1]
	v_pk_fma_f32 v[74:75], v[74:75], v[10:11], v[50:51] op_sel_hi:[0,1,1]
	ds_read_b128 v[8:11], v20 offset:23040
	ds_read_b128 v[12:15], v20 offset:23056
	ds_read_b128 v[30:33], v20 offset:23296
	ds_read_b128 v[34:37], v20 offset:23312
	ds_read_b128 v[38:41], v20 offset:23552
	ds_read_b128 v[42:45], v20 offset:23568
	ds_read_b128 v[46:49], v20 offset:23808
	ds_read_b128 v[50:53], v20 offset:23824
	ds_read_b128 v[54:57], v20 offset:24064
	ds_read_b128 v[58:61], v20 offset:24080
	ds_read2_b32 v[20:21], v21 offset0:192 offset1:200
	v_add_f32_dpp v78, v78, v78 quad_perm:[1,0,3,2] row_mask:0xf bank_mask:0xf bound_ctrl:1
	v_add_f32_dpp v79, v79, v79 quad_perm:[1,0,3,2] row_mask:0xf bank_mask:0xf bound_ctrl:1
	s_add_i32 s3, s3, 1
	v_add_f32_dpp v78, v78, v78 quad_perm:[2,3,0,1] row_mask:0xf bank_mask:0xf bound_ctrl:1
	v_add_f32_dpp v79, v79, v79 quad_perm:[2,3,0,1] row_mask:0xf bank_mask:0xf bound_ctrl:1
	s_waitcnt lgkmcnt(0)
; #define SCAN_STEP(w0, w1, a0, a1, b0, b1, k0, k1, r0, r1, vi, vj, t) do { \
;                 SCAN_ROW(S0, S1, S2, S3, w0, w1, a0, a1, b0, b1, k0, k1, r0, r1, vi, (t) * 512); \
;                 SCAN_ROW(T0, T1, T2, T3, w0, w1, a0, a1, b0, b1, k0, k1, r0, r1, vj, (t) * 512 + 256); } while (0)
;     ...
;             SCAN_LOAD(w0, w1, a0, a1, b0, b1, k0, k1, r0, r1, vi, vj, 0);
; #pragma unroll
;             for (int t = 0; t < 16; t += 2) {
;                 SCAN_LOAD(W0, W1, A0, A1, B0, B1, K0, K1, R0, R1, VI, VJ, t + 1);
;                 SCAN_STEP(w0, w1, a0, a1, b0, b1, k0, k1, r0, r1, vi, vj, t);
;                 if (t + 2 < 16) SCAN_LOAD(w0, w1, a0, a1, b0, b1, k0, k1, r0, r1, vi, vj, t + 2);
;                 SCAN_STEP(W0, W1, A0, A1, B0, B1, K0, K1, R0, R1, VI, VJ, t + 1);
;             }
;     ...
;             __syncthreads();
;         }
;         float* so = P.out + (samp ? O_RS + ((size_t)(l * 16 + b) * 16 + h) * 4096 : O_RP + ((size_t)(l * 4 + b) * 16 + h) * 4096) + js;
;         f32x4 o0, o1; o0.xy = S0; o0.zw = S1; o1.xy = S2; o1.zw = S3;
;         *(f32x4*)(so + i0 * 64) = o0; *(f32x4*)(so + i0 * 64 + 4) = o1;
;         o0.xy = T0; o0.zw = T1; o1.xy = T2; o1.zw = T3;
;         *(f32x4*)(so + i1 * 64) = o0; *(f32x4*)(so + i1 * 64 + 4) = o1;
	v_mov_b32_e32 v82, v21
	v_add_f32_dpp v78, v78, v78 row_half_mirror row_mask:0xf bank_mask:0xf bound_ctrl:1
	v_add_f32_dpp v80, v79, v79 row_half_mirror row_mask:0xf bank_mask:0xf bound_ctrl:1
	v_pk_fma_f32 v[62:63], v[26:27], v[78:79], v[62:63] op_sel_hi:[1,0,1]
	v_pk_fma_f32 v[66:67], v[22:23], v[78:79], v[66:67] op_sel_hi:[1,0,1]
	v_pk_fma_f32 v[26:27], v[26:27], v[80:81], v[70:71] op_sel_hi:[1,0,1]
	v_pk_fma_f32 v[22:23], v[22:23], v[80:81], v[76:77] op_sel_hi:[1,0,1]
	v_pk_fma_f32 v[64:65], v[28:29], v[78:79], v[64:65] op_sel_hi:[1,0,1]
	v_pk_fma_f32 v[68:69], v[24:25], v[78:79], v[68:69] op_sel_hi:[1,0,1]
	v_pk_fma_f32 v[28:29], v[28:29], v[80:81], v[72:73] op_sel_hi:[1,0,1]
	v_pk_fma_f32 v[24:25], v[24:25], v[80:81], v[74:75] op_sel_hi:[1,0,1]
	v_pk_mul_f32 v[70:71], v[4:5], v[62:63]
	v_pk_mul_f32 v[72:73], v[0:1], v[66:67]
	v_pk_mul_f32 v[4:5], v[4:5], v[26:27]
	v_pk_mul_f32 v[0:1], v[0:1], v[22:23]
	v_pk_mul_f32 v[74:75], v[30:31], v[62:63]
	v_pk_mul_f32 v[76:77], v[34:35], v[66:67]
	v_pk_mul_f32 v[30:31], v[30:31], v[26:27]
	v_pk_mul_f32 v[34:35], v[34:35], v[22:23]
	v_pk_mul_f32 v[62:63], v[8:9], v[62:63]
	v_pk_mul_f32 v[78:79], v[10:11], v[64:65]
	v_pk_mul_f32 v[66:67], v[12:13], v[66:67]
	v_pk_mul_f32 v[80:81], v[14:15], v[68:69]
	v_pk_mul_f32 v[8:9], v[8:9], v[26:27]
	v_pk_mul_f32 v[10:11], v[10:11], v[28:29]
	v_pk_mul_f32 v[12:13], v[12:13], v[22:23]
	v_pk_mul_f32 v[14:15], v[14:15], v[24:25]
	v_pk_fma_f32 v[22:23], v[6:7], v[64:65], v[70:71]
	v_pk_fma_f32 v[26:27], v[2:3], v[68:69], v[72:73]
	v_pk_fma_f32 v[4:5], v[6:7], v[28:29], v[4:5]
	v_pk_fma_f32 v[0:1], v[2:3], v[24:25], v[0:1]
	v_pk_fma_f32 v[2:3], v[32:33], v[64:65], v[74:75]
	v_pk_fma_f32 v[6:7], v[36:37], v[68:69], v[76:77]
	v_pk_fma_f32 v[28:29], v[32:33], v[28:29], v[30:31]
	v_pk_fma_f32 v[24:25], v[36:37], v[24:25], v[34:35]
	v_pk_fma_f32 v[30:31], v[46:47], v[82:83], v[8:9] op_sel_hi:[1,0,1]
	v_pk_add_f32 v[8:9], v[22:23], v[26:27]
	v_pk_add_f32 v[0:1], v[4:5], v[0:1]
	v_pk_add_f32 v[2:3], v[2:3], v[6:7]
	v_pk_add_f32 v[4:5], v[28:29], v[24:25]
	v_add_f32_e32 v6, v8, v9
	v_add_f32_e32 v0, v0, v1
	v_add_f32_e32 v1, v2, v3
	v_add_f32_e32 v2, v4, v5
	ds_write2st64_b32 v19, v6, v0 offset0:112 offset1:116
	v_add_f32_dpp v0, v1, v1 quad_perm:[1,0,3,2] row_mask:0xf bank_mask:0xf bound_ctrl:1
	v_add_f32_dpp v1, v2, v2 quad_perm:[1,0,3,2] row_mask:0xf bank_mask:0xf bound_ctrl:1
	v_pk_fma_f32 v[62:63], v[46:47], v[20:21], v[62:63] op_sel_hi:[1,0,1]
	v_add_f32_dpp v0, v0, v0 quad_perm:[2,3,0,1] row_mask:0xf bank_mask:0xf bound_ctrl:1
	v_add_f32_dpp v1, v1, v1 quad_perm:[2,3,0,1] row_mask:0xf bank_mask:0xf bound_ctrl:1
	v_pk_fma_f32 v[64:65], v[48:49], v[20:21], v[78:79] op_sel_hi:[1,0,1]
	v_pk_fma_f32 v[66:67], v[50:51], v[20:21], v[66:67] op_sel_hi:[1,0,1]
	v_pk_fma_f32 v[20:21], v[52:53], v[20:21], v[80:81] op_sel_hi:[1,0,1]
	v_pk_fma_f32 v[34:35], v[50:51], v[82:83], v[12:13] op_sel_hi:[1,0,1]
	v_add_f32_dpp v0, v0, v0 row_half_mirror row_mask:0xf bank_mask:0xf bound_ctrl:1
	v_add_f32_dpp v2, v1, v1 row_half_mirror row_mask:0xf bank_mask:0xf bound_ctrl:1
	v_pk_fma_f32 v[32:33], v[48:49], v[82:83], v[10:11] op_sel_hi:[1,0,1]
	v_pk_fma_f32 v[36:37], v[52:53], v[82:83], v[14:15] op_sel_hi:[1,0,1]
	v_pk_fma_f32 v[8:9], v[38:39], v[0:1], v[62:63] op_sel_hi:[1,0,1]
	v_pk_fma_f32 v[10:11], v[40:41], v[0:1], v[64:65] op_sel_hi:[1,0,1]
	v_pk_fma_f32 v[12:13], v[42:43], v[0:1], v[66:67] op_sel_hi:[1,0,1]
	v_pk_fma_f32 v[14:15], v[44:45], v[0:1], v[20:21] op_sel_hi:[1,0,1]
	v_pk_fma_f32 v[4:5], v[38:39], v[2:3], v[30:31] op_sel_hi:[1,0,1]
	v_pk_fma_f32 v[0:1], v[42:43], v[2:3], v[34:35] op_sel_hi:[1,0,1]
	v_pk_fma_f32 v[6:7], v[40:41], v[2:3], v[32:33] op_sel_hi:[1,0,1]
	v_pk_fma_f32 v[2:3], v[44:45], v[2:3], v[36:37] op_sel_hi:[1,0,1]
	v_pk_mul_f32 v[20:21], v[54:55], v[8:9]
	v_pk_mul_f32 v[22:23], v[58:59], v[12:13]
	v_pk_mul_f32 v[24:25], v[54:55], v[4:5]
	v_pk_mul_f32 v[26:27], v[58:59], v[0:1]
	v_pk_fma_f32 v[20:21], v[56:57], v[10:11], v[20:21]
	v_pk_fma_f32 v[22:23], v[60:61], v[14:15], v[22:23]
	v_pk_fma_f32 v[24:25], v[56:57], v[6:7], v[24:25]
	v_pk_fma_f32 v[26:27], v[60:61], v[2:3], v[26:27]
	v_pk_add_f32 v[20:21], v[20:21], v[22:23]
	v_pk_add_f32 v[22:23], v[24:25], v[26:27]
	s_cmpk_eq_i32 s3, 0xc8
	v_add_f32_e32 v20, v20, v21
	v_add_f32_e32 v21, v22, v23
	ds_write2st64_b32 v19, v20, v21 offset0:120 offset1:124
	s_waitcnt lgkmcnt(0)
	s_barrier
	s_cbranch_scc0 .LBB0_3706
	s_lshl_b64 s[4:5], s[8:9], 18
	s_add_u32 s3, s72, s4
	s_addc_u32 s4, s73, s5
	s_lshl_b32 s2, s2, 14
	s_add_u32 s2, s3, s2
	s_addc_u32 s3, s4, 0
	v_lshlrev_b32_e32 v18, 2, v17
	v_mov_b32_e32 v19, 0
	v_lshlrev_b32_e32 v16, 6, v16
	v_lshl_add_u64 v[18:19], s[2:3], 0, v[18:19]
	v_ashrrev_i32_e32 v17, 31, v16
	v_lshl_add_u64 v[16:17], v[16:17], 2, v[18:19]
	s_mov_b64 s[2:3], 0x8600000
	v_lshl_add_u64 v[18:19], v[16:17], 0, s[2:3]
	s_mov_b32 s2, 0x8600000
	v_add_co_u32_e32 v16, vcc, s2, v16
	s_nop 1
	v_addc_co_u32_e32 v17, vcc, 0, v17, vcc
	global_store_dwordx4 v[16:17], v[8:11], off
	global_store_dwordx4 v[18:19], v[12:15], off offset:16
	global_store_dwordx4 v[18:19], v[4:7], off offset:2048
	global_store_dwordx4 v[18:19], v[0:3], off offset:2064

; #define SCAN_STEP(w0, w1, a0, a1, b0, b1, k0, k1, r0, r1, vi, vj, t) do { \
;                 SCAN_ROW(S0, S1, S2, S3, w0, w1, a0, a1, b0, b1, k0, k1, r0, r1, vi, (t) * 512); \
;                 SCAN_ROW(T0, T1, T2, T3, w0, w1, a0, a1, b0, b1, k0, k1, r0, r1, vj, (t) * 512 + 256); } while (0)
;     ...
;         for (int c = c0; c < nch; ++c) {
;             const float* bb = bufs + (c & 1) * (16 * 384) + js;
;             const float* bv = bufs + (c & 1) * (16 * 384) + 320 + i0;
;             float* yb = ybuf + (c & 1) * 8192 + w * 64 + lane;
;             f32x4 w0, w1, a0, a1, b0, b1, k0, k1, r0, r1; float vi, vj;
;             f32x4 W0, W1, A0, A1, B0, B1, K0, K1, R0, R1; float VI, VJ;
;     ...
;             SCAN_LOAD(w0, w1, a0, a1, b0, b1, k0, k1, r0, r1, vi, vj, 0);
; #pragma unroll
;             for (int t = 0; t < 16; t += 2) {
;                 SCAN_LOAD(W0, W1, A0, A1, B0, B1, K0, K1, R0, R1, VI, VJ, t + 1);
;                 SCAN_STEP(w0, w1, a0, a1, b0, b1, k0, k1, r0, r1, vi, vj, t);
;                 if (t + 2 < 16) SCAN_LOAD(w0, w1, a0, a1, b0, b1, k0, k1, r0, r1, vi, vj, t + 2);
;                 SCAN_STEP(W0, W1, A0, A1, B0, B1, K0, K1, R0, R1, VI, VJ, t + 1);
;             }
.LBB0_4119:
	s_and_b32 s8, s7, 1
	s_mul_i32 s4, s8, 0x6000
	s_add_i32 s4, s4, 0
	v_lshl_add_u32 v23, v17, 2, s4
	v_lshl_add_u32 v22, v16, 2, s4
	v_add_u32_e32 v31, 0x400, v23
	v_add_u32_e32 v114, 0x800, v23
	ds_read_b128 v[40:43], v22 offset:256
	ds_read_b128 v[44:47], v22 offset:272
	ds_read_b128 v[56:59], v22 offset:768
	ds_read2_b32 v[112:113], v31 offset0:64 offset1:72
	ds_read_b128 v[60:63], v22 offset:784
	ds_read_b128 v[32:35], v22
	ds_read_b128 v[36:39], v22 offset:16
	ds_read_b128 v[48:51], v22 offset:512
	ds_read_b128 v[52:55], v22 offset:528
	ds_read_b128 v[64:67], v22 offset:1024
	ds_read_b128 v[68:71], v22 offset:1040
	ds_read_b128 v[80:83], v22 offset:1792
	ds_read_b128 v[84:87], v22 offset:1808
	s_waitcnt vmcnt(8)
	ds_read2_b32 v[114:115], v114 offset0:192 offset1:200
	s_waitcnt vmcnt(7)
	ds_read_b128 v[72:75], v22 offset:1536
	s_waitcnt vmcnt(6)
	ds_read_b128 v[76:79], v22 offset:1552
	ds_read_b128 v[100:103], v22 offset:2320
	ds_read_b128 v[96:99], v22 offset:2304
	ds_read_b128 v[88:91], v22 offset:2048
	ds_read_b128 v[92:95], v22 offset:2064
	ds_read_b128 v[104:107], v22 offset:2560
	ds_read_b128 v[108:111], v22 offset:2576
	s_waitcnt vmcnt(1)
	s_waitcnt lgkmcnt(14)
	v_pk_mul_f32 v[116:117], v[12:13], v[40:41]
	v_pk_mul_f32 v[118:119], v[8:9], v[44:45]
	v_pk_mul_f32 v[40:41], v[0:1], v[40:41]
	s_waitcnt vmcnt(0)
	v_pk_mul_f32 v[44:45], v[4:5], v[44:45]
	v_pk_fma_f32 v[116:117], v[14:15], v[42:43], v[116:117]
	v_pk_fma_f32 v[118:119], v[10:11], v[46:47], v[118:119]
	v_pk_mul_f32 v[120:121], v[56:57], v[112:113] op_sel_hi:[1,0]
	v_pk_mul_f32 v[122:123], v[58:59], v[112:113] op_sel_hi:[1,0]
	v_pk_mul_f32 v[124:125], v[60:61], v[112:113] op_sel_hi:[1,0]
	v_pk_mul_f32 v[126:127], v[62:63], v[112:113] op_sel_hi:[1,0]
	v_mov_b32_e32 v112, v113
	v_pk_fma_f32 v[40:41], v[2:3], v[42:43], v[40:41]
	v_pk_fma_f32 v[42:43], v[6:7], v[46:47], v[44:45]
	v_pk_add_f32 v[46:47], v[116:117], v[118:119]
	v_pk_mul_f32 v[56:57], v[56:57], v[112:113] op_sel_hi:[1,0]
	v_pk_add_f32 v[40:41], v[40:41], v[42:43]
	v_pk_fma_f32 v[12:13], v[12:13], v[32:33], v[120:121]
	v_add_f32_e32 v31, v46, v47
	v_pk_fma_f32 v[0:1], v[0:1], v[32:33], v[56:57]
	v_add_f32_e32 v32, v40, v41
	v_add_f32_dpp v31, v31, v31 quad_perm:[1,0,3,2] row_mask:0xf bank_mask:0xf bound_ctrl:1
	v_pk_mul_f32 v[58:59], v[58:59], v[112:113] op_sel_hi:[1,0]
	v_add_f32_dpp v32, v32, v32 quad_perm:[1,0,3,2] row_mask:0xf bank_mask:0xf bound_ctrl:1
	v_pk_mul_f32 v[60:61], v[60:61], v[112:113] op_sel_hi:[1,0]
	v_add_f32_dpp v31, v31, v31 quad_perm:[2,3,0,1] row_mask:0xf bank_mask:0xf bound_ctrl:1
	v_add_f32_dpp v33, v32, v32 quad_perm:[2,3,0,1] row_mask:0xf bank_mask:0xf bound_ctrl:1
	v_pk_fma_f32 v[14:15], v[14:15], v[34:35], v[122:123]
	v_pk_fma_f32 v[8:9], v[8:9], v[36:37], v[124:125]
	v_pk_mul_f32 v[62:63], v[62:63], v[112:113] op_sel_hi:[1,0]
	v_pk_fma_f32 v[2:3], v[2:3], v[34:35], v[58:59]
	v_pk_fma_f32 v[4:5], v[4:5], v[36:37], v[60:61]
	v_add_f32_dpp v32, v31, v31 row_half_mirror row_mask:0xf bank_mask:0xf bound_ctrl:1
	v_add_f32_dpp v34, v33, v33 row_half_mirror row_mask:0xf bank_mask:0xf bound_ctrl:1
	v_pk_fma_f32 v[10:11], v[10:11], v[38:39], v[126:127]
	v_pk_fma_f32 v[6:7], v[6:7], v[38:39], v[62:63]
	v_pk_fma_f32 v[12:13], v[48:49], v[32:33], v[12:13] op_sel_hi:[1,0,1]
	s_waitcnt lgkmcnt(13)
	v_pk_fma_f32 v[8:9], v[52:53], v[32:33], v[8:9] op_sel_hi:[1,0,1]
	v_pk_fma_f32 v[0:1], v[48:49], v[34:35], v[0:1] op_sel_hi:[1,0,1]
	v_pk_fma_f32 v[4:5], v[52:53], v[34:35], v[4:5] op_sel_hi:[1,0,1]
	v_pk_fma_f32 v[14:15], v[50:51], v[32:33], v[14:15] op_sel_hi:[1,0,1]
	v_pk_fma_f32 v[10:11], v[54:55], v[32:33], v[10:11] op_sel_hi:[1,0,1]
	v_pk_fma_f32 v[2:3], v[50:51], v[34:35], v[2:3] op_sel_hi:[1,0,1]
	v_pk_fma_f32 v[6:7], v[54:55], v[34:35], v[6:7] op_sel_hi:[1,0,1]
	s_waitcnt lgkmcnt(10)
	v_pk_mul_f32 v[32:33], v[64:65], v[12:13]
	v_pk_mul_f32 v[34:35], v[68:69], v[8:9]
	v_pk_mul_f32 v[36:37], v[64:65], v[0:1]
	v_pk_mul_f32 v[38:39], v[68:69], v[4:5]
	v_pk_mul_f32 v[40:41], v[80:81], v[12:13]
	s_waitcnt lgkmcnt(7)
	v_pk_mul_f32 v[42:43], v[84:85], v[8:9]
	v_pk_mul_f32 v[50:51], v[80:81], v[0:1]
	v_pk_mul_f32 v[52:53], v[84:85], v[4:5]
	v_mov_b32_e32 v44, v115
	v_pk_mul_f32 v[46:47], v[74:75], v[14:15]
	s_waitcnt lgkmcnt(6)
	v_pk_mul_f32 v[8:9], v[76:77], v[8:9]
	v_pk_mul_f32 v[48:49], v[78:79], v[10:11]
	v_pk_mul_f32 v[0:1], v[72:73], v[0:1]
	v_pk_mul_f32 v[54:55], v[74:75], v[2:3]
	v_pk_mul_f32 v[4:5], v[76:77], v[4:5]
	v_pk_mul_f32 v[56:57], v[78:79], v[6:7]
	v_pk_fma_f32 v[32:33], v[66:67], v[14:15], v[32:33]
	v_pk_fma_f32 v[34:35], v[70:71], v[10:11], v[34:35]
	v_pk_fma_f32 v[36:37], v[66:67], v[2:3], v[36:37]
	v_pk_fma_f32 v[38:39], v[70:71], v[6:7], v[38:39]
	v_pk_fma_f32 v[14:15], v[82:83], v[14:15], v[40:41]
	v_pk_fma_f32 v[10:11], v[86:87], v[10:11], v[42:43]
	v_pk_fma_f32 v[2:3], v[82:83], v[2:3], v[50:51]
	v_pk_fma_f32 v[6:7], v[86:87], v[6:7], v[52:53]
	s_waitcnt lgkmcnt(4)
; #define SCAN_STEP(w0, w1, a0, a1, b0, b1, k0, k1, r0, r1, vi, vj, t) do { \
;                 SCAN_ROW(S0, S1, S2, S3, w0, w1, a0, a1, b0, b1, k0, k1, r0, r1, vi, (t) * 512); \
;                 SCAN_ROW(T0, T1, T2, T3, w0, w1, a0, a1, b0, b1, k0, k1, r0, r1, vj, (t) * 512 + 256); } while (0)
;     ...
;             SCAN_LOAD(w0, w1, a0, a1, b0, b1, k0, k1, r0, r1, vi, vj, 0);
; #pragma unroll
;             for (int t = 0; t < 16; t += 2) {
;                 SCAN_LOAD(W0, W1, A0, A1, B0, B1, K0, K1, R0, R1, VI, VJ, t + 1);
;                 SCAN_STEP(w0, w1, a0, a1, b0, b1, k0, k1, r0, r1, vi, vj, t);
;                 if (t + 2 < 16) SCAN_LOAD(w0, w1, a0, a1, b0, b1, k0, k1, r0, r1, vi, vj, t + 2);
;                 SCAN_STEP(W0, W1, A0, A1, B0, B1, K0, K1, R0, R1, VI, VJ, t + 1);
;             }
	v_pk_fma_f32 v[62:63], v[100:101], v[114:115], v[8:9] op_sel_hi:[1,0,1]
	v_pk_fma_f32 v[66:67], v[96:97], v[44:45], v[0:1] op_sel_hi:[1,0,1]
	v_pk_fma_f32 v[70:71], v[100:101], v[44:45], v[4:5] op_sel_hi:[1,0,1]
	v_pk_add_f32 v[0:1], v[32:33], v[34:35]
	v_pk_add_f32 v[4:5], v[36:37], v[38:39]
	v_pk_add_f32 v[8:9], v[14:15], v[10:11]
	v_pk_add_f32 v[2:3], v[2:3], v[6:7]
	v_add_f32_e32 v0, v0, v1
	v_add_f32_e32 v1, v4, v5
	v_add_f32_e32 v4, v8, v9
	v_add_f32_e32 v2, v2, v3
	v_lshl_add_u32 v29, s8, 15, v20
	v_add_f32_dpp v31, v4, v4 quad_perm:[1,0,3,2] row_mask:0xf bank_mask:0xf bound_ctrl:1
	v_add_f32_dpp v74, v2, v2 quad_perm:[1,0,3,2] row_mask:0xf bank_mask:0xf bound_ctrl:1
	v_add_u32_e32 v128, 0x1000, v23
	v_pk_mul_f32 v[12:13], v[72:73], v[12:13]
	ds_write2st64_b32 v29, v0, v1 offset0:192 offset1:196
	v_add_f32_dpp v31, v31, v31 quad_perm:[2,3,0,1] row_mask:0xf bank_mask:0xf bound_ctrl:1
	v_add_f32_dpp v75, v74, v74 quad_perm:[2,3,0,1] row_mask:0xf bank_mask:0xf bound_ctrl:1
	v_pk_fma_f32 v[58:59], v[96:97], v[114:115], v[12:13] op_sel_hi:[1,0,1]
	v_pk_fma_f32 v[60:61], v[98:99], v[114:115], v[46:47] op_sel_hi:[1,0,1]
	v_pk_fma_f32 v[64:65], v[102:103], v[114:115], v[48:49] op_sel_hi:[1,0,1]
	v_pk_fma_f32 v[68:69], v[98:99], v[44:45], v[54:55] op_sel_hi:[1,0,1]
	v_pk_fma_f32 v[56:57], v[102:103], v[44:45], v[56:57] op_sel_hi:[1,0,1]
	ds_read_b128 v[44:47], v22 offset:3328
	ds_read_b128 v[40:43], v22 offset:3344
	ds_read_b128 v[48:51], v22 offset:3072
	ds_read_b128 v[52:55], v22 offset:3088
	ds_read2_b32 v[72:73], v128 offset0:64 offset1:72
	ds_read_b128 v[12:15], v22 offset:3840
	ds_read_b128 v[8:11], v22 offset:3856
	ds_read_b128 v[36:39], v22 offset:3584
	ds_read_b128 v[32:35], v22 offset:3600
	ds_read_b128 v[4:7], v22 offset:4096
	ds_read_b128 v[0:3], v22 offset:4112
	v_add_f32_dpp v74, v31, v31 row_half_mirror row_mask:0xf bank_mask:0xf bound_ctrl:1
	v_add_f32_dpp v76, v75, v75 row_half_mirror row_mask:0xf bank_mask:0xf bound_ctrl:1
	s_waitcnt lgkmcnt(14)
	v_pk_fma_f32 v[58:59], v[88:89], v[74:75], v[58:59] op_sel_hi:[1,0,1]
	v_pk_fma_f32 v[62:63], v[92:93], v[74:75], v[62:63] op_sel_hi:[1,0,1]
	v_pk_fma_f32 v[66:67], v[88:89], v[76:77], v[66:67] op_sel_hi:[1,0,1]
	v_pk_fma_f32 v[70:71], v[92:93], v[76:77], v[70:71] op_sel_hi:[1,0,1]
	v_pk_fma_f32 v[60:61], v[90:91], v[74:75], v[60:61] op_sel_hi:[1,0,1]
	v_pk_fma_f32 v[64:65], v[94:95], v[74:75], v[64:65] op_sel_hi:[1,0,1]
	v_pk_fma_f32 v[68:69], v[90:91], v[76:77], v[68:69] op_sel_hi:[1,0,1]
	v_pk_fma_f32 v[56:57], v[94:95], v[76:77], v[56:57] op_sel_hi:[1,0,1]
	s_waitcnt lgkmcnt(12)
	v_pk_mul_f32 v[74:75], v[104:105], v[58:59]
	v_pk_mul_f32 v[76:77], v[108:109], v[62:63]
	v_pk_mul_f32 v[78:79], v[104:105], v[66:67]
	v_pk_mul_f32 v[80:81], v[108:109], v[70:71]
	v_pk_fma_f32 v[74:75], v[106:107], v[60:61], v[74:75]
	v_pk_fma_f32 v[76:77], v[110:111], v[64:65], v[76:77]
	v_pk_fma_f32 v[78:79], v[106:107], v[68:69], v[78:79]
	v_pk_fma_f32 v[80:81], v[110:111], v[56:57], v[80:81]
	v_pk_add_f32 v[74:75], v[74:75], v[76:77]
	v_pk_add_f32 v[76:77], v[78:79], v[80:81]
	s_waitcnt lgkmcnt(8)
	v_pk_mul_f32 v[78:79], v[44:45], v[58:59]
	v_pk_mul_f32 v[80:81], v[40:41], v[62:63]
	v_pk_mul_f32 v[44:45], v[44:45], v[66:67]
	v_pk_mul_f32 v[40:41], v[40:41], v[70:71]
	v_pk_mul_f32 v[82:83], v[50:51], v[60:61]
	s_waitcnt lgkmcnt(7)
	v_pk_mul_f32 v[84:85], v[54:55], v[64:65]
	v_pk_fma_f32 v[60:61], v[46:47], v[60:61], v[78:79]
	v_pk_fma_f32 v[64:65], v[42:43], v[64:65], v[80:81]
	v_pk_fma_f32 v[44:45], v[46:47], v[68:69], v[44:45]
	v_pk_fma_f32 v[40:41], v[42:43], v[56:57], v[40:41]
	v_pk_mul_f32 v[58:59], v[48:49], v[58:59]
	v_pk_mul_f32 v[48:49], v[48:49], v[66:67]
	v_add_f32_e32 v31, v74, v75
	v_add_f32_e32 v66, v76, v77
	v_pk_add_f32 v[88:89], v[64:65], v[60:61]
	v_pk_add_f32 v[90:91], v[40:41], v[44:45]
	ds_write2st64_b32 v29, v31, v66 offset0:200 offset1:204
	v_add_f32_e32 v31, v88, v89
	v_add_f32_e32 v88, v90, v91
	v_pk_mul_f32 v[62:63], v[52:53], v[62:63]
	s_waitcnt lgkmcnt(7)
	v_mov_b32_e32 v86, v73
	v_pk_mul_f32 v[50:51], v[50:51], v[68:69]
	v_pk_mul_f32 v[52:53], v[52:53], v[70:71]
	v_pk_mul_f32 v[54:55], v[54:55], v[56:57]
	v_add_f32_dpp v31, v31, v31 quad_perm:[1,0,3,2] row_mask:0xf bank_mask:0xf bound_ctrl:1
	v_add_f32_dpp v88, v88, v88 quad_perm:[1,0,3,2] row_mask:0xf bank_mask:0xf bound_ctrl:1
	v_add_u32_e32 v129, 0x1400, v23
	s_waitcnt lgkmcnt(5)
	v_pk_fma_f32 v[74:75], v[72:73], v[12:13], v[58:59] op_sel_hi:[0,1,1]
	v_pk_fma_f32 v[76:77], v[72:73], v[14:15], v[82:83] op_sel_hi:[0,1,1]
	v_pk_fma_f32 v[78:79], v[72:73], v[8:9], v[62:63] op_sel_hi:[0,1,1]
	v_pk_fma_f32 v[72:73], v[72:73], v[10:11], v[84:85] op_sel_hi:[0,1,1]
	v_pk_fma_f32 v[80:81], v[86:87], v[12:13], v[48:49] op_sel_hi:[0,1,1]
	v_pk_fma_f32 v[82:83], v[86:87], v[14:15], v[50:51] op_sel_hi:[0,1,1]
	v_pk_fma_f32 v[84:85], v[86:87], v[8:9], v[52:53] op_sel_hi:[0,1,1]
	v_pk_fma_f32 v[86:87], v[86:87], v[10:11], v[54:55] op_sel_hi:[0,1,1]
	ds_read_b128 v[40:43], v22 offset:4864
	ds_read_b128 v[44:47], v22 offset:4880
	ds_read_b128 v[8:11], v22 offset:4608
	ds_read_b128 v[12:15], v22 offset:4624
	ds_read2_b32 v[92:93], v129 offset0:192 offset1:200
	ds_read_b128 v[56:59], v22 offset:5376
	ds_read_b128 v[60:63], v22 offset:5392
	ds_read_b128 v[48:51], v22 offset:5120
	ds_read_b128 v[52:55], v22 offset:5136
	ds_read_b128 v[64:67], v22 offset:5632
	ds_read_b128 v[68:71], v22 offset:5648
	v_add_f32_dpp v31, v31, v31 quad_perm:[2,3,0,1] row_mask:0xf bank_mask:0xf bound_ctrl:1
	v_add_f32_dpp v89, v88, v88 quad_perm:[2,3,0,1] row_mask:0xf bank_mask:0xf bound_ctrl:1
	v_add_u32_e32 v130, 0x1c00, v23
	v_add_f32_dpp v88, v31, v31 row_half_mirror row_mask:0xf bank_mask:0xf bound_ctrl:1
	v_add_f32_dpp v90, v89, v89 row_half_mirror row_mask:0xf bank_mask:0xf bound_ctrl:1
	s_waitcnt lgkmcnt(14)
; #define SCAN_STEP(w0, w1, a0, a1, b0, b1, k0, k1, r0, r1, vi, vj, t) do { \
;                 SCAN_ROW(S0, S1, S2, S3, w0, w1, a0, a1, b0, b1, k0, k1, r0, r1, vi, (t) * 512); \
;                 SCAN_ROW(T0, T1, T2, T3, w0, w1, a0, a1, b0, b1, k0, k1, r0, r1, vj, (t) * 512 + 256); } while (0)
;     ...
;             SCAN_LOAD(w0, w1, a0, a1, b0, b1, k0, k1, r0, r1, vi, vj, 0);
; #pragma unroll
;             for (int t = 0; t < 16; t += 2) {
;                 SCAN_LOAD(W0, W1, A0, A1, B0, B1, K0, K1, R0, R1, VI, VJ, t + 1);
;                 SCAN_STEP(w0, w1, a0, a1, b0, b1, k0, k1, r0, r1, vi, vj, t);
;                 if (t + 2 < 16) SCAN_LOAD(w0, w1, a0, a1, b0, b1, k0, k1, r0, r1, vi, vj, t + 2);
;                 SCAN_STEP(W0, W1, A0, A1, B0, B1, K0, K1, R0, R1, VI, VJ, t + 1);
;             }
	v_pk_fma_f32 v[74:75], v[36:37], v[88:89], v[74:75] op_sel_hi:[1,0,1]
	v_pk_fma_f32 v[78:79], v[32:33], v[88:89], v[78:79] op_sel_hi:[1,0,1]
	v_pk_fma_f32 v[36:37], v[36:37], v[90:91], v[80:81] op_sel_hi:[1,0,1]
	v_pk_fma_f32 v[32:33], v[32:33], v[90:91], v[84:85] op_sel_hi:[1,0,1]
	v_pk_fma_f32 v[76:77], v[38:39], v[88:89], v[76:77] op_sel_hi:[1,0,1]
	v_pk_fma_f32 v[72:73], v[34:35], v[88:89], v[72:73] op_sel_hi:[1,0,1]
	v_pk_fma_f32 v[38:39], v[38:39], v[90:91], v[82:83] op_sel_hi:[1,0,1]
	v_pk_fma_f32 v[34:35], v[34:35], v[90:91], v[86:87] op_sel_hi:[1,0,1]
	s_waitcnt lgkmcnt(12)
	v_pk_mul_f32 v[80:81], v[4:5], v[74:75]
	v_pk_mul_f32 v[82:83], v[0:1], v[78:79]
	v_pk_mul_f32 v[4:5], v[4:5], v[36:37]
	v_pk_mul_f32 v[0:1], v[0:1], v[32:33]
	s_waitcnt lgkmcnt(8)
	v_pk_mul_f32 v[84:85], v[40:41], v[74:75]
	v_pk_mul_f32 v[86:87], v[44:45], v[78:79]
	v_pk_mul_f32 v[40:41], v[40:41], v[36:37]
	v_pk_mul_f32 v[44:45], v[44:45], v[32:33]
	v_pk_mul_f32 v[74:75], v[8:9], v[74:75]
	v_pk_mul_f32 v[88:89], v[10:11], v[76:77]
	s_waitcnt lgkmcnt(7)
	v_pk_mul_f32 v[78:79], v[12:13], v[78:79]
	v_pk_mul_f32 v[90:91], v[14:15], v[72:73]
	v_pk_mul_f32 v[8:9], v[8:9], v[36:37]
	v_pk_mul_f32 v[10:11], v[10:11], v[38:39]
	v_pk_mul_f32 v[12:13], v[12:13], v[32:33]
	v_pk_mul_f32 v[14:15], v[14:15], v[34:35]
	v_pk_fma_f32 v[32:33], v[6:7], v[76:77], v[80:81]
	v_pk_fma_f32 v[36:37], v[2:3], v[72:73], v[82:83]
	v_pk_fma_f32 v[4:5], v[6:7], v[38:39], v[4:5]
	v_pk_fma_f32 v[0:1], v[2:3], v[34:35], v[0:1]
	v_pk_fma_f32 v[2:3], v[42:43], v[76:77], v[84:85]
	v_pk_fma_f32 v[6:7], v[46:47], v[72:73], v[86:87]
	v_pk_fma_f32 v[38:39], v[42:43], v[38:39], v[40:41]
	v_pk_fma_f32 v[34:35], v[46:47], v[34:35], v[44:45]
	s_waitcnt lgkmcnt(5)
	v_mov_b32_e32 v94, v93
	v_pk_add_f32 v[0:1], v[4:5], v[0:1]
	v_pk_add_f32 v[2:3], v[2:3], v[6:7]
	v_pk_add_f32 v[4:5], v[38:39], v[34:35]
	v_pk_fma_f32 v[80:81], v[56:57], v[94:95], v[8:9] op_sel_hi:[1,0,1]
	v_pk_add_f32 v[8:9], v[32:33], v[36:37]
	v_add_f32_e32 v0, v0, v1
	v_add_f32_e32 v1, v2, v3
	v_add_f32_e32 v2, v4, v5
	s_waitcnt lgkmcnt(4)
	v_pk_fma_f32 v[76:77], v[60:61], v[92:93], v[78:79] op_sel_hi:[1,0,1]
	v_pk_fma_f32 v[78:79], v[62:63], v[92:93], v[90:91] op_sel_hi:[1,0,1]
	v_add_f32_e32 v6, v8, v9
	v_add_f32_dpp v31, v1, v1 quad_perm:[1,0,3,2] row_mask:0xf bank_mask:0xf bound_ctrl:1
	v_add_f32_dpp v90, v2, v2 quad_perm:[1,0,3,2] row_mask:0xf bank_mask:0xf bound_ctrl:1
	ds_write2st64_b32 v29, v6, v0 offset0:208 offset1:212
	v_add_f32_dpp v31, v31, v31 quad_perm:[2,3,0,1] row_mask:0xf bank_mask:0xf bound_ctrl:1
	v_add_f32_dpp v91, v90, v90 quad_perm:[2,3,0,1] row_mask:0xf bank_mask:0xf bound_ctrl:1
	v_pk_fma_f32 v[72:73], v[56:57], v[92:93], v[74:75] op_sel_hi:[1,0,1]
	v_pk_fma_f32 v[74:75], v[58:59], v[92:93], v[88:89] op_sel_hi:[1,0,1]
	v_pk_fma_f32 v[82:83], v[58:59], v[94:95], v[10:11] op_sel_hi:[1,0,1]
	v_pk_fma_f32 v[84:85], v[60:61], v[94:95], v[12:13] op_sel_hi:[1,0,1]
	v_pk_fma_f32 v[86:87], v[62:63], v[94:95], v[14:15] op_sel_hi:[1,0,1]
	ds_read_b128 v[44:47], v22 offset:6400
	ds_read_b128 v[40:43], v22 offset:6416
	ds_read_b128 v[56:59], v22 offset:6144
	ds_read_b128 v[60:63], v22 offset:6160
	ds_read2_b32 v[88:89], v130 offset0:64 offset1:72
	ds_read_b128 v[12:15], v22 offset:6912
	ds_read_b128 v[8:11], v22 offset:6928
	ds_read_b128 v[36:39], v22 offset:6656
	ds_read_b128 v[32:35], v22 offset:6672
	ds_read_b128 v[4:7], v22 offset:7168
	ds_read_b128 v[0:3], v22 offset:7184
	v_add_f32_dpp v90, v31, v31 row_half_mirror row_mask:0xf bank_mask:0xf bound_ctrl:1
	v_add_f32_dpp v92, v91, v91 row_half_mirror row_mask:0xf bank_mask:0xf bound_ctrl:1
	s_waitcnt lgkmcnt(14)
	v_pk_fma_f32 v[72:73], v[48:49], v[90:91], v[72:73] op_sel_hi:[1,0,1]
	v_pk_fma_f32 v[76:77], v[52:53], v[90:91], v[76:77] op_sel_hi:[1,0,1]
	v_pk_fma_f32 v[48:49], v[48:49], v[92:93], v[80:81] op_sel_hi:[1,0,1]
	v_pk_fma_f32 v[52:53], v[52:53], v[92:93], v[84:85] op_sel_hi:[1,0,1]
	v_pk_fma_f32 v[74:75], v[50:51], v[90:91], v[74:75] op_sel_hi:[1,0,1]
	v_pk_fma_f32 v[78:79], v[54:55], v[90:91], v[78:79] op_sel_hi:[1,0,1]
	v_pk_fma_f32 v[50:51], v[50:51], v[92:93], v[82:83] op_sel_hi:[1,0,1]
	v_pk_fma_f32 v[54:55], v[54:55], v[92:93], v[86:87] op_sel_hi:[1,0,1]
	s_waitcnt lgkmcnt(12)
	v_pk_mul_f32 v[80:81], v[64:65], v[72:73]
	v_pk_mul_f32 v[82:83], v[68:69], v[76:77]
	v_pk_mul_f32 v[64:65], v[64:65], v[48:49]
	v_pk_mul_f32 v[68:69], v[68:69], v[52:53]
	v_pk_fma_f32 v[80:81], v[66:67], v[74:75], v[80:81]
	v_pk_fma_f32 v[64:65], v[66:67], v[50:51], v[64:65]
	v_pk_fma_f32 v[66:67], v[70:71], v[54:55], v[68:69]
	v_pk_fma_f32 v[82:83], v[70:71], v[78:79], v[82:83]
	v_pk_add_f32 v[64:65], v[64:65], v[66:67]
	s_waitcnt lgkmcnt(9)
	v_pk_mul_f32 v[66:67], v[44:45], v[72:73]
	v_pk_mul_f32 v[70:71], v[40:41], v[76:77]
	v_pk_mul_f32 v[44:45], v[44:45], v[48:49]
	v_pk_mul_f32 v[40:41], v[40:41], v[52:53]
	v_pk_add_f32 v[68:69], v[80:81], v[82:83]
	s_waitcnt lgkmcnt(7)
	v_pk_mul_f32 v[72:73], v[56:57], v[72:73]
	v_pk_mul_f32 v[80:81], v[58:59], v[74:75]
	v_pk_mul_f32 v[76:77], v[60:61], v[76:77]
	v_pk_mul_f32 v[82:83], v[62:63], v[78:79]
	v_pk_mul_f32 v[48:49], v[56:57], v[48:49]
	v_pk_mul_f32 v[56:57], v[58:59], v[50:51]
	v_pk_mul_f32 v[52:53], v[60:61], v[52:53]
	v_pk_mul_f32 v[58:59], v[62:63], v[54:55]
	v_pk_fma_f32 v[60:61], v[46:47], v[74:75], v[66:67]
	v_pk_fma_f32 v[62:63], v[42:43], v[78:79], v[70:71]
	v_pk_fma_f32 v[44:45], v[46:47], v[50:51], v[44:45]
	v_pk_fma_f32 v[40:41], v[42:43], v[54:55], v[40:41]
	s_waitcnt lgkmcnt(5)
	v_mov_b32_e32 v84, v89
	v_add_f32_e32 v31, v68, v69
	v_add_f32_e32 v64, v64, v65
	v_pk_fma_f32 v[72:73], v[88:89], v[12:13], v[72:73] op_sel_hi:[0,1,1]
	v_pk_fma_f32 v[74:75], v[88:89], v[14:15], v[80:81] op_sel_hi:[0,1,1]
	s_waitcnt lgkmcnt(4)
; #define SCAN_STEP(w0, w1, a0, a1, b0, b1, k0, k1, r0, r1, vi, vj, t) do { \
;                 SCAN_ROW(S0, S1, S2, S3, w0, w1, a0, a1, b0, b1, k0, k1, r0, r1, vi, (t) * 512); \
;                 SCAN_ROW(T0, T1, T2, T3, w0, w1, a0, a1, b0, b1, k0, k1, r0, r1, vj, (t) * 512 + 256); } while (0)
;     ...
;             SCAN_LOAD(w0, w1, a0, a1, b0, b1, k0, k1, r0, r1, vi, vj, 0);
; #pragma unroll
;             for (int t = 0; t < 16; t += 2) {
;                 SCAN_LOAD(W0, W1, A0, A1, B0, B1, K0, K1, R0, R1, VI, VJ, t + 1);
;                 SCAN_STEP(w0, w1, a0, a1, b0, b1, k0, k1, r0, r1, vi, vj, t);
;                 if (t + 2 < 16) SCAN_LOAD(w0, w1, a0, a1, b0, b1, k0, k1, r0, r1, vi, vj, t + 2);
;                 SCAN_STEP(W0, W1, A0, A1, B0, B1, K0, K1, R0, R1, VI, VJ, t + 1);
;             }
	v_pk_fma_f32 v[76:77], v[88:89], v[8:9], v[76:77] op_sel_hi:[0,1,1]
	v_pk_fma_f32 v[78:79], v[88:89], v[10:11], v[82:83] op_sel_hi:[0,1,1]
	v_pk_add_f32 v[88:89], v[62:63], v[60:61]
	v_pk_add_f32 v[90:91], v[40:41], v[44:45]
	ds_write2st64_b32 v29, v31, v64 offset0:216 offset1:220
	v_add_f32_e32 v31, v88, v89
	v_add_f32_e32 v88, v90, v91
	v_add_u32_e32 v131, 0x2000, v23
	v_add_f32_dpp v31, v31, v31 quad_perm:[1,0,3,2] row_mask:0xf bank_mask:0xf bound_ctrl:1
	v_add_f32_dpp v88, v88, v88 quad_perm:[1,0,3,2] row_mask:0xf bank_mask:0xf bound_ctrl:1
	v_pk_fma_f32 v[80:81], v[84:85], v[12:13], v[48:49] op_sel_hi:[0,1,1]
	v_pk_fma_f32 v[82:83], v[84:85], v[14:15], v[56:57] op_sel_hi:[0,1,1]
	v_pk_fma_f32 v[86:87], v[84:85], v[8:9], v[52:53] op_sel_hi:[0,1,1]
	v_pk_fma_f32 v[84:85], v[84:85], v[10:11], v[58:59] op_sel_hi:[0,1,1]
	ds_read_b128 v[40:43], v22 offset:7936
	ds_read_b128 v[44:47], v22 offset:7952
	ds_read_b128 v[8:11], v22 offset:7680
	ds_read_b128 v[12:15], v22 offset:7696
	ds_read2_b32 v[92:93], v131 offset0:192 offset1:200
	ds_read_b128 v[56:59], v22 offset:8448
	ds_read_b128 v[60:63], v22 offset:8464
	ds_read_b128 v[48:51], v22 offset:8192
	ds_read_b128 v[52:55], v22 offset:8208
	ds_read_b128 v[64:67], v22 offset:8704
	ds_read_b128 v[68:71], v22 offset:8720
	v_add_f32_dpp v31, v31, v31 quad_perm:[2,3,0,1] row_mask:0xf bank_mask:0xf bound_ctrl:1
	v_add_f32_dpp v89, v88, v88 quad_perm:[2,3,0,1] row_mask:0xf bank_mask:0xf bound_ctrl:1
	v_add_u32_e32 v132, 0x2800, v23
	v_add_f32_dpp v88, v31, v31 row_half_mirror row_mask:0xf bank_mask:0xf bound_ctrl:1
	v_add_f32_dpp v90, v89, v89 row_half_mirror row_mask:0xf bank_mask:0xf bound_ctrl:1
	s_waitcnt lgkmcnt(14)
	v_pk_fma_f32 v[72:73], v[36:37], v[88:89], v[72:73] op_sel_hi:[1,0,1]
	v_pk_fma_f32 v[76:77], v[32:33], v[88:89], v[76:77] op_sel_hi:[1,0,1]
	v_pk_fma_f32 v[36:37], v[36:37], v[90:91], v[80:81] op_sel_hi:[1,0,1]
	v_pk_fma_f32 v[32:33], v[32:33], v[90:91], v[86:87] op_sel_hi:[1,0,1]
	v_pk_fma_f32 v[74:75], v[38:39], v[88:89], v[74:75] op_sel_hi:[1,0,1]
	v_pk_fma_f32 v[78:79], v[34:35], v[88:89], v[78:79] op_sel_hi:[1,0,1]
	v_pk_fma_f32 v[38:39], v[38:39], v[90:91], v[82:83] op_sel_hi:[1,0,1]
	v_pk_fma_f32 v[34:35], v[34:35], v[90:91], v[84:85] op_sel_hi:[1,0,1]
	s_waitcnt lgkmcnt(12)
	v_pk_mul_f32 v[80:81], v[4:5], v[72:73]
	v_pk_mul_f32 v[82:83], v[0:1], v[76:77]
	v_pk_mul_f32 v[4:5], v[4:5], v[36:37]
	v_pk_mul_f32 v[0:1], v[0:1], v[32:33]
	s_waitcnt lgkmcnt(8)
	v_pk_mul_f32 v[84:85], v[40:41], v[72:73]
	v_pk_mul_f32 v[86:87], v[44:45], v[76:77]
	v_pk_mul_f32 v[40:41], v[40:41], v[36:37]
	v_pk_mul_f32 v[44:45], v[44:45], v[32:33]
	v_pk_mul_f32 v[72:73], v[8:9], v[72:73]
	v_pk_mul_f32 v[88:89], v[10:11], v[74:75]
	s_waitcnt lgkmcnt(7)
	v_pk_mul_f32 v[76:77], v[12:13], v[76:77]
	v_pk_mul_f32 v[90:91], v[14:15], v[78:79]
	v_pk_mul_f32 v[8:9], v[8:9], v[36:37]
	v_pk_mul_f32 v[10:11], v[10:11], v[38:39]
	v_pk_mul_f32 v[12:13], v[12:13], v[32:33]
	v_pk_mul_f32 v[14:15], v[14:15], v[34:35]
	v_pk_fma_f32 v[32:33], v[6:7], v[74:75], v[80:81]
	v_pk_fma_f32 v[36:37], v[2:3], v[78:79], v[82:83]
	v_pk_fma_f32 v[4:5], v[6:7], v[38:39], v[4:5]
	v_pk_fma_f32 v[0:1], v[2:3], v[34:35], v[0:1]
	v_pk_fma_f32 v[2:3], v[42:43], v[74:75], v[84:85]
	v_pk_fma_f32 v[6:7], v[46:47], v[78:79], v[86:87]
	v_pk_fma_f32 v[38:39], v[42:43], v[38:39], v[40:41]
	v_pk_fma_f32 v[34:35], v[46:47], v[34:35], v[44:45]
	s_waitcnt lgkmcnt(5)
	v_mov_b32_e32 v94, v93
	v_pk_add_f32 v[0:1], v[4:5], v[0:1]
	v_pk_add_f32 v[2:3], v[2:3], v[6:7]
	v_pk_add_f32 v[4:5], v[38:39], v[34:35]
	v_pk_fma_f32 v[80:81], v[56:57], v[94:95], v[8:9] op_sel_hi:[1,0,1]
	v_pk_add_f32 v[8:9], v[32:33], v[36:37]
	v_add_f32_e32 v0, v0, v1
	v_add_f32_e32 v1, v2, v3
	v_add_f32_e32 v2, v4, v5
	s_waitcnt lgkmcnt(4)
	v_pk_fma_f32 v[78:79], v[62:63], v[92:93], v[90:91] op_sel_hi:[1,0,1]
	v_add_f32_e32 v6, v8, v9
	v_add_f32_dpp v31, v1, v1 quad_perm:[1,0,3,2] row_mask:0xf bank_mask:0xf bound_ctrl:1
	v_add_f32_dpp v90, v2, v2 quad_perm:[1,0,3,2] row_mask:0xf bank_mask:0xf bound_ctrl:1
	ds_write2st64_b32 v29, v6, v0 offset0:224 offset1:228
	v_add_f32_dpp v31, v31, v31 quad_perm:[2,3,0,1] row_mask:0xf bank_mask:0xf bound_ctrl:1
	v_add_f32_dpp v91, v90, v90 quad_perm:[2,3,0,1] row_mask:0xf bank_mask:0xf bound_ctrl:1
	v_pk_fma_f32 v[72:73], v[56:57], v[92:93], v[72:73] op_sel_hi:[1,0,1]
	v_pk_fma_f32 v[74:75], v[58:59], v[92:93], v[88:89] op_sel_hi:[1,0,1]
	v_pk_fma_f32 v[76:77], v[60:61], v[92:93], v[76:77] op_sel_hi:[1,0,1]
	v_pk_fma_f32 v[82:83], v[58:59], v[94:95], v[10:11] op_sel_hi:[1,0,1]
	v_pk_fma_f32 v[84:85], v[60:61], v[94:95], v[12:13] op_sel_hi:[1,0,1]
	v_pk_fma_f32 v[86:87], v[62:63], v[94:95], v[14:15] op_sel_hi:[1,0,1]
	ds_read_b128 v[44:47], v22 offset:9472
	ds_read_b128 v[40:43], v22 offset:9488
	ds_read_b128 v[56:59], v22 offset:9216
	ds_read_b128 v[60:63], v22 offset:9232
	ds_read2_b32 v[88:89], v132 offset0:64 offset1:72
	ds_read_b128 v[12:15], v22 offset:9984
	ds_read_b128 v[8:11], v22 offset:10000
	ds_read_b128 v[36:39], v22 offset:9728
	ds_read_b128 v[32:35], v22 offset:9744
	ds_read_b128 v[4:7], v22 offset:10240
	ds_read_b128 v[0:3], v22 offset:10256
	v_add_f32_dpp v90, v31, v31 row_half_mirror row_mask:0xf bank_mask:0xf bound_ctrl:1
	v_add_f32_dpp v92, v91, v91 row_half_mirror row_mask:0xf bank_mask:0xf bound_ctrl:1
	s_waitcnt lgkmcnt(14)
	v_pk_fma_f32 v[72:73], v[48:49], v[90:91], v[72:73] op_sel_hi:[1,0,1]
	v_pk_fma_f32 v[76:77], v[52:53], v[90:91], v[76:77] op_sel_hi:[1,0,1]
	v_pk_fma_f32 v[48:49], v[48:49], v[92:93], v[80:81] op_sel_hi:[1,0,1]
	v_pk_fma_f32 v[52:53], v[52:53], v[92:93], v[84:85] op_sel_hi:[1,0,1]
	v_pk_fma_f32 v[74:75], v[50:51], v[90:91], v[74:75] op_sel_hi:[1,0,1]
	v_pk_fma_f32 v[78:79], v[54:55], v[90:91], v[78:79] op_sel_hi:[1,0,1]
	v_pk_fma_f32 v[50:51], v[50:51], v[92:93], v[82:83] op_sel_hi:[1,0,1]
	v_pk_fma_f32 v[54:55], v[54:55], v[92:93], v[86:87] op_sel_hi:[1,0,1]
	s_waitcnt lgkmcnt(12)
; #define SCAN_STEP(w0, w1, a0, a1, b0, b1, k0, k1, r0, r1, vi, vj, t) do { \
;                 SCAN_ROW(S0, S1, S2, S3, w0, w1, a0, a1, b0, b1, k0, k1, r0, r1, vi, (t) * 512); \
;                 SCAN_ROW(T0, T1, T2, T3, w0, w1, a0, a1, b0, b1, k0, k1, r0, r1, vj, (t) * 512 + 256); } while (0)
;     ...
;             SCAN_LOAD(w0, w1, a0, a1, b0, b1, k0, k1, r0, r1, vi, vj, 0);
; #pragma unroll
;             for (int t = 0; t < 16; t += 2) {
;                 SCAN_LOAD(W0, W1, A0, A1, B0, B1, K0, K1, R0, R1, VI, VJ, t + 1);
;                 SCAN_STEP(w0, w1, a0, a1, b0, b1, k0, k1, r0, r1, vi, vj, t);
;                 if (t + 2 < 16) SCAN_LOAD(w0, w1, a0, a1, b0, b1, k0, k1, r0, r1, vi, vj, t + 2);
;                 SCAN_STEP(W0, W1, A0, A1, B0, B1, K0, K1, R0, R1, VI, VJ, t + 1);
;             }
	v_pk_mul_f32 v[80:81], v[64:65], v[72:73]
	v_pk_mul_f32 v[82:83], v[68:69], v[76:77]
	v_pk_mul_f32 v[64:65], v[64:65], v[48:49]
	v_pk_mul_f32 v[68:69], v[68:69], v[52:53]
	v_pk_fma_f32 v[80:81], v[66:67], v[74:75], v[80:81]
	v_pk_fma_f32 v[64:65], v[66:67], v[50:51], v[64:65]
	v_pk_fma_f32 v[66:67], v[70:71], v[54:55], v[68:69]
	v_pk_fma_f32 v[82:83], v[70:71], v[78:79], v[82:83]
	v_pk_add_f32 v[64:65], v[64:65], v[66:67]
	s_waitcnt lgkmcnt(9)
	v_pk_mul_f32 v[66:67], v[44:45], v[72:73]
	v_pk_mul_f32 v[70:71], v[40:41], v[76:77]
	v_pk_mul_f32 v[44:45], v[44:45], v[48:49]
	v_pk_mul_f32 v[40:41], v[40:41], v[52:53]
	v_pk_add_f32 v[68:69], v[80:81], v[82:83]
	s_waitcnt lgkmcnt(7)
	v_pk_mul_f32 v[72:73], v[56:57], v[72:73]
	v_pk_mul_f32 v[80:81], v[58:59], v[74:75]
	v_pk_mul_f32 v[76:77], v[60:61], v[76:77]
	v_pk_mul_f32 v[82:83], v[62:63], v[78:79]
	v_pk_mul_f32 v[48:49], v[56:57], v[48:49]
	v_pk_mul_f32 v[56:57], v[58:59], v[50:51]
	v_pk_mul_f32 v[52:53], v[60:61], v[52:53]
	v_pk_mul_f32 v[58:59], v[62:63], v[54:55]
	v_pk_fma_f32 v[60:61], v[46:47], v[74:75], v[66:67]
	v_pk_fma_f32 v[62:63], v[42:43], v[78:79], v[70:71]
	v_pk_fma_f32 v[44:45], v[46:47], v[50:51], v[44:45]
	v_pk_fma_f32 v[40:41], v[42:43], v[54:55], v[40:41]
	s_waitcnt lgkmcnt(5)
	v_mov_b32_e32 v84, v89
	v_add_f32_e32 v31, v68, v69
	v_add_f32_e32 v64, v64, v65
	v_pk_fma_f32 v[72:73], v[88:89], v[12:13], v[72:73] op_sel_hi:[0,1,1]
	v_pk_fma_f32 v[74:75], v[88:89], v[14:15], v[80:81] op_sel_hi:[0,1,1]
	s_waitcnt lgkmcnt(4)
	v_pk_fma_f32 v[76:77], v[88:89], v[8:9], v[76:77] op_sel_hi:[0,1,1]
	v_pk_fma_f32 v[78:79], v[88:89], v[10:11], v[82:83] op_sel_hi:[0,1,1]
	v_pk_add_f32 v[88:89], v[62:63], v[60:61]
	v_pk_add_f32 v[90:91], v[40:41], v[44:45]
	ds_write2st64_b32 v29, v31, v64 offset0:232 offset1:236
	v_add_f32_e32 v31, v88, v89
	v_add_f32_e32 v88, v90, v91
	v_add_u32_e32 v133, 0x2c00, v23
	v_add_f32_dpp v31, v31, v31 quad_perm:[1,0,3,2] row_mask:0xf bank_mask:0xf bound_ctrl:1
	v_add_f32_dpp v88, v88, v88 quad_perm:[1,0,3,2] row_mask:0xf bank_mask:0xf bound_ctrl:1
	v_pk_fma_f32 v[80:81], v[84:85], v[12:13], v[48:49] op_sel_hi:[0,1,1]
	v_pk_fma_f32 v[82:83], v[84:85], v[14:15], v[56:57] op_sel_hi:[0,1,1]
	v_pk_fma_f32 v[86:87], v[84:85], v[8:9], v[52:53] op_sel_hi:[0,1,1]
	v_pk_fma_f32 v[84:85], v[84:85], v[10:11], v[58:59] op_sel_hi:[0,1,1]
	ds_read_b128 v[40:43], v22 offset:11008
	ds_read_b128 v[44:47], v22 offset:11024
	ds_read_b128 v[8:11], v22 offset:10752
	ds_read_b128 v[12:15], v22 offset:10768
	ds_read2_b32 v[92:93], v133 offset0:192 offset1:200
	ds_read_b128 v[56:59], v22 offset:11520
	ds_read_b128 v[60:63], v22 offset:11536
	ds_read_b128 v[48:51], v22 offset:11264
	ds_read_b128 v[52:55], v22 offset:11280
	ds_read_b128 v[64:67], v22 offset:11776
	ds_read_b128 v[68:71], v22 offset:11792
	v_add_f32_dpp v31, v31, v31 quad_perm:[2,3,0,1] row_mask:0xf bank_mask:0xf bound_ctrl:1
	v_add_f32_dpp v89, v88, v88 quad_perm:[2,3,0,1] row_mask:0xf bank_mask:0xf bound_ctrl:1
	v_add_u32_e32 v134, 0x3400, v23
	v_add_f32_dpp v88, v31, v31 row_half_mirror row_mask:0xf bank_mask:0xf bound_ctrl:1
	v_add_f32_dpp v90, v89, v89 row_half_mirror row_mask:0xf bank_mask:0xf bound_ctrl:1
	s_waitcnt lgkmcnt(14)
	v_pk_fma_f32 v[72:73], v[36:37], v[88:89], v[72:73] op_sel_hi:[1,0,1]
	v_pk_fma_f32 v[76:77], v[32:33], v[88:89], v[76:77] op_sel_hi:[1,0,1]
	v_pk_fma_f32 v[36:37], v[36:37], v[90:91], v[80:81] op_sel_hi:[1,0,1]
	v_pk_fma_f32 v[32:33], v[32:33], v[90:91], v[86:87] op_sel_hi:[1,0,1]
	v_pk_fma_f32 v[74:75], v[38:39], v[88:89], v[74:75] op_sel_hi:[1,0,1]
	v_pk_fma_f32 v[78:79], v[34:35], v[88:89], v[78:79] op_sel_hi:[1,0,1]
	v_pk_fma_f32 v[38:39], v[38:39], v[90:91], v[82:83] op_sel_hi:[1,0,1]
	v_pk_fma_f32 v[34:35], v[34:35], v[90:91], v[84:85] op_sel_hi:[1,0,1]
	s_waitcnt lgkmcnt(12)
	v_pk_mul_f32 v[80:81], v[4:5], v[72:73]
	v_pk_mul_f32 v[82:83], v[0:1], v[76:77]
	v_pk_mul_f32 v[4:5], v[4:5], v[36:37]
	v_pk_mul_f32 v[0:1], v[0:1], v[32:33]
	s_waitcnt lgkmcnt(8)
	v_pk_mul_f32 v[84:85], v[40:41], v[72:73]
	v_pk_mul_f32 v[86:87], v[44:45], v[76:77]
	v_pk_mul_f32 v[40:41], v[40:41], v[36:37]
	v_pk_mul_f32 v[44:45], v[44:45], v[32:33]
	v_pk_mul_f32 v[72:73], v[8:9], v[72:73]
	v_pk_mul_f32 v[88:89], v[10:11], v[74:75]
	s_waitcnt lgkmcnt(7)
	v_pk_mul_f32 v[76:77], v[12:13], v[76:77]
	v_pk_mul_f32 v[90:91], v[14:15], v[78:79]
	v_pk_mul_f32 v[8:9], v[8:9], v[36:37]
	v_pk_mul_f32 v[10:11], v[10:11], v[38:39]
	v_pk_mul_f32 v[12:13], v[12:13], v[32:33]
	v_pk_mul_f32 v[14:15], v[14:15], v[34:35]
	v_pk_fma_f32 v[32:33], v[6:7], v[74:75], v[80:81]
	v_pk_fma_f32 v[36:37], v[2:3], v[78:79], v[82:83]
	v_pk_fma_f32 v[4:5], v[6:7], v[38:39], v[4:5]
	v_pk_fma_f32 v[0:1], v[2:3], v[34:35], v[0:1]
	v_pk_fma_f32 v[2:3], v[42:43], v[74:75], v[84:85]
	v_pk_fma_f32 v[6:7], v[46:47], v[78:79], v[86:87]
	v_pk_fma_f32 v[38:39], v[42:43], v[38:39], v[40:41]
	v_pk_fma_f32 v[34:35], v[46:47], v[34:35], v[44:45]
	s_waitcnt lgkmcnt(5)
	v_mov_b32_e32 v94, v93
	v_pk_add_f32 v[0:1], v[4:5], v[0:1]
	v_pk_add_f32 v[2:3], v[2:3], v[6:7]
	v_pk_add_f32 v[4:5], v[38:39], v[34:35]
	v_pk_fma_f32 v[80:81], v[56:57], v[94:95], v[8:9] op_sel_hi:[1,0,1]
	v_pk_add_f32 v[8:9], v[32:33], v[36:37]
	v_add_f32_e32 v0, v0, v1
	v_add_f32_e32 v1, v2, v3
	v_add_f32_e32 v2, v4, v5
	s_waitcnt lgkmcnt(4)
; #define SCAN_STEP(w0, w1, a0, a1, b0, b1, k0, k1, r0, r1, vi, vj, t) do { \
;                 SCAN_ROW(S0, S1, S2, S3, w0, w1, a0, a1, b0, b1, k0, k1, r0, r1, vi, (t) * 512); \
;                 SCAN_ROW(T0, T1, T2, T3, w0, w1, a0, a1, b0, b1, k0, k1, r0, r1, vj, (t) * 512 + 256); } while (0)
;     ...
;             SCAN_LOAD(w0, w1, a0, a1, b0, b1, k0, k1, r0, r1, vi, vj, 0);
; #pragma unroll
;             for (int t = 0; t < 16; t += 2) {
;                 SCAN_LOAD(W0, W1, A0, A1, B0, B1, K0, K1, R0, R1, VI, VJ, t + 1);
;                 SCAN_STEP(w0, w1, a0, a1, b0, b1, k0, k1, r0, r1, vi, vj, t);
;                 if (t + 2 < 16) SCAN_LOAD(w0, w1, a0, a1, b0, b1, k0, k1, r0, r1, vi, vj, t + 2);
;                 SCAN_STEP(W0, W1, A0, A1, B0, B1, K0, K1, R0, R1, VI, VJ, t + 1);
;             }
	v_pk_fma_f32 v[78:79], v[62:63], v[92:93], v[90:91] op_sel_hi:[1,0,1]
	v_add_f32_e32 v6, v8, v9
	v_add_f32_dpp v31, v1, v1 quad_perm:[1,0,3,2] row_mask:0xf bank_mask:0xf bound_ctrl:1
	v_add_f32_dpp v90, v2, v2 quad_perm:[1,0,3,2] row_mask:0xf bank_mask:0xf bound_ctrl:1
	ds_write2st64_b32 v29, v6, v0 offset0:240 offset1:244
	v_add_f32_dpp v31, v31, v31 quad_perm:[2,3,0,1] row_mask:0xf bank_mask:0xf bound_ctrl:1
	v_add_f32_dpp v91, v90, v90 quad_perm:[2,3,0,1] row_mask:0xf bank_mask:0xf bound_ctrl:1
	v_pk_fma_f32 v[72:73], v[56:57], v[92:93], v[72:73] op_sel_hi:[1,0,1]
	v_pk_fma_f32 v[74:75], v[58:59], v[92:93], v[88:89] op_sel_hi:[1,0,1]
	v_pk_fma_f32 v[76:77], v[60:61], v[92:93], v[76:77] op_sel_hi:[1,0,1]
	v_pk_fma_f32 v[82:83], v[58:59], v[94:95], v[10:11] op_sel_hi:[1,0,1]
	v_pk_fma_f32 v[84:85], v[60:61], v[94:95], v[12:13] op_sel_hi:[1,0,1]
	v_pk_fma_f32 v[86:87], v[62:63], v[94:95], v[14:15] op_sel_hi:[1,0,1]
	ds_read_b128 v[44:47], v22 offset:12544
	ds_read_b128 v[40:43], v22 offset:12560
	ds_read_b128 v[56:59], v22 offset:12288
	ds_read_b128 v[60:63], v22 offset:12304
	ds_read2_b32 v[88:89], v134 offset0:64 offset1:72
	ds_read_b128 v[12:15], v22 offset:13056
	ds_read_b128 v[8:11], v22 offset:13072
	ds_read_b128 v[36:39], v22 offset:12800
	ds_read_b128 v[32:35], v22 offset:12816
	ds_read_b128 v[4:7], v22 offset:13312
	ds_read_b128 v[0:3], v22 offset:13328
	v_add_f32_dpp v90, v31, v31 row_half_mirror row_mask:0xf bank_mask:0xf bound_ctrl:1
	v_add_f32_dpp v92, v91, v91 row_half_mirror row_mask:0xf bank_mask:0xf bound_ctrl:1
	s_waitcnt lgkmcnt(14)
	v_pk_fma_f32 v[72:73], v[48:49], v[90:91], v[72:73] op_sel_hi:[1,0,1]
	v_pk_fma_f32 v[76:77], v[52:53], v[90:91], v[76:77] op_sel_hi:[1,0,1]
	v_pk_fma_f32 v[48:49], v[48:49], v[92:93], v[80:81] op_sel_hi:[1,0,1]
	v_pk_fma_f32 v[52:53], v[52:53], v[92:93], v[84:85] op_sel_hi:[1,0,1]
	v_pk_fma_f32 v[74:75], v[50:51], v[90:91], v[74:75] op_sel_hi:[1,0,1]
	v_pk_fma_f32 v[78:79], v[54:55], v[90:91], v[78:79] op_sel_hi:[1,0,1]
	v_pk_fma_f32 v[50:51], v[50:51], v[92:93], v[82:83] op_sel_hi:[1,0,1]
	v_pk_fma_f32 v[54:55], v[54:55], v[92:93], v[86:87] op_sel_hi:[1,0,1]
	s_waitcnt lgkmcnt(12)
	v_pk_mul_f32 v[80:81], v[64:65], v[72:73]
	v_pk_mul_f32 v[82:83], v[68:69], v[76:77]
	v_pk_mul_f32 v[64:65], v[64:65], v[48:49]
	v_pk_mul_f32 v[68:69], v[68:69], v[52:53]
	v_pk_fma_f32 v[80:81], v[66:67], v[74:75], v[80:81]
	v_pk_fma_f32 v[64:65], v[66:67], v[50:51], v[64:65]
	v_pk_fma_f32 v[66:67], v[70:71], v[54:55], v[68:69]
	v_pk_fma_f32 v[82:83], v[70:71], v[78:79], v[82:83]
	v_pk_add_f32 v[64:65], v[64:65], v[66:67]
	s_waitcnt lgkmcnt(9)
	v_pk_mul_f32 v[66:67], v[44:45], v[72:73]
	v_pk_mul_f32 v[70:71], v[40:41], v[76:77]
	v_pk_mul_f32 v[44:45], v[44:45], v[48:49]
	v_pk_mul_f32 v[40:41], v[40:41], v[52:53]
	v_pk_add_f32 v[68:69], v[80:81], v[82:83]
	s_waitcnt lgkmcnt(7)
	v_pk_mul_f32 v[72:73], v[56:57], v[72:73]
	v_pk_mul_f32 v[80:81], v[58:59], v[74:75]
	v_pk_mul_f32 v[76:77], v[60:61], v[76:77]
	v_pk_mul_f32 v[82:83], v[62:63], v[78:79]
	v_pk_mul_f32 v[48:49], v[56:57], v[48:49]
	v_pk_mul_f32 v[56:57], v[58:59], v[50:51]
	v_pk_mul_f32 v[52:53], v[60:61], v[52:53]
	v_pk_mul_f32 v[58:59], v[62:63], v[54:55]
	v_pk_fma_f32 v[60:61], v[46:47], v[74:75], v[66:67]
	v_pk_fma_f32 v[62:63], v[42:43], v[78:79], v[70:71]
	v_pk_fma_f32 v[44:45], v[46:47], v[50:51], v[44:45]
	v_pk_fma_f32 v[40:41], v[42:43], v[54:55], v[40:41]
	s_waitcnt lgkmcnt(5)
	v_mov_b32_e32 v84, v89
	v_add_f32_e32 v31, v68, v69
	v_add_f32_e32 v64, v64, v65
	v_pk_fma_f32 v[72:73], v[88:89], v[12:13], v[72:73] op_sel_hi:[0,1,1]
	v_pk_fma_f32 v[74:75], v[88:89], v[14:15], v[80:81] op_sel_hi:[0,1,1]
	s_waitcnt lgkmcnt(4)
	v_pk_fma_f32 v[76:77], v[88:89], v[8:9], v[76:77] op_sel_hi:[0,1,1]
	v_pk_fma_f32 v[78:79], v[88:89], v[10:11], v[82:83] op_sel_hi:[0,1,1]
	v_pk_add_f32 v[88:89], v[62:63], v[60:61]
	v_pk_add_f32 v[90:91], v[40:41], v[44:45]
	v_add_u32_e32 v21, 0xc000, v29
	v_add_u32_e32 v30, 0x3800, v23
	ds_write2st64_b32 v29, v31, v64 offset0:248 offset1:252
	v_add_f32_e32 v29, v88, v89
	v_add_f32_e32 v88, v90, v91
	v_pk_fma_f32 v[80:81], v[84:85], v[12:13], v[48:49] op_sel_hi:[0,1,1]
	v_pk_fma_f32 v[82:83], v[84:85], v[14:15], v[56:57] op_sel_hi:[0,1,1]
	v_pk_fma_f32 v[86:87], v[84:85], v[8:9], v[52:53] op_sel_hi:[0,1,1]
	v_pk_fma_f32 v[84:85], v[84:85], v[10:11], v[58:59] op_sel_hi:[0,1,1]
	ds_read2_b32 v[30:31], v30 offset0:192 offset1:200
	ds_read_b128 v[40:43], v22 offset:14080
	ds_read_b128 v[44:47], v22 offset:14096
	ds_read_b128 v[8:11], v22 offset:13824
	ds_read_b128 v[12:15], v22 offset:13840
	ds_read_b128 v[56:59], v22 offset:14592
	ds_read_b128 v[60:63], v22 offset:14608
	ds_read_b128 v[48:51], v22 offset:14336
	ds_read_b128 v[52:55], v22 offset:14352
	ds_read_b128 v[64:67], v22 offset:14848
	ds_read_b128 v[68:71], v22 offset:14864
	v_add_f32_dpp v29, v29, v29 quad_perm:[1,0,3,2] row_mask:0xf bank_mask:0xf bound_ctrl:1
	v_add_f32_dpp v88, v88, v88 quad_perm:[1,0,3,2] row_mask:0xf bank_mask:0xf bound_ctrl:1
	v_add_u32_e32 v28, 0x4000, v23
	v_add_f32_dpp v29, v29, v29 quad_perm:[2,3,0,1] row_mask:0xf bank_mask:0xf bound_ctrl:1
	v_add_f32_dpp v89, v88, v88 quad_perm:[2,3,0,1] row_mask:0xf bank_mask:0xf bound_ctrl:1
	s_waitcnt lgkmcnt(10)
; #define SCAN_STEP(w0, w1, a0, a1, b0, b1, k0, k1, r0, r1, vi, vj, t) do { \
;                 SCAN_ROW(S0, S1, S2, S3, w0, w1, a0, a1, b0, b1, k0, k1, r0, r1, vi, (t) * 512); \
;                 SCAN_ROW(T0, T1, T2, T3, w0, w1, a0, a1, b0, b1, k0, k1, r0, r1, vj, (t) * 512 + 256); } while (0)
;     ...
;             SCAN_LOAD(w0, w1, a0, a1, b0, b1, k0, k1, r0, r1, vi, vj, 0);
; #pragma unroll
;             for (int t = 0; t < 16; t += 2) {
;                 SCAN_LOAD(W0, W1, A0, A1, B0, B1, K0, K1, R0, R1, VI, VJ, t + 1);
;                 SCAN_STEP(w0, w1, a0, a1, b0, b1, k0, k1, r0, r1, vi, vj, t);
;                 if (t + 2 < 16) SCAN_LOAD(w0, w1, a0, a1, b0, b1, k0, k1, r0, r1, vi, vj, t + 2);
;                 SCAN_STEP(W0, W1, A0, A1, B0, B1, K0, K1, R0, R1, VI, VJ, t + 1);
;             }
	v_mov_b32_e32 v92, v31
	v_add_f32_dpp v88, v29, v29 row_half_mirror row_mask:0xf bank_mask:0xf bound_ctrl:1
	v_add_f32_dpp v90, v89, v89 row_half_mirror row_mask:0xf bank_mask:0xf bound_ctrl:1
	v_pk_fma_f32 v[72:73], v[36:37], v[88:89], v[72:73] op_sel_hi:[1,0,1]
	v_pk_fma_f32 v[74:75], v[38:39], v[88:89], v[74:75] op_sel_hi:[1,0,1]
	v_pk_fma_f32 v[76:77], v[32:33], v[88:89], v[76:77] op_sel_hi:[1,0,1]
	v_pk_fma_f32 v[78:79], v[34:35], v[88:89], v[78:79] op_sel_hi:[1,0,1]
	v_pk_fma_f32 v[36:37], v[36:37], v[90:91], v[80:81] op_sel_hi:[1,0,1]
	v_pk_fma_f32 v[32:33], v[32:33], v[90:91], v[86:87] op_sel_hi:[1,0,1]
	v_pk_fma_f32 v[38:39], v[38:39], v[90:91], v[82:83] op_sel_hi:[1,0,1]
	v_pk_fma_f32 v[34:35], v[34:35], v[90:91], v[84:85] op_sel_hi:[1,0,1]
	v_pk_mul_f32 v[80:81], v[4:5], v[72:73]
	v_pk_mul_f32 v[82:83], v[0:1], v[76:77]
	v_pk_mul_f32 v[4:5], v[4:5], v[36:37]
	v_pk_mul_f32 v[0:1], v[0:1], v[32:33]
	s_waitcnt lgkmcnt(6)
	v_pk_mul_f32 v[84:85], v[40:41], v[72:73]
	v_pk_mul_f32 v[86:87], v[44:45], v[76:77]
	v_pk_mul_f32 v[72:73], v[8:9], v[72:73]
	v_pk_mul_f32 v[88:89], v[10:11], v[74:75]
	v_pk_mul_f32 v[76:77], v[12:13], v[76:77]
	v_pk_mul_f32 v[90:91], v[14:15], v[78:79]
	v_pk_mul_f32 v[40:41], v[40:41], v[36:37]
	v_pk_mul_f32 v[44:45], v[44:45], v[32:33]
	v_pk_mul_f32 v[8:9], v[8:9], v[36:37]
	v_pk_mul_f32 v[12:13], v[12:13], v[32:33]
	v_pk_mul_f32 v[14:15], v[14:15], v[34:35]
	v_pk_fma_f32 v[32:33], v[6:7], v[74:75], v[80:81]
	v_pk_fma_f32 v[36:37], v[2:3], v[78:79], v[82:83]
	v_pk_fma_f32 v[4:5], v[6:7], v[38:39], v[4:5]
	v_pk_fma_f32 v[0:1], v[2:3], v[34:35], v[0:1]
	v_pk_fma_f32 v[2:3], v[42:43], v[74:75], v[84:85]
	v_pk_fma_f32 v[6:7], v[46:47], v[78:79], v[86:87]
	s_waitcnt lgkmcnt(4)
	v_pk_fma_f32 v[72:73], v[56:57], v[30:31], v[72:73] op_sel_hi:[1,0,1]
	v_pk_fma_f32 v[74:75], v[58:59], v[30:31], v[88:89] op_sel_hi:[1,0,1]
	v_pk_fma_f32 v[76:77], v[60:61], v[30:31], v[76:77] op_sel_hi:[1,0,1]
	v_pk_fma_f32 v[78:79], v[62:63], v[30:31], v[90:91] op_sel_hi:[1,0,1]
	v_pk_fma_f32 v[30:31], v[42:43], v[38:39], v[40:41]
	v_pk_fma_f32 v[34:35], v[46:47], v[34:35], v[44:45]
	v_pk_add_f32 v[0:1], v[4:5], v[0:1]
	v_pk_add_f32 v[2:3], v[2:3], v[6:7]
	v_pk_add_f32 v[4:5], v[30:31], v[34:35]
	v_pk_fma_f32 v[80:81], v[56:57], v[92:93], v[8:9] op_sel_hi:[1,0,1]
	v_pk_add_f32 v[8:9], v[32:33], v[36:37]
	v_add_f32_e32 v0, v0, v1
	v_add_f32_e32 v1, v2, v3
	v_add_f32_e32 v2, v4, v5
	v_add_f32_e32 v6, v8, v9
	v_add_f32_dpp v86, v1, v1 quad_perm:[1,0,3,2] row_mask:0xf bank_mask:0xf bound_ctrl:1
	v_add_f32_dpp v87, v2, v2 quad_perm:[1,0,3,2] row_mask:0xf bank_mask:0xf bound_ctrl:1
	v_pk_mul_f32 v[10:11], v[10:11], v[38:39]
	ds_write2st64_b32 v21, v6, v0 offset0:64 offset1:68
	v_add_f32_dpp v86, v86, v86 quad_perm:[2,3,0,1] row_mask:0xf bank_mask:0xf bound_ctrl:1
	v_add_f32_dpp v87, v87, v87 quad_perm:[2,3,0,1] row_mask:0xf bank_mask:0xf bound_ctrl:1
	v_pk_fma_f32 v[82:83], v[58:59], v[92:93], v[10:11] op_sel_hi:[1,0,1]
	v_pk_fma_f32 v[60:61], v[60:61], v[92:93], v[12:13] op_sel_hi:[1,0,1]
	v_pk_fma_f32 v[62:63], v[62:63], v[92:93], v[14:15] op_sel_hi:[1,0,1]
	ds_read2_b32 v[84:85], v28 offset0:64 offset1:72
	ds_read_b128 v[0:3], v22 offset:16400
	ds_read_b128 v[4:7], v22 offset:16384
	ds_read_b128 v[8:11], v22 offset:16144
	ds_read_b128 v[12:15], v22 offset:16128
	ds_read_b128 v[28:31], v22 offset:15888
	ds_read_b128 v[32:35], v22 offset:15872
	ds_read_b128 v[36:39], v22 offset:15632
	ds_read_b128 v[40:43], v22 offset:15616
	ds_read_b128 v[44:47], v22 offset:15360
	ds_read_b128 v[56:59], v22 offset:15376
	v_add_f32_dpp v86, v86, v86 row_half_mirror row_mask:0xf bank_mask:0xf bound_ctrl:1
	v_add_f32_dpp v88, v87, v87 row_half_mirror row_mask:0xf bank_mask:0xf bound_ctrl:1
	s_waitcnt lgkmcnt(14)
	v_pk_fma_f32 v[72:73], v[48:49], v[86:87], v[72:73] op_sel_hi:[1,0,1]
	v_pk_fma_f32 v[76:77], v[52:53], v[86:87], v[76:77] op_sel_hi:[1,0,1]
	v_pk_fma_f32 v[48:49], v[48:49], v[88:89], v[80:81] op_sel_hi:[1,0,1]
	v_pk_fma_f32 v[52:53], v[52:53], v[88:89], v[60:61] op_sel_hi:[1,0,1]
	v_pk_fma_f32 v[74:75], v[50:51], v[86:87], v[74:75] op_sel_hi:[1,0,1]
	v_pk_fma_f32 v[78:79], v[54:55], v[86:87], v[78:79] op_sel_hi:[1,0,1]
	v_pk_fma_f32 v[50:51], v[50:51], v[88:89], v[82:83] op_sel_hi:[1,0,1]
	v_pk_fma_f32 v[54:55], v[54:55], v[88:89], v[62:63] op_sel_hi:[1,0,1]
	s_waitcnt lgkmcnt(12)
	v_pk_mul_f32 v[60:61], v[64:65], v[72:73]
	v_pk_mul_f32 v[62:63], v[68:69], v[76:77]
	v_pk_mul_f32 v[64:65], v[64:65], v[48:49]
	v_pk_mul_f32 v[68:69], v[68:69], v[52:53]
	v_pk_fma_f32 v[60:61], v[66:67], v[74:75], v[60:61]
	v_pk_fma_f32 v[62:63], v[70:71], v[78:79], v[62:63]
	v_pk_fma_f32 v[64:65], v[66:67], v[50:51], v[64:65]
	v_pk_fma_f32 v[66:67], v[70:71], v[54:55], v[68:69]
	v_pk_add_f32 v[60:61], v[60:61], v[62:63]
	v_pk_add_f32 v[62:63], v[64:65], v[66:67]
	s_waitcnt lgkmcnt(1)
	v_pk_mul_f32 v[64:65], v[40:41], v[72:73]
	v_pk_mul_f32 v[66:67], v[36:37], v[76:77]
	v_pk_mul_f32 v[40:41], v[40:41], v[48:49]
	v_pk_mul_f32 v[36:37], v[36:37], v[52:53]
	v_pk_mul_f32 v[68:69], v[44:45], v[72:73]
	v_pk_mul_f32 v[70:71], v[46:47], v[74:75]
	s_waitcnt lgkmcnt(0)
; #define SCAN_STEP(w0, w1, a0, a1, b0, b1, k0, k1, r0, r1, vi, vj, t) do { \
;                 SCAN_ROW(S0, S1, S2, S3, w0, w1, a0, a1, b0, b1, k0, k1, r0, r1, vi, (t) * 512); \
;                 SCAN_ROW(T0, T1, T2, T3, w0, w1, a0, a1, b0, b1, k0, k1, r0, r1, vj, (t) * 512 + 256); } while (0)
;     ...
;             SCAN_LOAD(w0, w1, a0, a1, b0, b1, k0, k1, r0, r1, vi, vj, 0);
; #pragma unroll
;             for (int t = 0; t < 16; t += 2) {
;                 SCAN_LOAD(W0, W1, A0, A1, B0, B1, K0, K1, R0, R1, VI, VJ, t + 1);
;                 SCAN_STEP(w0, w1, a0, a1, b0, b1, k0, k1, r0, r1, vi, vj, t);
;                 if (t + 2 < 16) SCAN_LOAD(w0, w1, a0, a1, b0, b1, k0, k1, r0, r1, vi, vj, t + 2);
;                 SCAN_STEP(W0, W1, A0, A1, B0, B1, K0, K1, R0, R1, VI, VJ, t + 1);
;             }
	v_pk_mul_f32 v[72:73], v[56:57], v[76:77]
	v_pk_mul_f32 v[76:77], v[58:59], v[78:79]
	v_pk_mul_f32 v[44:45], v[44:45], v[48:49]
	v_pk_mul_f32 v[48:49], v[56:57], v[52:53]
	v_pk_mul_f32 v[52:53], v[58:59], v[54:55]
	v_add_f32_e32 v60, v60, v61
	v_add_f32_e32 v61, v62, v63
	v_pk_fma_f32 v[56:57], v[42:43], v[74:75], v[64:65]
	v_pk_fma_f32 v[58:59], v[38:39], v[78:79], v[66:67]
	v_pk_fma_f32 v[40:41], v[42:43], v[50:51], v[40:41]
	v_pk_fma_f32 v[36:37], v[38:39], v[54:55], v[36:37]
	v_add_u32_e32 v27, 0x4400, v23
	v_mov_b32_e32 v80, v85
	v_pk_mul_f32 v[46:47], v[46:47], v[50:51]
	v_pk_fma_f32 v[68:69], v[84:85], v[12:13], v[68:69] op_sel_hi:[0,1,1]
	v_pk_fma_f32 v[70:71], v[84:85], v[14:15], v[70:71] op_sel_hi:[0,1,1]
	v_pk_fma_f32 v[72:73], v[84:85], v[8:9], v[72:73] op_sel_hi:[0,1,1]
	v_pk_fma_f32 v[74:75], v[84:85], v[10:11], v[76:77] op_sel_hi:[0,1,1]
	ds_write2st64_b32 v21, v60, v61 offset0:72 offset1:76
	v_pk_add_f32 v[84:85], v[58:59], v[56:57]
	v_pk_add_f32 v[86:87], v[36:37], v[40:41]
	v_pk_fma_f32 v[76:77], v[80:81], v[12:13], v[44:45] op_sel_hi:[0,1,1]
	v_pk_fma_f32 v[78:79], v[80:81], v[14:15], v[46:47] op_sel_hi:[0,1,1]
	v_pk_fma_f32 v[82:83], v[80:81], v[8:9], v[48:49] op_sel_hi:[0,1,1]
	v_pk_fma_f32 v[80:81], v[80:81], v[10:11], v[52:53] op_sel_hi:[0,1,1]
	ds_read2_b32 v[88:89], v27 offset0:192 offset1:200
	ds_read_b128 v[36:39], v22 offset:17152
	ds_read_b128 v[40:43], v22 offset:17168
	ds_read_b128 v[8:11], v22 offset:16896
	ds_read_b128 v[12:15], v22 offset:16912
	ds_read_b128 v[52:55], v22 offset:17664
	ds_read_b128 v[56:59], v22 offset:17680
	ds_read_b128 v[44:47], v22 offset:17408
	ds_read_b128 v[48:51], v22 offset:17424
	ds_read_b128 v[60:63], v22 offset:17920
	ds_read_b128 v[64:67], v22 offset:17936
	v_add_f32_e32 v27, v84, v85
	v_add_f32_e32 v84, v86, v87
	v_add_u32_e32 v26, 0x4c00, v23
	v_add_f32_dpp v27, v27, v27 quad_perm:[1,0,3,2] row_mask:0xf bank_mask:0xf bound_ctrl:1
	v_add_f32_dpp v84, v84, v84 quad_perm:[1,0,3,2] row_mask:0xf bank_mask:0xf bound_ctrl:1
	s_waitcnt lgkmcnt(10)
	v_mov_b32_e32 v90, v89
	v_add_f32_dpp v27, v27, v27 quad_perm:[2,3,0,1] row_mask:0xf bank_mask:0xf bound_ctrl:1
	v_add_f32_dpp v85, v84, v84 quad_perm:[2,3,0,1] row_mask:0xf bank_mask:0xf bound_ctrl:1
	v_add_u32_e32 v25, 0x5000, v23
	v_add_f32_dpp v84, v27, v27 row_half_mirror row_mask:0xf bank_mask:0xf bound_ctrl:1
	v_add_f32_dpp v86, v85, v85 row_half_mirror row_mask:0xf bank_mask:0xf bound_ctrl:1
	v_pk_fma_f32 v[68:69], v[32:33], v[84:85], v[68:69] op_sel_hi:[1,0,1]
	v_pk_fma_f32 v[72:73], v[28:29], v[84:85], v[72:73] op_sel_hi:[1,0,1]
	v_pk_fma_f32 v[32:33], v[32:33], v[86:87], v[76:77] op_sel_hi:[1,0,1]
	v_pk_fma_f32 v[28:29], v[28:29], v[86:87], v[82:83] op_sel_hi:[1,0,1]
	v_pk_fma_f32 v[70:71], v[34:35], v[84:85], v[70:71] op_sel_hi:[1,0,1]
	v_pk_fma_f32 v[74:75], v[30:31], v[84:85], v[74:75] op_sel_hi:[1,0,1]
	v_pk_fma_f32 v[34:35], v[34:35], v[86:87], v[78:79] op_sel_hi:[1,0,1]
	v_pk_fma_f32 v[30:31], v[30:31], v[86:87], v[80:81] op_sel_hi:[1,0,1]
	v_pk_mul_f32 v[76:77], v[4:5], v[68:69]
	v_pk_mul_f32 v[78:79], v[0:1], v[72:73]
	v_pk_mul_f32 v[4:5], v[4:5], v[32:33]
	v_pk_mul_f32 v[0:1], v[0:1], v[28:29]
	s_waitcnt lgkmcnt(7)
	v_pk_mul_f32 v[80:81], v[36:37], v[68:69]
	v_pk_mul_f32 v[82:83], v[40:41], v[72:73]
	v_pk_mul_f32 v[36:37], v[36:37], v[32:33]
	v_pk_mul_f32 v[40:41], v[40:41], v[28:29]
	v_pk_mul_f32 v[68:69], v[8:9], v[68:69]
	v_pk_mul_f32 v[84:85], v[10:11], v[70:71]
	s_waitcnt lgkmcnt(6)
	v_pk_mul_f32 v[72:73], v[12:13], v[72:73]
	v_pk_mul_f32 v[86:87], v[14:15], v[74:75]
	v_pk_mul_f32 v[8:9], v[8:9], v[32:33]
	v_pk_mul_f32 v[10:11], v[10:11], v[34:35]
	v_pk_mul_f32 v[12:13], v[12:13], v[28:29]
	v_pk_mul_f32 v[14:15], v[14:15], v[30:31]
	v_pk_fma_f32 v[28:29], v[6:7], v[70:71], v[76:77]
	v_pk_fma_f32 v[32:33], v[2:3], v[74:75], v[78:79]
	v_pk_fma_f32 v[4:5], v[6:7], v[34:35], v[4:5]
	v_pk_fma_f32 v[0:1], v[2:3], v[30:31], v[0:1]
	v_pk_fma_f32 v[2:3], v[38:39], v[70:71], v[80:81]
	v_pk_fma_f32 v[6:7], v[42:43], v[74:75], v[82:83]
	v_pk_fma_f32 v[34:35], v[38:39], v[34:35], v[36:37]
	v_pk_fma_f32 v[30:31], v[42:43], v[30:31], v[40:41]
	v_pk_add_f32 v[0:1], v[4:5], v[0:1]
	v_pk_add_f32 v[2:3], v[2:3], v[6:7]
	v_pk_add_f32 v[4:5], v[34:35], v[30:31]
	s_waitcnt lgkmcnt(5)
	v_pk_fma_f32 v[42:43], v[52:53], v[90:91], v[8:9] op_sel_hi:[1,0,1]
	v_pk_add_f32 v[8:9], v[28:29], v[32:33]
	v_add_f32_e32 v0, v0, v1
	v_add_f32_e32 v1, v2, v3
	v_add_f32_e32 v2, v4, v5
	v_pk_fma_f32 v[70:71], v[54:55], v[88:89], v[84:85] op_sel_hi:[1,0,1]
	v_add_f32_e32 v6, v8, v9
	v_add_f32_dpp v84, v1, v1 quad_perm:[1,0,3,2] row_mask:0xf bank_mask:0xf bound_ctrl:1
	v_add_f32_dpp v85, v2, v2 quad_perm:[1,0,3,2] row_mask:0xf bank_mask:0xf bound_ctrl:1
	ds_write2st64_b32 v21, v6, v0 offset0:80 offset1:84
	v_add_f32_dpp v84, v84, v84 quad_perm:[2,3,0,1] row_mask:0xf bank_mask:0xf bound_ctrl:1
	v_add_f32_dpp v85, v85, v85 quad_perm:[2,3,0,1] row_mask:0xf bank_mask:0xf bound_ctrl:1
	v_pk_fma_f32 v[68:69], v[52:53], v[88:89], v[68:69] op_sel_hi:[1,0,1]
	s_waitcnt lgkmcnt(5)
	v_pk_fma_f32 v[72:73], v[56:57], v[88:89], v[72:73] op_sel_hi:[1,0,1]
	v_pk_fma_f32 v[74:75], v[58:59], v[88:89], v[86:87] op_sel_hi:[1,0,1]
	v_pk_fma_f32 v[76:77], v[54:55], v[90:91], v[10:11] op_sel_hi:[1,0,1]
	v_pk_fma_f32 v[78:79], v[56:57], v[90:91], v[12:13] op_sel_hi:[1,0,1]
	v_pk_fma_f32 v[80:81], v[58:59], v[90:91], v[14:15] op_sel_hi:[1,0,1]
	ds_read2_b32 v[82:83], v26 offset0:64 offset1:72
	ds_read_b128 v[0:3], v22 offset:19472
	ds_read_b128 v[4:7], v22 offset:19456
	ds_read_b128 v[8:11], v22 offset:19216
	ds_read_b128 v[12:15], v22 offset:19200
	ds_read_b128 v[26:29], v22 offset:18960
	ds_read_b128 v[30:33], v22 offset:18944
	ds_read_b128 v[34:37], v22 offset:18704
	ds_read_b128 v[38:41], v22 offset:18688
	ds_read_b128 v[52:55], v22 offset:18432
	ds_read_b128 v[56:59], v22 offset:18448
	v_add_f32_dpp v84, v84, v84 row_half_mirror row_mask:0xf bank_mask:0xf bound_ctrl:1
	v_add_f32_dpp v86, v85, v85 row_half_mirror row_mask:0xf bank_mask:0xf bound_ctrl:1
	s_waitcnt lgkmcnt(14)
; #define SCAN_STEP(w0, w1, a0, a1, b0, b1, k0, k1, r0, r1, vi, vj, t) do { \
;                 SCAN_ROW(S0, S1, S2, S3, w0, w1, a0, a1, b0, b1, k0, k1, r0, r1, vi, (t) * 512); \
;                 SCAN_ROW(T0, T1, T2, T3, w0, w1, a0, a1, b0, b1, k0, k1, r0, r1, vj, (t) * 512 + 256); } while (0)
;     ...
;             SCAN_LOAD(w0, w1, a0, a1, b0, b1, k0, k1, r0, r1, vi, vj, 0);
; #pragma unroll
;             for (int t = 0; t < 16; t += 2) {
;                 SCAN_LOAD(W0, W1, A0, A1, B0, B1, K0, K1, R0, R1, VI, VJ, t + 1);
;                 SCAN_STEP(w0, w1, a0, a1, b0, b1, k0, k1, r0, r1, vi, vj, t);
;                 if (t + 2 < 16) SCAN_LOAD(w0, w1, a0, a1, b0, b1, k0, k1, r0, r1, vi, vj, t + 2);
;                 SCAN_STEP(W0, W1, A0, A1, B0, B1, K0, K1, R0, R1, VI, VJ, t + 1);
;             }
	v_pk_fma_f32 v[68:69], v[44:45], v[84:85], v[68:69] op_sel_hi:[1,0,1]
	v_pk_fma_f32 v[70:71], v[46:47], v[84:85], v[70:71] op_sel_hi:[1,0,1]
	v_pk_fma_f32 v[72:73], v[48:49], v[84:85], v[72:73] op_sel_hi:[1,0,1]
	v_pk_fma_f32 v[42:43], v[44:45], v[86:87], v[42:43] op_sel_hi:[1,0,1]
	v_pk_fma_f32 v[44:45], v[46:47], v[86:87], v[76:77] op_sel_hi:[1,0,1]
	v_pk_fma_f32 v[46:47], v[48:49], v[86:87], v[78:79] op_sel_hi:[1,0,1]
	v_pk_fma_f32 v[74:75], v[50:51], v[84:85], v[74:75] op_sel_hi:[1,0,1]
	v_pk_fma_f32 v[48:49], v[50:51], v[86:87], v[80:81] op_sel_hi:[1,0,1]
	s_waitcnt lgkmcnt(12)
	v_pk_mul_f32 v[50:51], v[60:61], v[68:69]
	v_pk_mul_f32 v[76:77], v[64:65], v[72:73]
	v_pk_mul_f32 v[60:61], v[60:61], v[42:43]
	v_pk_mul_f32 v[64:65], v[64:65], v[46:47]
	v_pk_fma_f32 v[50:51], v[62:63], v[70:71], v[50:51]
	v_pk_fma_f32 v[76:77], v[66:67], v[74:75], v[76:77]
	v_pk_fma_f32 v[60:61], v[62:63], v[44:45], v[60:61]
	v_pk_fma_f32 v[62:63], v[66:67], v[48:49], v[64:65]
	v_pk_add_f32 v[50:51], v[50:51], v[76:77]
	v_pk_add_f32 v[60:61], v[60:61], v[62:63]
	s_waitcnt lgkmcnt(1)
	v_pk_mul_f32 v[62:63], v[38:39], v[68:69]
	v_pk_mul_f32 v[64:65], v[34:35], v[72:73]
	v_pk_mul_f32 v[38:39], v[38:39], v[42:43]
	v_pk_mul_f32 v[34:35], v[34:35], v[46:47]
	v_pk_mul_f32 v[66:67], v[52:53], v[68:69]
	v_pk_mul_f32 v[68:69], v[54:55], v[70:71]
	s_waitcnt lgkmcnt(0)
	v_pk_mul_f32 v[72:73], v[56:57], v[72:73]
	v_pk_mul_f32 v[76:77], v[58:59], v[74:75]
	v_pk_mul_f32 v[42:43], v[52:53], v[42:43]
	v_pk_mul_f32 v[52:53], v[54:55], v[44:45]
	v_pk_mul_f32 v[46:47], v[56:57], v[46:47]
	v_pk_mul_f32 v[54:55], v[58:59], v[48:49]
	v_add_f32_e32 v58, v50, v51
	v_add_f32_e32 v59, v60, v61
	v_pk_fma_f32 v[50:51], v[40:41], v[70:71], v[62:63]
	v_pk_fma_f32 v[56:57], v[36:37], v[74:75], v[64:65]
	v_pk_fma_f32 v[38:39], v[40:41], v[44:45], v[38:39]
	v_pk_fma_f32 v[34:35], v[36:37], v[48:49], v[34:35]
	v_mov_b32_e32 v78, v83
	v_pk_fma_f32 v[66:67], v[82:83], v[12:13], v[66:67] op_sel_hi:[0,1,1]
	v_pk_fma_f32 v[68:69], v[82:83], v[14:15], v[68:69] op_sel_hi:[0,1,1]
	v_pk_fma_f32 v[70:71], v[82:83], v[8:9], v[72:73] op_sel_hi:[0,1,1]
	v_pk_fma_f32 v[72:73], v[82:83], v[10:11], v[76:77] op_sel_hi:[0,1,1]
	ds_write2st64_b32 v21, v58, v59 offset0:88 offset1:92
	v_pk_add_f32 v[82:83], v[56:57], v[50:51]
	v_pk_add_f32 v[84:85], v[34:35], v[38:39]
	v_pk_fma_f32 v[74:75], v[78:79], v[12:13], v[42:43] op_sel_hi:[0,1,1]
	v_pk_fma_f32 v[76:77], v[78:79], v[14:15], v[52:53] op_sel_hi:[0,1,1]
	v_pk_fma_f32 v[80:81], v[78:79], v[8:9], v[46:47] op_sel_hi:[0,1,1]
	v_pk_fma_f32 v[78:79], v[78:79], v[10:11], v[54:55] op_sel_hi:[0,1,1]
	ds_read2_b32 v[86:87], v25 offset0:192 offset1:200
	ds_read_b128 v[34:37], v22 offset:20224
	ds_read_b128 v[38:41], v22 offset:20240
	ds_read_b128 v[8:11], v22 offset:19968
	ds_read_b128 v[12:15], v22 offset:19984
	ds_read_b128 v[50:53], v22 offset:20736
	ds_read_b128 v[54:57], v22 offset:20752
	ds_read_b128 v[42:45], v22 offset:20480
	ds_read_b128 v[46:49], v22 offset:20496
	ds_read_b128 v[58:61], v22 offset:20992
	ds_read_b128 v[62:65], v22 offset:21008
	v_add_f32_e32 v25, v82, v83
	v_add_f32_e32 v82, v84, v85
	v_add_u32_e32 v24, 0x5800, v23
	v_add_f32_dpp v25, v25, v25 quad_perm:[1,0,3,2] row_mask:0xf bank_mask:0xf bound_ctrl:1
	v_add_f32_dpp v82, v82, v82 quad_perm:[1,0,3,2] row_mask:0xf bank_mask:0xf bound_ctrl:1
	s_waitcnt lgkmcnt(10)
	v_mov_b32_e32 v88, v87
	v_add_f32_dpp v25, v25, v25 quad_perm:[2,3,0,1] row_mask:0xf bank_mask:0xf bound_ctrl:1
	v_add_f32_dpp v83, v82, v82 quad_perm:[2,3,0,1] row_mask:0xf bank_mask:0xf bound_ctrl:1
	v_add_u32_e32 v23, 0x5c00, v23
	v_add_f32_dpp v82, v25, v25 row_half_mirror row_mask:0xf bank_mask:0xf bound_ctrl:1
	v_add_f32_dpp v84, v83, v83 row_half_mirror row_mask:0xf bank_mask:0xf bound_ctrl:1
	v_pk_fma_f32 v[66:67], v[30:31], v[82:83], v[66:67] op_sel_hi:[1,0,1]
	v_pk_fma_f32 v[70:71], v[26:27], v[82:83], v[70:71] op_sel_hi:[1,0,1]
	v_pk_fma_f32 v[30:31], v[30:31], v[84:85], v[74:75] op_sel_hi:[1,0,1]
	v_pk_fma_f32 v[26:27], v[26:27], v[84:85], v[80:81] op_sel_hi:[1,0,1]
	v_pk_fma_f32 v[68:69], v[32:33], v[82:83], v[68:69] op_sel_hi:[1,0,1]
	v_pk_fma_f32 v[72:73], v[28:29], v[82:83], v[72:73] op_sel_hi:[1,0,1]
	v_pk_fma_f32 v[32:33], v[32:33], v[84:85], v[76:77] op_sel_hi:[1,0,1]
	v_pk_fma_f32 v[28:29], v[28:29], v[84:85], v[78:79] op_sel_hi:[1,0,1]
	v_pk_mul_f32 v[74:75], v[4:5], v[66:67]
	v_pk_mul_f32 v[76:77], v[0:1], v[70:71]
	v_pk_mul_f32 v[4:5], v[4:5], v[30:31]
	v_pk_mul_f32 v[0:1], v[0:1], v[26:27]
	s_waitcnt lgkmcnt(7)
	v_pk_mul_f32 v[78:79], v[34:35], v[66:67]
	v_pk_mul_f32 v[80:81], v[38:39], v[70:71]
	v_pk_mul_f32 v[34:35], v[34:35], v[30:31]
	v_pk_mul_f32 v[38:39], v[38:39], v[26:27]
	v_pk_mul_f32 v[66:67], v[8:9], v[66:67]
	v_pk_mul_f32 v[82:83], v[10:11], v[68:69]
	s_waitcnt lgkmcnt(6)
	v_pk_mul_f32 v[70:71], v[12:13], v[70:71]
	v_pk_mul_f32 v[84:85], v[14:15], v[72:73]
	v_pk_mul_f32 v[8:9], v[8:9], v[30:31]
	v_pk_mul_f32 v[10:11], v[10:11], v[32:33]
	v_pk_mul_f32 v[12:13], v[12:13], v[26:27]
	v_pk_mul_f32 v[14:15], v[14:15], v[28:29]
	v_pk_fma_f32 v[26:27], v[6:7], v[68:69], v[74:75]
	v_pk_fma_f32 v[30:31], v[2:3], v[72:73], v[76:77]
	v_pk_fma_f32 v[4:5], v[6:7], v[32:33], v[4:5]
	v_pk_fma_f32 v[0:1], v[2:3], v[28:29], v[0:1]
	v_pk_fma_f32 v[2:3], v[36:37], v[68:69], v[78:79]
	v_pk_fma_f32 v[6:7], v[40:41], v[72:73], v[80:81]
	v_pk_fma_f32 v[32:33], v[36:37], v[32:33], v[34:35]
	v_pk_fma_f32 v[28:29], v[40:41], v[28:29], v[38:39]
	v_pk_add_f32 v[0:1], v[4:5], v[0:1]
	v_pk_add_f32 v[2:3], v[2:3], v[6:7]
	v_pk_add_f32 v[4:5], v[32:33], v[28:29]
	s_waitcnt lgkmcnt(5)
; #define SCAN_STEP(w0, w1, a0, a1, b0, b1, k0, k1, r0, r1, vi, vj, t) do { \
;                 SCAN_ROW(S0, S1, S2, S3, w0, w1, a0, a1, b0, b1, k0, k1, r0, r1, vi, (t) * 512); \
;                 SCAN_ROW(T0, T1, T2, T3, w0, w1, a0, a1, b0, b1, k0, k1, r0, r1, vj, (t) * 512 + 256); } while (0)
;     ...
;             SCAN_LOAD(w0, w1, a0, a1, b0, b1, k0, k1, r0, r1, vi, vj, 0);
; #pragma unroll
;             for (int t = 0; t < 16; t += 2) {
;                 SCAN_LOAD(W0, W1, A0, A1, B0, B1, K0, K1, R0, R1, VI, VJ, t + 1);
;                 SCAN_STEP(w0, w1, a0, a1, b0, b1, k0, k1, r0, r1, vi, vj, t);
;                 if (t + 2 < 16) SCAN_LOAD(w0, w1, a0, a1, b0, b1, k0, k1, r0, r1, vi, vj, t + 2);
;                 SCAN_STEP(W0, W1, A0, A1, B0, B1, K0, K1, R0, R1, VI, VJ, t + 1);
;             }
	v_pk_fma_f32 v[40:41], v[50:51], v[88:89], v[8:9] op_sel_hi:[1,0,1]
	v_pk_add_f32 v[8:9], v[26:27], v[30:31]
	v_add_f32_e32 v0, v0, v1
	v_add_f32_e32 v1, v2, v3
	v_add_f32_e32 v2, v4, v5
	v_pk_fma_f32 v[68:69], v[52:53], v[86:87], v[82:83] op_sel_hi:[1,0,1]
	v_add_f32_e32 v6, v8, v9
	v_add_f32_dpp v82, v1, v1 quad_perm:[1,0,3,2] row_mask:0xf bank_mask:0xf bound_ctrl:1
	v_add_f32_dpp v83, v2, v2 quad_perm:[1,0,3,2] row_mask:0xf bank_mask:0xf bound_ctrl:1
	ds_write2st64_b32 v21, v6, v0 offset0:96 offset1:100
	v_add_f32_dpp v82, v82, v82 quad_perm:[2,3,0,1] row_mask:0xf bank_mask:0xf bound_ctrl:1
	v_add_f32_dpp v83, v83, v83 quad_perm:[2,3,0,1] row_mask:0xf bank_mask:0xf bound_ctrl:1
	v_pk_fma_f32 v[66:67], v[50:51], v[86:87], v[66:67] op_sel_hi:[1,0,1]
	s_waitcnt lgkmcnt(5)
	v_pk_fma_f32 v[70:71], v[54:55], v[86:87], v[70:71] op_sel_hi:[1,0,1]
	v_pk_fma_f32 v[72:73], v[56:57], v[86:87], v[84:85] op_sel_hi:[1,0,1]
	v_pk_fma_f32 v[74:75], v[52:53], v[88:89], v[10:11] op_sel_hi:[1,0,1]
	v_pk_fma_f32 v[76:77], v[54:55], v[88:89], v[12:13] op_sel_hi:[1,0,1]
	v_pk_fma_f32 v[78:79], v[56:57], v[88:89], v[14:15] op_sel_hi:[1,0,1]
	ds_read2_b32 v[80:81], v24 offset0:64 offset1:72
	ds_read_b128 v[0:3], v22 offset:22544
	ds_read_b128 v[4:7], v22 offset:22528
	ds_read_b128 v[8:11], v22 offset:22288
	ds_read_b128 v[12:15], v22 offset:22272
	ds_read_b128 v[24:27], v22 offset:22032
	ds_read_b128 v[28:31], v22 offset:22016
	ds_read_b128 v[32:35], v22 offset:21776
	ds_read_b128 v[36:39], v22 offset:21760
	ds_read_b128 v[50:53], v22 offset:21504
	ds_read_b128 v[54:57], v22 offset:21520
	v_add_f32_dpp v82, v82, v82 row_half_mirror row_mask:0xf bank_mask:0xf bound_ctrl:1
	v_add_f32_dpp v84, v83, v83 row_half_mirror row_mask:0xf bank_mask:0xf bound_ctrl:1
	s_waitcnt lgkmcnt(14)
	v_pk_fma_f32 v[66:67], v[42:43], v[82:83], v[66:67] op_sel_hi:[1,0,1]
	v_pk_fma_f32 v[68:69], v[44:45], v[82:83], v[68:69] op_sel_hi:[1,0,1]
	v_pk_fma_f32 v[70:71], v[46:47], v[82:83], v[70:71] op_sel_hi:[1,0,1]
	v_pk_fma_f32 v[40:41], v[42:43], v[84:85], v[40:41] op_sel_hi:[1,0,1]
	v_pk_fma_f32 v[42:43], v[44:45], v[84:85], v[74:75] op_sel_hi:[1,0,1]
	v_pk_fma_f32 v[44:45], v[46:47], v[84:85], v[76:77] op_sel_hi:[1,0,1]
	v_pk_fma_f32 v[72:73], v[48:49], v[82:83], v[72:73] op_sel_hi:[1,0,1]
	v_pk_fma_f32 v[46:47], v[48:49], v[84:85], v[78:79] op_sel_hi:[1,0,1]
	s_waitcnt lgkmcnt(12)
	v_pk_mul_f32 v[48:49], v[58:59], v[66:67]
	v_pk_mul_f32 v[74:75], v[62:63], v[70:71]
	v_pk_mul_f32 v[58:59], v[58:59], v[40:41]
	v_pk_mul_f32 v[62:63], v[62:63], v[44:45]
	v_pk_fma_f32 v[48:49], v[60:61], v[68:69], v[48:49]
	v_pk_fma_f32 v[74:75], v[64:65], v[72:73], v[74:75]
	v_pk_fma_f32 v[58:59], v[60:61], v[42:43], v[58:59]
	v_pk_fma_f32 v[60:61], v[64:65], v[46:47], v[62:63]
	v_pk_add_f32 v[48:49], v[48:49], v[74:75]
	v_pk_add_f32 v[58:59], v[58:59], v[60:61]
	s_waitcnt lgkmcnt(1)
	v_pk_mul_f32 v[60:61], v[36:37], v[66:67]
	v_pk_mul_f32 v[62:63], v[32:33], v[70:71]
	v_pk_mul_f32 v[36:37], v[36:37], v[40:41]
	v_pk_mul_f32 v[32:33], v[32:33], v[44:45]
	v_pk_mul_f32 v[64:65], v[50:51], v[66:67]
	v_pk_mul_f32 v[66:67], v[52:53], v[68:69]
	s_waitcnt lgkmcnt(0)
	v_pk_mul_f32 v[70:71], v[54:55], v[70:71]
	v_pk_mul_f32 v[74:75], v[56:57], v[72:73]
	v_pk_mul_f32 v[40:41], v[50:51], v[40:41]
	v_pk_mul_f32 v[50:51], v[52:53], v[42:43]
	v_pk_mul_f32 v[44:45], v[54:55], v[44:45]
	v_pk_mul_f32 v[52:53], v[56:57], v[46:47]
	v_add_f32_e32 v56, v48, v49
	v_pk_fma_f32 v[48:49], v[38:39], v[68:69], v[60:61]
	v_pk_fma_f32 v[54:55], v[34:35], v[72:73], v[62:63]
	v_pk_fma_f32 v[36:37], v[38:39], v[42:43], v[36:37]
	v_pk_fma_f32 v[32:33], v[34:35], v[46:47], v[32:33]
	v_mov_b32_e32 v76, v81
	v_add_f32_e32 v57, v58, v59
	v_pk_fma_f32 v[64:65], v[80:81], v[12:13], v[64:65] op_sel_hi:[0,1,1]
	v_pk_fma_f32 v[66:67], v[80:81], v[14:15], v[66:67] op_sel_hi:[0,1,1]
	v_pk_fma_f32 v[68:69], v[80:81], v[8:9], v[70:71] op_sel_hi:[0,1,1]
	v_pk_fma_f32 v[70:71], v[80:81], v[10:11], v[74:75] op_sel_hi:[0,1,1]
	v_pk_add_f32 v[80:81], v[54:55], v[48:49]
	v_pk_add_f32 v[82:83], v[32:33], v[36:37]
	ds_write2st64_b32 v21, v56, v57 offset0:104 offset1:108
	v_add_f32_e32 v80, v80, v81
	v_add_f32_e32 v81, v82, v83
	v_pk_fma_f32 v[72:73], v[76:77], v[12:13], v[40:41] op_sel_hi:[0,1,1]
	v_pk_fma_f32 v[74:75], v[76:77], v[14:15], v[50:51] op_sel_hi:[0,1,1]
	v_pk_fma_f32 v[78:79], v[76:77], v[8:9], v[44:45] op_sel_hi:[0,1,1]
	v_pk_fma_f32 v[76:77], v[76:77], v[10:11], v[52:53] op_sel_hi:[0,1,1]
	ds_read_b128 v[8:11], v22 offset:23040
	ds_read_b128 v[12:15], v22 offset:23056
	ds_read_b128 v[32:35], v22 offset:23296
	ds_read_b128 v[36:39], v22 offset:23312
	ds_read_b128 v[40:43], v22 offset:23552
	ds_read_b128 v[44:47], v22 offset:23568
	ds_read_b128 v[48:51], v22 offset:23808
	ds_read_b128 v[52:55], v22 offset:23824
	ds_read_b128 v[56:59], v22 offset:24064
	ds_read_b128 v[60:63], v22 offset:24080
	ds_read2_b32 v[22:23], v23 offset0:192 offset1:200
	v_add_f32_dpp v80, v80, v80 quad_perm:[1,0,3,2] row_mask:0xf bank_mask:0xf bound_ctrl:1
	v_add_f32_dpp v81, v81, v81 quad_perm:[1,0,3,2] row_mask:0xf bank_mask:0xf bound_ctrl:1
	s_add_i32 s7, s7, 1
	v_add_f32_dpp v80, v80, v80 quad_perm:[2,3,0,1] row_mask:0xf bank_mask:0xf bound_ctrl:1
	v_add_f32_dpp v81, v81, v81 quad_perm:[2,3,0,1] row_mask:0xf bank_mask:0xf bound_ctrl:1
	s_waitcnt lgkmcnt(0)
; #define SCAN_STEP(w0, w1, a0, a1, b0, b1, k0, k1, r0, r1, vi, vj, t) do { \
;                 SCAN_ROW(S0, S1, S2, S3, w0, w1, a0, a1, b0, b1, k0, k1, r0, r1, vi, (t) * 512); \
;                 SCAN_ROW(T0, T1, T2, T3, w0, w1, a0, a1, b0, b1, k0, k1, r0, r1, vj, (t) * 512 + 256); } while (0)
;     ...
;             SCAN_LOAD(w0, w1, a0, a1, b0, b1, k0, k1, r0, r1, vi, vj, 0);
; #pragma unroll
;             for (int t = 0; t < 16; t += 2) {
;                 SCAN_LOAD(W0, W1, A0, A1, B0, B1, K0, K1, R0, R1, VI, VJ, t + 1);
;                 SCAN_STEP(w0, w1, a0, a1, b0, b1, k0, k1, r0, r1, vi, vj, t);
;                 if (t + 2 < 16) SCAN_LOAD(w0, w1, a0, a1, b0, b1, k0, k1, r0, r1, vi, vj, t + 2);
;                 SCAN_STEP(W0, W1, A0, A1, B0, B1, K0, K1, R0, R1, VI, VJ, t + 1);
;             }
;     ...
;             __syncthreads();
;         }
;         float* so = P.out + (samp ? O_RS + ((size_t)(l * 16 + b) * 16 + h) * 4096 : O_RP + ((size_t)(l * 4 + b) * 16 + h) * 4096) + js;
;         f32x4 o0, o1; o0.xy = S0; o0.zw = S1; o1.xy = S2; o1.zw = S3;
;         *(f32x4*)(so + i0 * 64) = o0; *(f32x4*)(so + i0 * 64 + 4) = o1;
;         o0.xy = T0; o0.zw = T1; o1.xy = T2; o1.zw = T3;
;         *(f32x4*)(so + i1 * 64) = o0; *(f32x4*)(so + i1 * 64 + 4) = o1;
	v_mov_b32_e32 v84, v23
	v_add_f32_dpp v80, v80, v80 row_half_mirror row_mask:0xf bank_mask:0xf bound_ctrl:1
	v_add_f32_dpp v82, v81, v81 row_half_mirror row_mask:0xf bank_mask:0xf bound_ctrl:1
	v_pk_fma_f32 v[64:65], v[28:29], v[80:81], v[64:65] op_sel_hi:[1,0,1]
	v_pk_fma_f32 v[68:69], v[24:25], v[80:81], v[68:69] op_sel_hi:[1,0,1]
	v_pk_fma_f32 v[28:29], v[28:29], v[82:83], v[72:73] op_sel_hi:[1,0,1]
	v_pk_fma_f32 v[24:25], v[24:25], v[82:83], v[78:79] op_sel_hi:[1,0,1]
	v_pk_fma_f32 v[66:67], v[30:31], v[80:81], v[66:67] op_sel_hi:[1,0,1]
	v_pk_fma_f32 v[70:71], v[26:27], v[80:81], v[70:71] op_sel_hi:[1,0,1]
	v_pk_fma_f32 v[30:31], v[30:31], v[82:83], v[74:75] op_sel_hi:[1,0,1]
	v_pk_fma_f32 v[26:27], v[26:27], v[82:83], v[76:77] op_sel_hi:[1,0,1]
	v_pk_mul_f32 v[72:73], v[4:5], v[64:65]
	v_pk_mul_f32 v[74:75], v[0:1], v[68:69]
	v_pk_mul_f32 v[4:5], v[4:5], v[28:29]
	v_pk_mul_f32 v[0:1], v[0:1], v[24:25]
	v_pk_mul_f32 v[76:77], v[32:33], v[64:65]
	v_pk_mul_f32 v[78:79], v[36:37], v[68:69]
	v_pk_mul_f32 v[32:33], v[32:33], v[28:29]
	v_pk_mul_f32 v[36:37], v[36:37], v[24:25]
	v_pk_mul_f32 v[64:65], v[8:9], v[64:65]
	v_pk_mul_f32 v[80:81], v[10:11], v[66:67]
	v_pk_mul_f32 v[68:69], v[12:13], v[68:69]
	v_pk_mul_f32 v[82:83], v[14:15], v[70:71]
	v_pk_mul_f32 v[8:9], v[8:9], v[28:29]
	v_pk_mul_f32 v[10:11], v[10:11], v[30:31]
	v_pk_mul_f32 v[12:13], v[12:13], v[24:25]
	v_pk_mul_f32 v[14:15], v[14:15], v[26:27]
	v_pk_fma_f32 v[24:25], v[6:7], v[66:67], v[72:73]
	v_pk_fma_f32 v[28:29], v[2:3], v[70:71], v[74:75]
	v_pk_fma_f32 v[4:5], v[6:7], v[30:31], v[4:5]
	v_pk_fma_f32 v[0:1], v[2:3], v[26:27], v[0:1]
	v_pk_fma_f32 v[2:3], v[34:35], v[66:67], v[76:77]
	v_pk_fma_f32 v[6:7], v[38:39], v[70:71], v[78:79]
	v_pk_fma_f32 v[30:31], v[34:35], v[30:31], v[32:33]
	v_pk_fma_f32 v[26:27], v[38:39], v[26:27], v[36:37]
	v_pk_fma_f32 v[32:33], v[48:49], v[84:85], v[8:9] op_sel_hi:[1,0,1]
	v_pk_add_f32 v[8:9], v[24:25], v[28:29]
	v_pk_add_f32 v[0:1], v[4:5], v[0:1]
	v_pk_add_f32 v[2:3], v[2:3], v[6:7]
	v_pk_add_f32 v[4:5], v[30:31], v[26:27]
	v_add_f32_e32 v6, v8, v9
	v_add_f32_e32 v0, v0, v1
	v_add_f32_e32 v1, v2, v3
	v_add_f32_e32 v2, v4, v5
	ds_write2st64_b32 v21, v6, v0 offset0:112 offset1:116
	v_add_f32_dpp v0, v1, v1 quad_perm:[1,0,3,2] row_mask:0xf bank_mask:0xf bound_ctrl:1
	v_add_f32_dpp v1, v2, v2 quad_perm:[1,0,3,2] row_mask:0xf bank_mask:0xf bound_ctrl:1
	v_pk_fma_f32 v[64:65], v[48:49], v[22:23], v[64:65] op_sel_hi:[1,0,1]
	v_add_f32_dpp v0, v0, v0 quad_perm:[2,3,0,1] row_mask:0xf bank_mask:0xf bound_ctrl:1
	v_add_f32_dpp v1, v1, v1 quad_perm:[2,3,0,1] row_mask:0xf bank_mask:0xf bound_ctrl:1
	v_pk_fma_f32 v[66:67], v[50:51], v[22:23], v[80:81] op_sel_hi:[1,0,1]
	v_pk_fma_f32 v[68:69], v[52:53], v[22:23], v[68:69] op_sel_hi:[1,0,1]
	v_pk_fma_f32 v[22:23], v[54:55], v[22:23], v[82:83] op_sel_hi:[1,0,1]
	v_pk_fma_f32 v[36:37], v[52:53], v[84:85], v[12:13] op_sel_hi:[1,0,1]
	v_add_f32_dpp v0, v0, v0 row_half_mirror row_mask:0xf bank_mask:0xf bound_ctrl:1
	v_add_f32_dpp v6, v1, v1 row_half_mirror row_mask:0xf bank_mask:0xf bound_ctrl:1
	v_pk_fma_f32 v[34:35], v[50:51], v[84:85], v[10:11] op_sel_hi:[1,0,1]
	v_pk_fma_f32 v[38:39], v[54:55], v[84:85], v[14:15] op_sel_hi:[1,0,1]
	v_pk_fma_f32 v[12:13], v[40:41], v[0:1], v[64:65] op_sel_hi:[1,0,1]
	v_pk_fma_f32 v[14:15], v[42:43], v[0:1], v[66:67] op_sel_hi:[1,0,1]
	v_pk_fma_f32 v[8:9], v[44:45], v[0:1], v[68:69] op_sel_hi:[1,0,1]
	v_pk_fma_f32 v[10:11], v[46:47], v[0:1], v[22:23] op_sel_hi:[1,0,1]
	v_pk_fma_f32 v[0:1], v[40:41], v[6:7], v[32:33] op_sel_hi:[1,0,1]
	v_pk_fma_f32 v[4:5], v[44:45], v[6:7], v[36:37] op_sel_hi:[1,0,1]
	v_pk_fma_f32 v[2:3], v[42:43], v[6:7], v[34:35] op_sel_hi:[1,0,1]
	v_pk_fma_f32 v[6:7], v[46:47], v[6:7], v[38:39] op_sel_hi:[1,0,1]
	v_pk_mul_f32 v[22:23], v[56:57], v[12:13]
	v_pk_mul_f32 v[24:25], v[60:61], v[8:9]
	v_pk_mul_f32 v[26:27], v[56:57], v[0:1]
	v_pk_mul_f32 v[28:29], v[60:61], v[4:5]
	v_pk_fma_f32 v[22:23], v[58:59], v[14:15], v[22:23]
	v_pk_fma_f32 v[24:25], v[62:63], v[10:11], v[24:25]
	v_pk_fma_f32 v[26:27], v[58:59], v[2:3], v[26:27]
	v_pk_fma_f32 v[28:29], v[62:63], v[6:7], v[28:29]
	v_pk_add_f32 v[22:23], v[22:23], v[24:25]
	v_pk_add_f32 v[24:25], v[26:27], v[28:29]
	s_cmpk_eq_i32 s7, 0x100
	v_add_f32_e32 v22, v22, v23
	v_add_f32_e32 v23, v24, v25
	ds_write2st64_b32 v21, v22, v23 offset0:120 offset1:124
	s_waitcnt lgkmcnt(0)
	s_barrier
	s_cbranch_scc0 .LBB0_4119
	s_add_u32 s3, s72, s3
	s_addc_u32 s4, s73, s6
	s_add_u32 s2, s3, s2
	s_addc_u32 s3, s4, 0
	v_lshlrev_b32_e32 v16, 2, v16
	v_mov_b32_e32 v17, 0
	v_lshl_add_u64 v[16:17], s[2:3], 0, v[16:17]
	v_lshl_add_u64 v[16:17], v[18:19], 2, v[16:17]
	s_mov_b64 s[2:3], 0x8500000
	v_lshl_add_u64 v[18:19], v[16:17], 0, s[2:3]
	v_add_co_u32_e32 v16, vcc, 0x8500000, v16
	s_nop 1
	v_addc_co_u32_e32 v17, vcc, 0, v17, vcc
	global_store_dwordx4 v[16:17], v[12:15], off
	global_store_dwordx4 v[18:19], v[8:11], off offset:16
	global_store_dwordx4 v[18:19], v[0:3], off offset:2048
	global_store_dwordx4 v[18:19], v[4:7], off offset:2064
